# hand-written S5 passes: per-layer twiddle/power tables built once at PREP1, PASS-1 and PASS-3 items with prefetched params, DPP cumsum scan instead of Kogge-Stone with selects
# speedup vs baseline: 1.2151x; 1.0771x over previous
.LBB0_388:
	s_bitcmp0_b32 s94, 12
	s_cbranch_scc1 .LBB0_436
	v_readlane_b32 s36, v245, 21
	s_mov_b32 s37, 0
.Lss3_top:
	s_cmp_lt_u32 s36, 0x1000
	s_cbranch_scc1 .Lss3_body
	s_cmp_eq_u32 s37, 1
	s_cbranch_scc1 .Lss3_done
	v_readlane_b32 s0, v245, 17
	v_readlane_b32 s1, v245, 18
	s_mov_b32 s37, 1
	s_and_b64 vcc, exec, s[0:1]
	s_cbranch_vccz .Lss3_done
	v_readlane_b32 s36, v246, 0
.Lss3_body:
	s_mul_i32 s10, s36, 0xf0f1
	s_lshr_b32 s10, s10, 22
	s_mul_i32 s11, s10, 68
	s_sub_i32 s8, s36, s11
	s_and_b32 s7, s10, 15
	s_lshr_b32 s6, s10, 4
	s_lshl_b32 s10, s8, 6
	s_lshl_b32 s11, s6, 8
	s_add_i32 s9, s10, s11
	s_lshl_b32 s11, s6, 12
	s_add_i32 s11, s11, s10
	s_add_i32 s11, s11, 0x300
	s_cmp_lt_u32 s8, 4
	s_cselect_b32 s9, s9, s11
	v_mov_b32_e32 v0, 0
	v_mov_b32_e32 v1, 0
	v_mov_b32_e32 v2, 0
	v_mov_b32_e32 v3, 0
	v_mov_b32_e32 v4, 0
	v_mov_b32_e32 v5, 0
	v_mov_b32_e32 v6, 0
	v_mov_b32_e32 v7, 0
	v_mov_b32_e32 v8, 0
	v_mov_b32_e32 v9, 0
	v_mov_b32_e32 v10, 0
	v_mov_b32_e32 v11, 0
	v_mov_b32_e32 v12, 0
	v_mov_b32_e32 v13, 0
	v_mov_b32_e32 v14, 0
	v_mov_b32_e32 v15, 0
	v_and_b32_e32 v207, 15, v205
	v_mul_u32_u24_e32 v207, 0xe00, v207
	v_and_b32_e32 v208, 16, v205
	v_add_u32_e32 v207, v207, v208
	s_mul_i32 s18, s9, 0xe00
	s_lshl_b32 s19, s7, 5
	s_add_i32 s18, s18, s19
	s_add_u32 s18, s18, 0x5e00c00
	s_add_u32 s18, s4, s18
	s_addc_u32 s19, s5, 0
	s_mov_b32 exec_hi, 0
	global_load_dwordx4 v[0:3], v207, s[18:19]
	s_add_u32 s18, s18, 0xe000
	s_addc_u32 s19, s19, 0
	global_load_dwordx4 v[4:7], v207, s[18:19]
	s_add_u32 s18, s18, 0xe000
	s_addc_u32 s19, s19, 0
	global_load_dwordx4 v[8:11], v207, s[18:19]
	s_add_u32 s18, s18, 0xe000
	s_addc_u32 s19, s19, 0
	global_load_dwordx4 v[12:15], v207, s[18:19]
	s_mov_b64 exec, -1
	v_mov_b32_e32 v64, 0
	v_mov_b32_e32 v65, 0
	v_mov_b32_e32 v66, 0
	v_mov_b32_e32 v67, 0
	v_mov_b32_e32 v68, 0
	v_mov_b32_e32 v69, 0
	v_mov_b32_e32 v70, 0
	v_mov_b32_e32 v71, 0
	v_mov_b32_e32 v72, 0
	v_mov_b32_e32 v73, 0
	v_mov_b32_e32 v74, 0
	v_mov_b32_e32 v75, 0
	v_mov_b32_e32 v76, 0
	v_mov_b32_e32 v77, 0
	v_mov_b32_e32 v78, 0
	v_mov_b32_e32 v79, 0
	v_lshlrev_b32_e32 v134, 7, v205
	v_and_b32_e32 v135, 15, v205
	v_lshlrev_b32_e32 v136, 8, v135
	v_lshlrev_b32_e32 v135, 6, v135
	v_and_b32_e32 v207, 16, v205
	v_lshl_add_u32 v135, v207, 1, v135
	v_lshrrev_b32_e32 v207, 4, v205
	v_lshl_add_u32 v136, v207, 4, v136
	v_lshlrev_b32_e32 v206, 5, v207
	v_readlane_b32 s10, v247, 28
	s_mov_b32 s11, s8
	s_lshl_b32 s16, s10, 1
	s_add_i32 s16, s16, 0
	s_lshl_b32 s16, s16, 4
	s_add_i32 s16, s16, s7
	s_lshl_b32 s17, s6, 1
	s_add_i32 s17, s17, 0
	s_lshl_b32 s17, s17, 4
	s_add_i32 s17, s17, s7
	s_mul_i32 s17, s17, 68
	s_add_i32 s17, s17, s11
	s_lshl_b32 s17, s17, 6
	s_lshl_b32 s20, s16, 12
	s_add_u32 s20, s20, 0x11fb20
	s_add_u32 s20, s4, s20
	s_addc_u32 s21, s5, 0
	s_add_u32 s22, s20, 0x40000
	s_addc_u32 s23, s21, 0
	s_lshl_b32 s38, s16, 12
	s_add_u32 s38, s38, 0x19fb20
	s_add_u32 s38, s4, s38
	s_addc_u32 s39, s5, 0
	s_add_u32 s40, s38, 0x40000
	s_addc_u32 s41, s39, 0
	s_lshl_b32 s42, s16, 15
	s_add_u32 s42, s42, 0xf900000
	s_add_u32 s42, s4, s42
	s_addc_u32 s43, s5, 0
	s_lshl_b32 s44, s17, 3
	s_add_u32 s44, s44, 0x740000
	s_add_u32 s44, s4, s44
	s_addc_u32 s45, s5, 0
	s_mov_b32 exec_hi, 0
	global_load_dwordx4 v[64:67], v135, s[20:21]
	global_load_dwordx4 v[68:71], v135, s[20:21] offset:16
	global_load_dwordx4 v[72:75], v135, s[22:23]
	global_load_dwordx4 v[76:79], v135, s[22:23] offset:16
	s_mov_b64 exec, -1
	s_add_u32 s20, s20, 0x400
	s_addc_u32 s21, s21, 0
	s_add_u32 s22, s22, 0x400
	s_addc_u32 s23, s23, 0
	global_load_dwordx4 v[138:141], v134, s[42:43] offset:0
	global_load_dwordx4 v[142:145], v134, s[42:43] offset:16
	global_load_dwordx4 v[146:149], v134, s[42:43] offset:32
	global_load_dwordx4 v[150:153], v134, s[42:43] offset:48
	global_load_dwordx4 v[154:157], v134, s[42:43] offset:64
	global_load_dwordx4 v[158:161], v134, s[42:43] offset:80
	global_load_dwordx4 v[162:165], v134, s[42:43] offset:96
	global_load_dwordx4 v[166:169], v134, s[42:43] offset:112
	global_load_dwordx4 v[170:173], v206, s[44:45]
	global_load_dwordx4 v[174:177], v206, s[44:45] offset:16
	s_add_u32 s42, s42, 0x2000
	s_addc_u32 s43, s43, 0
	s_add_u32 s44, s44, 0x80
	s_addc_u32 s45, s45, 0
	s_waitcnt vmcnt(14)
	s_waitcnt vmcnt(10)
	v_cvt_pk_bf16_f32 v64, v64, v65
	v_cvt_pk_bf16_f32 v65, v66, v67
	v_cvt_pk_bf16_f32 v66, v68, v69
	v_cvt_pk_bf16_f32 v67, v70, v71
	v_cvt_pk_bf16_f32 v72, v72, v73
	v_cvt_pk_bf16_f32 v73, v74, v75
	v_cvt_pk_bf16_f32 v74, v76, v77
	v_cvt_pk_bf16_f32 v75, v78, v79
	global_load_dwordx4 v[80:83], v136, s[38:39]
	global_load_dwordx4 v[84:87], v136, s[40:41]
	s_add_u32 s38, s38, 0x40
	s_addc_u32 s39, s39, 0
	s_add_u32 s40, s40, 0x40
	s_addc_u32 s41, s41, 0
	s_nop 0
	v_mfma_f32_16x16x32_bf16 v[32:35], v[64:67], v[0:3], 0
	v_mfma_f32_16x16x32_bf16 v[36:39], v[72:75], v[0:3], 0
	v_mfma_f32_16x16x32_bf16 v[40:43], v[64:67], v[4:7], 0
	v_mfma_f32_16x16x32_bf16 v[44:47], v[72:75], v[4:7], 0
	v_mfma_f32_16x16x32_bf16 v[48:51], v[64:67], v[8:11], 0
	v_mfma_f32_16x16x32_bf16 v[52:55], v[72:75], v[8:11], 0
	v_mfma_f32_16x16x32_bf16 v[56:59], v[64:67], v[12:15], 0
	v_mfma_f32_16x16x32_bf16 v[60:63], v[72:75], v[12:15], 0
	s_mov_b32 exec_hi, 0
	global_load_dwordx4 v[64:67], v135, s[20:21]
	global_load_dwordx4 v[68:71], v135, s[20:21] offset:16
	global_load_dwordx4 v[72:75], v135, s[22:23]
	global_load_dwordx4 v[76:79], v135, s[22:23] offset:16
	s_mov_b64 exec, -1
	s_add_u32 s20, s20, 0x400
	s_addc_u32 s21, s21, 0
	s_add_u32 s22, s22, 0x400
	s_addc_u32 s23, s23, 0
	global_load_dwordx4 v[100:103], v134, s[42:43] offset:0
	global_load_dwordx4 v[104:107], v134, s[42:43] offset:16
	global_load_dwordx4 v[108:111], v134, s[42:43] offset:32
	global_load_dwordx4 v[112:115], v134, s[42:43] offset:48
	global_load_dwordx4 v[116:119], v134, s[42:43] offset:64
	global_load_dwordx4 v[120:123], v134, s[42:43] offset:80
	global_load_dwordx4 v[124:127], v134, s[42:43] offset:96
	global_load_dwordx4 v[128:131], v134, s[42:43] offset:112
	global_load_dwordx4 v[178:181], v206, s[44:45]
	global_load_dwordx4 v[182:185], v206, s[44:45] offset:16
	s_add_u32 s42, s42, 0x2000
	s_addc_u32 s43, s43, 0
	s_add_u32 s44, s44, 0x80
	s_addc_u32 s45, s45, 0
	s_waitcnt vmcnt(16)
	v_mul_f32_e32 v132, v171, v157
	v_mul_f32_e32 v133, v170, v157
	v_fma_f32 v170, v170, v156, -v132
	v_fma_f32 v171, v171, v156, v133
	v_mul_f32_e32 v132, v173, v161
	v_mul_f32_e32 v133, v172, v161
	v_fma_f32 v172, v172, v160, -v132
	v_fma_f32 v173, v173, v160, v133
	v_mul_f32_e32 v132, v175, v165
	v_mul_f32_e32 v133, v174, v165
	v_fma_f32 v174, v174, v164, -v132
	v_fma_f32 v175, v175, v164, v133
	v_mul_f32_e32 v132, v177, v169
	v_mul_f32_e32 v133, v176, v169
	v_fma_f32 v176, v176, v168, -v132
	v_fma_f32 v177, v177, v168, v133
	v_mul_f32_e32 v132, v32, v139
	v_mul_f32_e32 v32, v32, v138
	v_fma_f32 v32, -v36, v139, v32
	v_fma_f32 v36, v36, v138, v132
	v_mul_f32_e32 v133, v33, v143
	v_mul_f32_e32 v33, v33, v142
	v_fma_f32 v33, -v37, v143, v33
	v_fma_f32 v37, v37, v142, v133
	v_mul_f32_e32 v132, v34, v147
	v_mul_f32_e32 v34, v34, v146
	v_fma_f32 v34, -v38, v147, v34
	v_fma_f32 v38, v38, v146, v132
	v_mul_f32_e32 v133, v35, v151
	v_mul_f32_e32 v35, v35, v150
	v_fma_f32 v35, -v39, v151, v35
	v_fma_f32 v39, v39, v150, v133
	v_mov_b32_e32 v88, v32
	v_mov_b32_e32 v89, v33
	v_mov_b32_e32 v90, v34
	v_mov_b32_e32 v91, v35
	v_mov_b32_e32 v92, v36
	v_mov_b32_e32 v93, v37
	v_mov_b32_e32 v94, v38
	v_mov_b32_e32 v95, v39
	v_add_f32_dpp v32, v32, v32 row_shr:1 row_mask:0xf bank_mask:0xf bound_ctrl:1
	v_add_f32_dpp v33, v33, v33 row_shr:1 row_mask:0xf bank_mask:0xf bound_ctrl:1
	v_add_f32_dpp v34, v34, v34 row_shr:1 row_mask:0xf bank_mask:0xf bound_ctrl:1
	v_add_f32_dpp v35, v35, v35 row_shr:1 row_mask:0xf bank_mask:0xf bound_ctrl:1
	v_add_f32_dpp v36, v36, v36 row_shr:1 row_mask:0xf bank_mask:0xf bound_ctrl:1
	v_add_f32_dpp v37, v37, v37 row_shr:1 row_mask:0xf bank_mask:0xf bound_ctrl:1
	v_add_f32_dpp v38, v38, v38 row_shr:1 row_mask:0xf bank_mask:0xf bound_ctrl:1
	v_add_f32_dpp v39, v39, v39 row_shr:1 row_mask:0xf bank_mask:0xf bound_ctrl:1
	v_add_f32_dpp v88, v88, v88 row_ror:8 row_mask:0xf bank_mask:0xf
	v_add_f32_dpp v89, v89, v89 row_ror:8 row_mask:0xf bank_mask:0xf
	v_add_f32_dpp v90, v90, v90 row_ror:8 row_mask:0xf bank_mask:0xf
	v_add_f32_dpp v91, v91, v91 row_ror:8 row_mask:0xf bank_mask:0xf
	v_add_f32_dpp v92, v92, v92 row_ror:8 row_mask:0xf bank_mask:0xf
	v_add_f32_dpp v93, v93, v93 row_ror:8 row_mask:0xf bank_mask:0xf
	v_add_f32_dpp v94, v94, v94 row_ror:8 row_mask:0xf bank_mask:0xf
	v_add_f32_dpp v95, v95, v95 row_ror:8 row_mask:0xf bank_mask:0xf
	v_add_f32_dpp v32, v32, v32 row_shr:2 row_mask:0xf bank_mask:0xf bound_ctrl:1
	v_add_f32_dpp v33, v33, v33 row_shr:2 row_mask:0xf bank_mask:0xf bound_ctrl:1
	v_add_f32_dpp v34, v34, v34 row_shr:2 row_mask:0xf bank_mask:0xf bound_ctrl:1
	v_add_f32_dpp v35, v35, v35 row_shr:2 row_mask:0xf bank_mask:0xf bound_ctrl:1
	v_add_f32_dpp v36, v36, v36 row_shr:2 row_mask:0xf bank_mask:0xf bound_ctrl:1
	v_add_f32_dpp v37, v37, v37 row_shr:2 row_mask:0xf bank_mask:0xf bound_ctrl:1
	v_add_f32_dpp v38, v38, v38 row_shr:2 row_mask:0xf bank_mask:0xf bound_ctrl:1
	v_add_f32_dpp v39, v39, v39 row_shr:2 row_mask:0xf bank_mask:0xf bound_ctrl:1
	v_add_f32_dpp v88, v88, v88 row_ror:4 row_mask:0xf bank_mask:0xf
	v_add_f32_dpp v89, v89, v89 row_ror:4 row_mask:0xf bank_mask:0xf
	v_add_f32_dpp v90, v90, v90 row_ror:4 row_mask:0xf bank_mask:0xf
	v_add_f32_dpp v91, v91, v91 row_ror:4 row_mask:0xf bank_mask:0xf
	v_add_f32_dpp v92, v92, v92 row_ror:4 row_mask:0xf bank_mask:0xf
	v_add_f32_dpp v93, v93, v93 row_ror:4 row_mask:0xf bank_mask:0xf
	v_add_f32_dpp v94, v94, v94 row_ror:4 row_mask:0xf bank_mask:0xf
	v_add_f32_dpp v95, v95, v95 row_ror:4 row_mask:0xf bank_mask:0xf
	v_add_f32_dpp v32, v32, v32 row_shr:4 row_mask:0xf bank_mask:0xf bound_ctrl:1
	v_add_f32_dpp v33, v33, v33 row_shr:4 row_mask:0xf bank_mask:0xf bound_ctrl:1
	v_add_f32_dpp v34, v34, v34 row_shr:4 row_mask:0xf bank_mask:0xf bound_ctrl:1
	v_add_f32_dpp v35, v35, v35 row_shr:4 row_mask:0xf bank_mask:0xf bound_ctrl:1
	v_add_f32_dpp v36, v36, v36 row_shr:4 row_mask:0xf bank_mask:0xf bound_ctrl:1
	v_add_f32_dpp v37, v37, v37 row_shr:4 row_mask:0xf bank_mask:0xf bound_ctrl:1
	v_add_f32_dpp v38, v38, v38 row_shr:4 row_mask:0xf bank_mask:0xf bound_ctrl:1
	v_add_f32_dpp v39, v39, v39 row_shr:4 row_mask:0xf bank_mask:0xf bound_ctrl:1
	v_add_f32_dpp v88, v88, v88 row_ror:2 row_mask:0xf bank_mask:0xf
	v_add_f32_dpp v89, v89, v89 row_ror:2 row_mask:0xf bank_mask:0xf
	v_add_f32_dpp v90, v90, v90 row_ror:2 row_mask:0xf bank_mask:0xf
	v_add_f32_dpp v91, v91, v91 row_ror:2 row_mask:0xf bank_mask:0xf
	v_add_f32_dpp v92, v92, v92 row_ror:2 row_mask:0xf bank_mask:0xf
	v_add_f32_dpp v93, v93, v93 row_ror:2 row_mask:0xf bank_mask:0xf
	v_add_f32_dpp v94, v94, v94 row_ror:2 row_mask:0xf bank_mask:0xf
	v_add_f32_dpp v95, v95, v95 row_ror:2 row_mask:0xf bank_mask:0xf
	v_add_f32_dpp v32, v32, v32 row_shr:8 row_mask:0xf bank_mask:0xf bound_ctrl:1
	v_add_f32_dpp v33, v33, v33 row_shr:8 row_mask:0xf bank_mask:0xf bound_ctrl:1
	v_add_f32_dpp v34, v34, v34 row_shr:8 row_mask:0xf bank_mask:0xf bound_ctrl:1
	v_add_f32_dpp v35, v35, v35 row_shr:8 row_mask:0xf bank_mask:0xf bound_ctrl:1
	v_add_f32_dpp v36, v36, v36 row_shr:8 row_mask:0xf bank_mask:0xf bound_ctrl:1
	v_add_f32_dpp v37, v37, v37 row_shr:8 row_mask:0xf bank_mask:0xf bound_ctrl:1
	v_add_f32_dpp v38, v38, v38 row_shr:8 row_mask:0xf bank_mask:0xf bound_ctrl:1
	v_add_f32_dpp v39, v39, v39 row_shr:8 row_mask:0xf bank_mask:0xf bound_ctrl:1
	v_add_f32_dpp v88, v88, v88 row_ror:1 row_mask:0xf bank_mask:0xf
	v_add_f32_dpp v89, v89, v89 row_ror:1 row_mask:0xf bank_mask:0xf
	v_add_f32_dpp v90, v90, v90 row_ror:1 row_mask:0xf bank_mask:0xf
	v_add_f32_dpp v91, v91, v91 row_ror:1 row_mask:0xf bank_mask:0xf
	v_add_f32_dpp v92, v92, v92 row_ror:1 row_mask:0xf bank_mask:0xf
	v_add_f32_dpp v93, v93, v93 row_ror:1 row_mask:0xf bank_mask:0xf
	v_add_f32_dpp v94, v94, v94 row_ror:1 row_mask:0xf bank_mask:0xf
	v_add_f32_dpp v95, v95, v95 row_ror:1 row_mask:0xf bank_mask:0xf
	v_add_f32_e32 v32, v32, v170
	v_add_f32_e32 v36, v36, v171
	v_add_f32_e32 v33, v33, v172
	v_add_f32_e32 v37, v37, v173
	v_add_f32_e32 v34, v34, v174
	v_add_f32_e32 v38, v38, v175
	v_add_f32_e32 v35, v35, v176
	v_add_f32_e32 v39, v39, v177
	v_mul_f32_e32 v132, v32, v141
	v_mul_f32_e32 v32, v32, v140
	v_fma_f32 v32, -v36, v141, v32
	v_fma_f32 v36, v36, v140, v132
	v_mul_f32_e32 v133, v33, v145
	v_mul_f32_e32 v33, v33, v144
	v_fma_f32 v33, -v37, v145, v33
	v_fma_f32 v37, v37, v144, v133
	v_mul_f32_e32 v132, v34, v149
	v_mul_f32_e32 v34, v34, v148
	v_fma_f32 v34, -v38, v149, v34
	v_fma_f32 v38, v38, v148, v132
	v_mul_f32_e32 v133, v35, v153
	v_mul_f32_e32 v35, v35, v152
	v_fma_f32 v35, -v39, v153, v35
	v_fma_f32 v39, v39, v152, v133
	v_add_f32_e32 v88, v88, v170
	v_add_f32_e32 v92, v92, v171
	v_mul_f32_e32 v132, v92, v155
	v_mul_f32_e32 v171, v88, v155
	v_fma_f32 v170, v88, v154, -v132
	v_fma_f32 v171, v92, v154, v171
	v_add_f32_e32 v89, v89, v172
	v_add_f32_e32 v93, v93, v173
	v_mul_f32_e32 v133, v93, v159
	v_mul_f32_e32 v173, v89, v159
	v_fma_f32 v172, v89, v158, -v133
	v_fma_f32 v173, v93, v158, v173
	v_add_f32_e32 v90, v90, v174
	v_add_f32_e32 v94, v94, v175
	v_mul_f32_e32 v132, v94, v163
	v_mul_f32_e32 v175, v90, v163
	v_fma_f32 v174, v90, v162, -v132
	v_fma_f32 v175, v94, v162, v175
	v_add_f32_e32 v91, v91, v176
	v_add_f32_e32 v95, v95, v177
	v_mul_f32_e32 v133, v95, v167
	v_mul_f32_e32 v177, v91, v167
	v_fma_f32 v176, v91, v166, -v133
	v_fma_f32 v177, v95, v166, v177
	v_mul_f32_e32 v132, v40, v139
	v_mul_f32_e32 v40, v40, v138
	v_fma_f32 v40, -v44, v139, v40
	v_fma_f32 v44, v44, v138, v132
	v_mul_f32_e32 v133, v41, v143
	v_mul_f32_e32 v41, v41, v142
	v_fma_f32 v41, -v45, v143, v41
	v_fma_f32 v45, v45, v142, v133
	v_mul_f32_e32 v132, v42, v147
	v_mul_f32_e32 v42, v42, v146
	v_fma_f32 v42, -v46, v147, v42
	v_fma_f32 v46, v46, v146, v132
	v_mul_f32_e32 v133, v43, v151
	v_mul_f32_e32 v43, v43, v150
	v_fma_f32 v43, -v47, v151, v43
	v_fma_f32 v47, v47, v150, v133
	v_mov_b32_e32 v88, v40
	v_mov_b32_e32 v89, v41
	v_mov_b32_e32 v90, v42
	v_mov_b32_e32 v91, v43
	v_mov_b32_e32 v92, v44
	v_mov_b32_e32 v93, v45
	v_mov_b32_e32 v94, v46
	v_mov_b32_e32 v95, v47
	v_add_f32_dpp v40, v40, v40 row_shr:1 row_mask:0xf bank_mask:0xf bound_ctrl:1
	v_add_f32_dpp v41, v41, v41 row_shr:1 row_mask:0xf bank_mask:0xf bound_ctrl:1
	v_add_f32_dpp v42, v42, v42 row_shr:1 row_mask:0xf bank_mask:0xf bound_ctrl:1
	v_add_f32_dpp v43, v43, v43 row_shr:1 row_mask:0xf bank_mask:0xf bound_ctrl:1
	v_add_f32_dpp v44, v44, v44 row_shr:1 row_mask:0xf bank_mask:0xf bound_ctrl:1
	v_add_f32_dpp v45, v45, v45 row_shr:1 row_mask:0xf bank_mask:0xf bound_ctrl:1
	v_add_f32_dpp v46, v46, v46 row_shr:1 row_mask:0xf bank_mask:0xf bound_ctrl:1
	v_add_f32_dpp v47, v47, v47 row_shr:1 row_mask:0xf bank_mask:0xf bound_ctrl:1
	v_add_f32_dpp v88, v88, v88 row_ror:8 row_mask:0xf bank_mask:0xf
	v_add_f32_dpp v89, v89, v89 row_ror:8 row_mask:0xf bank_mask:0xf
	v_add_f32_dpp v90, v90, v90 row_ror:8 row_mask:0xf bank_mask:0xf
	v_add_f32_dpp v91, v91, v91 row_ror:8 row_mask:0xf bank_mask:0xf
	v_add_f32_dpp v92, v92, v92 row_ror:8 row_mask:0xf bank_mask:0xf
	v_add_f32_dpp v93, v93, v93 row_ror:8 row_mask:0xf bank_mask:0xf
	v_add_f32_dpp v94, v94, v94 row_ror:8 row_mask:0xf bank_mask:0xf
	v_add_f32_dpp v95, v95, v95 row_ror:8 row_mask:0xf bank_mask:0xf
	v_add_f32_dpp v40, v40, v40 row_shr:2 row_mask:0xf bank_mask:0xf bound_ctrl:1
	v_add_f32_dpp v41, v41, v41 row_shr:2 row_mask:0xf bank_mask:0xf bound_ctrl:1
	v_add_f32_dpp v42, v42, v42 row_shr:2 row_mask:0xf bank_mask:0xf bound_ctrl:1
	v_add_f32_dpp v43, v43, v43 row_shr:2 row_mask:0xf bank_mask:0xf bound_ctrl:1
	v_add_f32_dpp v44, v44, v44 row_shr:2 row_mask:0xf bank_mask:0xf bound_ctrl:1
	v_add_f32_dpp v45, v45, v45 row_shr:2 row_mask:0xf bank_mask:0xf bound_ctrl:1
	v_add_f32_dpp v46, v46, v46 row_shr:2 row_mask:0xf bank_mask:0xf bound_ctrl:1
	v_add_f32_dpp v47, v47, v47 row_shr:2 row_mask:0xf bank_mask:0xf bound_ctrl:1
	v_add_f32_dpp v88, v88, v88 row_ror:4 row_mask:0xf bank_mask:0xf
	v_add_f32_dpp v89, v89, v89 row_ror:4 row_mask:0xf bank_mask:0xf
	v_add_f32_dpp v90, v90, v90 row_ror:4 row_mask:0xf bank_mask:0xf
	v_add_f32_dpp v91, v91, v91 row_ror:4 row_mask:0xf bank_mask:0xf
	v_add_f32_dpp v92, v92, v92 row_ror:4 row_mask:0xf bank_mask:0xf
	v_add_f32_dpp v93, v93, v93 row_ror:4 row_mask:0xf bank_mask:0xf
	v_add_f32_dpp v94, v94, v94 row_ror:4 row_mask:0xf bank_mask:0xf
	v_add_f32_dpp v95, v95, v95 row_ror:4 row_mask:0xf bank_mask:0xf
	v_add_f32_dpp v40, v40, v40 row_shr:4 row_mask:0xf bank_mask:0xf bound_ctrl:1
	v_add_f32_dpp v41, v41, v41 row_shr:4 row_mask:0xf bank_mask:0xf bound_ctrl:1
	v_add_f32_dpp v42, v42, v42 row_shr:4 row_mask:0xf bank_mask:0xf bound_ctrl:1
	v_add_f32_dpp v43, v43, v43 row_shr:4 row_mask:0xf bank_mask:0xf bound_ctrl:1
	v_add_f32_dpp v44, v44, v44 row_shr:4 row_mask:0xf bank_mask:0xf bound_ctrl:1
	v_add_f32_dpp v45, v45, v45 row_shr:4 row_mask:0xf bank_mask:0xf bound_ctrl:1
	v_add_f32_dpp v46, v46, v46 row_shr:4 row_mask:0xf bank_mask:0xf bound_ctrl:1
	v_add_f32_dpp v47, v47, v47 row_shr:4 row_mask:0xf bank_mask:0xf bound_ctrl:1
	v_add_f32_dpp v88, v88, v88 row_ror:2 row_mask:0xf bank_mask:0xf
	v_add_f32_dpp v89, v89, v89 row_ror:2 row_mask:0xf bank_mask:0xf
	v_add_f32_dpp v90, v90, v90 row_ror:2 row_mask:0xf bank_mask:0xf
	v_add_f32_dpp v91, v91, v91 row_ror:2 row_mask:0xf bank_mask:0xf
	v_add_f32_dpp v92, v92, v92 row_ror:2 row_mask:0xf bank_mask:0xf
	v_add_f32_dpp v93, v93, v93 row_ror:2 row_mask:0xf bank_mask:0xf
	v_add_f32_dpp v94, v94, v94 row_ror:2 row_mask:0xf bank_mask:0xf
	v_add_f32_dpp v95, v95, v95 row_ror:2 row_mask:0xf bank_mask:0xf
	v_add_f32_dpp v40, v40, v40 row_shr:8 row_mask:0xf bank_mask:0xf bound_ctrl:1
	v_add_f32_dpp v41, v41, v41 row_shr:8 row_mask:0xf bank_mask:0xf bound_ctrl:1
	v_add_f32_dpp v42, v42, v42 row_shr:8 row_mask:0xf bank_mask:0xf bound_ctrl:1
	v_add_f32_dpp v43, v43, v43 row_shr:8 row_mask:0xf bank_mask:0xf bound_ctrl:1
	v_add_f32_dpp v44, v44, v44 row_shr:8 row_mask:0xf bank_mask:0xf bound_ctrl:1
	v_add_f32_dpp v45, v45, v45 row_shr:8 row_mask:0xf bank_mask:0xf bound_ctrl:1
	v_add_f32_dpp v46, v46, v46 row_shr:8 row_mask:0xf bank_mask:0xf bound_ctrl:1
	v_add_f32_dpp v47, v47, v47 row_shr:8 row_mask:0xf bank_mask:0xf bound_ctrl:1
	v_add_f32_dpp v88, v88, v88 row_ror:1 row_mask:0xf bank_mask:0xf
	v_add_f32_dpp v89, v89, v89 row_ror:1 row_mask:0xf bank_mask:0xf
	v_add_f32_dpp v90, v90, v90 row_ror:1 row_mask:0xf bank_mask:0xf
	v_add_f32_dpp v91, v91, v91 row_ror:1 row_mask:0xf bank_mask:0xf
	v_add_f32_dpp v92, v92, v92 row_ror:1 row_mask:0xf bank_mask:0xf
	v_add_f32_dpp v93, v93, v93 row_ror:1 row_mask:0xf bank_mask:0xf
	v_add_f32_dpp v94, v94, v94 row_ror:1 row_mask:0xf bank_mask:0xf
	v_add_f32_dpp v95, v95, v95 row_ror:1 row_mask:0xf bank_mask:0xf
	v_add_f32_e32 v40, v40, v170
	v_add_f32_e32 v44, v44, v171
	v_add_f32_e32 v41, v41, v172
	v_add_f32_e32 v45, v45, v173
	v_add_f32_e32 v42, v42, v174
	v_add_f32_e32 v46, v46, v175
	v_add_f32_e32 v43, v43, v176
	v_add_f32_e32 v47, v47, v177
	v_mul_f32_e32 v132, v40, v141
	v_mul_f32_e32 v40, v40, v140
	v_fma_f32 v40, -v44, v141, v40
	v_fma_f32 v44, v44, v140, v132
	v_mul_f32_e32 v133, v41, v145
	v_mul_f32_e32 v41, v41, v144
	v_fma_f32 v41, -v45, v145, v41
	v_fma_f32 v45, v45, v144, v133
	v_mul_f32_e32 v132, v42, v149
	v_mul_f32_e32 v42, v42, v148
	v_fma_f32 v42, -v46, v149, v42
	v_fma_f32 v46, v46, v148, v132
	v_mul_f32_e32 v133, v43, v153
	v_mul_f32_e32 v43, v43, v152
	v_fma_f32 v43, -v47, v153, v43
	v_fma_f32 v47, v47, v152, v133
	v_add_f32_e32 v88, v88, v170
	v_add_f32_e32 v92, v92, v171
	v_mul_f32_e32 v132, v92, v155
	v_mul_f32_e32 v171, v88, v155
	v_fma_f32 v170, v88, v154, -v132
	v_fma_f32 v171, v92, v154, v171
	v_add_f32_e32 v89, v89, v172
	v_add_f32_e32 v93, v93, v173
	v_mul_f32_e32 v133, v93, v159
	v_mul_f32_e32 v173, v89, v159
	v_fma_f32 v172, v89, v158, -v133
	v_fma_f32 v173, v93, v158, v173
	v_add_f32_e32 v90, v90, v174
	v_add_f32_e32 v94, v94, v175
	v_mul_f32_e32 v132, v94, v163
	v_mul_f32_e32 v175, v90, v163
	v_fma_f32 v174, v90, v162, -v132
	v_fma_f32 v175, v94, v162, v175
	v_add_f32_e32 v91, v91, v176
	v_add_f32_e32 v95, v95, v177
	v_mul_f32_e32 v133, v95, v167
	v_mul_f32_e32 v177, v91, v167
	v_fma_f32 v176, v91, v166, -v133
	v_fma_f32 v177, v95, v166, v177
	v_mul_f32_e32 v132, v48, v139
	v_mul_f32_e32 v48, v48, v138
	v_fma_f32 v48, -v52, v139, v48
	v_fma_f32 v52, v52, v138, v132
	v_mul_f32_e32 v133, v49, v143
	v_mul_f32_e32 v49, v49, v142
	v_fma_f32 v49, -v53, v143, v49
	v_fma_f32 v53, v53, v142, v133
	v_mul_f32_e32 v132, v50, v147
	v_mul_f32_e32 v50, v50, v146
	v_fma_f32 v50, -v54, v147, v50
	v_fma_f32 v54, v54, v146, v132
	v_mul_f32_e32 v133, v51, v151
	v_mul_f32_e32 v51, v51, v150
	v_fma_f32 v51, -v55, v151, v51
	v_fma_f32 v55, v55, v150, v133
	v_mov_b32_e32 v88, v48
	v_mov_b32_e32 v89, v49
	v_mov_b32_e32 v90, v50
	v_mov_b32_e32 v91, v51
	v_mov_b32_e32 v92, v52
	v_mov_b32_e32 v93, v53
	v_mov_b32_e32 v94, v54
	v_mov_b32_e32 v95, v55
	v_add_f32_dpp v48, v48, v48 row_shr:1 row_mask:0xf bank_mask:0xf bound_ctrl:1
	v_add_f32_dpp v49, v49, v49 row_shr:1 row_mask:0xf bank_mask:0xf bound_ctrl:1
	v_add_f32_dpp v50, v50, v50 row_shr:1 row_mask:0xf bank_mask:0xf bound_ctrl:1
	v_add_f32_dpp v51, v51, v51 row_shr:1 row_mask:0xf bank_mask:0xf bound_ctrl:1
	v_add_f32_dpp v52, v52, v52 row_shr:1 row_mask:0xf bank_mask:0xf bound_ctrl:1
	v_add_f32_dpp v53, v53, v53 row_shr:1 row_mask:0xf bank_mask:0xf bound_ctrl:1
	v_add_f32_dpp v54, v54, v54 row_shr:1 row_mask:0xf bank_mask:0xf bound_ctrl:1
	v_add_f32_dpp v55, v55, v55 row_shr:1 row_mask:0xf bank_mask:0xf bound_ctrl:1
	v_add_f32_dpp v88, v88, v88 row_ror:8 row_mask:0xf bank_mask:0xf
	v_add_f32_dpp v89, v89, v89 row_ror:8 row_mask:0xf bank_mask:0xf
	v_add_f32_dpp v90, v90, v90 row_ror:8 row_mask:0xf bank_mask:0xf
	v_add_f32_dpp v91, v91, v91 row_ror:8 row_mask:0xf bank_mask:0xf
	v_add_f32_dpp v92, v92, v92 row_ror:8 row_mask:0xf bank_mask:0xf
	v_add_f32_dpp v93, v93, v93 row_ror:8 row_mask:0xf bank_mask:0xf
	v_add_f32_dpp v94, v94, v94 row_ror:8 row_mask:0xf bank_mask:0xf
	v_add_f32_dpp v95, v95, v95 row_ror:8 row_mask:0xf bank_mask:0xf
	v_add_f32_dpp v48, v48, v48 row_shr:2 row_mask:0xf bank_mask:0xf bound_ctrl:1
	v_add_f32_dpp v49, v49, v49 row_shr:2 row_mask:0xf bank_mask:0xf bound_ctrl:1
	v_add_f32_dpp v50, v50, v50 row_shr:2 row_mask:0xf bank_mask:0xf bound_ctrl:1
	v_add_f32_dpp v51, v51, v51 row_shr:2 row_mask:0xf bank_mask:0xf bound_ctrl:1
	v_add_f32_dpp v52, v52, v52 row_shr:2 row_mask:0xf bank_mask:0xf bound_ctrl:1
	v_add_f32_dpp v53, v53, v53 row_shr:2 row_mask:0xf bank_mask:0xf bound_ctrl:1
	v_add_f32_dpp v54, v54, v54 row_shr:2 row_mask:0xf bank_mask:0xf bound_ctrl:1
	v_add_f32_dpp v55, v55, v55 row_shr:2 row_mask:0xf bank_mask:0xf bound_ctrl:1
	v_add_f32_dpp v88, v88, v88 row_ror:4 row_mask:0xf bank_mask:0xf
	v_add_f32_dpp v89, v89, v89 row_ror:4 row_mask:0xf bank_mask:0xf
	v_add_f32_dpp v90, v90, v90 row_ror:4 row_mask:0xf bank_mask:0xf
	v_add_f32_dpp v91, v91, v91 row_ror:4 row_mask:0xf bank_mask:0xf
	v_add_f32_dpp v92, v92, v92 row_ror:4 row_mask:0xf bank_mask:0xf
	v_add_f32_dpp v93, v93, v93 row_ror:4 row_mask:0xf bank_mask:0xf
	v_add_f32_dpp v94, v94, v94 row_ror:4 row_mask:0xf bank_mask:0xf
	v_add_f32_dpp v95, v95, v95 row_ror:4 row_mask:0xf bank_mask:0xf
	v_add_f32_dpp v48, v48, v48 row_shr:4 row_mask:0xf bank_mask:0xf bound_ctrl:1
	v_add_f32_dpp v49, v49, v49 row_shr:4 row_mask:0xf bank_mask:0xf bound_ctrl:1
	v_add_f32_dpp v50, v50, v50 row_shr:4 row_mask:0xf bank_mask:0xf bound_ctrl:1
	v_add_f32_dpp v51, v51, v51 row_shr:4 row_mask:0xf bank_mask:0xf bound_ctrl:1
	v_add_f32_dpp v52, v52, v52 row_shr:4 row_mask:0xf bank_mask:0xf bound_ctrl:1
	v_add_f32_dpp v53, v53, v53 row_shr:4 row_mask:0xf bank_mask:0xf bound_ctrl:1
	v_add_f32_dpp v54, v54, v54 row_shr:4 row_mask:0xf bank_mask:0xf bound_ctrl:1
	v_add_f32_dpp v55, v55, v55 row_shr:4 row_mask:0xf bank_mask:0xf bound_ctrl:1
	v_add_f32_dpp v88, v88, v88 row_ror:2 row_mask:0xf bank_mask:0xf
	v_add_f32_dpp v89, v89, v89 row_ror:2 row_mask:0xf bank_mask:0xf
	v_add_f32_dpp v90, v90, v90 row_ror:2 row_mask:0xf bank_mask:0xf
	v_add_f32_dpp v91, v91, v91 row_ror:2 row_mask:0xf bank_mask:0xf
	v_add_f32_dpp v92, v92, v92 row_ror:2 row_mask:0xf bank_mask:0xf
	v_add_f32_dpp v93, v93, v93 row_ror:2 row_mask:0xf bank_mask:0xf
	v_add_f32_dpp v94, v94, v94 row_ror:2 row_mask:0xf bank_mask:0xf
	v_add_f32_dpp v95, v95, v95 row_ror:2 row_mask:0xf bank_mask:0xf
	v_add_f32_dpp v48, v48, v48 row_shr:8 row_mask:0xf bank_mask:0xf bound_ctrl:1
	v_add_f32_dpp v49, v49, v49 row_shr:8 row_mask:0xf bank_mask:0xf bound_ctrl:1
	v_add_f32_dpp v50, v50, v50 row_shr:8 row_mask:0xf bank_mask:0xf bound_ctrl:1
	v_add_f32_dpp v51, v51, v51 row_shr:8 row_mask:0xf bank_mask:0xf bound_ctrl:1
	v_add_f32_dpp v52, v52, v52 row_shr:8 row_mask:0xf bank_mask:0xf bound_ctrl:1
	v_add_f32_dpp v53, v53, v53 row_shr:8 row_mask:0xf bank_mask:0xf bound_ctrl:1
	v_add_f32_dpp v54, v54, v54 row_shr:8 row_mask:0xf bank_mask:0xf bound_ctrl:1
	v_add_f32_dpp v55, v55, v55 row_shr:8 row_mask:0xf bank_mask:0xf bound_ctrl:1
	v_add_f32_dpp v88, v88, v88 row_ror:1 row_mask:0xf bank_mask:0xf
	v_add_f32_dpp v89, v89, v89 row_ror:1 row_mask:0xf bank_mask:0xf
	v_add_f32_dpp v90, v90, v90 row_ror:1 row_mask:0xf bank_mask:0xf
	v_add_f32_dpp v91, v91, v91 row_ror:1 row_mask:0xf bank_mask:0xf
	v_add_f32_dpp v92, v92, v92 row_ror:1 row_mask:0xf bank_mask:0xf
	v_add_f32_dpp v93, v93, v93 row_ror:1 row_mask:0xf bank_mask:0xf
	v_add_f32_dpp v94, v94, v94 row_ror:1 row_mask:0xf bank_mask:0xf
	v_add_f32_dpp v95, v95, v95 row_ror:1 row_mask:0xf bank_mask:0xf
	v_add_f32_e32 v48, v48, v170
	v_add_f32_e32 v52, v52, v171
	v_add_f32_e32 v49, v49, v172
	v_add_f32_e32 v53, v53, v173
	v_add_f32_e32 v50, v50, v174
	v_add_f32_e32 v54, v54, v175
	v_add_f32_e32 v51, v51, v176
	v_add_f32_e32 v55, v55, v177
	v_mul_f32_e32 v132, v48, v141
	v_mul_f32_e32 v48, v48, v140
	v_fma_f32 v48, -v52, v141, v48
	v_fma_f32 v52, v52, v140, v132
	v_mul_f32_e32 v133, v49, v145
	v_mul_f32_e32 v49, v49, v144
	v_fma_f32 v49, -v53, v145, v49
	v_fma_f32 v53, v53, v144, v133
	v_mul_f32_e32 v132, v50, v149
	v_mul_f32_e32 v50, v50, v148
	v_fma_f32 v50, -v54, v149, v50
	v_fma_f32 v54, v54, v148, v132
	v_mul_f32_e32 v133, v51, v153
	v_mul_f32_e32 v51, v51, v152
	v_fma_f32 v51, -v55, v153, v51
	v_fma_f32 v55, v55, v152, v133
	v_add_f32_e32 v88, v88, v170
	v_add_f32_e32 v92, v92, v171
	v_mul_f32_e32 v132, v92, v155
	v_mul_f32_e32 v171, v88, v155
	v_fma_f32 v170, v88, v154, -v132
	v_fma_f32 v171, v92, v154, v171
	v_add_f32_e32 v89, v89, v172
	v_add_f32_e32 v93, v93, v173
	v_mul_f32_e32 v133, v93, v159
	v_mul_f32_e32 v173, v89, v159
	v_fma_f32 v172, v89, v158, -v133
	v_fma_f32 v173, v93, v158, v173
	v_add_f32_e32 v90, v90, v174
	v_add_f32_e32 v94, v94, v175
	v_mul_f32_e32 v132, v94, v163
	v_mul_f32_e32 v175, v90, v163
	v_fma_f32 v174, v90, v162, -v132
	v_fma_f32 v175, v94, v162, v175
	v_add_f32_e32 v91, v91, v176
	v_add_f32_e32 v95, v95, v177
	v_mul_f32_e32 v133, v95, v167
	v_mul_f32_e32 v177, v91, v167
	v_fma_f32 v176, v91, v166, -v133
	v_fma_f32 v177, v95, v166, v177
	v_mul_f32_e32 v132, v56, v139
	v_mul_f32_e32 v56, v56, v138
	v_fma_f32 v56, -v60, v139, v56
	v_fma_f32 v60, v60, v138, v132
	v_mul_f32_e32 v133, v57, v143
	v_mul_f32_e32 v57, v57, v142
	v_fma_f32 v57, -v61, v143, v57
	v_fma_f32 v61, v61, v142, v133
	v_mul_f32_e32 v132, v58, v147
	v_mul_f32_e32 v58, v58, v146
	v_fma_f32 v58, -v62, v147, v58
	v_fma_f32 v62, v62, v146, v132
	v_mul_f32_e32 v133, v59, v151
	v_mul_f32_e32 v59, v59, v150
	v_fma_f32 v59, -v63, v151, v59
	v_fma_f32 v63, v63, v150, v133
	v_mov_b32_e32 v88, v56
	v_mov_b32_e32 v89, v57
	v_mov_b32_e32 v90, v58
	v_mov_b32_e32 v91, v59
	v_mov_b32_e32 v92, v60
	v_mov_b32_e32 v93, v61
	v_mov_b32_e32 v94, v62
	v_mov_b32_e32 v95, v63
	v_add_f32_dpp v56, v56, v56 row_shr:1 row_mask:0xf bank_mask:0xf bound_ctrl:1
	v_add_f32_dpp v57, v57, v57 row_shr:1 row_mask:0xf bank_mask:0xf bound_ctrl:1
	v_add_f32_dpp v58, v58, v58 row_shr:1 row_mask:0xf bank_mask:0xf bound_ctrl:1
	v_add_f32_dpp v59, v59, v59 row_shr:1 row_mask:0xf bank_mask:0xf bound_ctrl:1
	v_add_f32_dpp v60, v60, v60 row_shr:1 row_mask:0xf bank_mask:0xf bound_ctrl:1
	v_add_f32_dpp v61, v61, v61 row_shr:1 row_mask:0xf bank_mask:0xf bound_ctrl:1
	v_add_f32_dpp v62, v62, v62 row_shr:1 row_mask:0xf bank_mask:0xf bound_ctrl:1
	v_add_f32_dpp v63, v63, v63 row_shr:1 row_mask:0xf bank_mask:0xf bound_ctrl:1
	v_add_f32_dpp v88, v88, v88 row_ror:8 row_mask:0xf bank_mask:0xf
	v_add_f32_dpp v89, v89, v89 row_ror:8 row_mask:0xf bank_mask:0xf
	v_add_f32_dpp v90, v90, v90 row_ror:8 row_mask:0xf bank_mask:0xf
	v_add_f32_dpp v91, v91, v91 row_ror:8 row_mask:0xf bank_mask:0xf
	v_add_f32_dpp v92, v92, v92 row_ror:8 row_mask:0xf bank_mask:0xf
	v_add_f32_dpp v93, v93, v93 row_ror:8 row_mask:0xf bank_mask:0xf
	v_add_f32_dpp v94, v94, v94 row_ror:8 row_mask:0xf bank_mask:0xf
	v_add_f32_dpp v95, v95, v95 row_ror:8 row_mask:0xf bank_mask:0xf
	v_add_f32_dpp v56, v56, v56 row_shr:2 row_mask:0xf bank_mask:0xf bound_ctrl:1
	v_add_f32_dpp v57, v57, v57 row_shr:2 row_mask:0xf bank_mask:0xf bound_ctrl:1
	v_add_f32_dpp v58, v58, v58 row_shr:2 row_mask:0xf bank_mask:0xf bound_ctrl:1
	v_add_f32_dpp v59, v59, v59 row_shr:2 row_mask:0xf bank_mask:0xf bound_ctrl:1
	v_add_f32_dpp v60, v60, v60 row_shr:2 row_mask:0xf bank_mask:0xf bound_ctrl:1
	v_add_f32_dpp v61, v61, v61 row_shr:2 row_mask:0xf bank_mask:0xf bound_ctrl:1
	v_add_f32_dpp v62, v62, v62 row_shr:2 row_mask:0xf bank_mask:0xf bound_ctrl:1
	v_add_f32_dpp v63, v63, v63 row_shr:2 row_mask:0xf bank_mask:0xf bound_ctrl:1
	v_add_f32_dpp v88, v88, v88 row_ror:4 row_mask:0xf bank_mask:0xf
	v_add_f32_dpp v89, v89, v89 row_ror:4 row_mask:0xf bank_mask:0xf
	v_add_f32_dpp v90, v90, v90 row_ror:4 row_mask:0xf bank_mask:0xf
	v_add_f32_dpp v91, v91, v91 row_ror:4 row_mask:0xf bank_mask:0xf
	v_add_f32_dpp v92, v92, v92 row_ror:4 row_mask:0xf bank_mask:0xf
	v_add_f32_dpp v93, v93, v93 row_ror:4 row_mask:0xf bank_mask:0xf
	v_add_f32_dpp v94, v94, v94 row_ror:4 row_mask:0xf bank_mask:0xf
	v_add_f32_dpp v95, v95, v95 row_ror:4 row_mask:0xf bank_mask:0xf
	v_add_f32_dpp v56, v56, v56 row_shr:4 row_mask:0xf bank_mask:0xf bound_ctrl:1
	v_add_f32_dpp v57, v57, v57 row_shr:4 row_mask:0xf bank_mask:0xf bound_ctrl:1
	v_add_f32_dpp v58, v58, v58 row_shr:4 row_mask:0xf bank_mask:0xf bound_ctrl:1
	v_add_f32_dpp v59, v59, v59 row_shr:4 row_mask:0xf bank_mask:0xf bound_ctrl:1
	v_add_f32_dpp v60, v60, v60 row_shr:4 row_mask:0xf bank_mask:0xf bound_ctrl:1
	v_add_f32_dpp v61, v61, v61 row_shr:4 row_mask:0xf bank_mask:0xf bound_ctrl:1
	v_add_f32_dpp v62, v62, v62 row_shr:4 row_mask:0xf bank_mask:0xf bound_ctrl:1
	v_add_f32_dpp v63, v63, v63 row_shr:4 row_mask:0xf bank_mask:0xf bound_ctrl:1
	v_add_f32_dpp v88, v88, v88 row_ror:2 row_mask:0xf bank_mask:0xf
	v_add_f32_dpp v89, v89, v89 row_ror:2 row_mask:0xf bank_mask:0xf
	v_add_f32_dpp v90, v90, v90 row_ror:2 row_mask:0xf bank_mask:0xf
	v_add_f32_dpp v91, v91, v91 row_ror:2 row_mask:0xf bank_mask:0xf
	v_add_f32_dpp v92, v92, v92 row_ror:2 row_mask:0xf bank_mask:0xf
	v_add_f32_dpp v93, v93, v93 row_ror:2 row_mask:0xf bank_mask:0xf
	v_add_f32_dpp v94, v94, v94 row_ror:2 row_mask:0xf bank_mask:0xf
	v_add_f32_dpp v95, v95, v95 row_ror:2 row_mask:0xf bank_mask:0xf
	v_add_f32_dpp v56, v56, v56 row_shr:8 row_mask:0xf bank_mask:0xf bound_ctrl:1
	v_add_f32_dpp v57, v57, v57 row_shr:8 row_mask:0xf bank_mask:0xf bound_ctrl:1
	v_add_f32_dpp v58, v58, v58 row_shr:8 row_mask:0xf bank_mask:0xf bound_ctrl:1
	v_add_f32_dpp v59, v59, v59 row_shr:8 row_mask:0xf bank_mask:0xf bound_ctrl:1
	v_add_f32_dpp v60, v60, v60 row_shr:8 row_mask:0xf bank_mask:0xf bound_ctrl:1
	v_add_f32_dpp v61, v61, v61 row_shr:8 row_mask:0xf bank_mask:0xf bound_ctrl:1
	v_add_f32_dpp v62, v62, v62 row_shr:8 row_mask:0xf bank_mask:0xf bound_ctrl:1
	v_add_f32_dpp v63, v63, v63 row_shr:8 row_mask:0xf bank_mask:0xf bound_ctrl:1
	v_add_f32_dpp v88, v88, v88 row_ror:1 row_mask:0xf bank_mask:0xf
	v_add_f32_dpp v89, v89, v89 row_ror:1 row_mask:0xf bank_mask:0xf
	v_add_f32_dpp v90, v90, v90 row_ror:1 row_mask:0xf bank_mask:0xf
	v_add_f32_dpp v91, v91, v91 row_ror:1 row_mask:0xf bank_mask:0xf
	v_add_f32_dpp v92, v92, v92 row_ror:1 row_mask:0xf bank_mask:0xf
	v_add_f32_dpp v93, v93, v93 row_ror:1 row_mask:0xf bank_mask:0xf
	v_add_f32_dpp v94, v94, v94 row_ror:1 row_mask:0xf bank_mask:0xf
	v_add_f32_dpp v95, v95, v95 row_ror:1 row_mask:0xf bank_mask:0xf
	v_add_f32_e32 v56, v56, v170
	v_add_f32_e32 v60, v60, v171
	v_add_f32_e32 v57, v57, v172
	v_add_f32_e32 v61, v61, v173
	v_add_f32_e32 v58, v58, v174
	v_add_f32_e32 v62, v62, v175
	v_add_f32_e32 v59, v59, v176
	v_add_f32_e32 v63, v63, v177
	v_mul_f32_e32 v132, v56, v141
	v_mul_f32_e32 v56, v56, v140
	v_fma_f32 v56, -v60, v141, v56
	v_fma_f32 v60, v60, v140, v132
	v_mul_f32_e32 v133, v57, v145
	v_mul_f32_e32 v57, v57, v144
	v_fma_f32 v57, -v61, v145, v57
	v_fma_f32 v61, v61, v144, v133
	v_mul_f32_e32 v132, v58, v149
	v_mul_f32_e32 v58, v58, v148
	v_fma_f32 v58, -v62, v149, v58
	v_fma_f32 v62, v62, v148, v132
	v_mul_f32_e32 v133, v59, v153
	v_mul_f32_e32 v59, v59, v152
	v_fma_f32 v59, -v63, v153, v59
	v_fma_f32 v63, v63, v152, v133
	v_add_f32_e32 v88, v88, v170
	v_add_f32_e32 v92, v92, v171
	v_mul_f32_e32 v132, v92, v155
	v_mul_f32_e32 v171, v88, v155
	v_fma_f32 v170, v88, v154, -v132
	v_fma_f32 v171, v92, v154, v171
	v_add_f32_e32 v89, v89, v172
	v_add_f32_e32 v93, v93, v173
	v_mul_f32_e32 v133, v93, v159
	v_mul_f32_e32 v173, v89, v159
	v_fma_f32 v172, v89, v158, -v133
	v_fma_f32 v173, v93, v158, v173
	v_add_f32_e32 v90, v90, v174
	v_add_f32_e32 v94, v94, v175
	v_mul_f32_e32 v132, v94, v163
	v_mul_f32_e32 v175, v90, v163
	v_fma_f32 v174, v90, v162, -v132
	v_fma_f32 v175, v94, v162, v175
	v_add_f32_e32 v91, v91, v176
	v_add_f32_e32 v95, v95, v177
	v_mul_f32_e32 v133, v95, v167
	v_mul_f32_e32 v177, v91, v167
	v_fma_f32 v176, v91, v166, -v133
	v_fma_f32 v177, v95, v166, v177
	s_waitcnt vmcnt(14)
	v_cvt_pk_bf16_f32 v80, v80, v81
	v_cvt_pk_bf16_f32 v81, v82, v83
	v_cvt_pk_bf16_f32 v82, -v84, -v85
	v_cvt_pk_bf16_f32 v83, -v86, -v87
	v_cvt_pk_bf16_f32 v96, v32, v33
	v_cvt_pk_bf16_f32 v97, v34, v35
	v_cvt_pk_bf16_f32 v98, v36, v37
	v_cvt_pk_bf16_f32 v99, v38, v39
	s_nop 1
	v_mfma_f32_16x16x32_bf16 v[16:19], v[80:83], v[96:99], 0
	v_cvt_pk_bf16_f32 v96, v40, v41
	v_cvt_pk_bf16_f32 v97, v42, v43
	v_cvt_pk_bf16_f32 v98, v44, v45
	v_cvt_pk_bf16_f32 v99, v46, v47
	s_nop 1
	v_mfma_f32_16x16x32_bf16 v[20:23], v[80:83], v[96:99], 0
	v_cvt_pk_bf16_f32 v96, v48, v49
	v_cvt_pk_bf16_f32 v97, v50, v51
	v_cvt_pk_bf16_f32 v98, v52, v53
	v_cvt_pk_bf16_f32 v99, v54, v55
	s_nop 1
	v_mfma_f32_16x16x32_bf16 v[24:27], v[80:83], v[96:99], 0
	v_cvt_pk_bf16_f32 v96, v56, v57
	v_cvt_pk_bf16_f32 v97, v58, v59
	v_cvt_pk_bf16_f32 v98, v60, v61
	v_cvt_pk_bf16_f32 v99, v62, v63
	s_nop 1
	v_mfma_f32_16x16x32_bf16 v[28:31], v[80:83], v[96:99], 0
	s_waitcnt vmcnt(10)
	v_cvt_pk_bf16_f32 v64, v64, v65
	v_cvt_pk_bf16_f32 v65, v66, v67
	v_cvt_pk_bf16_f32 v66, v68, v69
	v_cvt_pk_bf16_f32 v67, v70, v71
	v_cvt_pk_bf16_f32 v72, v72, v73
	v_cvt_pk_bf16_f32 v73, v74, v75
	v_cvt_pk_bf16_f32 v74, v76, v77
	v_cvt_pk_bf16_f32 v75, v78, v79
	global_load_dwordx4 v[80:83], v136, s[38:39]
	global_load_dwordx4 v[84:87], v136, s[40:41]
	s_add_u32 s38, s38, 0x40
	s_addc_u32 s39, s39, 0
	s_add_u32 s40, s40, 0x40
	s_addc_u32 s41, s41, 0
	s_nop 0
	v_mfma_f32_16x16x32_bf16 v[32:35], v[64:67], v[0:3], 0
	v_mfma_f32_16x16x32_bf16 v[36:39], v[72:75], v[0:3], 0
	v_mfma_f32_16x16x32_bf16 v[40:43], v[64:67], v[4:7], 0
	v_mfma_f32_16x16x32_bf16 v[44:47], v[72:75], v[4:7], 0
	v_mfma_f32_16x16x32_bf16 v[48:51], v[64:67], v[8:11], 0
	v_mfma_f32_16x16x32_bf16 v[52:55], v[72:75], v[8:11], 0
	v_mfma_f32_16x16x32_bf16 v[56:59], v[64:67], v[12:15], 0
	v_mfma_f32_16x16x32_bf16 v[60:63], v[72:75], v[12:15], 0
	s_mov_b32 exec_hi, 0
	global_load_dwordx4 v[64:67], v135, s[20:21]
	global_load_dwordx4 v[68:71], v135, s[20:21] offset:16
	global_load_dwordx4 v[72:75], v135, s[22:23]
	global_load_dwordx4 v[76:79], v135, s[22:23] offset:16
	s_mov_b64 exec, -1
	s_add_u32 s20, s20, 0x400
	s_addc_u32 s21, s21, 0
	s_add_u32 s22, s22, 0x400
	s_addc_u32 s23, s23, 0
	global_load_dwordx4 v[138:141], v134, s[42:43] offset:0
	global_load_dwordx4 v[142:145], v134, s[42:43] offset:16
	global_load_dwordx4 v[146:149], v134, s[42:43] offset:32
	global_load_dwordx4 v[150:153], v134, s[42:43] offset:48
	global_load_dwordx4 v[154:157], v134, s[42:43] offset:64
	global_load_dwordx4 v[158:161], v134, s[42:43] offset:80
	global_load_dwordx4 v[162:165], v134, s[42:43] offset:96
	global_load_dwordx4 v[166:169], v134, s[42:43] offset:112
	global_load_dwordx4 v[170:173], v206, s[44:45]
	global_load_dwordx4 v[174:177], v206, s[44:45] offset:16
	s_add_u32 s42, s42, 0x2000
	s_addc_u32 s43, s43, 0
	s_add_u32 s44, s44, 0x80
	s_addc_u32 s45, s45, 0
	s_waitcnt vmcnt(16)
	v_mul_f32_e32 v132, v179, v119
	v_mul_f32_e32 v133, v178, v119
	v_fma_f32 v178, v178, v118, -v132
	v_fma_f32 v179, v179, v118, v133
	v_mul_f32_e32 v132, v181, v123
	v_mul_f32_e32 v133, v180, v123
	v_fma_f32 v180, v180, v122, -v132
	v_fma_f32 v181, v181, v122, v133
	v_mul_f32_e32 v132, v183, v127
	v_mul_f32_e32 v133, v182, v127
	v_fma_f32 v182, v182, v126, -v132
	v_fma_f32 v183, v183, v126, v133
	v_mul_f32_e32 v132, v185, v131
	v_mul_f32_e32 v133, v184, v131
	v_fma_f32 v184, v184, v130, -v132
	v_fma_f32 v185, v185, v130, v133
	v_mul_f32_e32 v132, v32, v101
	v_mul_f32_e32 v32, v32, v100
	v_fma_f32 v32, -v36, v101, v32
	v_fma_f32 v36, v36, v100, v132
	v_mul_f32_e32 v133, v33, v105
	v_mul_f32_e32 v33, v33, v104
	v_fma_f32 v33, -v37, v105, v33
	v_fma_f32 v37, v37, v104, v133
	v_mul_f32_e32 v132, v34, v109
	v_mul_f32_e32 v34, v34, v108
	v_fma_f32 v34, -v38, v109, v34
	v_fma_f32 v38, v38, v108, v132
	v_mul_f32_e32 v133, v35, v113
	v_mul_f32_e32 v35, v35, v112
	v_fma_f32 v35, -v39, v113, v35
	v_fma_f32 v39, v39, v112, v133
	v_mov_b32_e32 v88, v32
	v_mov_b32_e32 v89, v33
	v_mov_b32_e32 v90, v34
	v_mov_b32_e32 v91, v35
	v_mov_b32_e32 v92, v36
	v_mov_b32_e32 v93, v37
	v_mov_b32_e32 v94, v38
	v_mov_b32_e32 v95, v39
	v_add_f32_dpp v32, v32, v32 row_shr:1 row_mask:0xf bank_mask:0xf bound_ctrl:1
	v_add_f32_dpp v33, v33, v33 row_shr:1 row_mask:0xf bank_mask:0xf bound_ctrl:1
	v_add_f32_dpp v34, v34, v34 row_shr:1 row_mask:0xf bank_mask:0xf bound_ctrl:1
	v_add_f32_dpp v35, v35, v35 row_shr:1 row_mask:0xf bank_mask:0xf bound_ctrl:1
	v_add_f32_dpp v36, v36, v36 row_shr:1 row_mask:0xf bank_mask:0xf bound_ctrl:1
	v_add_f32_dpp v37, v37, v37 row_shr:1 row_mask:0xf bank_mask:0xf bound_ctrl:1
	v_add_f32_dpp v38, v38, v38 row_shr:1 row_mask:0xf bank_mask:0xf bound_ctrl:1
	v_add_f32_dpp v39, v39, v39 row_shr:1 row_mask:0xf bank_mask:0xf bound_ctrl:1
	v_add_f32_dpp v88, v88, v88 row_ror:8 row_mask:0xf bank_mask:0xf
	v_add_f32_dpp v89, v89, v89 row_ror:8 row_mask:0xf bank_mask:0xf
	v_add_f32_dpp v90, v90, v90 row_ror:8 row_mask:0xf bank_mask:0xf
	v_add_f32_dpp v91, v91, v91 row_ror:8 row_mask:0xf bank_mask:0xf
	v_add_f32_dpp v92, v92, v92 row_ror:8 row_mask:0xf bank_mask:0xf
	v_add_f32_dpp v93, v93, v93 row_ror:8 row_mask:0xf bank_mask:0xf
	v_add_f32_dpp v94, v94, v94 row_ror:8 row_mask:0xf bank_mask:0xf
	v_add_f32_dpp v95, v95, v95 row_ror:8 row_mask:0xf bank_mask:0xf
	v_add_f32_dpp v32, v32, v32 row_shr:2 row_mask:0xf bank_mask:0xf bound_ctrl:1
	v_add_f32_dpp v33, v33, v33 row_shr:2 row_mask:0xf bank_mask:0xf bound_ctrl:1
	v_add_f32_dpp v34, v34, v34 row_shr:2 row_mask:0xf bank_mask:0xf bound_ctrl:1
	v_add_f32_dpp v35, v35, v35 row_shr:2 row_mask:0xf bank_mask:0xf bound_ctrl:1
	v_add_f32_dpp v36, v36, v36 row_shr:2 row_mask:0xf bank_mask:0xf bound_ctrl:1
	v_add_f32_dpp v37, v37, v37 row_shr:2 row_mask:0xf bank_mask:0xf bound_ctrl:1
	v_add_f32_dpp v38, v38, v38 row_shr:2 row_mask:0xf bank_mask:0xf bound_ctrl:1
	v_add_f32_dpp v39, v39, v39 row_shr:2 row_mask:0xf bank_mask:0xf bound_ctrl:1
	v_add_f32_dpp v88, v88, v88 row_ror:4 row_mask:0xf bank_mask:0xf
	v_add_f32_dpp v89, v89, v89 row_ror:4 row_mask:0xf bank_mask:0xf
	v_add_f32_dpp v90, v90, v90 row_ror:4 row_mask:0xf bank_mask:0xf
	v_add_f32_dpp v91, v91, v91 row_ror:4 row_mask:0xf bank_mask:0xf
	v_add_f32_dpp v92, v92, v92 row_ror:4 row_mask:0xf bank_mask:0xf
	v_add_f32_dpp v93, v93, v93 row_ror:4 row_mask:0xf bank_mask:0xf
	v_add_f32_dpp v94, v94, v94 row_ror:4 row_mask:0xf bank_mask:0xf
	v_add_f32_dpp v95, v95, v95 row_ror:4 row_mask:0xf bank_mask:0xf
	v_add_f32_dpp v32, v32, v32 row_shr:4 row_mask:0xf bank_mask:0xf bound_ctrl:1
	v_add_f32_dpp v33, v33, v33 row_shr:4 row_mask:0xf bank_mask:0xf bound_ctrl:1
	v_add_f32_dpp v34, v34, v34 row_shr:4 row_mask:0xf bank_mask:0xf bound_ctrl:1
	v_add_f32_dpp v35, v35, v35 row_shr:4 row_mask:0xf bank_mask:0xf bound_ctrl:1
	v_add_f32_dpp v36, v36, v36 row_shr:4 row_mask:0xf bank_mask:0xf bound_ctrl:1
	v_add_f32_dpp v37, v37, v37 row_shr:4 row_mask:0xf bank_mask:0xf bound_ctrl:1
	v_add_f32_dpp v38, v38, v38 row_shr:4 row_mask:0xf bank_mask:0xf bound_ctrl:1
	v_add_f32_dpp v39, v39, v39 row_shr:4 row_mask:0xf bank_mask:0xf bound_ctrl:1
	v_add_f32_dpp v88, v88, v88 row_ror:2 row_mask:0xf bank_mask:0xf
	v_add_f32_dpp v89, v89, v89 row_ror:2 row_mask:0xf bank_mask:0xf
	v_add_f32_dpp v90, v90, v90 row_ror:2 row_mask:0xf bank_mask:0xf
	v_add_f32_dpp v91, v91, v91 row_ror:2 row_mask:0xf bank_mask:0xf
	v_add_f32_dpp v92, v92, v92 row_ror:2 row_mask:0xf bank_mask:0xf
	v_add_f32_dpp v93, v93, v93 row_ror:2 row_mask:0xf bank_mask:0xf
	v_add_f32_dpp v94, v94, v94 row_ror:2 row_mask:0xf bank_mask:0xf
	v_add_f32_dpp v95, v95, v95 row_ror:2 row_mask:0xf bank_mask:0xf
	v_add_f32_dpp v32, v32, v32 row_shr:8 row_mask:0xf bank_mask:0xf bound_ctrl:1
	v_add_f32_dpp v33, v33, v33 row_shr:8 row_mask:0xf bank_mask:0xf bound_ctrl:1
	v_add_f32_dpp v34, v34, v34 row_shr:8 row_mask:0xf bank_mask:0xf bound_ctrl:1
	v_add_f32_dpp v35, v35, v35 row_shr:8 row_mask:0xf bank_mask:0xf bound_ctrl:1
	v_add_f32_dpp v36, v36, v36 row_shr:8 row_mask:0xf bank_mask:0xf bound_ctrl:1
	v_add_f32_dpp v37, v37, v37 row_shr:8 row_mask:0xf bank_mask:0xf bound_ctrl:1
	v_add_f32_dpp v38, v38, v38 row_shr:8 row_mask:0xf bank_mask:0xf bound_ctrl:1
	v_add_f32_dpp v39, v39, v39 row_shr:8 row_mask:0xf bank_mask:0xf bound_ctrl:1
	v_add_f32_dpp v88, v88, v88 row_ror:1 row_mask:0xf bank_mask:0xf
	v_add_f32_dpp v89, v89, v89 row_ror:1 row_mask:0xf bank_mask:0xf
	v_add_f32_dpp v90, v90, v90 row_ror:1 row_mask:0xf bank_mask:0xf
	v_add_f32_dpp v91, v91, v91 row_ror:1 row_mask:0xf bank_mask:0xf
	v_add_f32_dpp v92, v92, v92 row_ror:1 row_mask:0xf bank_mask:0xf
	v_add_f32_dpp v93, v93, v93 row_ror:1 row_mask:0xf bank_mask:0xf
	v_add_f32_dpp v94, v94, v94 row_ror:1 row_mask:0xf bank_mask:0xf
	v_add_f32_dpp v95, v95, v95 row_ror:1 row_mask:0xf bank_mask:0xf
	v_add_f32_e32 v32, v32, v178
	v_add_f32_e32 v36, v36, v179
	v_add_f32_e32 v33, v33, v180
	v_add_f32_e32 v37, v37, v181
	v_add_f32_e32 v34, v34, v182
	v_add_f32_e32 v38, v38, v183
	v_add_f32_e32 v35, v35, v184
	v_add_f32_e32 v39, v39, v185
	v_mul_f32_e32 v132, v32, v103
	v_mul_f32_e32 v32, v32, v102
	v_fma_f32 v32, -v36, v103, v32
	v_fma_f32 v36, v36, v102, v132
	v_mul_f32_e32 v133, v33, v107
	v_mul_f32_e32 v33, v33, v106
	v_fma_f32 v33, -v37, v107, v33
	v_fma_f32 v37, v37, v106, v133
	v_mul_f32_e32 v132, v34, v111
	v_mul_f32_e32 v34, v34, v110
	v_fma_f32 v34, -v38, v111, v34
	v_fma_f32 v38, v38, v110, v132
	v_mul_f32_e32 v133, v35, v115
	v_mul_f32_e32 v35, v35, v114
	v_fma_f32 v35, -v39, v115, v35
	v_fma_f32 v39, v39, v114, v133
	v_add_f32_e32 v88, v88, v178
	v_add_f32_e32 v92, v92, v179
	v_mul_f32_e32 v132, v92, v117
	v_mul_f32_e32 v179, v88, v117
	v_fma_f32 v178, v88, v116, -v132
	v_fma_f32 v179, v92, v116, v179
	v_add_f32_e32 v89, v89, v180
	v_add_f32_e32 v93, v93, v181
	v_mul_f32_e32 v133, v93, v121
	v_mul_f32_e32 v181, v89, v121
	v_fma_f32 v180, v89, v120, -v133
	v_fma_f32 v181, v93, v120, v181
	v_add_f32_e32 v90, v90, v182
	v_add_f32_e32 v94, v94, v183
	v_mul_f32_e32 v132, v94, v125
	v_mul_f32_e32 v183, v90, v125
	v_fma_f32 v182, v90, v124, -v132
	v_fma_f32 v183, v94, v124, v183
	v_add_f32_e32 v91, v91, v184
	v_add_f32_e32 v95, v95, v185
	v_mul_f32_e32 v133, v95, v129
	v_mul_f32_e32 v185, v91, v129
	v_fma_f32 v184, v91, v128, -v133
	v_fma_f32 v185, v95, v128, v185
	v_mul_f32_e32 v132, v40, v101
	v_mul_f32_e32 v40, v40, v100
	v_fma_f32 v40, -v44, v101, v40
	v_fma_f32 v44, v44, v100, v132
	v_mul_f32_e32 v133, v41, v105
	v_mul_f32_e32 v41, v41, v104
	v_fma_f32 v41, -v45, v105, v41
	v_fma_f32 v45, v45, v104, v133
	v_mul_f32_e32 v132, v42, v109
	v_mul_f32_e32 v42, v42, v108
	v_fma_f32 v42, -v46, v109, v42
	v_fma_f32 v46, v46, v108, v132
	v_mul_f32_e32 v133, v43, v113
	v_mul_f32_e32 v43, v43, v112
	v_fma_f32 v43, -v47, v113, v43
	v_fma_f32 v47, v47, v112, v133
	v_mov_b32_e32 v88, v40
	v_mov_b32_e32 v89, v41
	v_mov_b32_e32 v90, v42
	v_mov_b32_e32 v91, v43
	v_mov_b32_e32 v92, v44
	v_mov_b32_e32 v93, v45
	v_mov_b32_e32 v94, v46
	v_mov_b32_e32 v95, v47
	v_add_f32_dpp v40, v40, v40 row_shr:1 row_mask:0xf bank_mask:0xf bound_ctrl:1
	v_add_f32_dpp v41, v41, v41 row_shr:1 row_mask:0xf bank_mask:0xf bound_ctrl:1
	v_add_f32_dpp v42, v42, v42 row_shr:1 row_mask:0xf bank_mask:0xf bound_ctrl:1
	v_add_f32_dpp v43, v43, v43 row_shr:1 row_mask:0xf bank_mask:0xf bound_ctrl:1
	v_add_f32_dpp v44, v44, v44 row_shr:1 row_mask:0xf bank_mask:0xf bound_ctrl:1
	v_add_f32_dpp v45, v45, v45 row_shr:1 row_mask:0xf bank_mask:0xf bound_ctrl:1
	v_add_f32_dpp v46, v46, v46 row_shr:1 row_mask:0xf bank_mask:0xf bound_ctrl:1
	v_add_f32_dpp v47, v47, v47 row_shr:1 row_mask:0xf bank_mask:0xf bound_ctrl:1
	v_add_f32_dpp v88, v88, v88 row_ror:8 row_mask:0xf bank_mask:0xf
	v_add_f32_dpp v89, v89, v89 row_ror:8 row_mask:0xf bank_mask:0xf
	v_add_f32_dpp v90, v90, v90 row_ror:8 row_mask:0xf bank_mask:0xf
	v_add_f32_dpp v91, v91, v91 row_ror:8 row_mask:0xf bank_mask:0xf
	v_add_f32_dpp v92, v92, v92 row_ror:8 row_mask:0xf bank_mask:0xf
	v_add_f32_dpp v93, v93, v93 row_ror:8 row_mask:0xf bank_mask:0xf
	v_add_f32_dpp v94, v94, v94 row_ror:8 row_mask:0xf bank_mask:0xf
	v_add_f32_dpp v95, v95, v95 row_ror:8 row_mask:0xf bank_mask:0xf
	v_add_f32_dpp v40, v40, v40 row_shr:2 row_mask:0xf bank_mask:0xf bound_ctrl:1
	v_add_f32_dpp v41, v41, v41 row_shr:2 row_mask:0xf bank_mask:0xf bound_ctrl:1
	v_add_f32_dpp v42, v42, v42 row_shr:2 row_mask:0xf bank_mask:0xf bound_ctrl:1
	v_add_f32_dpp v43, v43, v43 row_shr:2 row_mask:0xf bank_mask:0xf bound_ctrl:1
	v_add_f32_dpp v44, v44, v44 row_shr:2 row_mask:0xf bank_mask:0xf bound_ctrl:1
	v_add_f32_dpp v45, v45, v45 row_shr:2 row_mask:0xf bank_mask:0xf bound_ctrl:1
	v_add_f32_dpp v46, v46, v46 row_shr:2 row_mask:0xf bank_mask:0xf bound_ctrl:1
	v_add_f32_dpp v47, v47, v47 row_shr:2 row_mask:0xf bank_mask:0xf bound_ctrl:1
	v_add_f32_dpp v88, v88, v88 row_ror:4 row_mask:0xf bank_mask:0xf
	v_add_f32_dpp v89, v89, v89 row_ror:4 row_mask:0xf bank_mask:0xf
	v_add_f32_dpp v90, v90, v90 row_ror:4 row_mask:0xf bank_mask:0xf
	v_add_f32_dpp v91, v91, v91 row_ror:4 row_mask:0xf bank_mask:0xf
	v_add_f32_dpp v92, v92, v92 row_ror:4 row_mask:0xf bank_mask:0xf
	v_add_f32_dpp v93, v93, v93 row_ror:4 row_mask:0xf bank_mask:0xf
	v_add_f32_dpp v94, v94, v94 row_ror:4 row_mask:0xf bank_mask:0xf
	v_add_f32_dpp v95, v95, v95 row_ror:4 row_mask:0xf bank_mask:0xf
	v_add_f32_dpp v40, v40, v40 row_shr:4 row_mask:0xf bank_mask:0xf bound_ctrl:1
	v_add_f32_dpp v41, v41, v41 row_shr:4 row_mask:0xf bank_mask:0xf bound_ctrl:1
	v_add_f32_dpp v42, v42, v42 row_shr:4 row_mask:0xf bank_mask:0xf bound_ctrl:1
	v_add_f32_dpp v43, v43, v43 row_shr:4 row_mask:0xf bank_mask:0xf bound_ctrl:1
	v_add_f32_dpp v44, v44, v44 row_shr:4 row_mask:0xf bank_mask:0xf bound_ctrl:1
	v_add_f32_dpp v45, v45, v45 row_shr:4 row_mask:0xf bank_mask:0xf bound_ctrl:1
	v_add_f32_dpp v46, v46, v46 row_shr:4 row_mask:0xf bank_mask:0xf bound_ctrl:1
	v_add_f32_dpp v47, v47, v47 row_shr:4 row_mask:0xf bank_mask:0xf bound_ctrl:1
	v_add_f32_dpp v88, v88, v88 row_ror:2 row_mask:0xf bank_mask:0xf
	v_add_f32_dpp v89, v89, v89 row_ror:2 row_mask:0xf bank_mask:0xf
	v_add_f32_dpp v90, v90, v90 row_ror:2 row_mask:0xf bank_mask:0xf
	v_add_f32_dpp v91, v91, v91 row_ror:2 row_mask:0xf bank_mask:0xf
	v_add_f32_dpp v92, v92, v92 row_ror:2 row_mask:0xf bank_mask:0xf
	v_add_f32_dpp v93, v93, v93 row_ror:2 row_mask:0xf bank_mask:0xf
	v_add_f32_dpp v94, v94, v94 row_ror:2 row_mask:0xf bank_mask:0xf
	v_add_f32_dpp v95, v95, v95 row_ror:2 row_mask:0xf bank_mask:0xf
	v_add_f32_dpp v40, v40, v40 row_shr:8 row_mask:0xf bank_mask:0xf bound_ctrl:1
	v_add_f32_dpp v41, v41, v41 row_shr:8 row_mask:0xf bank_mask:0xf bound_ctrl:1
	v_add_f32_dpp v42, v42, v42 row_shr:8 row_mask:0xf bank_mask:0xf bound_ctrl:1
	v_add_f32_dpp v43, v43, v43 row_shr:8 row_mask:0xf bank_mask:0xf bound_ctrl:1
	v_add_f32_dpp v44, v44, v44 row_shr:8 row_mask:0xf bank_mask:0xf bound_ctrl:1
	v_add_f32_dpp v45, v45, v45 row_shr:8 row_mask:0xf bank_mask:0xf bound_ctrl:1
	v_add_f32_dpp v46, v46, v46 row_shr:8 row_mask:0xf bank_mask:0xf bound_ctrl:1
	v_add_f32_dpp v47, v47, v47 row_shr:8 row_mask:0xf bank_mask:0xf bound_ctrl:1
	v_add_f32_dpp v88, v88, v88 row_ror:1 row_mask:0xf bank_mask:0xf
	v_add_f32_dpp v89, v89, v89 row_ror:1 row_mask:0xf bank_mask:0xf
	v_add_f32_dpp v90, v90, v90 row_ror:1 row_mask:0xf bank_mask:0xf
	v_add_f32_dpp v91, v91, v91 row_ror:1 row_mask:0xf bank_mask:0xf
	v_add_f32_dpp v92, v92, v92 row_ror:1 row_mask:0xf bank_mask:0xf
	v_add_f32_dpp v93, v93, v93 row_ror:1 row_mask:0xf bank_mask:0xf
	v_add_f32_dpp v94, v94, v94 row_ror:1 row_mask:0xf bank_mask:0xf
	v_add_f32_dpp v95, v95, v95 row_ror:1 row_mask:0xf bank_mask:0xf
	v_add_f32_e32 v40, v40, v178
	v_add_f32_e32 v44, v44, v179
	v_add_f32_e32 v41, v41, v180
	v_add_f32_e32 v45, v45, v181
	v_add_f32_e32 v42, v42, v182
	v_add_f32_e32 v46, v46, v183
	v_add_f32_e32 v43, v43, v184
	v_add_f32_e32 v47, v47, v185
	v_mul_f32_e32 v132, v40, v103
	v_mul_f32_e32 v40, v40, v102
	v_fma_f32 v40, -v44, v103, v40
	v_fma_f32 v44, v44, v102, v132
	v_mul_f32_e32 v133, v41, v107
	v_mul_f32_e32 v41, v41, v106
	v_fma_f32 v41, -v45, v107, v41
	v_fma_f32 v45, v45, v106, v133
	v_mul_f32_e32 v132, v42, v111
	v_mul_f32_e32 v42, v42, v110
	v_fma_f32 v42, -v46, v111, v42
	v_fma_f32 v46, v46, v110, v132
	v_mul_f32_e32 v133, v43, v115
	v_mul_f32_e32 v43, v43, v114
	v_fma_f32 v43, -v47, v115, v43
	v_fma_f32 v47, v47, v114, v133
	v_add_f32_e32 v88, v88, v178
	v_add_f32_e32 v92, v92, v179
	v_mul_f32_e32 v132, v92, v117
	v_mul_f32_e32 v179, v88, v117
	v_fma_f32 v178, v88, v116, -v132
	v_fma_f32 v179, v92, v116, v179
	v_add_f32_e32 v89, v89, v180
	v_add_f32_e32 v93, v93, v181
	v_mul_f32_e32 v133, v93, v121
	v_mul_f32_e32 v181, v89, v121
	v_fma_f32 v180, v89, v120, -v133
	v_fma_f32 v181, v93, v120, v181
	v_add_f32_e32 v90, v90, v182
	v_add_f32_e32 v94, v94, v183
	v_mul_f32_e32 v132, v94, v125
	v_mul_f32_e32 v183, v90, v125
	v_fma_f32 v182, v90, v124, -v132
	v_fma_f32 v183, v94, v124, v183
	v_add_f32_e32 v91, v91, v184
	v_add_f32_e32 v95, v95, v185
	v_mul_f32_e32 v133, v95, v129
	v_mul_f32_e32 v185, v91, v129
	v_fma_f32 v184, v91, v128, -v133
	v_fma_f32 v185, v95, v128, v185
	v_mul_f32_e32 v132, v48, v101
	v_mul_f32_e32 v48, v48, v100
	v_fma_f32 v48, -v52, v101, v48
	v_fma_f32 v52, v52, v100, v132
	v_mul_f32_e32 v133, v49, v105
	v_mul_f32_e32 v49, v49, v104
	v_fma_f32 v49, -v53, v105, v49
	v_fma_f32 v53, v53, v104, v133
	v_mul_f32_e32 v132, v50, v109
	v_mul_f32_e32 v50, v50, v108
	v_fma_f32 v50, -v54, v109, v50
	v_fma_f32 v54, v54, v108, v132
	v_mul_f32_e32 v133, v51, v113
	v_mul_f32_e32 v51, v51, v112
	v_fma_f32 v51, -v55, v113, v51
	v_fma_f32 v55, v55, v112, v133
	v_mov_b32_e32 v88, v48
	v_mov_b32_e32 v89, v49
	v_mov_b32_e32 v90, v50
	v_mov_b32_e32 v91, v51
	v_mov_b32_e32 v92, v52
	v_mov_b32_e32 v93, v53
	v_mov_b32_e32 v94, v54
	v_mov_b32_e32 v95, v55
	v_add_f32_dpp v48, v48, v48 row_shr:1 row_mask:0xf bank_mask:0xf bound_ctrl:1
	v_add_f32_dpp v49, v49, v49 row_shr:1 row_mask:0xf bank_mask:0xf bound_ctrl:1
	v_add_f32_dpp v50, v50, v50 row_shr:1 row_mask:0xf bank_mask:0xf bound_ctrl:1
	v_add_f32_dpp v51, v51, v51 row_shr:1 row_mask:0xf bank_mask:0xf bound_ctrl:1
	v_add_f32_dpp v52, v52, v52 row_shr:1 row_mask:0xf bank_mask:0xf bound_ctrl:1
	v_add_f32_dpp v53, v53, v53 row_shr:1 row_mask:0xf bank_mask:0xf bound_ctrl:1
	v_add_f32_dpp v54, v54, v54 row_shr:1 row_mask:0xf bank_mask:0xf bound_ctrl:1
	v_add_f32_dpp v55, v55, v55 row_shr:1 row_mask:0xf bank_mask:0xf bound_ctrl:1
	v_add_f32_dpp v88, v88, v88 row_ror:8 row_mask:0xf bank_mask:0xf
	v_add_f32_dpp v89, v89, v89 row_ror:8 row_mask:0xf bank_mask:0xf
	v_add_f32_dpp v90, v90, v90 row_ror:8 row_mask:0xf bank_mask:0xf
	v_add_f32_dpp v91, v91, v91 row_ror:8 row_mask:0xf bank_mask:0xf
	v_add_f32_dpp v92, v92, v92 row_ror:8 row_mask:0xf bank_mask:0xf
	v_add_f32_dpp v93, v93, v93 row_ror:8 row_mask:0xf bank_mask:0xf
	v_add_f32_dpp v94, v94, v94 row_ror:8 row_mask:0xf bank_mask:0xf
	v_add_f32_dpp v95, v95, v95 row_ror:8 row_mask:0xf bank_mask:0xf
	v_add_f32_dpp v48, v48, v48 row_shr:2 row_mask:0xf bank_mask:0xf bound_ctrl:1
	v_add_f32_dpp v49, v49, v49 row_shr:2 row_mask:0xf bank_mask:0xf bound_ctrl:1
	v_add_f32_dpp v50, v50, v50 row_shr:2 row_mask:0xf bank_mask:0xf bound_ctrl:1
	v_add_f32_dpp v51, v51, v51 row_shr:2 row_mask:0xf bank_mask:0xf bound_ctrl:1
	v_add_f32_dpp v52, v52, v52 row_shr:2 row_mask:0xf bank_mask:0xf bound_ctrl:1
	v_add_f32_dpp v53, v53, v53 row_shr:2 row_mask:0xf bank_mask:0xf bound_ctrl:1
	v_add_f32_dpp v54, v54, v54 row_shr:2 row_mask:0xf bank_mask:0xf bound_ctrl:1
	v_add_f32_dpp v55, v55, v55 row_shr:2 row_mask:0xf bank_mask:0xf bound_ctrl:1
	v_add_f32_dpp v88, v88, v88 row_ror:4 row_mask:0xf bank_mask:0xf
	v_add_f32_dpp v89, v89, v89 row_ror:4 row_mask:0xf bank_mask:0xf
	v_add_f32_dpp v90, v90, v90 row_ror:4 row_mask:0xf bank_mask:0xf
	v_add_f32_dpp v91, v91, v91 row_ror:4 row_mask:0xf bank_mask:0xf
	v_add_f32_dpp v92, v92, v92 row_ror:4 row_mask:0xf bank_mask:0xf
	v_add_f32_dpp v93, v93, v93 row_ror:4 row_mask:0xf bank_mask:0xf
	v_add_f32_dpp v94, v94, v94 row_ror:4 row_mask:0xf bank_mask:0xf
	v_add_f32_dpp v95, v95, v95 row_ror:4 row_mask:0xf bank_mask:0xf
	v_add_f32_dpp v48, v48, v48 row_shr:4 row_mask:0xf bank_mask:0xf bound_ctrl:1
	v_add_f32_dpp v49, v49, v49 row_shr:4 row_mask:0xf bank_mask:0xf bound_ctrl:1
	v_add_f32_dpp v50, v50, v50 row_shr:4 row_mask:0xf bank_mask:0xf bound_ctrl:1
	v_add_f32_dpp v51, v51, v51 row_shr:4 row_mask:0xf bank_mask:0xf bound_ctrl:1
	v_add_f32_dpp v52, v52, v52 row_shr:4 row_mask:0xf bank_mask:0xf bound_ctrl:1
	v_add_f32_dpp v53, v53, v53 row_shr:4 row_mask:0xf bank_mask:0xf bound_ctrl:1
	v_add_f32_dpp v54, v54, v54 row_shr:4 row_mask:0xf bank_mask:0xf bound_ctrl:1
	v_add_f32_dpp v55, v55, v55 row_shr:4 row_mask:0xf bank_mask:0xf bound_ctrl:1
	v_add_f32_dpp v88, v88, v88 row_ror:2 row_mask:0xf bank_mask:0xf
	v_add_f32_dpp v89, v89, v89 row_ror:2 row_mask:0xf bank_mask:0xf
	v_add_f32_dpp v90, v90, v90 row_ror:2 row_mask:0xf bank_mask:0xf
	v_add_f32_dpp v91, v91, v91 row_ror:2 row_mask:0xf bank_mask:0xf
	v_add_f32_dpp v92, v92, v92 row_ror:2 row_mask:0xf bank_mask:0xf
	v_add_f32_dpp v93, v93, v93 row_ror:2 row_mask:0xf bank_mask:0xf
	v_add_f32_dpp v94, v94, v94 row_ror:2 row_mask:0xf bank_mask:0xf
	v_add_f32_dpp v95, v95, v95 row_ror:2 row_mask:0xf bank_mask:0xf
	v_add_f32_dpp v48, v48, v48 row_shr:8 row_mask:0xf bank_mask:0xf bound_ctrl:1
	v_add_f32_dpp v49, v49, v49 row_shr:8 row_mask:0xf bank_mask:0xf bound_ctrl:1
	v_add_f32_dpp v50, v50, v50 row_shr:8 row_mask:0xf bank_mask:0xf bound_ctrl:1
	v_add_f32_dpp v51, v51, v51 row_shr:8 row_mask:0xf bank_mask:0xf bound_ctrl:1
	v_add_f32_dpp v52, v52, v52 row_shr:8 row_mask:0xf bank_mask:0xf bound_ctrl:1
	v_add_f32_dpp v53, v53, v53 row_shr:8 row_mask:0xf bank_mask:0xf bound_ctrl:1
	v_add_f32_dpp v54, v54, v54 row_shr:8 row_mask:0xf bank_mask:0xf bound_ctrl:1
	v_add_f32_dpp v55, v55, v55 row_shr:8 row_mask:0xf bank_mask:0xf bound_ctrl:1
	v_add_f32_dpp v88, v88, v88 row_ror:1 row_mask:0xf bank_mask:0xf
	v_add_f32_dpp v89, v89, v89 row_ror:1 row_mask:0xf bank_mask:0xf
	v_add_f32_dpp v90, v90, v90 row_ror:1 row_mask:0xf bank_mask:0xf
	v_add_f32_dpp v91, v91, v91 row_ror:1 row_mask:0xf bank_mask:0xf
	v_add_f32_dpp v92, v92, v92 row_ror:1 row_mask:0xf bank_mask:0xf
	v_add_f32_dpp v93, v93, v93 row_ror:1 row_mask:0xf bank_mask:0xf
	v_add_f32_dpp v94, v94, v94 row_ror:1 row_mask:0xf bank_mask:0xf
	v_add_f32_dpp v95, v95, v95 row_ror:1 row_mask:0xf bank_mask:0xf
	v_add_f32_e32 v48, v48, v178
	v_add_f32_e32 v52, v52, v179
	v_add_f32_e32 v49, v49, v180
	v_add_f32_e32 v53, v53, v181
	v_add_f32_e32 v50, v50, v182
	v_add_f32_e32 v54, v54, v183
	v_add_f32_e32 v51, v51, v184
	v_add_f32_e32 v55, v55, v185
	v_mul_f32_e32 v132, v48, v103
	v_mul_f32_e32 v48, v48, v102
	v_fma_f32 v48, -v52, v103, v48
	v_fma_f32 v52, v52, v102, v132
	v_mul_f32_e32 v133, v49, v107
	v_mul_f32_e32 v49, v49, v106
	v_fma_f32 v49, -v53, v107, v49
	v_fma_f32 v53, v53, v106, v133
	v_mul_f32_e32 v132, v50, v111
	v_mul_f32_e32 v50, v50, v110
	v_fma_f32 v50, -v54, v111, v50
	v_fma_f32 v54, v54, v110, v132
	v_mul_f32_e32 v133, v51, v115
	v_mul_f32_e32 v51, v51, v114
	v_fma_f32 v51, -v55, v115, v51
	v_fma_f32 v55, v55, v114, v133
	v_add_f32_e32 v88, v88, v178
	v_add_f32_e32 v92, v92, v179
	v_mul_f32_e32 v132, v92, v117
	v_mul_f32_e32 v179, v88, v117
	v_fma_f32 v178, v88, v116, -v132
	v_fma_f32 v179, v92, v116, v179
	v_add_f32_e32 v89, v89, v180
	v_add_f32_e32 v93, v93, v181
	v_mul_f32_e32 v133, v93, v121
	v_mul_f32_e32 v181, v89, v121
	v_fma_f32 v180, v89, v120, -v133
	v_fma_f32 v181, v93, v120, v181
	v_add_f32_e32 v90, v90, v182
	v_add_f32_e32 v94, v94, v183
	v_mul_f32_e32 v132, v94, v125
	v_mul_f32_e32 v183, v90, v125
	v_fma_f32 v182, v90, v124, -v132
	v_fma_f32 v183, v94, v124, v183
	v_add_f32_e32 v91, v91, v184
	v_add_f32_e32 v95, v95, v185
	v_mul_f32_e32 v133, v95, v129
	v_mul_f32_e32 v185, v91, v129
	v_fma_f32 v184, v91, v128, -v133
	v_fma_f32 v185, v95, v128, v185
	v_mul_f32_e32 v132, v56, v101
	v_mul_f32_e32 v56, v56, v100
	v_fma_f32 v56, -v60, v101, v56
	v_fma_f32 v60, v60, v100, v132
	v_mul_f32_e32 v133, v57, v105
	v_mul_f32_e32 v57, v57, v104
	v_fma_f32 v57, -v61, v105, v57
	v_fma_f32 v61, v61, v104, v133
	v_mul_f32_e32 v132, v58, v109
	v_mul_f32_e32 v58, v58, v108
	v_fma_f32 v58, -v62, v109, v58
	v_fma_f32 v62, v62, v108, v132
	v_mul_f32_e32 v133, v59, v113
	v_mul_f32_e32 v59, v59, v112
	v_fma_f32 v59, -v63, v113, v59
	v_fma_f32 v63, v63, v112, v133
	v_mov_b32_e32 v88, v56
	v_mov_b32_e32 v89, v57
	v_mov_b32_e32 v90, v58
	v_mov_b32_e32 v91, v59
	v_mov_b32_e32 v92, v60
	v_mov_b32_e32 v93, v61
	v_mov_b32_e32 v94, v62
	v_mov_b32_e32 v95, v63
	v_add_f32_dpp v56, v56, v56 row_shr:1 row_mask:0xf bank_mask:0xf bound_ctrl:1
	v_add_f32_dpp v57, v57, v57 row_shr:1 row_mask:0xf bank_mask:0xf bound_ctrl:1
	v_add_f32_dpp v58, v58, v58 row_shr:1 row_mask:0xf bank_mask:0xf bound_ctrl:1
	v_add_f32_dpp v59, v59, v59 row_shr:1 row_mask:0xf bank_mask:0xf bound_ctrl:1
	v_add_f32_dpp v60, v60, v60 row_shr:1 row_mask:0xf bank_mask:0xf bound_ctrl:1
	v_add_f32_dpp v61, v61, v61 row_shr:1 row_mask:0xf bank_mask:0xf bound_ctrl:1
	v_add_f32_dpp v62, v62, v62 row_shr:1 row_mask:0xf bank_mask:0xf bound_ctrl:1
	v_add_f32_dpp v63, v63, v63 row_shr:1 row_mask:0xf bank_mask:0xf bound_ctrl:1
	v_add_f32_dpp v88, v88, v88 row_ror:8 row_mask:0xf bank_mask:0xf
	v_add_f32_dpp v89, v89, v89 row_ror:8 row_mask:0xf bank_mask:0xf
	v_add_f32_dpp v90, v90, v90 row_ror:8 row_mask:0xf bank_mask:0xf
	v_add_f32_dpp v91, v91, v91 row_ror:8 row_mask:0xf bank_mask:0xf
	v_add_f32_dpp v92, v92, v92 row_ror:8 row_mask:0xf bank_mask:0xf
	v_add_f32_dpp v93, v93, v93 row_ror:8 row_mask:0xf bank_mask:0xf
	v_add_f32_dpp v94, v94, v94 row_ror:8 row_mask:0xf bank_mask:0xf
	v_add_f32_dpp v95, v95, v95 row_ror:8 row_mask:0xf bank_mask:0xf
	v_add_f32_dpp v56, v56, v56 row_shr:2 row_mask:0xf bank_mask:0xf bound_ctrl:1
	v_add_f32_dpp v57, v57, v57 row_shr:2 row_mask:0xf bank_mask:0xf bound_ctrl:1
	v_add_f32_dpp v58, v58, v58 row_shr:2 row_mask:0xf bank_mask:0xf bound_ctrl:1
	v_add_f32_dpp v59, v59, v59 row_shr:2 row_mask:0xf bank_mask:0xf bound_ctrl:1
	v_add_f32_dpp v60, v60, v60 row_shr:2 row_mask:0xf bank_mask:0xf bound_ctrl:1
	v_add_f32_dpp v61, v61, v61 row_shr:2 row_mask:0xf bank_mask:0xf bound_ctrl:1
	v_add_f32_dpp v62, v62, v62 row_shr:2 row_mask:0xf bank_mask:0xf bound_ctrl:1
	v_add_f32_dpp v63, v63, v63 row_shr:2 row_mask:0xf bank_mask:0xf bound_ctrl:1
	v_add_f32_dpp v88, v88, v88 row_ror:4 row_mask:0xf bank_mask:0xf
	v_add_f32_dpp v89, v89, v89 row_ror:4 row_mask:0xf bank_mask:0xf
	v_add_f32_dpp v90, v90, v90 row_ror:4 row_mask:0xf bank_mask:0xf
	v_add_f32_dpp v91, v91, v91 row_ror:4 row_mask:0xf bank_mask:0xf
	v_add_f32_dpp v92, v92, v92 row_ror:4 row_mask:0xf bank_mask:0xf
	v_add_f32_dpp v93, v93, v93 row_ror:4 row_mask:0xf bank_mask:0xf
	v_add_f32_dpp v94, v94, v94 row_ror:4 row_mask:0xf bank_mask:0xf
	v_add_f32_dpp v95, v95, v95 row_ror:4 row_mask:0xf bank_mask:0xf
	v_add_f32_dpp v56, v56, v56 row_shr:4 row_mask:0xf bank_mask:0xf bound_ctrl:1
	v_add_f32_dpp v57, v57, v57 row_shr:4 row_mask:0xf bank_mask:0xf bound_ctrl:1
	v_add_f32_dpp v58, v58, v58 row_shr:4 row_mask:0xf bank_mask:0xf bound_ctrl:1
	v_add_f32_dpp v59, v59, v59 row_shr:4 row_mask:0xf bank_mask:0xf bound_ctrl:1
	v_add_f32_dpp v60, v60, v60 row_shr:4 row_mask:0xf bank_mask:0xf bound_ctrl:1
	v_add_f32_dpp v61, v61, v61 row_shr:4 row_mask:0xf bank_mask:0xf bound_ctrl:1
	v_add_f32_dpp v62, v62, v62 row_shr:4 row_mask:0xf bank_mask:0xf bound_ctrl:1
	v_add_f32_dpp v63, v63, v63 row_shr:4 row_mask:0xf bank_mask:0xf bound_ctrl:1
	v_add_f32_dpp v88, v88, v88 row_ror:2 row_mask:0xf bank_mask:0xf
	v_add_f32_dpp v89, v89, v89 row_ror:2 row_mask:0xf bank_mask:0xf
	v_add_f32_dpp v90, v90, v90 row_ror:2 row_mask:0xf bank_mask:0xf
	v_add_f32_dpp v91, v91, v91 row_ror:2 row_mask:0xf bank_mask:0xf
	v_add_f32_dpp v92, v92, v92 row_ror:2 row_mask:0xf bank_mask:0xf
	v_add_f32_dpp v93, v93, v93 row_ror:2 row_mask:0xf bank_mask:0xf
	v_add_f32_dpp v94, v94, v94 row_ror:2 row_mask:0xf bank_mask:0xf
	v_add_f32_dpp v95, v95, v95 row_ror:2 row_mask:0xf bank_mask:0xf
	v_add_f32_dpp v56, v56, v56 row_shr:8 row_mask:0xf bank_mask:0xf bound_ctrl:1
	v_add_f32_dpp v57, v57, v57 row_shr:8 row_mask:0xf bank_mask:0xf bound_ctrl:1
	v_add_f32_dpp v58, v58, v58 row_shr:8 row_mask:0xf bank_mask:0xf bound_ctrl:1
	v_add_f32_dpp v59, v59, v59 row_shr:8 row_mask:0xf bank_mask:0xf bound_ctrl:1
	v_add_f32_dpp v60, v60, v60 row_shr:8 row_mask:0xf bank_mask:0xf bound_ctrl:1
	v_add_f32_dpp v61, v61, v61 row_shr:8 row_mask:0xf bank_mask:0xf bound_ctrl:1
	v_add_f32_dpp v62, v62, v62 row_shr:8 row_mask:0xf bank_mask:0xf bound_ctrl:1
	v_add_f32_dpp v63, v63, v63 row_shr:8 row_mask:0xf bank_mask:0xf bound_ctrl:1
	v_add_f32_dpp v88, v88, v88 row_ror:1 row_mask:0xf bank_mask:0xf
	v_add_f32_dpp v89, v89, v89 row_ror:1 row_mask:0xf bank_mask:0xf
	v_add_f32_dpp v90, v90, v90 row_ror:1 row_mask:0xf bank_mask:0xf
	v_add_f32_dpp v91, v91, v91 row_ror:1 row_mask:0xf bank_mask:0xf
	v_add_f32_dpp v92, v92, v92 row_ror:1 row_mask:0xf bank_mask:0xf
	v_add_f32_dpp v93, v93, v93 row_ror:1 row_mask:0xf bank_mask:0xf
	v_add_f32_dpp v94, v94, v94 row_ror:1 row_mask:0xf bank_mask:0xf
	v_add_f32_dpp v95, v95, v95 row_ror:1 row_mask:0xf bank_mask:0xf
	v_add_f32_e32 v56, v56, v178
	v_add_f32_e32 v60, v60, v179
	v_add_f32_e32 v57, v57, v180
	v_add_f32_e32 v61, v61, v181
	v_add_f32_e32 v58, v58, v182
	v_add_f32_e32 v62, v62, v183
	v_add_f32_e32 v59, v59, v184
	v_add_f32_e32 v63, v63, v185
	v_mul_f32_e32 v132, v56, v103
	v_mul_f32_e32 v56, v56, v102
	v_fma_f32 v56, -v60, v103, v56
	v_fma_f32 v60, v60, v102, v132
	v_mul_f32_e32 v133, v57, v107
	v_mul_f32_e32 v57, v57, v106
	v_fma_f32 v57, -v61, v107, v57
	v_fma_f32 v61, v61, v106, v133
	v_mul_f32_e32 v132, v58, v111
	v_mul_f32_e32 v58, v58, v110
	v_fma_f32 v58, -v62, v111, v58
	v_fma_f32 v62, v62, v110, v132
	v_mul_f32_e32 v133, v59, v115
	v_mul_f32_e32 v59, v59, v114
	v_fma_f32 v59, -v63, v115, v59
	v_fma_f32 v63, v63, v114, v133
	v_add_f32_e32 v88, v88, v178
	v_add_f32_e32 v92, v92, v179
	v_mul_f32_e32 v132, v92, v117
	v_mul_f32_e32 v179, v88, v117
	v_fma_f32 v178, v88, v116, -v132
	v_fma_f32 v179, v92, v116, v179
	v_add_f32_e32 v89, v89, v180
	v_add_f32_e32 v93, v93, v181
	v_mul_f32_e32 v133, v93, v121
	v_mul_f32_e32 v181, v89, v121
	v_fma_f32 v180, v89, v120, -v133
	v_fma_f32 v181, v93, v120, v181
	v_add_f32_e32 v90, v90, v182
	v_add_f32_e32 v94, v94, v183
	v_mul_f32_e32 v132, v94, v125
	v_mul_f32_e32 v183, v90, v125
	v_fma_f32 v182, v90, v124, -v132
	v_fma_f32 v183, v94, v124, v183
	v_add_f32_e32 v91, v91, v184
	v_add_f32_e32 v95, v95, v185
	v_mul_f32_e32 v133, v95, v129
	v_mul_f32_e32 v185, v91, v129
	v_fma_f32 v184, v91, v128, -v133
	v_fma_f32 v185, v95, v128, v185
	s_waitcnt vmcnt(14)
	v_cvt_pk_bf16_f32 v80, v80, v81
	v_cvt_pk_bf16_f32 v81, v82, v83
	v_cvt_pk_bf16_f32 v82, -v84, -v85
	v_cvt_pk_bf16_f32 v83, -v86, -v87
	v_cvt_pk_bf16_f32 v96, v32, v33
	v_cvt_pk_bf16_f32 v97, v34, v35
	v_cvt_pk_bf16_f32 v98, v36, v37
	v_cvt_pk_bf16_f32 v99, v38, v39
	s_nop 1
	v_mfma_f32_16x16x32_bf16 v[16:19], v[80:83], v[96:99], v[16:19]
	v_cvt_pk_bf16_f32 v96, v40, v41
	v_cvt_pk_bf16_f32 v97, v42, v43
	v_cvt_pk_bf16_f32 v98, v44, v45
	v_cvt_pk_bf16_f32 v99, v46, v47
	s_nop 1
	v_mfma_f32_16x16x32_bf16 v[20:23], v[80:83], v[96:99], v[20:23]
	v_cvt_pk_bf16_f32 v96, v48, v49
	v_cvt_pk_bf16_f32 v97, v50, v51
	v_cvt_pk_bf16_f32 v98, v52, v53
	v_cvt_pk_bf16_f32 v99, v54, v55
	s_nop 1
	v_mfma_f32_16x16x32_bf16 v[24:27], v[80:83], v[96:99], v[24:27]
	v_cvt_pk_bf16_f32 v96, v56, v57
	v_cvt_pk_bf16_f32 v97, v58, v59
	v_cvt_pk_bf16_f32 v98, v60, v61
	v_cvt_pk_bf16_f32 v99, v62, v63
	s_nop 1
	v_mfma_f32_16x16x32_bf16 v[28:31], v[80:83], v[96:99], v[28:31]
	s_waitcnt vmcnt(10)
	v_cvt_pk_bf16_f32 v64, v64, v65
	v_cvt_pk_bf16_f32 v65, v66, v67
	v_cvt_pk_bf16_f32 v66, v68, v69
	v_cvt_pk_bf16_f32 v67, v70, v71
	v_cvt_pk_bf16_f32 v72, v72, v73
	v_cvt_pk_bf16_f32 v73, v74, v75
	v_cvt_pk_bf16_f32 v74, v76, v77
	v_cvt_pk_bf16_f32 v75, v78, v79
	global_load_dwordx4 v[80:83], v136, s[38:39]
	global_load_dwordx4 v[84:87], v136, s[40:41]
	s_add_u32 s38, s38, 0x40
	s_addc_u32 s39, s39, 0
	s_add_u32 s40, s40, 0x40
	s_addc_u32 s41, s41, 0
	s_nop 0
	v_mfma_f32_16x16x32_bf16 v[32:35], v[64:67], v[0:3], 0
	v_mfma_f32_16x16x32_bf16 v[36:39], v[72:75], v[0:3], 0
	v_mfma_f32_16x16x32_bf16 v[40:43], v[64:67], v[4:7], 0
	v_mfma_f32_16x16x32_bf16 v[44:47], v[72:75], v[4:7], 0
	v_mfma_f32_16x16x32_bf16 v[48:51], v[64:67], v[8:11], 0
	v_mfma_f32_16x16x32_bf16 v[52:55], v[72:75], v[8:11], 0
	v_mfma_f32_16x16x32_bf16 v[56:59], v[64:67], v[12:15], 0
	v_mfma_f32_16x16x32_bf16 v[60:63], v[72:75], v[12:15], 0
	s_mov_b32 exec_hi, 0
	global_load_dwordx4 v[64:67], v135, s[20:21]
	global_load_dwordx4 v[68:71], v135, s[20:21] offset:16
	global_load_dwordx4 v[72:75], v135, s[22:23]
	global_load_dwordx4 v[76:79], v135, s[22:23] offset:16
	s_mov_b64 exec, -1
	global_load_dwordx4 v[100:103], v134, s[42:43] offset:0
	global_load_dwordx4 v[104:107], v134, s[42:43] offset:16
	global_load_dwordx4 v[108:111], v134, s[42:43] offset:32
	global_load_dwordx4 v[112:115], v134, s[42:43] offset:48
	global_load_dwordx4 v[116:119], v134, s[42:43] offset:64
	global_load_dwordx4 v[120:123], v134, s[42:43] offset:80
	global_load_dwordx4 v[124:127], v134, s[42:43] offset:96
	global_load_dwordx4 v[128:131], v134, s[42:43] offset:112
	global_load_dwordx4 v[178:181], v206, s[44:45]
	global_load_dwordx4 v[182:185], v206, s[44:45] offset:16
	s_waitcnt vmcnt(16)
	v_mul_f32_e32 v132, v171, v157
	v_mul_f32_e32 v133, v170, v157
	v_fma_f32 v170, v170, v156, -v132
	v_fma_f32 v171, v171, v156, v133
	v_mul_f32_e32 v132, v173, v161
	v_mul_f32_e32 v133, v172, v161
	v_fma_f32 v172, v172, v160, -v132
	v_fma_f32 v173, v173, v160, v133
	v_mul_f32_e32 v132, v175, v165
	v_mul_f32_e32 v133, v174, v165
	v_fma_f32 v174, v174, v164, -v132
	v_fma_f32 v175, v175, v164, v133
	v_mul_f32_e32 v132, v177, v169
	v_mul_f32_e32 v133, v176, v169
	v_fma_f32 v176, v176, v168, -v132
	v_fma_f32 v177, v177, v168, v133
	v_mul_f32_e32 v132, v32, v139
	v_mul_f32_e32 v32, v32, v138
	v_fma_f32 v32, -v36, v139, v32
	v_fma_f32 v36, v36, v138, v132
	v_mul_f32_e32 v133, v33, v143
	v_mul_f32_e32 v33, v33, v142
	v_fma_f32 v33, -v37, v143, v33
	v_fma_f32 v37, v37, v142, v133
	v_mul_f32_e32 v132, v34, v147
	v_mul_f32_e32 v34, v34, v146
	v_fma_f32 v34, -v38, v147, v34
	v_fma_f32 v38, v38, v146, v132
	v_mul_f32_e32 v133, v35, v151
	v_mul_f32_e32 v35, v35, v150
	v_fma_f32 v35, -v39, v151, v35
	v_fma_f32 v39, v39, v150, v133
	v_mov_b32_e32 v88, v32
	v_mov_b32_e32 v89, v33
	v_mov_b32_e32 v90, v34
	v_mov_b32_e32 v91, v35
	v_mov_b32_e32 v92, v36
	v_mov_b32_e32 v93, v37
	v_mov_b32_e32 v94, v38
	v_mov_b32_e32 v95, v39
	v_add_f32_dpp v32, v32, v32 row_shr:1 row_mask:0xf bank_mask:0xf bound_ctrl:1
	v_add_f32_dpp v33, v33, v33 row_shr:1 row_mask:0xf bank_mask:0xf bound_ctrl:1
	v_add_f32_dpp v34, v34, v34 row_shr:1 row_mask:0xf bank_mask:0xf bound_ctrl:1
	v_add_f32_dpp v35, v35, v35 row_shr:1 row_mask:0xf bank_mask:0xf bound_ctrl:1
	v_add_f32_dpp v36, v36, v36 row_shr:1 row_mask:0xf bank_mask:0xf bound_ctrl:1
	v_add_f32_dpp v37, v37, v37 row_shr:1 row_mask:0xf bank_mask:0xf bound_ctrl:1
	v_add_f32_dpp v38, v38, v38 row_shr:1 row_mask:0xf bank_mask:0xf bound_ctrl:1
	v_add_f32_dpp v39, v39, v39 row_shr:1 row_mask:0xf bank_mask:0xf bound_ctrl:1
	v_add_f32_dpp v88, v88, v88 row_ror:8 row_mask:0xf bank_mask:0xf
	v_add_f32_dpp v89, v89, v89 row_ror:8 row_mask:0xf bank_mask:0xf
	v_add_f32_dpp v90, v90, v90 row_ror:8 row_mask:0xf bank_mask:0xf
	v_add_f32_dpp v91, v91, v91 row_ror:8 row_mask:0xf bank_mask:0xf
	v_add_f32_dpp v92, v92, v92 row_ror:8 row_mask:0xf bank_mask:0xf
	v_add_f32_dpp v93, v93, v93 row_ror:8 row_mask:0xf bank_mask:0xf
	v_add_f32_dpp v94, v94, v94 row_ror:8 row_mask:0xf bank_mask:0xf
	v_add_f32_dpp v95, v95, v95 row_ror:8 row_mask:0xf bank_mask:0xf
	v_add_f32_dpp v32, v32, v32 row_shr:2 row_mask:0xf bank_mask:0xf bound_ctrl:1
	v_add_f32_dpp v33, v33, v33 row_shr:2 row_mask:0xf bank_mask:0xf bound_ctrl:1
	v_add_f32_dpp v34, v34, v34 row_shr:2 row_mask:0xf bank_mask:0xf bound_ctrl:1
	v_add_f32_dpp v35, v35, v35 row_shr:2 row_mask:0xf bank_mask:0xf bound_ctrl:1
	v_add_f32_dpp v36, v36, v36 row_shr:2 row_mask:0xf bank_mask:0xf bound_ctrl:1
	v_add_f32_dpp v37, v37, v37 row_shr:2 row_mask:0xf bank_mask:0xf bound_ctrl:1
	v_add_f32_dpp v38, v38, v38 row_shr:2 row_mask:0xf bank_mask:0xf bound_ctrl:1
	v_add_f32_dpp v39, v39, v39 row_shr:2 row_mask:0xf bank_mask:0xf bound_ctrl:1
	v_add_f32_dpp v88, v88, v88 row_ror:4 row_mask:0xf bank_mask:0xf
	v_add_f32_dpp v89, v89, v89 row_ror:4 row_mask:0xf bank_mask:0xf
	v_add_f32_dpp v90, v90, v90 row_ror:4 row_mask:0xf bank_mask:0xf
	v_add_f32_dpp v91, v91, v91 row_ror:4 row_mask:0xf bank_mask:0xf
	v_add_f32_dpp v92, v92, v92 row_ror:4 row_mask:0xf bank_mask:0xf
	v_add_f32_dpp v93, v93, v93 row_ror:4 row_mask:0xf bank_mask:0xf
	v_add_f32_dpp v94, v94, v94 row_ror:4 row_mask:0xf bank_mask:0xf
	v_add_f32_dpp v95, v95, v95 row_ror:4 row_mask:0xf bank_mask:0xf
	v_add_f32_dpp v32, v32, v32 row_shr:4 row_mask:0xf bank_mask:0xf bound_ctrl:1
	v_add_f32_dpp v33, v33, v33 row_shr:4 row_mask:0xf bank_mask:0xf bound_ctrl:1
	v_add_f32_dpp v34, v34, v34 row_shr:4 row_mask:0xf bank_mask:0xf bound_ctrl:1
	v_add_f32_dpp v35, v35, v35 row_shr:4 row_mask:0xf bank_mask:0xf bound_ctrl:1
	v_add_f32_dpp v36, v36, v36 row_shr:4 row_mask:0xf bank_mask:0xf bound_ctrl:1
	v_add_f32_dpp v37, v37, v37 row_shr:4 row_mask:0xf bank_mask:0xf bound_ctrl:1
	v_add_f32_dpp v38, v38, v38 row_shr:4 row_mask:0xf bank_mask:0xf bound_ctrl:1
	v_add_f32_dpp v39, v39, v39 row_shr:4 row_mask:0xf bank_mask:0xf bound_ctrl:1
	v_add_f32_dpp v88, v88, v88 row_ror:2 row_mask:0xf bank_mask:0xf
	v_add_f32_dpp v89, v89, v89 row_ror:2 row_mask:0xf bank_mask:0xf
	v_add_f32_dpp v90, v90, v90 row_ror:2 row_mask:0xf bank_mask:0xf
	v_add_f32_dpp v91, v91, v91 row_ror:2 row_mask:0xf bank_mask:0xf
	v_add_f32_dpp v92, v92, v92 row_ror:2 row_mask:0xf bank_mask:0xf
	v_add_f32_dpp v93, v93, v93 row_ror:2 row_mask:0xf bank_mask:0xf
	v_add_f32_dpp v94, v94, v94 row_ror:2 row_mask:0xf bank_mask:0xf
	v_add_f32_dpp v95, v95, v95 row_ror:2 row_mask:0xf bank_mask:0xf
	v_add_f32_dpp v32, v32, v32 row_shr:8 row_mask:0xf bank_mask:0xf bound_ctrl:1
	v_add_f32_dpp v33, v33, v33 row_shr:8 row_mask:0xf bank_mask:0xf bound_ctrl:1
	v_add_f32_dpp v34, v34, v34 row_shr:8 row_mask:0xf bank_mask:0xf bound_ctrl:1
	v_add_f32_dpp v35, v35, v35 row_shr:8 row_mask:0xf bank_mask:0xf bound_ctrl:1
	v_add_f32_dpp v36, v36, v36 row_shr:8 row_mask:0xf bank_mask:0xf bound_ctrl:1
	v_add_f32_dpp v37, v37, v37 row_shr:8 row_mask:0xf bank_mask:0xf bound_ctrl:1
	v_add_f32_dpp v38, v38, v38 row_shr:8 row_mask:0xf bank_mask:0xf bound_ctrl:1
	v_add_f32_dpp v39, v39, v39 row_shr:8 row_mask:0xf bank_mask:0xf bound_ctrl:1
	v_add_f32_dpp v88, v88, v88 row_ror:1 row_mask:0xf bank_mask:0xf
	v_add_f32_dpp v89, v89, v89 row_ror:1 row_mask:0xf bank_mask:0xf
	v_add_f32_dpp v90, v90, v90 row_ror:1 row_mask:0xf bank_mask:0xf
	v_add_f32_dpp v91, v91, v91 row_ror:1 row_mask:0xf bank_mask:0xf
	v_add_f32_dpp v92, v92, v92 row_ror:1 row_mask:0xf bank_mask:0xf
	v_add_f32_dpp v93, v93, v93 row_ror:1 row_mask:0xf bank_mask:0xf
	v_add_f32_dpp v94, v94, v94 row_ror:1 row_mask:0xf bank_mask:0xf
	v_add_f32_dpp v95, v95, v95 row_ror:1 row_mask:0xf bank_mask:0xf
	v_add_f32_e32 v32, v32, v170
	v_add_f32_e32 v36, v36, v171
	v_add_f32_e32 v33, v33, v172
	v_add_f32_e32 v37, v37, v173
	v_add_f32_e32 v34, v34, v174
	v_add_f32_e32 v38, v38, v175
	v_add_f32_e32 v35, v35, v176
	v_add_f32_e32 v39, v39, v177
	v_mul_f32_e32 v132, v32, v141
	v_mul_f32_e32 v32, v32, v140
	v_fma_f32 v32, -v36, v141, v32
	v_fma_f32 v36, v36, v140, v132
	v_mul_f32_e32 v133, v33, v145
	v_mul_f32_e32 v33, v33, v144
	v_fma_f32 v33, -v37, v145, v33
	v_fma_f32 v37, v37, v144, v133
	v_mul_f32_e32 v132, v34, v149
	v_mul_f32_e32 v34, v34, v148
	v_fma_f32 v34, -v38, v149, v34
	v_fma_f32 v38, v38, v148, v132
	v_mul_f32_e32 v133, v35, v153
	v_mul_f32_e32 v35, v35, v152
	v_fma_f32 v35, -v39, v153, v35
	v_fma_f32 v39, v39, v152, v133
	v_add_f32_e32 v88, v88, v170
	v_add_f32_e32 v92, v92, v171
	v_mul_f32_e32 v132, v92, v155
	v_mul_f32_e32 v171, v88, v155
	v_fma_f32 v170, v88, v154, -v132
	v_fma_f32 v171, v92, v154, v171
	v_add_f32_e32 v89, v89, v172
	v_add_f32_e32 v93, v93, v173
	v_mul_f32_e32 v133, v93, v159
	v_mul_f32_e32 v173, v89, v159
	v_fma_f32 v172, v89, v158, -v133
	v_fma_f32 v173, v93, v158, v173
	v_add_f32_e32 v90, v90, v174
	v_add_f32_e32 v94, v94, v175
	v_mul_f32_e32 v132, v94, v163
	v_mul_f32_e32 v175, v90, v163
	v_fma_f32 v174, v90, v162, -v132
	v_fma_f32 v175, v94, v162, v175
	v_add_f32_e32 v91, v91, v176
	v_add_f32_e32 v95, v95, v177
	v_mul_f32_e32 v133, v95, v167
	v_mul_f32_e32 v177, v91, v167
	v_fma_f32 v176, v91, v166, -v133
	v_fma_f32 v177, v95, v166, v177
	v_mul_f32_e32 v132, v40, v139
	v_mul_f32_e32 v40, v40, v138
	v_fma_f32 v40, -v44, v139, v40
	v_fma_f32 v44, v44, v138, v132
	v_mul_f32_e32 v133, v41, v143
	v_mul_f32_e32 v41, v41, v142
	v_fma_f32 v41, -v45, v143, v41
	v_fma_f32 v45, v45, v142, v133
	v_mul_f32_e32 v132, v42, v147
	v_mul_f32_e32 v42, v42, v146
	v_fma_f32 v42, -v46, v147, v42
	v_fma_f32 v46, v46, v146, v132
	v_mul_f32_e32 v133, v43, v151
	v_mul_f32_e32 v43, v43, v150
	v_fma_f32 v43, -v47, v151, v43
	v_fma_f32 v47, v47, v150, v133
	v_mov_b32_e32 v88, v40
	v_mov_b32_e32 v89, v41
	v_mov_b32_e32 v90, v42
	v_mov_b32_e32 v91, v43
	v_mov_b32_e32 v92, v44
	v_mov_b32_e32 v93, v45
	v_mov_b32_e32 v94, v46
	v_mov_b32_e32 v95, v47
	v_add_f32_dpp v40, v40, v40 row_shr:1 row_mask:0xf bank_mask:0xf bound_ctrl:1
	v_add_f32_dpp v41, v41, v41 row_shr:1 row_mask:0xf bank_mask:0xf bound_ctrl:1
	v_add_f32_dpp v42, v42, v42 row_shr:1 row_mask:0xf bank_mask:0xf bound_ctrl:1
	v_add_f32_dpp v43, v43, v43 row_shr:1 row_mask:0xf bank_mask:0xf bound_ctrl:1
	v_add_f32_dpp v44, v44, v44 row_shr:1 row_mask:0xf bank_mask:0xf bound_ctrl:1
	v_add_f32_dpp v45, v45, v45 row_shr:1 row_mask:0xf bank_mask:0xf bound_ctrl:1
	v_add_f32_dpp v46, v46, v46 row_shr:1 row_mask:0xf bank_mask:0xf bound_ctrl:1
	v_add_f32_dpp v47, v47, v47 row_shr:1 row_mask:0xf bank_mask:0xf bound_ctrl:1
	v_add_f32_dpp v88, v88, v88 row_ror:8 row_mask:0xf bank_mask:0xf
	v_add_f32_dpp v89, v89, v89 row_ror:8 row_mask:0xf bank_mask:0xf
	v_add_f32_dpp v90, v90, v90 row_ror:8 row_mask:0xf bank_mask:0xf
	v_add_f32_dpp v91, v91, v91 row_ror:8 row_mask:0xf bank_mask:0xf
	v_add_f32_dpp v92, v92, v92 row_ror:8 row_mask:0xf bank_mask:0xf
	v_add_f32_dpp v93, v93, v93 row_ror:8 row_mask:0xf bank_mask:0xf
	v_add_f32_dpp v94, v94, v94 row_ror:8 row_mask:0xf bank_mask:0xf
	v_add_f32_dpp v95, v95, v95 row_ror:8 row_mask:0xf bank_mask:0xf
	v_add_f32_dpp v40, v40, v40 row_shr:2 row_mask:0xf bank_mask:0xf bound_ctrl:1
	v_add_f32_dpp v41, v41, v41 row_shr:2 row_mask:0xf bank_mask:0xf bound_ctrl:1
	v_add_f32_dpp v42, v42, v42 row_shr:2 row_mask:0xf bank_mask:0xf bound_ctrl:1
	v_add_f32_dpp v43, v43, v43 row_shr:2 row_mask:0xf bank_mask:0xf bound_ctrl:1
	v_add_f32_dpp v44, v44, v44 row_shr:2 row_mask:0xf bank_mask:0xf bound_ctrl:1
	v_add_f32_dpp v45, v45, v45 row_shr:2 row_mask:0xf bank_mask:0xf bound_ctrl:1
	v_add_f32_dpp v46, v46, v46 row_shr:2 row_mask:0xf bank_mask:0xf bound_ctrl:1
	v_add_f32_dpp v47, v47, v47 row_shr:2 row_mask:0xf bank_mask:0xf bound_ctrl:1
	v_add_f32_dpp v88, v88, v88 row_ror:4 row_mask:0xf bank_mask:0xf
	v_add_f32_dpp v89, v89, v89 row_ror:4 row_mask:0xf bank_mask:0xf
	v_add_f32_dpp v90, v90, v90 row_ror:4 row_mask:0xf bank_mask:0xf
	v_add_f32_dpp v91, v91, v91 row_ror:4 row_mask:0xf bank_mask:0xf
	v_add_f32_dpp v92, v92, v92 row_ror:4 row_mask:0xf bank_mask:0xf
	v_add_f32_dpp v93, v93, v93 row_ror:4 row_mask:0xf bank_mask:0xf
	v_add_f32_dpp v94, v94, v94 row_ror:4 row_mask:0xf bank_mask:0xf
	v_add_f32_dpp v95, v95, v95 row_ror:4 row_mask:0xf bank_mask:0xf
	v_add_f32_dpp v40, v40, v40 row_shr:4 row_mask:0xf bank_mask:0xf bound_ctrl:1
	v_add_f32_dpp v41, v41, v41 row_shr:4 row_mask:0xf bank_mask:0xf bound_ctrl:1
	v_add_f32_dpp v42, v42, v42 row_shr:4 row_mask:0xf bank_mask:0xf bound_ctrl:1
	v_add_f32_dpp v43, v43, v43 row_shr:4 row_mask:0xf bank_mask:0xf bound_ctrl:1
	v_add_f32_dpp v44, v44, v44 row_shr:4 row_mask:0xf bank_mask:0xf bound_ctrl:1
	v_add_f32_dpp v45, v45, v45 row_shr:4 row_mask:0xf bank_mask:0xf bound_ctrl:1
	v_add_f32_dpp v46, v46, v46 row_shr:4 row_mask:0xf bank_mask:0xf bound_ctrl:1
	v_add_f32_dpp v47, v47, v47 row_shr:4 row_mask:0xf bank_mask:0xf bound_ctrl:1
	v_add_f32_dpp v88, v88, v88 row_ror:2 row_mask:0xf bank_mask:0xf
	v_add_f32_dpp v89, v89, v89 row_ror:2 row_mask:0xf bank_mask:0xf
	v_add_f32_dpp v90, v90, v90 row_ror:2 row_mask:0xf bank_mask:0xf
	v_add_f32_dpp v91, v91, v91 row_ror:2 row_mask:0xf bank_mask:0xf
	v_add_f32_dpp v92, v92, v92 row_ror:2 row_mask:0xf bank_mask:0xf
	v_add_f32_dpp v93, v93, v93 row_ror:2 row_mask:0xf bank_mask:0xf
	v_add_f32_dpp v94, v94, v94 row_ror:2 row_mask:0xf bank_mask:0xf
	v_add_f32_dpp v95, v95, v95 row_ror:2 row_mask:0xf bank_mask:0xf
	v_add_f32_dpp v40, v40, v40 row_shr:8 row_mask:0xf bank_mask:0xf bound_ctrl:1
	v_add_f32_dpp v41, v41, v41 row_shr:8 row_mask:0xf bank_mask:0xf bound_ctrl:1
	v_add_f32_dpp v42, v42, v42 row_shr:8 row_mask:0xf bank_mask:0xf bound_ctrl:1
	v_add_f32_dpp v43, v43, v43 row_shr:8 row_mask:0xf bank_mask:0xf bound_ctrl:1
	v_add_f32_dpp v44, v44, v44 row_shr:8 row_mask:0xf bank_mask:0xf bound_ctrl:1
	v_add_f32_dpp v45, v45, v45 row_shr:8 row_mask:0xf bank_mask:0xf bound_ctrl:1
	v_add_f32_dpp v46, v46, v46 row_shr:8 row_mask:0xf bank_mask:0xf bound_ctrl:1
	v_add_f32_dpp v47, v47, v47 row_shr:8 row_mask:0xf bank_mask:0xf bound_ctrl:1
	v_add_f32_dpp v88, v88, v88 row_ror:1 row_mask:0xf bank_mask:0xf
	v_add_f32_dpp v89, v89, v89 row_ror:1 row_mask:0xf bank_mask:0xf
	v_add_f32_dpp v90, v90, v90 row_ror:1 row_mask:0xf bank_mask:0xf
	v_add_f32_dpp v91, v91, v91 row_ror:1 row_mask:0xf bank_mask:0xf
	v_add_f32_dpp v92, v92, v92 row_ror:1 row_mask:0xf bank_mask:0xf
	v_add_f32_dpp v93, v93, v93 row_ror:1 row_mask:0xf bank_mask:0xf
	v_add_f32_dpp v94, v94, v94 row_ror:1 row_mask:0xf bank_mask:0xf
	v_add_f32_dpp v95, v95, v95 row_ror:1 row_mask:0xf bank_mask:0xf
	v_add_f32_e32 v40, v40, v170
	v_add_f32_e32 v44, v44, v171
	v_add_f32_e32 v41, v41, v172
	v_add_f32_e32 v45, v45, v173
	v_add_f32_e32 v42, v42, v174
	v_add_f32_e32 v46, v46, v175
	v_add_f32_e32 v43, v43, v176
	v_add_f32_e32 v47, v47, v177
	v_mul_f32_e32 v132, v40, v141
	v_mul_f32_e32 v40, v40, v140
	v_fma_f32 v40, -v44, v141, v40
	v_fma_f32 v44, v44, v140, v132
	v_mul_f32_e32 v133, v41, v145
	v_mul_f32_e32 v41, v41, v144
	v_fma_f32 v41, -v45, v145, v41
	v_fma_f32 v45, v45, v144, v133
	v_mul_f32_e32 v132, v42, v149
	v_mul_f32_e32 v42, v42, v148
	v_fma_f32 v42, -v46, v149, v42
	v_fma_f32 v46, v46, v148, v132
	v_mul_f32_e32 v133, v43, v153
	v_mul_f32_e32 v43, v43, v152
	v_fma_f32 v43, -v47, v153, v43
	v_fma_f32 v47, v47, v152, v133
	v_add_f32_e32 v88, v88, v170
	v_add_f32_e32 v92, v92, v171
	v_mul_f32_e32 v132, v92, v155
	v_mul_f32_e32 v171, v88, v155
	v_fma_f32 v170, v88, v154, -v132
	v_fma_f32 v171, v92, v154, v171
	v_add_f32_e32 v89, v89, v172
	v_add_f32_e32 v93, v93, v173
	v_mul_f32_e32 v133, v93, v159
	v_mul_f32_e32 v173, v89, v159
	v_fma_f32 v172, v89, v158, -v133
	v_fma_f32 v173, v93, v158, v173
	v_add_f32_e32 v90, v90, v174
	v_add_f32_e32 v94, v94, v175
	v_mul_f32_e32 v132, v94, v163
	v_mul_f32_e32 v175, v90, v163
	v_fma_f32 v174, v90, v162, -v132
	v_fma_f32 v175, v94, v162, v175
	v_add_f32_e32 v91, v91, v176
	v_add_f32_e32 v95, v95, v177
	v_mul_f32_e32 v133, v95, v167
	v_mul_f32_e32 v177, v91, v167
	v_fma_f32 v176, v91, v166, -v133
	v_fma_f32 v177, v95, v166, v177
	v_mul_f32_e32 v132, v48, v139
	v_mul_f32_e32 v48, v48, v138
	v_fma_f32 v48, -v52, v139, v48
	v_fma_f32 v52, v52, v138, v132
	v_mul_f32_e32 v133, v49, v143
	v_mul_f32_e32 v49, v49, v142
	v_fma_f32 v49, -v53, v143, v49
	v_fma_f32 v53, v53, v142, v133
	v_mul_f32_e32 v132, v50, v147
	v_mul_f32_e32 v50, v50, v146
	v_fma_f32 v50, -v54, v147, v50
	v_fma_f32 v54, v54, v146, v132
	v_mul_f32_e32 v133, v51, v151
	v_mul_f32_e32 v51, v51, v150
	v_fma_f32 v51, -v55, v151, v51
	v_fma_f32 v55, v55, v150, v133
	v_mov_b32_e32 v88, v48
	v_mov_b32_e32 v89, v49
	v_mov_b32_e32 v90, v50
	v_mov_b32_e32 v91, v51
	v_mov_b32_e32 v92, v52
	v_mov_b32_e32 v93, v53
	v_mov_b32_e32 v94, v54
	v_mov_b32_e32 v95, v55
	v_add_f32_dpp v48, v48, v48 row_shr:1 row_mask:0xf bank_mask:0xf bound_ctrl:1
	v_add_f32_dpp v49, v49, v49 row_shr:1 row_mask:0xf bank_mask:0xf bound_ctrl:1
	v_add_f32_dpp v50, v50, v50 row_shr:1 row_mask:0xf bank_mask:0xf bound_ctrl:1
	v_add_f32_dpp v51, v51, v51 row_shr:1 row_mask:0xf bank_mask:0xf bound_ctrl:1
	v_add_f32_dpp v52, v52, v52 row_shr:1 row_mask:0xf bank_mask:0xf bound_ctrl:1
	v_add_f32_dpp v53, v53, v53 row_shr:1 row_mask:0xf bank_mask:0xf bound_ctrl:1
	v_add_f32_dpp v54, v54, v54 row_shr:1 row_mask:0xf bank_mask:0xf bound_ctrl:1
	v_add_f32_dpp v55, v55, v55 row_shr:1 row_mask:0xf bank_mask:0xf bound_ctrl:1
	v_add_f32_dpp v88, v88, v88 row_ror:8 row_mask:0xf bank_mask:0xf
	v_add_f32_dpp v89, v89, v89 row_ror:8 row_mask:0xf bank_mask:0xf
	v_add_f32_dpp v90, v90, v90 row_ror:8 row_mask:0xf bank_mask:0xf
	v_add_f32_dpp v91, v91, v91 row_ror:8 row_mask:0xf bank_mask:0xf
	v_add_f32_dpp v92, v92, v92 row_ror:8 row_mask:0xf bank_mask:0xf
	v_add_f32_dpp v93, v93, v93 row_ror:8 row_mask:0xf bank_mask:0xf
	v_add_f32_dpp v94, v94, v94 row_ror:8 row_mask:0xf bank_mask:0xf
	v_add_f32_dpp v95, v95, v95 row_ror:8 row_mask:0xf bank_mask:0xf
	v_add_f32_dpp v48, v48, v48 row_shr:2 row_mask:0xf bank_mask:0xf bound_ctrl:1
	v_add_f32_dpp v49, v49, v49 row_shr:2 row_mask:0xf bank_mask:0xf bound_ctrl:1
	v_add_f32_dpp v50, v50, v50 row_shr:2 row_mask:0xf bank_mask:0xf bound_ctrl:1
	v_add_f32_dpp v51, v51, v51 row_shr:2 row_mask:0xf bank_mask:0xf bound_ctrl:1
	v_add_f32_dpp v52, v52, v52 row_shr:2 row_mask:0xf bank_mask:0xf bound_ctrl:1
	v_add_f32_dpp v53, v53, v53 row_shr:2 row_mask:0xf bank_mask:0xf bound_ctrl:1
	v_add_f32_dpp v54, v54, v54 row_shr:2 row_mask:0xf bank_mask:0xf bound_ctrl:1
	v_add_f32_dpp v55, v55, v55 row_shr:2 row_mask:0xf bank_mask:0xf bound_ctrl:1
	v_add_f32_dpp v88, v88, v88 row_ror:4 row_mask:0xf bank_mask:0xf
	v_add_f32_dpp v89, v89, v89 row_ror:4 row_mask:0xf bank_mask:0xf
	v_add_f32_dpp v90, v90, v90 row_ror:4 row_mask:0xf bank_mask:0xf
	v_add_f32_dpp v91, v91, v91 row_ror:4 row_mask:0xf bank_mask:0xf
	v_add_f32_dpp v92, v92, v92 row_ror:4 row_mask:0xf bank_mask:0xf
	v_add_f32_dpp v93, v93, v93 row_ror:4 row_mask:0xf bank_mask:0xf
	v_add_f32_dpp v94, v94, v94 row_ror:4 row_mask:0xf bank_mask:0xf
	v_add_f32_dpp v95, v95, v95 row_ror:4 row_mask:0xf bank_mask:0xf
	v_add_f32_dpp v48, v48, v48 row_shr:4 row_mask:0xf bank_mask:0xf bound_ctrl:1
	v_add_f32_dpp v49, v49, v49 row_shr:4 row_mask:0xf bank_mask:0xf bound_ctrl:1
	v_add_f32_dpp v50, v50, v50 row_shr:4 row_mask:0xf bank_mask:0xf bound_ctrl:1
	v_add_f32_dpp v51, v51, v51 row_shr:4 row_mask:0xf bank_mask:0xf bound_ctrl:1
	v_add_f32_dpp v52, v52, v52 row_shr:4 row_mask:0xf bank_mask:0xf bound_ctrl:1
	v_add_f32_dpp v53, v53, v53 row_shr:4 row_mask:0xf bank_mask:0xf bound_ctrl:1
	v_add_f32_dpp v54, v54, v54 row_shr:4 row_mask:0xf bank_mask:0xf bound_ctrl:1
	v_add_f32_dpp v55, v55, v55 row_shr:4 row_mask:0xf bank_mask:0xf bound_ctrl:1
	v_add_f32_dpp v88, v88, v88 row_ror:2 row_mask:0xf bank_mask:0xf
	v_add_f32_dpp v89, v89, v89 row_ror:2 row_mask:0xf bank_mask:0xf
	v_add_f32_dpp v90, v90, v90 row_ror:2 row_mask:0xf bank_mask:0xf
	v_add_f32_dpp v91, v91, v91 row_ror:2 row_mask:0xf bank_mask:0xf
	v_add_f32_dpp v92, v92, v92 row_ror:2 row_mask:0xf bank_mask:0xf
	v_add_f32_dpp v93, v93, v93 row_ror:2 row_mask:0xf bank_mask:0xf
	v_add_f32_dpp v94, v94, v94 row_ror:2 row_mask:0xf bank_mask:0xf
	v_add_f32_dpp v95, v95, v95 row_ror:2 row_mask:0xf bank_mask:0xf
	v_add_f32_dpp v48, v48, v48 row_shr:8 row_mask:0xf bank_mask:0xf bound_ctrl:1
	v_add_f32_dpp v49, v49, v49 row_shr:8 row_mask:0xf bank_mask:0xf bound_ctrl:1
	v_add_f32_dpp v50, v50, v50 row_shr:8 row_mask:0xf bank_mask:0xf bound_ctrl:1
	v_add_f32_dpp v51, v51, v51 row_shr:8 row_mask:0xf bank_mask:0xf bound_ctrl:1
	v_add_f32_dpp v52, v52, v52 row_shr:8 row_mask:0xf bank_mask:0xf bound_ctrl:1
	v_add_f32_dpp v53, v53, v53 row_shr:8 row_mask:0xf bank_mask:0xf bound_ctrl:1
	v_add_f32_dpp v54, v54, v54 row_shr:8 row_mask:0xf bank_mask:0xf bound_ctrl:1
	v_add_f32_dpp v55, v55, v55 row_shr:8 row_mask:0xf bank_mask:0xf bound_ctrl:1
	v_add_f32_dpp v88, v88, v88 row_ror:1 row_mask:0xf bank_mask:0xf
	v_add_f32_dpp v89, v89, v89 row_ror:1 row_mask:0xf bank_mask:0xf
	v_add_f32_dpp v90, v90, v90 row_ror:1 row_mask:0xf bank_mask:0xf
	v_add_f32_dpp v91, v91, v91 row_ror:1 row_mask:0xf bank_mask:0xf
	v_add_f32_dpp v92, v92, v92 row_ror:1 row_mask:0xf bank_mask:0xf
	v_add_f32_dpp v93, v93, v93 row_ror:1 row_mask:0xf bank_mask:0xf
	v_add_f32_dpp v94, v94, v94 row_ror:1 row_mask:0xf bank_mask:0xf
	v_add_f32_dpp v95, v95, v95 row_ror:1 row_mask:0xf bank_mask:0xf
	v_add_f32_e32 v48, v48, v170
	v_add_f32_e32 v52, v52, v171
	v_add_f32_e32 v49, v49, v172
	v_add_f32_e32 v53, v53, v173
	v_add_f32_e32 v50, v50, v174
	v_add_f32_e32 v54, v54, v175
	v_add_f32_e32 v51, v51, v176
	v_add_f32_e32 v55, v55, v177
	v_mul_f32_e32 v132, v48, v141
	v_mul_f32_e32 v48, v48, v140
	v_fma_f32 v48, -v52, v141, v48
	v_fma_f32 v52, v52, v140, v132
	v_mul_f32_e32 v133, v49, v145
	v_mul_f32_e32 v49, v49, v144
	v_fma_f32 v49, -v53, v145, v49
	v_fma_f32 v53, v53, v144, v133
	v_mul_f32_e32 v132, v50, v149
	v_mul_f32_e32 v50, v50, v148
	v_fma_f32 v50, -v54, v149, v50
	v_fma_f32 v54, v54, v148, v132
	v_mul_f32_e32 v133, v51, v153
	v_mul_f32_e32 v51, v51, v152
	v_fma_f32 v51, -v55, v153, v51
	v_fma_f32 v55, v55, v152, v133
	v_add_f32_e32 v88, v88, v170
	v_add_f32_e32 v92, v92, v171
	v_mul_f32_e32 v132, v92, v155
	v_mul_f32_e32 v171, v88, v155
	v_fma_f32 v170, v88, v154, -v132
	v_fma_f32 v171, v92, v154, v171
	v_add_f32_e32 v89, v89, v172
	v_add_f32_e32 v93, v93, v173
	v_mul_f32_e32 v133, v93, v159
	v_mul_f32_e32 v173, v89, v159
	v_fma_f32 v172, v89, v158, -v133
	v_fma_f32 v173, v93, v158, v173
	v_add_f32_e32 v90, v90, v174
	v_add_f32_e32 v94, v94, v175
	v_mul_f32_e32 v132, v94, v163
	v_mul_f32_e32 v175, v90, v163
	v_fma_f32 v174, v90, v162, -v132
	v_fma_f32 v175, v94, v162, v175
	v_add_f32_e32 v91, v91, v176
	v_add_f32_e32 v95, v95, v177
	v_mul_f32_e32 v133, v95, v167
	v_mul_f32_e32 v177, v91, v167
	v_fma_f32 v176, v91, v166, -v133
	v_fma_f32 v177, v95, v166, v177
	v_mul_f32_e32 v132, v56, v139
	v_mul_f32_e32 v56, v56, v138
	v_fma_f32 v56, -v60, v139, v56
	v_fma_f32 v60, v60, v138, v132
	v_mul_f32_e32 v133, v57, v143
	v_mul_f32_e32 v57, v57, v142
	v_fma_f32 v57, -v61, v143, v57
	v_fma_f32 v61, v61, v142, v133
	v_mul_f32_e32 v132, v58, v147
	v_mul_f32_e32 v58, v58, v146
	v_fma_f32 v58, -v62, v147, v58
	v_fma_f32 v62, v62, v146, v132
	v_mul_f32_e32 v133, v59, v151
	v_mul_f32_e32 v59, v59, v150
	v_fma_f32 v59, -v63, v151, v59
	v_fma_f32 v63, v63, v150, v133
	v_mov_b32_e32 v88, v56
	v_mov_b32_e32 v89, v57
	v_mov_b32_e32 v90, v58
	v_mov_b32_e32 v91, v59
	v_mov_b32_e32 v92, v60
	v_mov_b32_e32 v93, v61
	v_mov_b32_e32 v94, v62
	v_mov_b32_e32 v95, v63
	v_add_f32_dpp v56, v56, v56 row_shr:1 row_mask:0xf bank_mask:0xf bound_ctrl:1
	v_add_f32_dpp v57, v57, v57 row_shr:1 row_mask:0xf bank_mask:0xf bound_ctrl:1
	v_add_f32_dpp v58, v58, v58 row_shr:1 row_mask:0xf bank_mask:0xf bound_ctrl:1
	v_add_f32_dpp v59, v59, v59 row_shr:1 row_mask:0xf bank_mask:0xf bound_ctrl:1
	v_add_f32_dpp v60, v60, v60 row_shr:1 row_mask:0xf bank_mask:0xf bound_ctrl:1
	v_add_f32_dpp v61, v61, v61 row_shr:1 row_mask:0xf bank_mask:0xf bound_ctrl:1
	v_add_f32_dpp v62, v62, v62 row_shr:1 row_mask:0xf bank_mask:0xf bound_ctrl:1
	v_add_f32_dpp v63, v63, v63 row_shr:1 row_mask:0xf bank_mask:0xf bound_ctrl:1
	v_add_f32_dpp v88, v88, v88 row_ror:8 row_mask:0xf bank_mask:0xf
	v_add_f32_dpp v89, v89, v89 row_ror:8 row_mask:0xf bank_mask:0xf
	v_add_f32_dpp v90, v90, v90 row_ror:8 row_mask:0xf bank_mask:0xf
	v_add_f32_dpp v91, v91, v91 row_ror:8 row_mask:0xf bank_mask:0xf
	v_add_f32_dpp v92, v92, v92 row_ror:8 row_mask:0xf bank_mask:0xf
	v_add_f32_dpp v93, v93, v93 row_ror:8 row_mask:0xf bank_mask:0xf
	v_add_f32_dpp v94, v94, v94 row_ror:8 row_mask:0xf bank_mask:0xf
	v_add_f32_dpp v95, v95, v95 row_ror:8 row_mask:0xf bank_mask:0xf
	v_add_f32_dpp v56, v56, v56 row_shr:2 row_mask:0xf bank_mask:0xf bound_ctrl:1
	v_add_f32_dpp v57, v57, v57 row_shr:2 row_mask:0xf bank_mask:0xf bound_ctrl:1
	v_add_f32_dpp v58, v58, v58 row_shr:2 row_mask:0xf bank_mask:0xf bound_ctrl:1
	v_add_f32_dpp v59, v59, v59 row_shr:2 row_mask:0xf bank_mask:0xf bound_ctrl:1
	v_add_f32_dpp v60, v60, v60 row_shr:2 row_mask:0xf bank_mask:0xf bound_ctrl:1
	v_add_f32_dpp v61, v61, v61 row_shr:2 row_mask:0xf bank_mask:0xf bound_ctrl:1
	v_add_f32_dpp v62, v62, v62 row_shr:2 row_mask:0xf bank_mask:0xf bound_ctrl:1
	v_add_f32_dpp v63, v63, v63 row_shr:2 row_mask:0xf bank_mask:0xf bound_ctrl:1
	v_add_f32_dpp v88, v88, v88 row_ror:4 row_mask:0xf bank_mask:0xf
	v_add_f32_dpp v89, v89, v89 row_ror:4 row_mask:0xf bank_mask:0xf
	v_add_f32_dpp v90, v90, v90 row_ror:4 row_mask:0xf bank_mask:0xf
	v_add_f32_dpp v91, v91, v91 row_ror:4 row_mask:0xf bank_mask:0xf
	v_add_f32_dpp v92, v92, v92 row_ror:4 row_mask:0xf bank_mask:0xf
	v_add_f32_dpp v93, v93, v93 row_ror:4 row_mask:0xf bank_mask:0xf
	v_add_f32_dpp v94, v94, v94 row_ror:4 row_mask:0xf bank_mask:0xf
	v_add_f32_dpp v95, v95, v95 row_ror:4 row_mask:0xf bank_mask:0xf
	v_add_f32_dpp v56, v56, v56 row_shr:4 row_mask:0xf bank_mask:0xf bound_ctrl:1
	v_add_f32_dpp v57, v57, v57 row_shr:4 row_mask:0xf bank_mask:0xf bound_ctrl:1
	v_add_f32_dpp v58, v58, v58 row_shr:4 row_mask:0xf bank_mask:0xf bound_ctrl:1
	v_add_f32_dpp v59, v59, v59 row_shr:4 row_mask:0xf bank_mask:0xf bound_ctrl:1
	v_add_f32_dpp v60, v60, v60 row_shr:4 row_mask:0xf bank_mask:0xf bound_ctrl:1
	v_add_f32_dpp v61, v61, v61 row_shr:4 row_mask:0xf bank_mask:0xf bound_ctrl:1
	v_add_f32_dpp v62, v62, v62 row_shr:4 row_mask:0xf bank_mask:0xf bound_ctrl:1
	v_add_f32_dpp v63, v63, v63 row_shr:4 row_mask:0xf bank_mask:0xf bound_ctrl:1
	v_add_f32_dpp v88, v88, v88 row_ror:2 row_mask:0xf bank_mask:0xf
	v_add_f32_dpp v89, v89, v89 row_ror:2 row_mask:0xf bank_mask:0xf
	v_add_f32_dpp v90, v90, v90 row_ror:2 row_mask:0xf bank_mask:0xf
	v_add_f32_dpp v91, v91, v91 row_ror:2 row_mask:0xf bank_mask:0xf
	v_add_f32_dpp v92, v92, v92 row_ror:2 row_mask:0xf bank_mask:0xf
	v_add_f32_dpp v93, v93, v93 row_ror:2 row_mask:0xf bank_mask:0xf
	v_add_f32_dpp v94, v94, v94 row_ror:2 row_mask:0xf bank_mask:0xf
	v_add_f32_dpp v95, v95, v95 row_ror:2 row_mask:0xf bank_mask:0xf
	v_add_f32_dpp v56, v56, v56 row_shr:8 row_mask:0xf bank_mask:0xf bound_ctrl:1
	v_add_f32_dpp v57, v57, v57 row_shr:8 row_mask:0xf bank_mask:0xf bound_ctrl:1
	v_add_f32_dpp v58, v58, v58 row_shr:8 row_mask:0xf bank_mask:0xf bound_ctrl:1
	v_add_f32_dpp v59, v59, v59 row_shr:8 row_mask:0xf bank_mask:0xf bound_ctrl:1
	v_add_f32_dpp v60, v60, v60 row_shr:8 row_mask:0xf bank_mask:0xf bound_ctrl:1
	v_add_f32_dpp v61, v61, v61 row_shr:8 row_mask:0xf bank_mask:0xf bound_ctrl:1
	v_add_f32_dpp v62, v62, v62 row_shr:8 row_mask:0xf bank_mask:0xf bound_ctrl:1
	v_add_f32_dpp v63, v63, v63 row_shr:8 row_mask:0xf bank_mask:0xf bound_ctrl:1
	v_add_f32_dpp v88, v88, v88 row_ror:1 row_mask:0xf bank_mask:0xf
	v_add_f32_dpp v89, v89, v89 row_ror:1 row_mask:0xf bank_mask:0xf
	v_add_f32_dpp v90, v90, v90 row_ror:1 row_mask:0xf bank_mask:0xf
	v_add_f32_dpp v91, v91, v91 row_ror:1 row_mask:0xf bank_mask:0xf
	v_add_f32_dpp v92, v92, v92 row_ror:1 row_mask:0xf bank_mask:0xf
	v_add_f32_dpp v93, v93, v93 row_ror:1 row_mask:0xf bank_mask:0xf
	v_add_f32_dpp v94, v94, v94 row_ror:1 row_mask:0xf bank_mask:0xf
	v_add_f32_dpp v95, v95, v95 row_ror:1 row_mask:0xf bank_mask:0xf
	v_add_f32_e32 v56, v56, v170
	v_add_f32_e32 v60, v60, v171
	v_add_f32_e32 v57, v57, v172
	v_add_f32_e32 v61, v61, v173
	v_add_f32_e32 v58, v58, v174
	v_add_f32_e32 v62, v62, v175
	v_add_f32_e32 v59, v59, v176
	v_add_f32_e32 v63, v63, v177
	v_mul_f32_e32 v132, v56, v141
	v_mul_f32_e32 v56, v56, v140
	v_fma_f32 v56, -v60, v141, v56
	v_fma_f32 v60, v60, v140, v132
	v_mul_f32_e32 v133, v57, v145
	v_mul_f32_e32 v57, v57, v144
	v_fma_f32 v57, -v61, v145, v57
	v_fma_f32 v61, v61, v144, v133
	v_mul_f32_e32 v132, v58, v149
	v_mul_f32_e32 v58, v58, v148
	v_fma_f32 v58, -v62, v149, v58
	v_fma_f32 v62, v62, v148, v132
	v_mul_f32_e32 v133, v59, v153
	v_mul_f32_e32 v59, v59, v152
	v_fma_f32 v59, -v63, v153, v59
	v_fma_f32 v63, v63, v152, v133
	v_add_f32_e32 v88, v88, v170
	v_add_f32_e32 v92, v92, v171
	v_mul_f32_e32 v132, v92, v155
	v_mul_f32_e32 v171, v88, v155
	v_fma_f32 v170, v88, v154, -v132
	v_fma_f32 v171, v92, v154, v171
	v_add_f32_e32 v89, v89, v172
	v_add_f32_e32 v93, v93, v173
	v_mul_f32_e32 v133, v93, v159
	v_mul_f32_e32 v173, v89, v159
	v_fma_f32 v172, v89, v158, -v133
	v_fma_f32 v173, v93, v158, v173
	v_add_f32_e32 v90, v90, v174
	v_add_f32_e32 v94, v94, v175
	v_mul_f32_e32 v132, v94, v163
	v_mul_f32_e32 v175, v90, v163
	v_fma_f32 v174, v90, v162, -v132
	v_fma_f32 v175, v94, v162, v175
	v_add_f32_e32 v91, v91, v176
	v_add_f32_e32 v95, v95, v177
	v_mul_f32_e32 v133, v95, v167
	v_mul_f32_e32 v177, v91, v167
	v_fma_f32 v176, v91, v166, -v133
	v_fma_f32 v177, v95, v166, v177
	s_waitcnt vmcnt(14)
	v_cvt_pk_bf16_f32 v80, v80, v81
	v_cvt_pk_bf16_f32 v81, v82, v83
	v_cvt_pk_bf16_f32 v82, -v84, -v85
	v_cvt_pk_bf16_f32 v83, -v86, -v87
	v_cvt_pk_bf16_f32 v96, v32, v33
	v_cvt_pk_bf16_f32 v97, v34, v35
	v_cvt_pk_bf16_f32 v98, v36, v37
	v_cvt_pk_bf16_f32 v99, v38, v39
	s_nop 1
	v_mfma_f32_16x16x32_bf16 v[16:19], v[80:83], v[96:99], v[16:19]
	v_cvt_pk_bf16_f32 v96, v40, v41
	v_cvt_pk_bf16_f32 v97, v42, v43
	v_cvt_pk_bf16_f32 v98, v44, v45
	v_cvt_pk_bf16_f32 v99, v46, v47
	s_nop 1
	v_mfma_f32_16x16x32_bf16 v[20:23], v[80:83], v[96:99], v[20:23]
	v_cvt_pk_bf16_f32 v96, v48, v49
	v_cvt_pk_bf16_f32 v97, v50, v51
	v_cvt_pk_bf16_f32 v98, v52, v53
	v_cvt_pk_bf16_f32 v99, v54, v55
	s_nop 1
	v_mfma_f32_16x16x32_bf16 v[24:27], v[80:83], v[96:99], v[24:27]
	v_cvt_pk_bf16_f32 v96, v56, v57
	v_cvt_pk_bf16_f32 v97, v58, v59
	v_cvt_pk_bf16_f32 v98, v60, v61
	v_cvt_pk_bf16_f32 v99, v62, v63
	s_nop 1
	v_mfma_f32_16x16x32_bf16 v[28:31], v[80:83], v[96:99], v[28:31]
	s_waitcnt vmcnt(10)
	v_cvt_pk_bf16_f32 v64, v64, v65
	v_cvt_pk_bf16_f32 v65, v66, v67
	v_cvt_pk_bf16_f32 v66, v68, v69
	v_cvt_pk_bf16_f32 v67, v70, v71
	v_cvt_pk_bf16_f32 v72, v72, v73
	v_cvt_pk_bf16_f32 v73, v74, v75
	v_cvt_pk_bf16_f32 v74, v76, v77
	v_cvt_pk_bf16_f32 v75, v78, v79
	global_load_dwordx4 v[80:83], v136, s[38:39]
	global_load_dwordx4 v[84:87], v136, s[40:41]
	s_nop 0
	v_mfma_f32_16x16x32_bf16 v[32:35], v[64:67], v[0:3], 0
	v_mfma_f32_16x16x32_bf16 v[36:39], v[72:75], v[0:3], 0
	v_mfma_f32_16x16x32_bf16 v[40:43], v[64:67], v[4:7], 0
	v_mfma_f32_16x16x32_bf16 v[44:47], v[72:75], v[4:7], 0
	v_mfma_f32_16x16x32_bf16 v[48:51], v[64:67], v[8:11], 0
	v_mfma_f32_16x16x32_bf16 v[52:55], v[72:75], v[8:11], 0
	v_mfma_f32_16x16x32_bf16 v[56:59], v[64:67], v[12:15], 0
	v_mfma_f32_16x16x32_bf16 v[60:63], v[72:75], v[12:15], 0
	v_readlane_b32 s10, v247, 28
	s_sub_i32 s11, 3, s8
	s_sub_i32 s17, 71, s8
	s_cmp_lt_u32 s8, 4
	s_cselect_b32 s11, s11, s17
	s_lshl_b32 s16, s10, 1
	s_add_i32 s16, s16, 1
	s_lshl_b32 s16, s16, 4
	s_add_i32 s16, s16, s7
	s_lshl_b32 s17, s6, 1
	s_add_i32 s17, s17, 1
	s_lshl_b32 s17, s17, 4
	s_add_i32 s17, s17, s7
	s_mul_i32 s17, s17, 68
	s_add_i32 s17, s17, s11
	s_lshl_b32 s17, s17, 6
	s_lshl_b32 s20, s16, 12
	s_add_u32 s20, s20, 0x11fb20
	s_add_u32 s20, s4, s20
	s_addc_u32 s21, s5, 0
	s_add_u32 s22, s20, 0x40000
	s_addc_u32 s23, s21, 0
	s_lshl_b32 s38, s16, 12
	s_add_u32 s38, s38, 0x19fb20
	s_add_u32 s38, s4, s38
	s_addc_u32 s39, s5, 0
	s_add_u32 s40, s38, 0x40000
	s_addc_u32 s41, s39, 0
	s_lshl_b32 s42, s16, 15
	s_add_u32 s42, s42, 0xf900000
	s_add_u32 s42, s4, s42
	s_addc_u32 s43, s5, 0
	s_lshl_b32 s44, s17, 3
	s_add_u32 s44, s44, 0x740000
	s_add_u32 s44, s4, s44
	s_addc_u32 s45, s5, 0
	s_mov_b32 exec_hi, 0
	global_load_dwordx4 v[64:67], v135, s[20:21]
	global_load_dwordx4 v[68:71], v135, s[20:21] offset:16
	global_load_dwordx4 v[72:75], v135, s[22:23]
	global_load_dwordx4 v[76:79], v135, s[22:23] offset:16
	s_mov_b64 exec, -1
	s_add_u32 s20, s20, 0x400
	s_addc_u32 s21, s21, 0
	s_add_u32 s22, s22, 0x400
	s_addc_u32 s23, s23, 0
	global_load_dwordx4 v[138:141], v134, s[42:43] offset:0
	global_load_dwordx4 v[142:145], v134, s[42:43] offset:16
	global_load_dwordx4 v[146:149], v134, s[42:43] offset:32
	global_load_dwordx4 v[150:153], v134, s[42:43] offset:48
	global_load_dwordx4 v[154:157], v134, s[42:43] offset:64
	global_load_dwordx4 v[158:161], v134, s[42:43] offset:80
	global_load_dwordx4 v[162:165], v134, s[42:43] offset:96
	global_load_dwordx4 v[166:169], v134, s[42:43] offset:112
	global_load_dwordx4 v[170:173], v206, s[44:45]
	global_load_dwordx4 v[174:177], v206, s[44:45] offset:16
	s_add_u32 s42, s42, 0x2000
	s_addc_u32 s43, s43, 0
	s_add_u32 s44, s44, 0x80
	s_addc_u32 s45, s45, 0
	s_waitcnt vmcnt(16)
	v_mul_f32_e32 v132, v179, v119
	v_mul_f32_e32 v133, v178, v119
	v_fma_f32 v178, v178, v118, -v132
	v_fma_f32 v179, v179, v118, v133
	v_mul_f32_e32 v132, v181, v123
	v_mul_f32_e32 v133, v180, v123
	v_fma_f32 v180, v180, v122, -v132
	v_fma_f32 v181, v181, v122, v133
	v_mul_f32_e32 v132, v183, v127
	v_mul_f32_e32 v133, v182, v127
	v_fma_f32 v182, v182, v126, -v132
	v_fma_f32 v183, v183, v126, v133
	v_mul_f32_e32 v132, v185, v131
	v_mul_f32_e32 v133, v184, v131
	v_fma_f32 v184, v184, v130, -v132
	v_fma_f32 v185, v185, v130, v133
	v_mul_f32_e32 v132, v32, v101
	v_mul_f32_e32 v32, v32, v100
	v_fma_f32 v32, -v36, v101, v32
	v_fma_f32 v36, v36, v100, v132
	v_mul_f32_e32 v133, v33, v105
	v_mul_f32_e32 v33, v33, v104
	v_fma_f32 v33, -v37, v105, v33
	v_fma_f32 v37, v37, v104, v133
	v_mul_f32_e32 v132, v34, v109
	v_mul_f32_e32 v34, v34, v108
	v_fma_f32 v34, -v38, v109, v34
	v_fma_f32 v38, v38, v108, v132
	v_mul_f32_e32 v133, v35, v113
	v_mul_f32_e32 v35, v35, v112
	v_fma_f32 v35, -v39, v113, v35
	v_fma_f32 v39, v39, v112, v133
	v_mov_b32_e32 v88, v32
	v_mov_b32_e32 v89, v33
	v_mov_b32_e32 v90, v34
	v_mov_b32_e32 v91, v35
	v_mov_b32_e32 v92, v36
	v_mov_b32_e32 v93, v37
	v_mov_b32_e32 v94, v38
	v_mov_b32_e32 v95, v39
	v_add_f32_dpp v32, v32, v32 row_shr:1 row_mask:0xf bank_mask:0xf bound_ctrl:1
	v_add_f32_dpp v33, v33, v33 row_shr:1 row_mask:0xf bank_mask:0xf bound_ctrl:1
	v_add_f32_dpp v34, v34, v34 row_shr:1 row_mask:0xf bank_mask:0xf bound_ctrl:1
	v_add_f32_dpp v35, v35, v35 row_shr:1 row_mask:0xf bank_mask:0xf bound_ctrl:1
	v_add_f32_dpp v36, v36, v36 row_shr:1 row_mask:0xf bank_mask:0xf bound_ctrl:1
	v_add_f32_dpp v37, v37, v37 row_shr:1 row_mask:0xf bank_mask:0xf bound_ctrl:1
	v_add_f32_dpp v38, v38, v38 row_shr:1 row_mask:0xf bank_mask:0xf bound_ctrl:1
	v_add_f32_dpp v39, v39, v39 row_shr:1 row_mask:0xf bank_mask:0xf bound_ctrl:1
	v_add_f32_dpp v88, v88, v88 row_ror:8 row_mask:0xf bank_mask:0xf
	v_add_f32_dpp v89, v89, v89 row_ror:8 row_mask:0xf bank_mask:0xf
	v_add_f32_dpp v90, v90, v90 row_ror:8 row_mask:0xf bank_mask:0xf
	v_add_f32_dpp v91, v91, v91 row_ror:8 row_mask:0xf bank_mask:0xf
	v_add_f32_dpp v92, v92, v92 row_ror:8 row_mask:0xf bank_mask:0xf
	v_add_f32_dpp v93, v93, v93 row_ror:8 row_mask:0xf bank_mask:0xf
	v_add_f32_dpp v94, v94, v94 row_ror:8 row_mask:0xf bank_mask:0xf
	v_add_f32_dpp v95, v95, v95 row_ror:8 row_mask:0xf bank_mask:0xf
	v_add_f32_dpp v32, v32, v32 row_shr:2 row_mask:0xf bank_mask:0xf bound_ctrl:1
	v_add_f32_dpp v33, v33, v33 row_shr:2 row_mask:0xf bank_mask:0xf bound_ctrl:1
	v_add_f32_dpp v34, v34, v34 row_shr:2 row_mask:0xf bank_mask:0xf bound_ctrl:1
	v_add_f32_dpp v35, v35, v35 row_shr:2 row_mask:0xf bank_mask:0xf bound_ctrl:1
	v_add_f32_dpp v36, v36, v36 row_shr:2 row_mask:0xf bank_mask:0xf bound_ctrl:1
	v_add_f32_dpp v37, v37, v37 row_shr:2 row_mask:0xf bank_mask:0xf bound_ctrl:1
	v_add_f32_dpp v38, v38, v38 row_shr:2 row_mask:0xf bank_mask:0xf bound_ctrl:1
	v_add_f32_dpp v39, v39, v39 row_shr:2 row_mask:0xf bank_mask:0xf bound_ctrl:1
	v_add_f32_dpp v88, v88, v88 row_ror:4 row_mask:0xf bank_mask:0xf
	v_add_f32_dpp v89, v89, v89 row_ror:4 row_mask:0xf bank_mask:0xf
	v_add_f32_dpp v90, v90, v90 row_ror:4 row_mask:0xf bank_mask:0xf
	v_add_f32_dpp v91, v91, v91 row_ror:4 row_mask:0xf bank_mask:0xf
	v_add_f32_dpp v92, v92, v92 row_ror:4 row_mask:0xf bank_mask:0xf
	v_add_f32_dpp v93, v93, v93 row_ror:4 row_mask:0xf bank_mask:0xf
	v_add_f32_dpp v94, v94, v94 row_ror:4 row_mask:0xf bank_mask:0xf
	v_add_f32_dpp v95, v95, v95 row_ror:4 row_mask:0xf bank_mask:0xf
	v_add_f32_dpp v32, v32, v32 row_shr:4 row_mask:0xf bank_mask:0xf bound_ctrl:1
	v_add_f32_dpp v33, v33, v33 row_shr:4 row_mask:0xf bank_mask:0xf bound_ctrl:1
	v_add_f32_dpp v34, v34, v34 row_shr:4 row_mask:0xf bank_mask:0xf bound_ctrl:1
	v_add_f32_dpp v35, v35, v35 row_shr:4 row_mask:0xf bank_mask:0xf bound_ctrl:1
	v_add_f32_dpp v36, v36, v36 row_shr:4 row_mask:0xf bank_mask:0xf bound_ctrl:1
	v_add_f32_dpp v37, v37, v37 row_shr:4 row_mask:0xf bank_mask:0xf bound_ctrl:1
	v_add_f32_dpp v38, v38, v38 row_shr:4 row_mask:0xf bank_mask:0xf bound_ctrl:1
	v_add_f32_dpp v39, v39, v39 row_shr:4 row_mask:0xf bank_mask:0xf bound_ctrl:1
	v_add_f32_dpp v88, v88, v88 row_ror:2 row_mask:0xf bank_mask:0xf
	v_add_f32_dpp v89, v89, v89 row_ror:2 row_mask:0xf bank_mask:0xf
	v_add_f32_dpp v90, v90, v90 row_ror:2 row_mask:0xf bank_mask:0xf
	v_add_f32_dpp v91, v91, v91 row_ror:2 row_mask:0xf bank_mask:0xf
	v_add_f32_dpp v92, v92, v92 row_ror:2 row_mask:0xf bank_mask:0xf
	v_add_f32_dpp v93, v93, v93 row_ror:2 row_mask:0xf bank_mask:0xf
	v_add_f32_dpp v94, v94, v94 row_ror:2 row_mask:0xf bank_mask:0xf
	v_add_f32_dpp v95, v95, v95 row_ror:2 row_mask:0xf bank_mask:0xf
	v_add_f32_dpp v32, v32, v32 row_shr:8 row_mask:0xf bank_mask:0xf bound_ctrl:1
	v_add_f32_dpp v33, v33, v33 row_shr:8 row_mask:0xf bank_mask:0xf bound_ctrl:1
	v_add_f32_dpp v34, v34, v34 row_shr:8 row_mask:0xf bank_mask:0xf bound_ctrl:1
	v_add_f32_dpp v35, v35, v35 row_shr:8 row_mask:0xf bank_mask:0xf bound_ctrl:1
	v_add_f32_dpp v36, v36, v36 row_shr:8 row_mask:0xf bank_mask:0xf bound_ctrl:1
	v_add_f32_dpp v37, v37, v37 row_shr:8 row_mask:0xf bank_mask:0xf bound_ctrl:1
	v_add_f32_dpp v38, v38, v38 row_shr:8 row_mask:0xf bank_mask:0xf bound_ctrl:1
	v_add_f32_dpp v39, v39, v39 row_shr:8 row_mask:0xf bank_mask:0xf bound_ctrl:1
	v_add_f32_dpp v88, v88, v88 row_ror:1 row_mask:0xf bank_mask:0xf
	v_add_f32_dpp v89, v89, v89 row_ror:1 row_mask:0xf bank_mask:0xf
	v_add_f32_dpp v90, v90, v90 row_ror:1 row_mask:0xf bank_mask:0xf
	v_add_f32_dpp v91, v91, v91 row_ror:1 row_mask:0xf bank_mask:0xf
	v_add_f32_dpp v92, v92, v92 row_ror:1 row_mask:0xf bank_mask:0xf
	v_add_f32_dpp v93, v93, v93 row_ror:1 row_mask:0xf bank_mask:0xf
	v_add_f32_dpp v94, v94, v94 row_ror:1 row_mask:0xf bank_mask:0xf
	v_add_f32_dpp v95, v95, v95 row_ror:1 row_mask:0xf bank_mask:0xf
	v_add_f32_e32 v32, v32, v178
	v_add_f32_e32 v36, v36, v179
	v_add_f32_e32 v33, v33, v180
	v_add_f32_e32 v37, v37, v181
	v_add_f32_e32 v34, v34, v182
	v_add_f32_e32 v38, v38, v183
	v_add_f32_e32 v35, v35, v184
	v_add_f32_e32 v39, v39, v185
	v_mul_f32_e32 v132, v32, v103
	v_mul_f32_e32 v32, v32, v102
	v_fma_f32 v32, -v36, v103, v32
	v_fma_f32 v36, v36, v102, v132
	v_mul_f32_e32 v133, v33, v107
	v_mul_f32_e32 v33, v33, v106
	v_fma_f32 v33, -v37, v107, v33
	v_fma_f32 v37, v37, v106, v133
	v_mul_f32_e32 v132, v34, v111
	v_mul_f32_e32 v34, v34, v110
	v_fma_f32 v34, -v38, v111, v34
	v_fma_f32 v38, v38, v110, v132
	v_mul_f32_e32 v133, v35, v115
	v_mul_f32_e32 v35, v35, v114
	v_fma_f32 v35, -v39, v115, v35
	v_fma_f32 v39, v39, v114, v133
	v_add_f32_e32 v88, v88, v178
	v_add_f32_e32 v92, v92, v179
	v_mul_f32_e32 v132, v92, v117
	v_mul_f32_e32 v179, v88, v117
	v_fma_f32 v178, v88, v116, -v132
	v_fma_f32 v179, v92, v116, v179
	v_add_f32_e32 v89, v89, v180
	v_add_f32_e32 v93, v93, v181
	v_mul_f32_e32 v133, v93, v121
	v_mul_f32_e32 v181, v89, v121
	v_fma_f32 v180, v89, v120, -v133
	v_fma_f32 v181, v93, v120, v181
	v_add_f32_e32 v90, v90, v182
	v_add_f32_e32 v94, v94, v183
	v_mul_f32_e32 v132, v94, v125
	v_mul_f32_e32 v183, v90, v125
	v_fma_f32 v182, v90, v124, -v132
	v_fma_f32 v183, v94, v124, v183
	v_add_f32_e32 v91, v91, v184
	v_add_f32_e32 v95, v95, v185
	v_mul_f32_e32 v133, v95, v129
	v_mul_f32_e32 v185, v91, v129
	v_fma_f32 v184, v91, v128, -v133
	v_fma_f32 v185, v95, v128, v185
	v_mul_f32_e32 v132, v40, v101
	v_mul_f32_e32 v40, v40, v100
	v_fma_f32 v40, -v44, v101, v40
	v_fma_f32 v44, v44, v100, v132
	v_mul_f32_e32 v133, v41, v105
	v_mul_f32_e32 v41, v41, v104
	v_fma_f32 v41, -v45, v105, v41
	v_fma_f32 v45, v45, v104, v133
	v_mul_f32_e32 v132, v42, v109
	v_mul_f32_e32 v42, v42, v108
	v_fma_f32 v42, -v46, v109, v42
	v_fma_f32 v46, v46, v108, v132
	v_mul_f32_e32 v133, v43, v113
	v_mul_f32_e32 v43, v43, v112
	v_fma_f32 v43, -v47, v113, v43
	v_fma_f32 v47, v47, v112, v133
	v_mov_b32_e32 v88, v40
	v_mov_b32_e32 v89, v41
	v_mov_b32_e32 v90, v42
	v_mov_b32_e32 v91, v43
	v_mov_b32_e32 v92, v44
	v_mov_b32_e32 v93, v45
	v_mov_b32_e32 v94, v46
	v_mov_b32_e32 v95, v47
	v_add_f32_dpp v40, v40, v40 row_shr:1 row_mask:0xf bank_mask:0xf bound_ctrl:1
	v_add_f32_dpp v41, v41, v41 row_shr:1 row_mask:0xf bank_mask:0xf bound_ctrl:1
	v_add_f32_dpp v42, v42, v42 row_shr:1 row_mask:0xf bank_mask:0xf bound_ctrl:1
	v_add_f32_dpp v43, v43, v43 row_shr:1 row_mask:0xf bank_mask:0xf bound_ctrl:1
	v_add_f32_dpp v44, v44, v44 row_shr:1 row_mask:0xf bank_mask:0xf bound_ctrl:1
	v_add_f32_dpp v45, v45, v45 row_shr:1 row_mask:0xf bank_mask:0xf bound_ctrl:1
	v_add_f32_dpp v46, v46, v46 row_shr:1 row_mask:0xf bank_mask:0xf bound_ctrl:1
	v_add_f32_dpp v47, v47, v47 row_shr:1 row_mask:0xf bank_mask:0xf bound_ctrl:1
	v_add_f32_dpp v88, v88, v88 row_ror:8 row_mask:0xf bank_mask:0xf
	v_add_f32_dpp v89, v89, v89 row_ror:8 row_mask:0xf bank_mask:0xf
	v_add_f32_dpp v90, v90, v90 row_ror:8 row_mask:0xf bank_mask:0xf
	v_add_f32_dpp v91, v91, v91 row_ror:8 row_mask:0xf bank_mask:0xf
	v_add_f32_dpp v92, v92, v92 row_ror:8 row_mask:0xf bank_mask:0xf
	v_add_f32_dpp v93, v93, v93 row_ror:8 row_mask:0xf bank_mask:0xf
	v_add_f32_dpp v94, v94, v94 row_ror:8 row_mask:0xf bank_mask:0xf
	v_add_f32_dpp v95, v95, v95 row_ror:8 row_mask:0xf bank_mask:0xf
	v_add_f32_dpp v40, v40, v40 row_shr:2 row_mask:0xf bank_mask:0xf bound_ctrl:1
	v_add_f32_dpp v41, v41, v41 row_shr:2 row_mask:0xf bank_mask:0xf bound_ctrl:1
	v_add_f32_dpp v42, v42, v42 row_shr:2 row_mask:0xf bank_mask:0xf bound_ctrl:1
	v_add_f32_dpp v43, v43, v43 row_shr:2 row_mask:0xf bank_mask:0xf bound_ctrl:1
	v_add_f32_dpp v44, v44, v44 row_shr:2 row_mask:0xf bank_mask:0xf bound_ctrl:1
	v_add_f32_dpp v45, v45, v45 row_shr:2 row_mask:0xf bank_mask:0xf bound_ctrl:1
	v_add_f32_dpp v46, v46, v46 row_shr:2 row_mask:0xf bank_mask:0xf bound_ctrl:1
	v_add_f32_dpp v47, v47, v47 row_shr:2 row_mask:0xf bank_mask:0xf bound_ctrl:1
	v_add_f32_dpp v88, v88, v88 row_ror:4 row_mask:0xf bank_mask:0xf
	v_add_f32_dpp v89, v89, v89 row_ror:4 row_mask:0xf bank_mask:0xf
	v_add_f32_dpp v90, v90, v90 row_ror:4 row_mask:0xf bank_mask:0xf
	v_add_f32_dpp v91, v91, v91 row_ror:4 row_mask:0xf bank_mask:0xf
	v_add_f32_dpp v92, v92, v92 row_ror:4 row_mask:0xf bank_mask:0xf
	v_add_f32_dpp v93, v93, v93 row_ror:4 row_mask:0xf bank_mask:0xf
	v_add_f32_dpp v94, v94, v94 row_ror:4 row_mask:0xf bank_mask:0xf
	v_add_f32_dpp v95, v95, v95 row_ror:4 row_mask:0xf bank_mask:0xf
	v_add_f32_dpp v40, v40, v40 row_shr:4 row_mask:0xf bank_mask:0xf bound_ctrl:1
	v_add_f32_dpp v41, v41, v41 row_shr:4 row_mask:0xf bank_mask:0xf bound_ctrl:1
	v_add_f32_dpp v42, v42, v42 row_shr:4 row_mask:0xf bank_mask:0xf bound_ctrl:1
	v_add_f32_dpp v43, v43, v43 row_shr:4 row_mask:0xf bank_mask:0xf bound_ctrl:1
	v_add_f32_dpp v44, v44, v44 row_shr:4 row_mask:0xf bank_mask:0xf bound_ctrl:1
	v_add_f32_dpp v45, v45, v45 row_shr:4 row_mask:0xf bank_mask:0xf bound_ctrl:1
	v_add_f32_dpp v46, v46, v46 row_shr:4 row_mask:0xf bank_mask:0xf bound_ctrl:1
	v_add_f32_dpp v47, v47, v47 row_shr:4 row_mask:0xf bank_mask:0xf bound_ctrl:1
	v_add_f32_dpp v88, v88, v88 row_ror:2 row_mask:0xf bank_mask:0xf
	v_add_f32_dpp v89, v89, v89 row_ror:2 row_mask:0xf bank_mask:0xf
	v_add_f32_dpp v90, v90, v90 row_ror:2 row_mask:0xf bank_mask:0xf
	v_add_f32_dpp v91, v91, v91 row_ror:2 row_mask:0xf bank_mask:0xf
	v_add_f32_dpp v92, v92, v92 row_ror:2 row_mask:0xf bank_mask:0xf
	v_add_f32_dpp v93, v93, v93 row_ror:2 row_mask:0xf bank_mask:0xf
	v_add_f32_dpp v94, v94, v94 row_ror:2 row_mask:0xf bank_mask:0xf
	v_add_f32_dpp v95, v95, v95 row_ror:2 row_mask:0xf bank_mask:0xf
	v_add_f32_dpp v40, v40, v40 row_shr:8 row_mask:0xf bank_mask:0xf bound_ctrl:1
	v_add_f32_dpp v41, v41, v41 row_shr:8 row_mask:0xf bank_mask:0xf bound_ctrl:1
	v_add_f32_dpp v42, v42, v42 row_shr:8 row_mask:0xf bank_mask:0xf bound_ctrl:1
	v_add_f32_dpp v43, v43, v43 row_shr:8 row_mask:0xf bank_mask:0xf bound_ctrl:1
	v_add_f32_dpp v44, v44, v44 row_shr:8 row_mask:0xf bank_mask:0xf bound_ctrl:1
	v_add_f32_dpp v45, v45, v45 row_shr:8 row_mask:0xf bank_mask:0xf bound_ctrl:1
	v_add_f32_dpp v46, v46, v46 row_shr:8 row_mask:0xf bank_mask:0xf bound_ctrl:1
	v_add_f32_dpp v47, v47, v47 row_shr:8 row_mask:0xf bank_mask:0xf bound_ctrl:1
	v_add_f32_dpp v88, v88, v88 row_ror:1 row_mask:0xf bank_mask:0xf
	v_add_f32_dpp v89, v89, v89 row_ror:1 row_mask:0xf bank_mask:0xf
	v_add_f32_dpp v90, v90, v90 row_ror:1 row_mask:0xf bank_mask:0xf
	v_add_f32_dpp v91, v91, v91 row_ror:1 row_mask:0xf bank_mask:0xf
	v_add_f32_dpp v92, v92, v92 row_ror:1 row_mask:0xf bank_mask:0xf
	v_add_f32_dpp v93, v93, v93 row_ror:1 row_mask:0xf bank_mask:0xf
	v_add_f32_dpp v94, v94, v94 row_ror:1 row_mask:0xf bank_mask:0xf
	v_add_f32_dpp v95, v95, v95 row_ror:1 row_mask:0xf bank_mask:0xf
	v_add_f32_e32 v40, v40, v178
	v_add_f32_e32 v44, v44, v179
	v_add_f32_e32 v41, v41, v180
	v_add_f32_e32 v45, v45, v181
	v_add_f32_e32 v42, v42, v182
	v_add_f32_e32 v46, v46, v183
	v_add_f32_e32 v43, v43, v184
	v_add_f32_e32 v47, v47, v185
	v_mul_f32_e32 v132, v40, v103
	v_mul_f32_e32 v40, v40, v102
	v_fma_f32 v40, -v44, v103, v40
	v_fma_f32 v44, v44, v102, v132
	v_mul_f32_e32 v133, v41, v107
	v_mul_f32_e32 v41, v41, v106
	v_fma_f32 v41, -v45, v107, v41
	v_fma_f32 v45, v45, v106, v133
	v_mul_f32_e32 v132, v42, v111
	v_mul_f32_e32 v42, v42, v110
	v_fma_f32 v42, -v46, v111, v42
	v_fma_f32 v46, v46, v110, v132
	v_mul_f32_e32 v133, v43, v115
	v_mul_f32_e32 v43, v43, v114
	v_fma_f32 v43, -v47, v115, v43
	v_fma_f32 v47, v47, v114, v133
	v_add_f32_e32 v88, v88, v178
	v_add_f32_e32 v92, v92, v179
	v_mul_f32_e32 v132, v92, v117
	v_mul_f32_e32 v179, v88, v117
	v_fma_f32 v178, v88, v116, -v132
	v_fma_f32 v179, v92, v116, v179
	v_add_f32_e32 v89, v89, v180
	v_add_f32_e32 v93, v93, v181
	v_mul_f32_e32 v133, v93, v121
	v_mul_f32_e32 v181, v89, v121
	v_fma_f32 v180, v89, v120, -v133
	v_fma_f32 v181, v93, v120, v181
	v_add_f32_e32 v90, v90, v182
	v_add_f32_e32 v94, v94, v183
	v_mul_f32_e32 v132, v94, v125
	v_mul_f32_e32 v183, v90, v125
	v_fma_f32 v182, v90, v124, -v132
	v_fma_f32 v183, v94, v124, v183
	v_add_f32_e32 v91, v91, v184
	v_add_f32_e32 v95, v95, v185
	v_mul_f32_e32 v133, v95, v129
	v_mul_f32_e32 v185, v91, v129
	v_fma_f32 v184, v91, v128, -v133
	v_fma_f32 v185, v95, v128, v185
	v_mul_f32_e32 v132, v48, v101
	v_mul_f32_e32 v48, v48, v100
	v_fma_f32 v48, -v52, v101, v48
	v_fma_f32 v52, v52, v100, v132
	v_mul_f32_e32 v133, v49, v105
	v_mul_f32_e32 v49, v49, v104
	v_fma_f32 v49, -v53, v105, v49
	v_fma_f32 v53, v53, v104, v133
	v_mul_f32_e32 v132, v50, v109
	v_mul_f32_e32 v50, v50, v108
	v_fma_f32 v50, -v54, v109, v50
	v_fma_f32 v54, v54, v108, v132
	v_mul_f32_e32 v133, v51, v113
	v_mul_f32_e32 v51, v51, v112
	v_fma_f32 v51, -v55, v113, v51
	v_fma_f32 v55, v55, v112, v133
	v_mov_b32_e32 v88, v48
	v_mov_b32_e32 v89, v49
	v_mov_b32_e32 v90, v50
	v_mov_b32_e32 v91, v51
	v_mov_b32_e32 v92, v52
	v_mov_b32_e32 v93, v53
	v_mov_b32_e32 v94, v54
	v_mov_b32_e32 v95, v55
	v_add_f32_dpp v48, v48, v48 row_shr:1 row_mask:0xf bank_mask:0xf bound_ctrl:1
	v_add_f32_dpp v49, v49, v49 row_shr:1 row_mask:0xf bank_mask:0xf bound_ctrl:1
	v_add_f32_dpp v50, v50, v50 row_shr:1 row_mask:0xf bank_mask:0xf bound_ctrl:1
	v_add_f32_dpp v51, v51, v51 row_shr:1 row_mask:0xf bank_mask:0xf bound_ctrl:1
	v_add_f32_dpp v52, v52, v52 row_shr:1 row_mask:0xf bank_mask:0xf bound_ctrl:1
	v_add_f32_dpp v53, v53, v53 row_shr:1 row_mask:0xf bank_mask:0xf bound_ctrl:1
	v_add_f32_dpp v54, v54, v54 row_shr:1 row_mask:0xf bank_mask:0xf bound_ctrl:1
	v_add_f32_dpp v55, v55, v55 row_shr:1 row_mask:0xf bank_mask:0xf bound_ctrl:1
	v_add_f32_dpp v88, v88, v88 row_ror:8 row_mask:0xf bank_mask:0xf
	v_add_f32_dpp v89, v89, v89 row_ror:8 row_mask:0xf bank_mask:0xf
	v_add_f32_dpp v90, v90, v90 row_ror:8 row_mask:0xf bank_mask:0xf
	v_add_f32_dpp v91, v91, v91 row_ror:8 row_mask:0xf bank_mask:0xf
	v_add_f32_dpp v92, v92, v92 row_ror:8 row_mask:0xf bank_mask:0xf
	v_add_f32_dpp v93, v93, v93 row_ror:8 row_mask:0xf bank_mask:0xf
	v_add_f32_dpp v94, v94, v94 row_ror:8 row_mask:0xf bank_mask:0xf
	v_add_f32_dpp v95, v95, v95 row_ror:8 row_mask:0xf bank_mask:0xf
	v_add_f32_dpp v48, v48, v48 row_shr:2 row_mask:0xf bank_mask:0xf bound_ctrl:1
	v_add_f32_dpp v49, v49, v49 row_shr:2 row_mask:0xf bank_mask:0xf bound_ctrl:1
	v_add_f32_dpp v50, v50, v50 row_shr:2 row_mask:0xf bank_mask:0xf bound_ctrl:1
	v_add_f32_dpp v51, v51, v51 row_shr:2 row_mask:0xf bank_mask:0xf bound_ctrl:1
	v_add_f32_dpp v52, v52, v52 row_shr:2 row_mask:0xf bank_mask:0xf bound_ctrl:1
	v_add_f32_dpp v53, v53, v53 row_shr:2 row_mask:0xf bank_mask:0xf bound_ctrl:1
	v_add_f32_dpp v54, v54, v54 row_shr:2 row_mask:0xf bank_mask:0xf bound_ctrl:1
	v_add_f32_dpp v55, v55, v55 row_shr:2 row_mask:0xf bank_mask:0xf bound_ctrl:1
	v_add_f32_dpp v88, v88, v88 row_ror:4 row_mask:0xf bank_mask:0xf
	v_add_f32_dpp v89, v89, v89 row_ror:4 row_mask:0xf bank_mask:0xf
	v_add_f32_dpp v90, v90, v90 row_ror:4 row_mask:0xf bank_mask:0xf
	v_add_f32_dpp v91, v91, v91 row_ror:4 row_mask:0xf bank_mask:0xf
	v_add_f32_dpp v92, v92, v92 row_ror:4 row_mask:0xf bank_mask:0xf
	v_add_f32_dpp v93, v93, v93 row_ror:4 row_mask:0xf bank_mask:0xf
	v_add_f32_dpp v94, v94, v94 row_ror:4 row_mask:0xf bank_mask:0xf
	v_add_f32_dpp v95, v95, v95 row_ror:4 row_mask:0xf bank_mask:0xf
	v_add_f32_dpp v48, v48, v48 row_shr:4 row_mask:0xf bank_mask:0xf bound_ctrl:1
	v_add_f32_dpp v49, v49, v49 row_shr:4 row_mask:0xf bank_mask:0xf bound_ctrl:1
	v_add_f32_dpp v50, v50, v50 row_shr:4 row_mask:0xf bank_mask:0xf bound_ctrl:1
	v_add_f32_dpp v51, v51, v51 row_shr:4 row_mask:0xf bank_mask:0xf bound_ctrl:1
	v_add_f32_dpp v52, v52, v52 row_shr:4 row_mask:0xf bank_mask:0xf bound_ctrl:1
	v_add_f32_dpp v53, v53, v53 row_shr:4 row_mask:0xf bank_mask:0xf bound_ctrl:1
	v_add_f32_dpp v54, v54, v54 row_shr:4 row_mask:0xf bank_mask:0xf bound_ctrl:1
	v_add_f32_dpp v55, v55, v55 row_shr:4 row_mask:0xf bank_mask:0xf bound_ctrl:1
	v_add_f32_dpp v88, v88, v88 row_ror:2 row_mask:0xf bank_mask:0xf
	v_add_f32_dpp v89, v89, v89 row_ror:2 row_mask:0xf bank_mask:0xf
	v_add_f32_dpp v90, v90, v90 row_ror:2 row_mask:0xf bank_mask:0xf
	v_add_f32_dpp v91, v91, v91 row_ror:2 row_mask:0xf bank_mask:0xf
	v_add_f32_dpp v92, v92, v92 row_ror:2 row_mask:0xf bank_mask:0xf
	v_add_f32_dpp v93, v93, v93 row_ror:2 row_mask:0xf bank_mask:0xf
	v_add_f32_dpp v94, v94, v94 row_ror:2 row_mask:0xf bank_mask:0xf
	v_add_f32_dpp v95, v95, v95 row_ror:2 row_mask:0xf bank_mask:0xf
	v_add_f32_dpp v48, v48, v48 row_shr:8 row_mask:0xf bank_mask:0xf bound_ctrl:1
	v_add_f32_dpp v49, v49, v49 row_shr:8 row_mask:0xf bank_mask:0xf bound_ctrl:1
	v_add_f32_dpp v50, v50, v50 row_shr:8 row_mask:0xf bank_mask:0xf bound_ctrl:1
	v_add_f32_dpp v51, v51, v51 row_shr:8 row_mask:0xf bank_mask:0xf bound_ctrl:1
	v_add_f32_dpp v52, v52, v52 row_shr:8 row_mask:0xf bank_mask:0xf bound_ctrl:1
	v_add_f32_dpp v53, v53, v53 row_shr:8 row_mask:0xf bank_mask:0xf bound_ctrl:1
	v_add_f32_dpp v54, v54, v54 row_shr:8 row_mask:0xf bank_mask:0xf bound_ctrl:1
	v_add_f32_dpp v55, v55, v55 row_shr:8 row_mask:0xf bank_mask:0xf bound_ctrl:1
	v_add_f32_dpp v88, v88, v88 row_ror:1 row_mask:0xf bank_mask:0xf
	v_add_f32_dpp v89, v89, v89 row_ror:1 row_mask:0xf bank_mask:0xf
	v_add_f32_dpp v90, v90, v90 row_ror:1 row_mask:0xf bank_mask:0xf
	v_add_f32_dpp v91, v91, v91 row_ror:1 row_mask:0xf bank_mask:0xf
	v_add_f32_dpp v92, v92, v92 row_ror:1 row_mask:0xf bank_mask:0xf
	v_add_f32_dpp v93, v93, v93 row_ror:1 row_mask:0xf bank_mask:0xf
	v_add_f32_dpp v94, v94, v94 row_ror:1 row_mask:0xf bank_mask:0xf
	v_add_f32_dpp v95, v95, v95 row_ror:1 row_mask:0xf bank_mask:0xf
	v_add_f32_e32 v48, v48, v178
	v_add_f32_e32 v52, v52, v179
	v_add_f32_e32 v49, v49, v180
	v_add_f32_e32 v53, v53, v181
	v_add_f32_e32 v50, v50, v182
	v_add_f32_e32 v54, v54, v183
	v_add_f32_e32 v51, v51, v184
	v_add_f32_e32 v55, v55, v185
	v_mul_f32_e32 v132, v48, v103
	v_mul_f32_e32 v48, v48, v102
	v_fma_f32 v48, -v52, v103, v48
	v_fma_f32 v52, v52, v102, v132
	v_mul_f32_e32 v133, v49, v107
	v_mul_f32_e32 v49, v49, v106
	v_fma_f32 v49, -v53, v107, v49
	v_fma_f32 v53, v53, v106, v133
	v_mul_f32_e32 v132, v50, v111
	v_mul_f32_e32 v50, v50, v110
	v_fma_f32 v50, -v54, v111, v50
	v_fma_f32 v54, v54, v110, v132
	v_mul_f32_e32 v133, v51, v115
	v_mul_f32_e32 v51, v51, v114
	v_fma_f32 v51, -v55, v115, v51
	v_fma_f32 v55, v55, v114, v133
	v_add_f32_e32 v88, v88, v178
	v_add_f32_e32 v92, v92, v179
	v_mul_f32_e32 v132, v92, v117
	v_mul_f32_e32 v179, v88, v117
	v_fma_f32 v178, v88, v116, -v132
	v_fma_f32 v179, v92, v116, v179
	v_add_f32_e32 v89, v89, v180
	v_add_f32_e32 v93, v93, v181
	v_mul_f32_e32 v133, v93, v121
	v_mul_f32_e32 v181, v89, v121
	v_fma_f32 v180, v89, v120, -v133
	v_fma_f32 v181, v93, v120, v181
	v_add_f32_e32 v90, v90, v182
	v_add_f32_e32 v94, v94, v183
	v_mul_f32_e32 v132, v94, v125
	v_mul_f32_e32 v183, v90, v125
	v_fma_f32 v182, v90, v124, -v132
	v_fma_f32 v183, v94, v124, v183
	v_add_f32_e32 v91, v91, v184
	v_add_f32_e32 v95, v95, v185
	v_mul_f32_e32 v133, v95, v129
	v_mul_f32_e32 v185, v91, v129
	v_fma_f32 v184, v91, v128, -v133
	v_fma_f32 v185, v95, v128, v185
	v_mul_f32_e32 v132, v56, v101
	v_mul_f32_e32 v56, v56, v100
	v_fma_f32 v56, -v60, v101, v56
	v_fma_f32 v60, v60, v100, v132
	v_mul_f32_e32 v133, v57, v105
	v_mul_f32_e32 v57, v57, v104
	v_fma_f32 v57, -v61, v105, v57
	v_fma_f32 v61, v61, v104, v133
	v_mul_f32_e32 v132, v58, v109
	v_mul_f32_e32 v58, v58, v108
	v_fma_f32 v58, -v62, v109, v58
	v_fma_f32 v62, v62, v108, v132
	v_mul_f32_e32 v133, v59, v113
	v_mul_f32_e32 v59, v59, v112
	v_fma_f32 v59, -v63, v113, v59
	v_fma_f32 v63, v63, v112, v133
	v_mov_b32_e32 v88, v56
	v_mov_b32_e32 v89, v57
	v_mov_b32_e32 v90, v58
	v_mov_b32_e32 v91, v59
	v_mov_b32_e32 v92, v60
	v_mov_b32_e32 v93, v61
	v_mov_b32_e32 v94, v62
	v_mov_b32_e32 v95, v63
	v_add_f32_dpp v56, v56, v56 row_shr:1 row_mask:0xf bank_mask:0xf bound_ctrl:1
	v_add_f32_dpp v57, v57, v57 row_shr:1 row_mask:0xf bank_mask:0xf bound_ctrl:1
	v_add_f32_dpp v58, v58, v58 row_shr:1 row_mask:0xf bank_mask:0xf bound_ctrl:1
	v_add_f32_dpp v59, v59, v59 row_shr:1 row_mask:0xf bank_mask:0xf bound_ctrl:1
	v_add_f32_dpp v60, v60, v60 row_shr:1 row_mask:0xf bank_mask:0xf bound_ctrl:1
	v_add_f32_dpp v61, v61, v61 row_shr:1 row_mask:0xf bank_mask:0xf bound_ctrl:1
	v_add_f32_dpp v62, v62, v62 row_shr:1 row_mask:0xf bank_mask:0xf bound_ctrl:1
	v_add_f32_dpp v63, v63, v63 row_shr:1 row_mask:0xf bank_mask:0xf bound_ctrl:1
	v_add_f32_dpp v88, v88, v88 row_ror:8 row_mask:0xf bank_mask:0xf
	v_add_f32_dpp v89, v89, v89 row_ror:8 row_mask:0xf bank_mask:0xf
	v_add_f32_dpp v90, v90, v90 row_ror:8 row_mask:0xf bank_mask:0xf
	v_add_f32_dpp v91, v91, v91 row_ror:8 row_mask:0xf bank_mask:0xf
	v_add_f32_dpp v92, v92, v92 row_ror:8 row_mask:0xf bank_mask:0xf
	v_add_f32_dpp v93, v93, v93 row_ror:8 row_mask:0xf bank_mask:0xf
	v_add_f32_dpp v94, v94, v94 row_ror:8 row_mask:0xf bank_mask:0xf
	v_add_f32_dpp v95, v95, v95 row_ror:8 row_mask:0xf bank_mask:0xf
	v_add_f32_dpp v56, v56, v56 row_shr:2 row_mask:0xf bank_mask:0xf bound_ctrl:1
	v_add_f32_dpp v57, v57, v57 row_shr:2 row_mask:0xf bank_mask:0xf bound_ctrl:1
	v_add_f32_dpp v58, v58, v58 row_shr:2 row_mask:0xf bank_mask:0xf bound_ctrl:1
	v_add_f32_dpp v59, v59, v59 row_shr:2 row_mask:0xf bank_mask:0xf bound_ctrl:1
	v_add_f32_dpp v60, v60, v60 row_shr:2 row_mask:0xf bank_mask:0xf bound_ctrl:1
	v_add_f32_dpp v61, v61, v61 row_shr:2 row_mask:0xf bank_mask:0xf bound_ctrl:1
	v_add_f32_dpp v62, v62, v62 row_shr:2 row_mask:0xf bank_mask:0xf bound_ctrl:1
	v_add_f32_dpp v63, v63, v63 row_shr:2 row_mask:0xf bank_mask:0xf bound_ctrl:1
	v_add_f32_dpp v88, v88, v88 row_ror:4 row_mask:0xf bank_mask:0xf
	v_add_f32_dpp v89, v89, v89 row_ror:4 row_mask:0xf bank_mask:0xf
	v_add_f32_dpp v90, v90, v90 row_ror:4 row_mask:0xf bank_mask:0xf
	v_add_f32_dpp v91, v91, v91 row_ror:4 row_mask:0xf bank_mask:0xf
	v_add_f32_dpp v92, v92, v92 row_ror:4 row_mask:0xf bank_mask:0xf
	v_add_f32_dpp v93, v93, v93 row_ror:4 row_mask:0xf bank_mask:0xf
	v_add_f32_dpp v94, v94, v94 row_ror:4 row_mask:0xf bank_mask:0xf
	v_add_f32_dpp v95, v95, v95 row_ror:4 row_mask:0xf bank_mask:0xf
	v_add_f32_dpp v56, v56, v56 row_shr:4 row_mask:0xf bank_mask:0xf bound_ctrl:1
	v_add_f32_dpp v57, v57, v57 row_shr:4 row_mask:0xf bank_mask:0xf bound_ctrl:1
	v_add_f32_dpp v58, v58, v58 row_shr:4 row_mask:0xf bank_mask:0xf bound_ctrl:1
	v_add_f32_dpp v59, v59, v59 row_shr:4 row_mask:0xf bank_mask:0xf bound_ctrl:1
	v_add_f32_dpp v60, v60, v60 row_shr:4 row_mask:0xf bank_mask:0xf bound_ctrl:1
	v_add_f32_dpp v61, v61, v61 row_shr:4 row_mask:0xf bank_mask:0xf bound_ctrl:1
	v_add_f32_dpp v62, v62, v62 row_shr:4 row_mask:0xf bank_mask:0xf bound_ctrl:1
	v_add_f32_dpp v63, v63, v63 row_shr:4 row_mask:0xf bank_mask:0xf bound_ctrl:1
	v_add_f32_dpp v88, v88, v88 row_ror:2 row_mask:0xf bank_mask:0xf
	v_add_f32_dpp v89, v89, v89 row_ror:2 row_mask:0xf bank_mask:0xf
	v_add_f32_dpp v90, v90, v90 row_ror:2 row_mask:0xf bank_mask:0xf
	v_add_f32_dpp v91, v91, v91 row_ror:2 row_mask:0xf bank_mask:0xf
	v_add_f32_dpp v92, v92, v92 row_ror:2 row_mask:0xf bank_mask:0xf
	v_add_f32_dpp v93, v93, v93 row_ror:2 row_mask:0xf bank_mask:0xf
	v_add_f32_dpp v94, v94, v94 row_ror:2 row_mask:0xf bank_mask:0xf
	v_add_f32_dpp v95, v95, v95 row_ror:2 row_mask:0xf bank_mask:0xf
	v_add_f32_dpp v56, v56, v56 row_shr:8 row_mask:0xf bank_mask:0xf bound_ctrl:1
	v_add_f32_dpp v57, v57, v57 row_shr:8 row_mask:0xf bank_mask:0xf bound_ctrl:1
	v_add_f32_dpp v58, v58, v58 row_shr:8 row_mask:0xf bank_mask:0xf bound_ctrl:1
	v_add_f32_dpp v59, v59, v59 row_shr:8 row_mask:0xf bank_mask:0xf bound_ctrl:1
	v_add_f32_dpp v60, v60, v60 row_shr:8 row_mask:0xf bank_mask:0xf bound_ctrl:1
	v_add_f32_dpp v61, v61, v61 row_shr:8 row_mask:0xf bank_mask:0xf bound_ctrl:1
	v_add_f32_dpp v62, v62, v62 row_shr:8 row_mask:0xf bank_mask:0xf bound_ctrl:1
	v_add_f32_dpp v63, v63, v63 row_shr:8 row_mask:0xf bank_mask:0xf bound_ctrl:1
	v_add_f32_dpp v88, v88, v88 row_ror:1 row_mask:0xf bank_mask:0xf
	v_add_f32_dpp v89, v89, v89 row_ror:1 row_mask:0xf bank_mask:0xf
	v_add_f32_dpp v90, v90, v90 row_ror:1 row_mask:0xf bank_mask:0xf
	v_add_f32_dpp v91, v91, v91 row_ror:1 row_mask:0xf bank_mask:0xf
	v_add_f32_dpp v92, v92, v92 row_ror:1 row_mask:0xf bank_mask:0xf
	v_add_f32_dpp v93, v93, v93 row_ror:1 row_mask:0xf bank_mask:0xf
	v_add_f32_dpp v94, v94, v94 row_ror:1 row_mask:0xf bank_mask:0xf
	v_add_f32_dpp v95, v95, v95 row_ror:1 row_mask:0xf bank_mask:0xf
	v_add_f32_e32 v56, v56, v178
	v_add_f32_e32 v60, v60, v179
	v_add_f32_e32 v57, v57, v180
	v_add_f32_e32 v61, v61, v181
	v_add_f32_e32 v58, v58, v182
	v_add_f32_e32 v62, v62, v183
	v_add_f32_e32 v59, v59, v184
	v_add_f32_e32 v63, v63, v185
	v_mul_f32_e32 v132, v56, v103
	v_mul_f32_e32 v56, v56, v102
	v_fma_f32 v56, -v60, v103, v56
	v_fma_f32 v60, v60, v102, v132
	v_mul_f32_e32 v133, v57, v107
	v_mul_f32_e32 v57, v57, v106
	v_fma_f32 v57, -v61, v107, v57
	v_fma_f32 v61, v61, v106, v133
	v_mul_f32_e32 v132, v58, v111
	v_mul_f32_e32 v58, v58, v110
	v_fma_f32 v58, -v62, v111, v58
	v_fma_f32 v62, v62, v110, v132
	v_mul_f32_e32 v133, v59, v115
	v_mul_f32_e32 v59, v59, v114
	v_fma_f32 v59, -v63, v115, v59
	v_fma_f32 v63, v63, v114, v133
	v_add_f32_e32 v88, v88, v178
	v_add_f32_e32 v92, v92, v179
	v_mul_f32_e32 v132, v92, v117
	v_mul_f32_e32 v179, v88, v117
	v_fma_f32 v178, v88, v116, -v132
	v_fma_f32 v179, v92, v116, v179
	v_add_f32_e32 v89, v89, v180
	v_add_f32_e32 v93, v93, v181
	v_mul_f32_e32 v133, v93, v121
	v_mul_f32_e32 v181, v89, v121
	v_fma_f32 v180, v89, v120, -v133
	v_fma_f32 v181, v93, v120, v181
	v_add_f32_e32 v90, v90, v182
	v_add_f32_e32 v94, v94, v183
	v_mul_f32_e32 v132, v94, v125
	v_mul_f32_e32 v183, v90, v125
	v_fma_f32 v182, v90, v124, -v132
	v_fma_f32 v183, v94, v124, v183
	v_add_f32_e32 v91, v91, v184
	v_add_f32_e32 v95, v95, v185
	v_mul_f32_e32 v133, v95, v129
	v_mul_f32_e32 v185, v91, v129
	v_fma_f32 v184, v91, v128, -v133
	v_fma_f32 v185, v95, v128, v185
	s_waitcnt vmcnt(14)
	v_cvt_pk_bf16_f32 v80, v80, v81
	v_cvt_pk_bf16_f32 v81, v82, v83
	v_cvt_pk_bf16_f32 v82, -v84, -v85
	v_cvt_pk_bf16_f32 v83, -v86, -v87
	v_cvt_pk_bf16_f32 v96, v32, v33
	v_cvt_pk_bf16_f32 v97, v34, v35
	v_cvt_pk_bf16_f32 v98, v36, v37
	v_cvt_pk_bf16_f32 v99, v38, v39
	s_nop 1
	v_mfma_f32_16x16x32_bf16 v[16:19], v[80:83], v[96:99], v[16:19]
	v_cvt_pk_bf16_f32 v96, v40, v41
	v_cvt_pk_bf16_f32 v97, v42, v43
	v_cvt_pk_bf16_f32 v98, v44, v45
	v_cvt_pk_bf16_f32 v99, v46, v47
	s_nop 1
	v_mfma_f32_16x16x32_bf16 v[20:23], v[80:83], v[96:99], v[20:23]
	v_cvt_pk_bf16_f32 v96, v48, v49
	v_cvt_pk_bf16_f32 v97, v50, v51
	v_cvt_pk_bf16_f32 v98, v52, v53
	v_cvt_pk_bf16_f32 v99, v54, v55
	s_nop 1
	v_mfma_f32_16x16x32_bf16 v[24:27], v[80:83], v[96:99], v[24:27]
	v_cvt_pk_bf16_f32 v96, v56, v57
	v_cvt_pk_bf16_f32 v97, v58, v59
	v_cvt_pk_bf16_f32 v98, v60, v61
	v_cvt_pk_bf16_f32 v99, v62, v63
	s_nop 1
	v_mfma_f32_16x16x32_bf16 v[28:31], v[80:83], v[96:99], v[28:31]
	s_waitcnt vmcnt(10)
	v_cvt_pk_bf16_f32 v64, v64, v65
	v_cvt_pk_bf16_f32 v65, v66, v67
	v_cvt_pk_bf16_f32 v66, v68, v69
	v_cvt_pk_bf16_f32 v67, v70, v71
	v_cvt_pk_bf16_f32 v72, v72, v73
	v_cvt_pk_bf16_f32 v73, v74, v75
	v_cvt_pk_bf16_f32 v74, v76, v77
	v_cvt_pk_bf16_f32 v75, v78, v79
	global_load_dwordx4 v[80:83], v136, s[38:39]
	global_load_dwordx4 v[84:87], v136, s[40:41]
	s_add_u32 s38, s38, 0x40
	s_addc_u32 s39, s39, 0
	s_add_u32 s40, s40, 0x40
	s_addc_u32 s41, s41, 0
	s_nop 0
	v_mfma_f32_16x16x32_bf16 v[32:35], v[64:67], v[0:3], 0
	v_mfma_f32_16x16x32_bf16 v[36:39], v[72:75], v[0:3], 0
	v_mfma_f32_16x16x32_bf16 v[40:43], v[64:67], v[4:7], 0
	v_mfma_f32_16x16x32_bf16 v[44:47], v[72:75], v[4:7], 0
	v_mfma_f32_16x16x32_bf16 v[48:51], v[64:67], v[8:11], 0
	v_mfma_f32_16x16x32_bf16 v[52:55], v[72:75], v[8:11], 0
	v_mfma_f32_16x16x32_bf16 v[56:59], v[64:67], v[12:15], 0
	v_mfma_f32_16x16x32_bf16 v[60:63], v[72:75], v[12:15], 0
	s_mov_b32 exec_hi, 0
	global_load_dwordx4 v[64:67], v135, s[20:21]
	global_load_dwordx4 v[68:71], v135, s[20:21] offset:16
	global_load_dwordx4 v[72:75], v135, s[22:23]
	global_load_dwordx4 v[76:79], v135, s[22:23] offset:16
	s_mov_b64 exec, -1
	s_add_u32 s20, s20, 0x400
	s_addc_u32 s21, s21, 0
	s_add_u32 s22, s22, 0x400
	s_addc_u32 s23, s23, 0
	global_load_dwordx4 v[100:103], v134, s[42:43] offset:0
	global_load_dwordx4 v[104:107], v134, s[42:43] offset:16
	global_load_dwordx4 v[108:111], v134, s[42:43] offset:32
	global_load_dwordx4 v[112:115], v134, s[42:43] offset:48
	global_load_dwordx4 v[116:119], v134, s[42:43] offset:64
	global_load_dwordx4 v[120:123], v134, s[42:43] offset:80
	global_load_dwordx4 v[124:127], v134, s[42:43] offset:96
	global_load_dwordx4 v[128:131], v134, s[42:43] offset:112
	global_load_dwordx4 v[178:181], v206, s[44:45]
	global_load_dwordx4 v[182:185], v206, s[44:45] offset:16
	s_add_u32 s42, s42, 0x2000
	s_addc_u32 s43, s43, 0
	s_add_u32 s44, s44, 0x80
	s_addc_u32 s45, s45, 0
	s_waitcnt vmcnt(16)
	v_mul_f32_e32 v132, v171, v157
	v_mul_f32_e32 v133, v170, v157
	v_fma_f32 v170, v170, v156, -v132
	v_fma_f32 v171, v171, v156, v133
	v_mul_f32_e32 v132, v173, v161
	v_mul_f32_e32 v133, v172, v161
	v_fma_f32 v172, v172, v160, -v132
	v_fma_f32 v173, v173, v160, v133
	v_mul_f32_e32 v132, v175, v165
	v_mul_f32_e32 v133, v174, v165
	v_fma_f32 v174, v174, v164, -v132
	v_fma_f32 v175, v175, v164, v133
	v_mul_f32_e32 v132, v177, v169
	v_mul_f32_e32 v133, v176, v169
	v_fma_f32 v176, v176, v168, -v132
	v_fma_f32 v177, v177, v168, v133
	v_mul_f32_e32 v132, v56, v139
	v_mul_f32_e32 v56, v56, v138
	v_fma_f32 v56, -v60, v139, v56
	v_fma_f32 v60, v60, v138, v132
	v_mul_f32_e32 v133, v57, v143
	v_mul_f32_e32 v57, v57, v142
	v_fma_f32 v57, -v61, v143, v57
	v_fma_f32 v61, v61, v142, v133
	v_mul_f32_e32 v132, v58, v147
	v_mul_f32_e32 v58, v58, v146
	v_fma_f32 v58, -v62, v147, v58
	v_fma_f32 v62, v62, v146, v132
	v_mul_f32_e32 v133, v59, v151
	v_mul_f32_e32 v59, v59, v150
	v_fma_f32 v59, -v63, v151, v59
	v_fma_f32 v63, v63, v150, v133
	v_mov_b32_e32 v88, v56
	v_mov_b32_e32 v89, v57
	v_mov_b32_e32 v90, v58
	v_mov_b32_e32 v91, v59
	v_mov_b32_e32 v92, v60
	v_mov_b32_e32 v93, v61
	v_mov_b32_e32 v94, v62
	v_mov_b32_e32 v95, v63
	v_add_f32_dpp v56, v56, v56 row_shl:1 row_mask:0xf bank_mask:0xf bound_ctrl:1
	v_add_f32_dpp v57, v57, v57 row_shl:1 row_mask:0xf bank_mask:0xf bound_ctrl:1
	v_add_f32_dpp v58, v58, v58 row_shl:1 row_mask:0xf bank_mask:0xf bound_ctrl:1
	v_add_f32_dpp v59, v59, v59 row_shl:1 row_mask:0xf bank_mask:0xf bound_ctrl:1
	v_add_f32_dpp v60, v60, v60 row_shl:1 row_mask:0xf bank_mask:0xf bound_ctrl:1
	v_add_f32_dpp v61, v61, v61 row_shl:1 row_mask:0xf bank_mask:0xf bound_ctrl:1
	v_add_f32_dpp v62, v62, v62 row_shl:1 row_mask:0xf bank_mask:0xf bound_ctrl:1
	v_add_f32_dpp v63, v63, v63 row_shl:1 row_mask:0xf bank_mask:0xf bound_ctrl:1
	v_add_f32_dpp v88, v88, v88 row_ror:8 row_mask:0xf bank_mask:0xf
	v_add_f32_dpp v89, v89, v89 row_ror:8 row_mask:0xf bank_mask:0xf
	v_add_f32_dpp v90, v90, v90 row_ror:8 row_mask:0xf bank_mask:0xf
	v_add_f32_dpp v91, v91, v91 row_ror:8 row_mask:0xf bank_mask:0xf
	v_add_f32_dpp v92, v92, v92 row_ror:8 row_mask:0xf bank_mask:0xf
	v_add_f32_dpp v93, v93, v93 row_ror:8 row_mask:0xf bank_mask:0xf
	v_add_f32_dpp v94, v94, v94 row_ror:8 row_mask:0xf bank_mask:0xf
	v_add_f32_dpp v95, v95, v95 row_ror:8 row_mask:0xf bank_mask:0xf
	v_add_f32_dpp v56, v56, v56 row_shl:2 row_mask:0xf bank_mask:0xf bound_ctrl:1
	v_add_f32_dpp v57, v57, v57 row_shl:2 row_mask:0xf bank_mask:0xf bound_ctrl:1
	v_add_f32_dpp v58, v58, v58 row_shl:2 row_mask:0xf bank_mask:0xf bound_ctrl:1
	v_add_f32_dpp v59, v59, v59 row_shl:2 row_mask:0xf bank_mask:0xf bound_ctrl:1
	v_add_f32_dpp v60, v60, v60 row_shl:2 row_mask:0xf bank_mask:0xf bound_ctrl:1
	v_add_f32_dpp v61, v61, v61 row_shl:2 row_mask:0xf bank_mask:0xf bound_ctrl:1
	v_add_f32_dpp v62, v62, v62 row_shl:2 row_mask:0xf bank_mask:0xf bound_ctrl:1
	v_add_f32_dpp v63, v63, v63 row_shl:2 row_mask:0xf bank_mask:0xf bound_ctrl:1
	v_add_f32_dpp v88, v88, v88 row_ror:4 row_mask:0xf bank_mask:0xf
	v_add_f32_dpp v89, v89, v89 row_ror:4 row_mask:0xf bank_mask:0xf
	v_add_f32_dpp v90, v90, v90 row_ror:4 row_mask:0xf bank_mask:0xf
	v_add_f32_dpp v91, v91, v91 row_ror:4 row_mask:0xf bank_mask:0xf
	v_add_f32_dpp v92, v92, v92 row_ror:4 row_mask:0xf bank_mask:0xf
	v_add_f32_dpp v93, v93, v93 row_ror:4 row_mask:0xf bank_mask:0xf
	v_add_f32_dpp v94, v94, v94 row_ror:4 row_mask:0xf bank_mask:0xf
	v_add_f32_dpp v95, v95, v95 row_ror:4 row_mask:0xf bank_mask:0xf
	v_add_f32_dpp v56, v56, v56 row_shl:4 row_mask:0xf bank_mask:0xf bound_ctrl:1
	v_add_f32_dpp v57, v57, v57 row_shl:4 row_mask:0xf bank_mask:0xf bound_ctrl:1
	v_add_f32_dpp v58, v58, v58 row_shl:4 row_mask:0xf bank_mask:0xf bound_ctrl:1
	v_add_f32_dpp v59, v59, v59 row_shl:4 row_mask:0xf bank_mask:0xf bound_ctrl:1
	v_add_f32_dpp v60, v60, v60 row_shl:4 row_mask:0xf bank_mask:0xf bound_ctrl:1
	v_add_f32_dpp v61, v61, v61 row_shl:4 row_mask:0xf bank_mask:0xf bound_ctrl:1
	v_add_f32_dpp v62, v62, v62 row_shl:4 row_mask:0xf bank_mask:0xf bound_ctrl:1
	v_add_f32_dpp v63, v63, v63 row_shl:4 row_mask:0xf bank_mask:0xf bound_ctrl:1
	v_add_f32_dpp v88, v88, v88 row_ror:2 row_mask:0xf bank_mask:0xf
	v_add_f32_dpp v89, v89, v89 row_ror:2 row_mask:0xf bank_mask:0xf
	v_add_f32_dpp v90, v90, v90 row_ror:2 row_mask:0xf bank_mask:0xf
	v_add_f32_dpp v91, v91, v91 row_ror:2 row_mask:0xf bank_mask:0xf
	v_add_f32_dpp v92, v92, v92 row_ror:2 row_mask:0xf bank_mask:0xf
	v_add_f32_dpp v93, v93, v93 row_ror:2 row_mask:0xf bank_mask:0xf
	v_add_f32_dpp v94, v94, v94 row_ror:2 row_mask:0xf bank_mask:0xf
	v_add_f32_dpp v95, v95, v95 row_ror:2 row_mask:0xf bank_mask:0xf
	v_add_f32_dpp v56, v56, v56 row_shl:8 row_mask:0xf bank_mask:0xf bound_ctrl:1
	v_add_f32_dpp v57, v57, v57 row_shl:8 row_mask:0xf bank_mask:0xf bound_ctrl:1
	v_add_f32_dpp v58, v58, v58 row_shl:8 row_mask:0xf bank_mask:0xf bound_ctrl:1
	v_add_f32_dpp v59, v59, v59 row_shl:8 row_mask:0xf bank_mask:0xf bound_ctrl:1
	v_add_f32_dpp v60, v60, v60 row_shl:8 row_mask:0xf bank_mask:0xf bound_ctrl:1
	v_add_f32_dpp v61, v61, v61 row_shl:8 row_mask:0xf bank_mask:0xf bound_ctrl:1
	v_add_f32_dpp v62, v62, v62 row_shl:8 row_mask:0xf bank_mask:0xf bound_ctrl:1
	v_add_f32_dpp v63, v63, v63 row_shl:8 row_mask:0xf bank_mask:0xf bound_ctrl:1
	v_add_f32_dpp v88, v88, v88 row_ror:1 row_mask:0xf bank_mask:0xf
	v_add_f32_dpp v89, v89, v89 row_ror:1 row_mask:0xf bank_mask:0xf
	v_add_f32_dpp v90, v90, v90 row_ror:1 row_mask:0xf bank_mask:0xf
	v_add_f32_dpp v91, v91, v91 row_ror:1 row_mask:0xf bank_mask:0xf
	v_add_f32_dpp v92, v92, v92 row_ror:1 row_mask:0xf bank_mask:0xf
	v_add_f32_dpp v93, v93, v93 row_ror:1 row_mask:0xf bank_mask:0xf
	v_add_f32_dpp v94, v94, v94 row_ror:1 row_mask:0xf bank_mask:0xf
	v_add_f32_dpp v95, v95, v95 row_ror:1 row_mask:0xf bank_mask:0xf
	v_add_f32_e32 v56, v56, v170
	v_add_f32_e32 v60, v60, v171
	v_add_f32_e32 v57, v57, v172
	v_add_f32_e32 v61, v61, v173
	v_add_f32_e32 v58, v58, v174
	v_add_f32_e32 v62, v62, v175
	v_add_f32_e32 v59, v59, v176
	v_add_f32_e32 v63, v63, v177
	v_mul_f32_e32 v132, v56, v141
	v_mul_f32_e32 v56, v56, v140
	v_fma_f32 v56, -v60, v141, v56
	v_fma_f32 v60, v60, v140, v132
	v_mul_f32_e32 v133, v57, v145
	v_mul_f32_e32 v57, v57, v144
	v_fma_f32 v57, -v61, v145, v57
	v_fma_f32 v61, v61, v144, v133
	v_mul_f32_e32 v132, v58, v149
	v_mul_f32_e32 v58, v58, v148
	v_fma_f32 v58, -v62, v149, v58
	v_fma_f32 v62, v62, v148, v132
	v_mul_f32_e32 v133, v59, v153
	v_mul_f32_e32 v59, v59, v152
	v_fma_f32 v59, -v63, v153, v59
	v_fma_f32 v63, v63, v152, v133
	v_add_f32_e32 v88, v88, v170
	v_add_f32_e32 v92, v92, v171
	v_mul_f32_e32 v132, v92, v155
	v_mul_f32_e32 v171, v88, v155
	v_fma_f32 v170, v88, v154, -v132
	v_fma_f32 v171, v92, v154, v171
	v_add_f32_e32 v89, v89, v172
	v_add_f32_e32 v93, v93, v173
	v_mul_f32_e32 v133, v93, v159
	v_mul_f32_e32 v173, v89, v159
	v_fma_f32 v172, v89, v158, -v133
	v_fma_f32 v173, v93, v158, v173
	v_add_f32_e32 v90, v90, v174
	v_add_f32_e32 v94, v94, v175
	v_mul_f32_e32 v132, v94, v163
	v_mul_f32_e32 v175, v90, v163
	v_fma_f32 v174, v90, v162, -v132
	v_fma_f32 v175, v94, v162, v175
	v_add_f32_e32 v91, v91, v176
	v_add_f32_e32 v95, v95, v177
	v_mul_f32_e32 v133, v95, v167
	v_mul_f32_e32 v177, v91, v167
	v_fma_f32 v176, v91, v166, -v133
	v_fma_f32 v177, v95, v166, v177
	v_mul_f32_e32 v132, v48, v139
	v_mul_f32_e32 v48, v48, v138
	v_fma_f32 v48, -v52, v139, v48
	v_fma_f32 v52, v52, v138, v132
	v_mul_f32_e32 v133, v49, v143
	v_mul_f32_e32 v49, v49, v142
	v_fma_f32 v49, -v53, v143, v49
	v_fma_f32 v53, v53, v142, v133
	v_mul_f32_e32 v132, v50, v147
	v_mul_f32_e32 v50, v50, v146
	v_fma_f32 v50, -v54, v147, v50
	v_fma_f32 v54, v54, v146, v132
	v_mul_f32_e32 v133, v51, v151
	v_mul_f32_e32 v51, v51, v150
	v_fma_f32 v51, -v55, v151, v51
	v_fma_f32 v55, v55, v150, v133
	v_mov_b32_e32 v88, v48
	v_mov_b32_e32 v89, v49
	v_mov_b32_e32 v90, v50
	v_mov_b32_e32 v91, v51
	v_mov_b32_e32 v92, v52
	v_mov_b32_e32 v93, v53
	v_mov_b32_e32 v94, v54
	v_mov_b32_e32 v95, v55
	v_add_f32_dpp v48, v48, v48 row_shl:1 row_mask:0xf bank_mask:0xf bound_ctrl:1
	v_add_f32_dpp v49, v49, v49 row_shl:1 row_mask:0xf bank_mask:0xf bound_ctrl:1
	v_add_f32_dpp v50, v50, v50 row_shl:1 row_mask:0xf bank_mask:0xf bound_ctrl:1
	v_add_f32_dpp v51, v51, v51 row_shl:1 row_mask:0xf bank_mask:0xf bound_ctrl:1
	v_add_f32_dpp v52, v52, v52 row_shl:1 row_mask:0xf bank_mask:0xf bound_ctrl:1
	v_add_f32_dpp v53, v53, v53 row_shl:1 row_mask:0xf bank_mask:0xf bound_ctrl:1
	v_add_f32_dpp v54, v54, v54 row_shl:1 row_mask:0xf bank_mask:0xf bound_ctrl:1
	v_add_f32_dpp v55, v55, v55 row_shl:1 row_mask:0xf bank_mask:0xf bound_ctrl:1
	v_add_f32_dpp v88, v88, v88 row_ror:8 row_mask:0xf bank_mask:0xf
	v_add_f32_dpp v89, v89, v89 row_ror:8 row_mask:0xf bank_mask:0xf
	v_add_f32_dpp v90, v90, v90 row_ror:8 row_mask:0xf bank_mask:0xf
	v_add_f32_dpp v91, v91, v91 row_ror:8 row_mask:0xf bank_mask:0xf
	v_add_f32_dpp v92, v92, v92 row_ror:8 row_mask:0xf bank_mask:0xf
	v_add_f32_dpp v93, v93, v93 row_ror:8 row_mask:0xf bank_mask:0xf
	v_add_f32_dpp v94, v94, v94 row_ror:8 row_mask:0xf bank_mask:0xf
	v_add_f32_dpp v95, v95, v95 row_ror:8 row_mask:0xf bank_mask:0xf
	v_add_f32_dpp v48, v48, v48 row_shl:2 row_mask:0xf bank_mask:0xf bound_ctrl:1
	v_add_f32_dpp v49, v49, v49 row_shl:2 row_mask:0xf bank_mask:0xf bound_ctrl:1
	v_add_f32_dpp v50, v50, v50 row_shl:2 row_mask:0xf bank_mask:0xf bound_ctrl:1
	v_add_f32_dpp v51, v51, v51 row_shl:2 row_mask:0xf bank_mask:0xf bound_ctrl:1
	v_add_f32_dpp v52, v52, v52 row_shl:2 row_mask:0xf bank_mask:0xf bound_ctrl:1
	v_add_f32_dpp v53, v53, v53 row_shl:2 row_mask:0xf bank_mask:0xf bound_ctrl:1
	v_add_f32_dpp v54, v54, v54 row_shl:2 row_mask:0xf bank_mask:0xf bound_ctrl:1
	v_add_f32_dpp v55, v55, v55 row_shl:2 row_mask:0xf bank_mask:0xf bound_ctrl:1
	v_add_f32_dpp v88, v88, v88 row_ror:4 row_mask:0xf bank_mask:0xf
	v_add_f32_dpp v89, v89, v89 row_ror:4 row_mask:0xf bank_mask:0xf
	v_add_f32_dpp v90, v90, v90 row_ror:4 row_mask:0xf bank_mask:0xf
	v_add_f32_dpp v91, v91, v91 row_ror:4 row_mask:0xf bank_mask:0xf
	v_add_f32_dpp v92, v92, v92 row_ror:4 row_mask:0xf bank_mask:0xf
	v_add_f32_dpp v93, v93, v93 row_ror:4 row_mask:0xf bank_mask:0xf
	v_add_f32_dpp v94, v94, v94 row_ror:4 row_mask:0xf bank_mask:0xf
	v_add_f32_dpp v95, v95, v95 row_ror:4 row_mask:0xf bank_mask:0xf
	v_add_f32_dpp v48, v48, v48 row_shl:4 row_mask:0xf bank_mask:0xf bound_ctrl:1
	v_add_f32_dpp v49, v49, v49 row_shl:4 row_mask:0xf bank_mask:0xf bound_ctrl:1
	v_add_f32_dpp v50, v50, v50 row_shl:4 row_mask:0xf bank_mask:0xf bound_ctrl:1
	v_add_f32_dpp v51, v51, v51 row_shl:4 row_mask:0xf bank_mask:0xf bound_ctrl:1
	v_add_f32_dpp v52, v52, v52 row_shl:4 row_mask:0xf bank_mask:0xf bound_ctrl:1
	v_add_f32_dpp v53, v53, v53 row_shl:4 row_mask:0xf bank_mask:0xf bound_ctrl:1
	v_add_f32_dpp v54, v54, v54 row_shl:4 row_mask:0xf bank_mask:0xf bound_ctrl:1
	v_add_f32_dpp v55, v55, v55 row_shl:4 row_mask:0xf bank_mask:0xf bound_ctrl:1
	v_add_f32_dpp v88, v88, v88 row_ror:2 row_mask:0xf bank_mask:0xf
	v_add_f32_dpp v89, v89, v89 row_ror:2 row_mask:0xf bank_mask:0xf
	v_add_f32_dpp v90, v90, v90 row_ror:2 row_mask:0xf bank_mask:0xf
	v_add_f32_dpp v91, v91, v91 row_ror:2 row_mask:0xf bank_mask:0xf
	v_add_f32_dpp v92, v92, v92 row_ror:2 row_mask:0xf bank_mask:0xf
	v_add_f32_dpp v93, v93, v93 row_ror:2 row_mask:0xf bank_mask:0xf
	v_add_f32_dpp v94, v94, v94 row_ror:2 row_mask:0xf bank_mask:0xf
	v_add_f32_dpp v95, v95, v95 row_ror:2 row_mask:0xf bank_mask:0xf
	v_add_f32_dpp v48, v48, v48 row_shl:8 row_mask:0xf bank_mask:0xf bound_ctrl:1
	v_add_f32_dpp v49, v49, v49 row_shl:8 row_mask:0xf bank_mask:0xf bound_ctrl:1
	v_add_f32_dpp v50, v50, v50 row_shl:8 row_mask:0xf bank_mask:0xf bound_ctrl:1
	v_add_f32_dpp v51, v51, v51 row_shl:8 row_mask:0xf bank_mask:0xf bound_ctrl:1
	v_add_f32_dpp v52, v52, v52 row_shl:8 row_mask:0xf bank_mask:0xf bound_ctrl:1
	v_add_f32_dpp v53, v53, v53 row_shl:8 row_mask:0xf bank_mask:0xf bound_ctrl:1
	v_add_f32_dpp v54, v54, v54 row_shl:8 row_mask:0xf bank_mask:0xf bound_ctrl:1
	v_add_f32_dpp v55, v55, v55 row_shl:8 row_mask:0xf bank_mask:0xf bound_ctrl:1
	v_add_f32_dpp v88, v88, v88 row_ror:1 row_mask:0xf bank_mask:0xf
	v_add_f32_dpp v89, v89, v89 row_ror:1 row_mask:0xf bank_mask:0xf
	v_add_f32_dpp v90, v90, v90 row_ror:1 row_mask:0xf bank_mask:0xf
	v_add_f32_dpp v91, v91, v91 row_ror:1 row_mask:0xf bank_mask:0xf
	v_add_f32_dpp v92, v92, v92 row_ror:1 row_mask:0xf bank_mask:0xf
	v_add_f32_dpp v93, v93, v93 row_ror:1 row_mask:0xf bank_mask:0xf
	v_add_f32_dpp v94, v94, v94 row_ror:1 row_mask:0xf bank_mask:0xf
	v_add_f32_dpp v95, v95, v95 row_ror:1 row_mask:0xf bank_mask:0xf
	v_add_f32_e32 v48, v48, v170
	v_add_f32_e32 v52, v52, v171
	v_add_f32_e32 v49, v49, v172
	v_add_f32_e32 v53, v53, v173
	v_add_f32_e32 v50, v50, v174
	v_add_f32_e32 v54, v54, v175
	v_add_f32_e32 v51, v51, v176
	v_add_f32_e32 v55, v55, v177
	v_mul_f32_e32 v132, v48, v141
	v_mul_f32_e32 v48, v48, v140
	v_fma_f32 v48, -v52, v141, v48
	v_fma_f32 v52, v52, v140, v132
	v_mul_f32_e32 v133, v49, v145
	v_mul_f32_e32 v49, v49, v144
	v_fma_f32 v49, -v53, v145, v49
	v_fma_f32 v53, v53, v144, v133
	v_mul_f32_e32 v132, v50, v149
	v_mul_f32_e32 v50, v50, v148
	v_fma_f32 v50, -v54, v149, v50
	v_fma_f32 v54, v54, v148, v132
	v_mul_f32_e32 v133, v51, v153
	v_mul_f32_e32 v51, v51, v152
	v_fma_f32 v51, -v55, v153, v51
	v_fma_f32 v55, v55, v152, v133
	v_add_f32_e32 v88, v88, v170
	v_add_f32_e32 v92, v92, v171
	v_mul_f32_e32 v132, v92, v155
	v_mul_f32_e32 v171, v88, v155
	v_fma_f32 v170, v88, v154, -v132
	v_fma_f32 v171, v92, v154, v171
	v_add_f32_e32 v89, v89, v172
	v_add_f32_e32 v93, v93, v173
	v_mul_f32_e32 v133, v93, v159
	v_mul_f32_e32 v173, v89, v159
	v_fma_f32 v172, v89, v158, -v133
	v_fma_f32 v173, v93, v158, v173
	v_add_f32_e32 v90, v90, v174
	v_add_f32_e32 v94, v94, v175
	v_mul_f32_e32 v132, v94, v163
	v_mul_f32_e32 v175, v90, v163
	v_fma_f32 v174, v90, v162, -v132
	v_fma_f32 v175, v94, v162, v175
	v_add_f32_e32 v91, v91, v176
	v_add_f32_e32 v95, v95, v177
	v_mul_f32_e32 v133, v95, v167
	v_mul_f32_e32 v177, v91, v167
	v_fma_f32 v176, v91, v166, -v133
	v_fma_f32 v177, v95, v166, v177
	v_mul_f32_e32 v132, v40, v139
	v_mul_f32_e32 v40, v40, v138
	v_fma_f32 v40, -v44, v139, v40
	v_fma_f32 v44, v44, v138, v132
	v_mul_f32_e32 v133, v41, v143
	v_mul_f32_e32 v41, v41, v142
	v_fma_f32 v41, -v45, v143, v41
	v_fma_f32 v45, v45, v142, v133
	v_mul_f32_e32 v132, v42, v147
	v_mul_f32_e32 v42, v42, v146
	v_fma_f32 v42, -v46, v147, v42
	v_fma_f32 v46, v46, v146, v132
	v_mul_f32_e32 v133, v43, v151
	v_mul_f32_e32 v43, v43, v150
	v_fma_f32 v43, -v47, v151, v43
	v_fma_f32 v47, v47, v150, v133
	v_mov_b32_e32 v88, v40
	v_mov_b32_e32 v89, v41
	v_mov_b32_e32 v90, v42
	v_mov_b32_e32 v91, v43
	v_mov_b32_e32 v92, v44
	v_mov_b32_e32 v93, v45
	v_mov_b32_e32 v94, v46
	v_mov_b32_e32 v95, v47
	v_add_f32_dpp v40, v40, v40 row_shl:1 row_mask:0xf bank_mask:0xf bound_ctrl:1
	v_add_f32_dpp v41, v41, v41 row_shl:1 row_mask:0xf bank_mask:0xf bound_ctrl:1
	v_add_f32_dpp v42, v42, v42 row_shl:1 row_mask:0xf bank_mask:0xf bound_ctrl:1
	v_add_f32_dpp v43, v43, v43 row_shl:1 row_mask:0xf bank_mask:0xf bound_ctrl:1
	v_add_f32_dpp v44, v44, v44 row_shl:1 row_mask:0xf bank_mask:0xf bound_ctrl:1
	v_add_f32_dpp v45, v45, v45 row_shl:1 row_mask:0xf bank_mask:0xf bound_ctrl:1
	v_add_f32_dpp v46, v46, v46 row_shl:1 row_mask:0xf bank_mask:0xf bound_ctrl:1
	v_add_f32_dpp v47, v47, v47 row_shl:1 row_mask:0xf bank_mask:0xf bound_ctrl:1
	v_add_f32_dpp v88, v88, v88 row_ror:8 row_mask:0xf bank_mask:0xf
	v_add_f32_dpp v89, v89, v89 row_ror:8 row_mask:0xf bank_mask:0xf
	v_add_f32_dpp v90, v90, v90 row_ror:8 row_mask:0xf bank_mask:0xf
	v_add_f32_dpp v91, v91, v91 row_ror:8 row_mask:0xf bank_mask:0xf
	v_add_f32_dpp v92, v92, v92 row_ror:8 row_mask:0xf bank_mask:0xf
	v_add_f32_dpp v93, v93, v93 row_ror:8 row_mask:0xf bank_mask:0xf
	v_add_f32_dpp v94, v94, v94 row_ror:8 row_mask:0xf bank_mask:0xf
	v_add_f32_dpp v95, v95, v95 row_ror:8 row_mask:0xf bank_mask:0xf
	v_add_f32_dpp v40, v40, v40 row_shl:2 row_mask:0xf bank_mask:0xf bound_ctrl:1
	v_add_f32_dpp v41, v41, v41 row_shl:2 row_mask:0xf bank_mask:0xf bound_ctrl:1
	v_add_f32_dpp v42, v42, v42 row_shl:2 row_mask:0xf bank_mask:0xf bound_ctrl:1
	v_add_f32_dpp v43, v43, v43 row_shl:2 row_mask:0xf bank_mask:0xf bound_ctrl:1
	v_add_f32_dpp v44, v44, v44 row_shl:2 row_mask:0xf bank_mask:0xf bound_ctrl:1
	v_add_f32_dpp v45, v45, v45 row_shl:2 row_mask:0xf bank_mask:0xf bound_ctrl:1
	v_add_f32_dpp v46, v46, v46 row_shl:2 row_mask:0xf bank_mask:0xf bound_ctrl:1
	v_add_f32_dpp v47, v47, v47 row_shl:2 row_mask:0xf bank_mask:0xf bound_ctrl:1
	v_add_f32_dpp v88, v88, v88 row_ror:4 row_mask:0xf bank_mask:0xf
	v_add_f32_dpp v89, v89, v89 row_ror:4 row_mask:0xf bank_mask:0xf
	v_add_f32_dpp v90, v90, v90 row_ror:4 row_mask:0xf bank_mask:0xf
	v_add_f32_dpp v91, v91, v91 row_ror:4 row_mask:0xf bank_mask:0xf
	v_add_f32_dpp v92, v92, v92 row_ror:4 row_mask:0xf bank_mask:0xf
	v_add_f32_dpp v93, v93, v93 row_ror:4 row_mask:0xf bank_mask:0xf
	v_add_f32_dpp v94, v94, v94 row_ror:4 row_mask:0xf bank_mask:0xf
	v_add_f32_dpp v95, v95, v95 row_ror:4 row_mask:0xf bank_mask:0xf
	v_add_f32_dpp v40, v40, v40 row_shl:4 row_mask:0xf bank_mask:0xf bound_ctrl:1
	v_add_f32_dpp v41, v41, v41 row_shl:4 row_mask:0xf bank_mask:0xf bound_ctrl:1
	v_add_f32_dpp v42, v42, v42 row_shl:4 row_mask:0xf bank_mask:0xf bound_ctrl:1
	v_add_f32_dpp v43, v43, v43 row_shl:4 row_mask:0xf bank_mask:0xf bound_ctrl:1
	v_add_f32_dpp v44, v44, v44 row_shl:4 row_mask:0xf bank_mask:0xf bound_ctrl:1
	v_add_f32_dpp v45, v45, v45 row_shl:4 row_mask:0xf bank_mask:0xf bound_ctrl:1
	v_add_f32_dpp v46, v46, v46 row_shl:4 row_mask:0xf bank_mask:0xf bound_ctrl:1
	v_add_f32_dpp v47, v47, v47 row_shl:4 row_mask:0xf bank_mask:0xf bound_ctrl:1
	v_add_f32_dpp v88, v88, v88 row_ror:2 row_mask:0xf bank_mask:0xf
	v_add_f32_dpp v89, v89, v89 row_ror:2 row_mask:0xf bank_mask:0xf
	v_add_f32_dpp v90, v90, v90 row_ror:2 row_mask:0xf bank_mask:0xf
	v_add_f32_dpp v91, v91, v91 row_ror:2 row_mask:0xf bank_mask:0xf
	v_add_f32_dpp v92, v92, v92 row_ror:2 row_mask:0xf bank_mask:0xf
	v_add_f32_dpp v93, v93, v93 row_ror:2 row_mask:0xf bank_mask:0xf
	v_add_f32_dpp v94, v94, v94 row_ror:2 row_mask:0xf bank_mask:0xf
	v_add_f32_dpp v95, v95, v95 row_ror:2 row_mask:0xf bank_mask:0xf
	v_add_f32_dpp v40, v40, v40 row_shl:8 row_mask:0xf bank_mask:0xf bound_ctrl:1
	v_add_f32_dpp v41, v41, v41 row_shl:8 row_mask:0xf bank_mask:0xf bound_ctrl:1
	v_add_f32_dpp v42, v42, v42 row_shl:8 row_mask:0xf bank_mask:0xf bound_ctrl:1
	v_add_f32_dpp v43, v43, v43 row_shl:8 row_mask:0xf bank_mask:0xf bound_ctrl:1
	v_add_f32_dpp v44, v44, v44 row_shl:8 row_mask:0xf bank_mask:0xf bound_ctrl:1
	v_add_f32_dpp v45, v45, v45 row_shl:8 row_mask:0xf bank_mask:0xf bound_ctrl:1
	v_add_f32_dpp v46, v46, v46 row_shl:8 row_mask:0xf bank_mask:0xf bound_ctrl:1
	v_add_f32_dpp v47, v47, v47 row_shl:8 row_mask:0xf bank_mask:0xf bound_ctrl:1
	v_add_f32_dpp v88, v88, v88 row_ror:1 row_mask:0xf bank_mask:0xf
	v_add_f32_dpp v89, v89, v89 row_ror:1 row_mask:0xf bank_mask:0xf
	v_add_f32_dpp v90, v90, v90 row_ror:1 row_mask:0xf bank_mask:0xf
	v_add_f32_dpp v91, v91, v91 row_ror:1 row_mask:0xf bank_mask:0xf
	v_add_f32_dpp v92, v92, v92 row_ror:1 row_mask:0xf bank_mask:0xf
	v_add_f32_dpp v93, v93, v93 row_ror:1 row_mask:0xf bank_mask:0xf
	v_add_f32_dpp v94, v94, v94 row_ror:1 row_mask:0xf bank_mask:0xf
	v_add_f32_dpp v95, v95, v95 row_ror:1 row_mask:0xf bank_mask:0xf
	v_add_f32_e32 v40, v40, v170
	v_add_f32_e32 v44, v44, v171
	v_add_f32_e32 v41, v41, v172
	v_add_f32_e32 v45, v45, v173
	v_add_f32_e32 v42, v42, v174
	v_add_f32_e32 v46, v46, v175
	v_add_f32_e32 v43, v43, v176
	v_add_f32_e32 v47, v47, v177
	v_mul_f32_e32 v132, v40, v141
	v_mul_f32_e32 v40, v40, v140
	v_fma_f32 v40, -v44, v141, v40
	v_fma_f32 v44, v44, v140, v132
	v_mul_f32_e32 v133, v41, v145
	v_mul_f32_e32 v41, v41, v144
	v_fma_f32 v41, -v45, v145, v41
	v_fma_f32 v45, v45, v144, v133
	v_mul_f32_e32 v132, v42, v149
	v_mul_f32_e32 v42, v42, v148
	v_fma_f32 v42, -v46, v149, v42
	v_fma_f32 v46, v46, v148, v132
	v_mul_f32_e32 v133, v43, v153
	v_mul_f32_e32 v43, v43, v152
	v_fma_f32 v43, -v47, v153, v43
	v_fma_f32 v47, v47, v152, v133
	v_add_f32_e32 v88, v88, v170
	v_add_f32_e32 v92, v92, v171
	v_mul_f32_e32 v132, v92, v155
	v_mul_f32_e32 v171, v88, v155
	v_fma_f32 v170, v88, v154, -v132
	v_fma_f32 v171, v92, v154, v171
	v_add_f32_e32 v89, v89, v172
	v_add_f32_e32 v93, v93, v173
	v_mul_f32_e32 v133, v93, v159
	v_mul_f32_e32 v173, v89, v159
	v_fma_f32 v172, v89, v158, -v133
	v_fma_f32 v173, v93, v158, v173
	v_add_f32_e32 v90, v90, v174
	v_add_f32_e32 v94, v94, v175
	v_mul_f32_e32 v132, v94, v163
	v_mul_f32_e32 v175, v90, v163
	v_fma_f32 v174, v90, v162, -v132
	v_fma_f32 v175, v94, v162, v175
	v_add_f32_e32 v91, v91, v176
	v_add_f32_e32 v95, v95, v177
	v_mul_f32_e32 v133, v95, v167
	v_mul_f32_e32 v177, v91, v167
	v_fma_f32 v176, v91, v166, -v133
	v_fma_f32 v177, v95, v166, v177
	v_mul_f32_e32 v132, v32, v139
	v_mul_f32_e32 v32, v32, v138
	v_fma_f32 v32, -v36, v139, v32
	v_fma_f32 v36, v36, v138, v132
	v_mul_f32_e32 v133, v33, v143
	v_mul_f32_e32 v33, v33, v142
	v_fma_f32 v33, -v37, v143, v33
	v_fma_f32 v37, v37, v142, v133
	v_mul_f32_e32 v132, v34, v147
	v_mul_f32_e32 v34, v34, v146
	v_fma_f32 v34, -v38, v147, v34
	v_fma_f32 v38, v38, v146, v132
	v_mul_f32_e32 v133, v35, v151
	v_mul_f32_e32 v35, v35, v150
	v_fma_f32 v35, -v39, v151, v35
	v_fma_f32 v39, v39, v150, v133
	v_mov_b32_e32 v88, v32
	v_mov_b32_e32 v89, v33
	v_mov_b32_e32 v90, v34
	v_mov_b32_e32 v91, v35
	v_mov_b32_e32 v92, v36
	v_mov_b32_e32 v93, v37
	v_mov_b32_e32 v94, v38
	v_mov_b32_e32 v95, v39
	v_add_f32_dpp v32, v32, v32 row_shl:1 row_mask:0xf bank_mask:0xf bound_ctrl:1
	v_add_f32_dpp v33, v33, v33 row_shl:1 row_mask:0xf bank_mask:0xf bound_ctrl:1
	v_add_f32_dpp v34, v34, v34 row_shl:1 row_mask:0xf bank_mask:0xf bound_ctrl:1
	v_add_f32_dpp v35, v35, v35 row_shl:1 row_mask:0xf bank_mask:0xf bound_ctrl:1
	v_add_f32_dpp v36, v36, v36 row_shl:1 row_mask:0xf bank_mask:0xf bound_ctrl:1
	v_add_f32_dpp v37, v37, v37 row_shl:1 row_mask:0xf bank_mask:0xf bound_ctrl:1
	v_add_f32_dpp v38, v38, v38 row_shl:1 row_mask:0xf bank_mask:0xf bound_ctrl:1
	v_add_f32_dpp v39, v39, v39 row_shl:1 row_mask:0xf bank_mask:0xf bound_ctrl:1
	v_add_f32_dpp v88, v88, v88 row_ror:8 row_mask:0xf bank_mask:0xf
	v_add_f32_dpp v89, v89, v89 row_ror:8 row_mask:0xf bank_mask:0xf
	v_add_f32_dpp v90, v90, v90 row_ror:8 row_mask:0xf bank_mask:0xf
	v_add_f32_dpp v91, v91, v91 row_ror:8 row_mask:0xf bank_mask:0xf
	v_add_f32_dpp v92, v92, v92 row_ror:8 row_mask:0xf bank_mask:0xf
	v_add_f32_dpp v93, v93, v93 row_ror:8 row_mask:0xf bank_mask:0xf
	v_add_f32_dpp v94, v94, v94 row_ror:8 row_mask:0xf bank_mask:0xf
	v_add_f32_dpp v95, v95, v95 row_ror:8 row_mask:0xf bank_mask:0xf
	v_add_f32_dpp v32, v32, v32 row_shl:2 row_mask:0xf bank_mask:0xf bound_ctrl:1
	v_add_f32_dpp v33, v33, v33 row_shl:2 row_mask:0xf bank_mask:0xf bound_ctrl:1
	v_add_f32_dpp v34, v34, v34 row_shl:2 row_mask:0xf bank_mask:0xf bound_ctrl:1
	v_add_f32_dpp v35, v35, v35 row_shl:2 row_mask:0xf bank_mask:0xf bound_ctrl:1
	v_add_f32_dpp v36, v36, v36 row_shl:2 row_mask:0xf bank_mask:0xf bound_ctrl:1
	v_add_f32_dpp v37, v37, v37 row_shl:2 row_mask:0xf bank_mask:0xf bound_ctrl:1
	v_add_f32_dpp v38, v38, v38 row_shl:2 row_mask:0xf bank_mask:0xf bound_ctrl:1
	v_add_f32_dpp v39, v39, v39 row_shl:2 row_mask:0xf bank_mask:0xf bound_ctrl:1
	v_add_f32_dpp v88, v88, v88 row_ror:4 row_mask:0xf bank_mask:0xf
	v_add_f32_dpp v89, v89, v89 row_ror:4 row_mask:0xf bank_mask:0xf
	v_add_f32_dpp v90, v90, v90 row_ror:4 row_mask:0xf bank_mask:0xf
	v_add_f32_dpp v91, v91, v91 row_ror:4 row_mask:0xf bank_mask:0xf
	v_add_f32_dpp v92, v92, v92 row_ror:4 row_mask:0xf bank_mask:0xf
	v_add_f32_dpp v93, v93, v93 row_ror:4 row_mask:0xf bank_mask:0xf
	v_add_f32_dpp v94, v94, v94 row_ror:4 row_mask:0xf bank_mask:0xf
	v_add_f32_dpp v95, v95, v95 row_ror:4 row_mask:0xf bank_mask:0xf
	v_add_f32_dpp v32, v32, v32 row_shl:4 row_mask:0xf bank_mask:0xf bound_ctrl:1
	v_add_f32_dpp v33, v33, v33 row_shl:4 row_mask:0xf bank_mask:0xf bound_ctrl:1
	v_add_f32_dpp v34, v34, v34 row_shl:4 row_mask:0xf bank_mask:0xf bound_ctrl:1
	v_add_f32_dpp v35, v35, v35 row_shl:4 row_mask:0xf bank_mask:0xf bound_ctrl:1
	v_add_f32_dpp v36, v36, v36 row_shl:4 row_mask:0xf bank_mask:0xf bound_ctrl:1
	v_add_f32_dpp v37, v37, v37 row_shl:4 row_mask:0xf bank_mask:0xf bound_ctrl:1
	v_add_f32_dpp v38, v38, v38 row_shl:4 row_mask:0xf bank_mask:0xf bound_ctrl:1
	v_add_f32_dpp v39, v39, v39 row_shl:4 row_mask:0xf bank_mask:0xf bound_ctrl:1
	v_add_f32_dpp v88, v88, v88 row_ror:2 row_mask:0xf bank_mask:0xf
	v_add_f32_dpp v89, v89, v89 row_ror:2 row_mask:0xf bank_mask:0xf
	v_add_f32_dpp v90, v90, v90 row_ror:2 row_mask:0xf bank_mask:0xf
	v_add_f32_dpp v91, v91, v91 row_ror:2 row_mask:0xf bank_mask:0xf
	v_add_f32_dpp v92, v92, v92 row_ror:2 row_mask:0xf bank_mask:0xf
	v_add_f32_dpp v93, v93, v93 row_ror:2 row_mask:0xf bank_mask:0xf
	v_add_f32_dpp v94, v94, v94 row_ror:2 row_mask:0xf bank_mask:0xf
	v_add_f32_dpp v95, v95, v95 row_ror:2 row_mask:0xf bank_mask:0xf
	v_add_f32_dpp v32, v32, v32 row_shl:8 row_mask:0xf bank_mask:0xf bound_ctrl:1
	v_add_f32_dpp v33, v33, v33 row_shl:8 row_mask:0xf bank_mask:0xf bound_ctrl:1
	v_add_f32_dpp v34, v34, v34 row_shl:8 row_mask:0xf bank_mask:0xf bound_ctrl:1
	v_add_f32_dpp v35, v35, v35 row_shl:8 row_mask:0xf bank_mask:0xf bound_ctrl:1
	v_add_f32_dpp v36, v36, v36 row_shl:8 row_mask:0xf bank_mask:0xf bound_ctrl:1
	v_add_f32_dpp v37, v37, v37 row_shl:8 row_mask:0xf bank_mask:0xf bound_ctrl:1
	v_add_f32_dpp v38, v38, v38 row_shl:8 row_mask:0xf bank_mask:0xf bound_ctrl:1
	v_add_f32_dpp v39, v39, v39 row_shl:8 row_mask:0xf bank_mask:0xf bound_ctrl:1
	v_add_f32_dpp v88, v88, v88 row_ror:1 row_mask:0xf bank_mask:0xf
	v_add_f32_dpp v89, v89, v89 row_ror:1 row_mask:0xf bank_mask:0xf
	v_add_f32_dpp v90, v90, v90 row_ror:1 row_mask:0xf bank_mask:0xf
	v_add_f32_dpp v91, v91, v91 row_ror:1 row_mask:0xf bank_mask:0xf
	v_add_f32_dpp v92, v92, v92 row_ror:1 row_mask:0xf bank_mask:0xf
	v_add_f32_dpp v93, v93, v93 row_ror:1 row_mask:0xf bank_mask:0xf
	v_add_f32_dpp v94, v94, v94 row_ror:1 row_mask:0xf bank_mask:0xf
	v_add_f32_dpp v95, v95, v95 row_ror:1 row_mask:0xf bank_mask:0xf
	v_add_f32_e32 v32, v32, v170
	v_add_f32_e32 v36, v36, v171
	v_add_f32_e32 v33, v33, v172
	v_add_f32_e32 v37, v37, v173
	v_add_f32_e32 v34, v34, v174
	v_add_f32_e32 v38, v38, v175
	v_add_f32_e32 v35, v35, v176
	v_add_f32_e32 v39, v39, v177
	v_mul_f32_e32 v132, v32, v141
	v_mul_f32_e32 v32, v32, v140
	v_fma_f32 v32, -v36, v141, v32
	v_fma_f32 v36, v36, v140, v132
	v_mul_f32_e32 v133, v33, v145
	v_mul_f32_e32 v33, v33, v144
	v_fma_f32 v33, -v37, v145, v33
	v_fma_f32 v37, v37, v144, v133
	v_mul_f32_e32 v132, v34, v149
	v_mul_f32_e32 v34, v34, v148
	v_fma_f32 v34, -v38, v149, v34
	v_fma_f32 v38, v38, v148, v132
	v_mul_f32_e32 v133, v35, v153
	v_mul_f32_e32 v35, v35, v152
	v_fma_f32 v35, -v39, v153, v35
	v_fma_f32 v39, v39, v152, v133
	v_add_f32_e32 v88, v88, v170
	v_add_f32_e32 v92, v92, v171
	v_mul_f32_e32 v132, v92, v155
	v_mul_f32_e32 v171, v88, v155
	v_fma_f32 v170, v88, v154, -v132
	v_fma_f32 v171, v92, v154, v171
	v_add_f32_e32 v89, v89, v172
	v_add_f32_e32 v93, v93, v173
	v_mul_f32_e32 v133, v93, v159
	v_mul_f32_e32 v173, v89, v159
	v_fma_f32 v172, v89, v158, -v133
	v_fma_f32 v173, v93, v158, v173
	v_add_f32_e32 v90, v90, v174
	v_add_f32_e32 v94, v94, v175
	v_mul_f32_e32 v132, v94, v163
	v_mul_f32_e32 v175, v90, v163
	v_fma_f32 v174, v90, v162, -v132
	v_fma_f32 v175, v94, v162, v175
	v_add_f32_e32 v91, v91, v176
	v_add_f32_e32 v95, v95, v177
	v_mul_f32_e32 v133, v95, v167
	v_mul_f32_e32 v177, v91, v167
	v_fma_f32 v176, v91, v166, -v133
	v_fma_f32 v177, v95, v166, v177
	s_waitcnt vmcnt(14)
	v_cvt_pk_bf16_f32 v80, v80, v81
	v_cvt_pk_bf16_f32 v81, v82, v83
	v_cvt_pk_bf16_f32 v82, -v84, -v85
	v_cvt_pk_bf16_f32 v83, -v86, -v87
	v_cvt_pk_bf16_f32 v96, v32, v33
	v_cvt_pk_bf16_f32 v97, v34, v35
	v_cvt_pk_bf16_f32 v98, v36, v37
	v_cvt_pk_bf16_f32 v99, v38, v39
	s_nop 1
	v_mfma_f32_16x16x32_bf16 v[16:19], v[80:83], v[96:99], v[16:19]
	v_cvt_pk_bf16_f32 v96, v40, v41
	v_cvt_pk_bf16_f32 v97, v42, v43
	v_cvt_pk_bf16_f32 v98, v44, v45
	v_cvt_pk_bf16_f32 v99, v46, v47
	s_nop 1
	v_mfma_f32_16x16x32_bf16 v[20:23], v[80:83], v[96:99], v[20:23]
	v_cvt_pk_bf16_f32 v96, v48, v49
	v_cvt_pk_bf16_f32 v97, v50, v51
	v_cvt_pk_bf16_f32 v98, v52, v53
	v_cvt_pk_bf16_f32 v99, v54, v55
	s_nop 1
	v_mfma_f32_16x16x32_bf16 v[24:27], v[80:83], v[96:99], v[24:27]
	v_cvt_pk_bf16_f32 v96, v56, v57
	v_cvt_pk_bf16_f32 v97, v58, v59
	v_cvt_pk_bf16_f32 v98, v60, v61
	v_cvt_pk_bf16_f32 v99, v62, v63
	s_nop 1
	v_mfma_f32_16x16x32_bf16 v[28:31], v[80:83], v[96:99], v[28:31]
	s_waitcnt vmcnt(10)
	v_cvt_pk_bf16_f32 v64, v64, v65
	v_cvt_pk_bf16_f32 v65, v66, v67
	v_cvt_pk_bf16_f32 v66, v68, v69
	v_cvt_pk_bf16_f32 v67, v70, v71
	v_cvt_pk_bf16_f32 v72, v72, v73
	v_cvt_pk_bf16_f32 v73, v74, v75
	v_cvt_pk_bf16_f32 v74, v76, v77
	v_cvt_pk_bf16_f32 v75, v78, v79
	global_load_dwordx4 v[80:83], v136, s[38:39]
	global_load_dwordx4 v[84:87], v136, s[40:41]
	s_add_u32 s38, s38, 0x40
	s_addc_u32 s39, s39, 0
	s_add_u32 s40, s40, 0x40
	s_addc_u32 s41, s41, 0
	s_nop 0
	v_mfma_f32_16x16x32_bf16 v[32:35], v[64:67], v[0:3], 0
	v_mfma_f32_16x16x32_bf16 v[36:39], v[72:75], v[0:3], 0
	v_mfma_f32_16x16x32_bf16 v[40:43], v[64:67], v[4:7], 0
	v_mfma_f32_16x16x32_bf16 v[44:47], v[72:75], v[4:7], 0
	v_mfma_f32_16x16x32_bf16 v[48:51], v[64:67], v[8:11], 0
	v_mfma_f32_16x16x32_bf16 v[52:55], v[72:75], v[8:11], 0
	v_mfma_f32_16x16x32_bf16 v[56:59], v[64:67], v[12:15], 0
	v_mfma_f32_16x16x32_bf16 v[60:63], v[72:75], v[12:15], 0
	s_mov_b32 exec_hi, 0
	global_load_dwordx4 v[64:67], v135, s[20:21]
	global_load_dwordx4 v[68:71], v135, s[20:21] offset:16
	global_load_dwordx4 v[72:75], v135, s[22:23]
	global_load_dwordx4 v[76:79], v135, s[22:23] offset:16
	s_mov_b64 exec, -1
	s_add_u32 s20, s20, 0x400
	s_addc_u32 s21, s21, 0
	s_add_u32 s22, s22, 0x400
	s_addc_u32 s23, s23, 0
	global_load_dwordx4 v[138:141], v134, s[42:43] offset:0
	global_load_dwordx4 v[142:145], v134, s[42:43] offset:16
	global_load_dwordx4 v[146:149], v134, s[42:43] offset:32
	global_load_dwordx4 v[150:153], v134, s[42:43] offset:48
	global_load_dwordx4 v[154:157], v134, s[42:43] offset:64
	global_load_dwordx4 v[158:161], v134, s[42:43] offset:80
	global_load_dwordx4 v[162:165], v134, s[42:43] offset:96
	global_load_dwordx4 v[166:169], v134, s[42:43] offset:112
	global_load_dwordx4 v[170:173], v206, s[44:45]
	global_load_dwordx4 v[174:177], v206, s[44:45] offset:16
	s_add_u32 s42, s42, 0x2000
	s_addc_u32 s43, s43, 0
	s_add_u32 s44, s44, 0x80
	s_addc_u32 s45, s45, 0
	s_waitcnt vmcnt(16)
	v_mul_f32_e32 v132, v179, v119
	v_mul_f32_e32 v133, v178, v119
	v_fma_f32 v178, v178, v118, -v132
	v_fma_f32 v179, v179, v118, v133
	v_mul_f32_e32 v132, v181, v123
	v_mul_f32_e32 v133, v180, v123
	v_fma_f32 v180, v180, v122, -v132
	v_fma_f32 v181, v181, v122, v133
	v_mul_f32_e32 v132, v183, v127
	v_mul_f32_e32 v133, v182, v127
	v_fma_f32 v182, v182, v126, -v132
	v_fma_f32 v183, v183, v126, v133
	v_mul_f32_e32 v132, v185, v131
	v_mul_f32_e32 v133, v184, v131
	v_fma_f32 v184, v184, v130, -v132
	v_fma_f32 v185, v185, v130, v133
	v_mul_f32_e32 v132, v56, v101
	v_mul_f32_e32 v56, v56, v100
	v_fma_f32 v56, -v60, v101, v56
	v_fma_f32 v60, v60, v100, v132
	v_mul_f32_e32 v133, v57, v105
	v_mul_f32_e32 v57, v57, v104
	v_fma_f32 v57, -v61, v105, v57
	v_fma_f32 v61, v61, v104, v133
	v_mul_f32_e32 v132, v58, v109
	v_mul_f32_e32 v58, v58, v108
	v_fma_f32 v58, -v62, v109, v58
	v_fma_f32 v62, v62, v108, v132
	v_mul_f32_e32 v133, v59, v113
	v_mul_f32_e32 v59, v59, v112
	v_fma_f32 v59, -v63, v113, v59
	v_fma_f32 v63, v63, v112, v133
	v_mov_b32_e32 v88, v56
	v_mov_b32_e32 v89, v57
	v_mov_b32_e32 v90, v58
	v_mov_b32_e32 v91, v59
	v_mov_b32_e32 v92, v60
	v_mov_b32_e32 v93, v61
	v_mov_b32_e32 v94, v62
	v_mov_b32_e32 v95, v63
	v_add_f32_dpp v56, v56, v56 row_shl:1 row_mask:0xf bank_mask:0xf bound_ctrl:1
	v_add_f32_dpp v57, v57, v57 row_shl:1 row_mask:0xf bank_mask:0xf bound_ctrl:1
	v_add_f32_dpp v58, v58, v58 row_shl:1 row_mask:0xf bank_mask:0xf bound_ctrl:1
	v_add_f32_dpp v59, v59, v59 row_shl:1 row_mask:0xf bank_mask:0xf bound_ctrl:1
	v_add_f32_dpp v60, v60, v60 row_shl:1 row_mask:0xf bank_mask:0xf bound_ctrl:1
	v_add_f32_dpp v61, v61, v61 row_shl:1 row_mask:0xf bank_mask:0xf bound_ctrl:1
	v_add_f32_dpp v62, v62, v62 row_shl:1 row_mask:0xf bank_mask:0xf bound_ctrl:1
	v_add_f32_dpp v63, v63, v63 row_shl:1 row_mask:0xf bank_mask:0xf bound_ctrl:1
	v_add_f32_dpp v88, v88, v88 row_ror:8 row_mask:0xf bank_mask:0xf
	v_add_f32_dpp v89, v89, v89 row_ror:8 row_mask:0xf bank_mask:0xf
	v_add_f32_dpp v90, v90, v90 row_ror:8 row_mask:0xf bank_mask:0xf
	v_add_f32_dpp v91, v91, v91 row_ror:8 row_mask:0xf bank_mask:0xf
	v_add_f32_dpp v92, v92, v92 row_ror:8 row_mask:0xf bank_mask:0xf
	v_add_f32_dpp v93, v93, v93 row_ror:8 row_mask:0xf bank_mask:0xf
	v_add_f32_dpp v94, v94, v94 row_ror:8 row_mask:0xf bank_mask:0xf
	v_add_f32_dpp v95, v95, v95 row_ror:8 row_mask:0xf bank_mask:0xf
	v_add_f32_dpp v56, v56, v56 row_shl:2 row_mask:0xf bank_mask:0xf bound_ctrl:1
	v_add_f32_dpp v57, v57, v57 row_shl:2 row_mask:0xf bank_mask:0xf bound_ctrl:1
	v_add_f32_dpp v58, v58, v58 row_shl:2 row_mask:0xf bank_mask:0xf bound_ctrl:1
	v_add_f32_dpp v59, v59, v59 row_shl:2 row_mask:0xf bank_mask:0xf bound_ctrl:1
	v_add_f32_dpp v60, v60, v60 row_shl:2 row_mask:0xf bank_mask:0xf bound_ctrl:1
	v_add_f32_dpp v61, v61, v61 row_shl:2 row_mask:0xf bank_mask:0xf bound_ctrl:1
	v_add_f32_dpp v62, v62, v62 row_shl:2 row_mask:0xf bank_mask:0xf bound_ctrl:1
	v_add_f32_dpp v63, v63, v63 row_shl:2 row_mask:0xf bank_mask:0xf bound_ctrl:1
	v_add_f32_dpp v88, v88, v88 row_ror:4 row_mask:0xf bank_mask:0xf
	v_add_f32_dpp v89, v89, v89 row_ror:4 row_mask:0xf bank_mask:0xf
	v_add_f32_dpp v90, v90, v90 row_ror:4 row_mask:0xf bank_mask:0xf
	v_add_f32_dpp v91, v91, v91 row_ror:4 row_mask:0xf bank_mask:0xf
	v_add_f32_dpp v92, v92, v92 row_ror:4 row_mask:0xf bank_mask:0xf
	v_add_f32_dpp v93, v93, v93 row_ror:4 row_mask:0xf bank_mask:0xf
	v_add_f32_dpp v94, v94, v94 row_ror:4 row_mask:0xf bank_mask:0xf
	v_add_f32_dpp v95, v95, v95 row_ror:4 row_mask:0xf bank_mask:0xf
	v_add_f32_dpp v56, v56, v56 row_shl:4 row_mask:0xf bank_mask:0xf bound_ctrl:1
	v_add_f32_dpp v57, v57, v57 row_shl:4 row_mask:0xf bank_mask:0xf bound_ctrl:1
	v_add_f32_dpp v58, v58, v58 row_shl:4 row_mask:0xf bank_mask:0xf bound_ctrl:1
	v_add_f32_dpp v59, v59, v59 row_shl:4 row_mask:0xf bank_mask:0xf bound_ctrl:1
	v_add_f32_dpp v60, v60, v60 row_shl:4 row_mask:0xf bank_mask:0xf bound_ctrl:1
	v_add_f32_dpp v61, v61, v61 row_shl:4 row_mask:0xf bank_mask:0xf bound_ctrl:1
	v_add_f32_dpp v62, v62, v62 row_shl:4 row_mask:0xf bank_mask:0xf bound_ctrl:1
	v_add_f32_dpp v63, v63, v63 row_shl:4 row_mask:0xf bank_mask:0xf bound_ctrl:1
	v_add_f32_dpp v88, v88, v88 row_ror:2 row_mask:0xf bank_mask:0xf
	v_add_f32_dpp v89, v89, v89 row_ror:2 row_mask:0xf bank_mask:0xf
	v_add_f32_dpp v90, v90, v90 row_ror:2 row_mask:0xf bank_mask:0xf
	v_add_f32_dpp v91, v91, v91 row_ror:2 row_mask:0xf bank_mask:0xf
	v_add_f32_dpp v92, v92, v92 row_ror:2 row_mask:0xf bank_mask:0xf
	v_add_f32_dpp v93, v93, v93 row_ror:2 row_mask:0xf bank_mask:0xf
	v_add_f32_dpp v94, v94, v94 row_ror:2 row_mask:0xf bank_mask:0xf
	v_add_f32_dpp v95, v95, v95 row_ror:2 row_mask:0xf bank_mask:0xf
	v_add_f32_dpp v56, v56, v56 row_shl:8 row_mask:0xf bank_mask:0xf bound_ctrl:1
	v_add_f32_dpp v57, v57, v57 row_shl:8 row_mask:0xf bank_mask:0xf bound_ctrl:1
	v_add_f32_dpp v58, v58, v58 row_shl:8 row_mask:0xf bank_mask:0xf bound_ctrl:1
	v_add_f32_dpp v59, v59, v59 row_shl:8 row_mask:0xf bank_mask:0xf bound_ctrl:1
	v_add_f32_dpp v60, v60, v60 row_shl:8 row_mask:0xf bank_mask:0xf bound_ctrl:1
	v_add_f32_dpp v61, v61, v61 row_shl:8 row_mask:0xf bank_mask:0xf bound_ctrl:1
	v_add_f32_dpp v62, v62, v62 row_shl:8 row_mask:0xf bank_mask:0xf bound_ctrl:1
	v_add_f32_dpp v63, v63, v63 row_shl:8 row_mask:0xf bank_mask:0xf bound_ctrl:1
	v_add_f32_dpp v88, v88, v88 row_ror:1 row_mask:0xf bank_mask:0xf
	v_add_f32_dpp v89, v89, v89 row_ror:1 row_mask:0xf bank_mask:0xf
	v_add_f32_dpp v90, v90, v90 row_ror:1 row_mask:0xf bank_mask:0xf
	v_add_f32_dpp v91, v91, v91 row_ror:1 row_mask:0xf bank_mask:0xf
	v_add_f32_dpp v92, v92, v92 row_ror:1 row_mask:0xf bank_mask:0xf
	v_add_f32_dpp v93, v93, v93 row_ror:1 row_mask:0xf bank_mask:0xf
	v_add_f32_dpp v94, v94, v94 row_ror:1 row_mask:0xf bank_mask:0xf
	v_add_f32_dpp v95, v95, v95 row_ror:1 row_mask:0xf bank_mask:0xf
	v_add_f32_e32 v56, v56, v178
	v_add_f32_e32 v60, v60, v179
	v_add_f32_e32 v57, v57, v180
	v_add_f32_e32 v61, v61, v181
	v_add_f32_e32 v58, v58, v182
	v_add_f32_e32 v62, v62, v183
	v_add_f32_e32 v59, v59, v184
	v_add_f32_e32 v63, v63, v185
	v_mul_f32_e32 v132, v56, v103
	v_mul_f32_e32 v56, v56, v102
	v_fma_f32 v56, -v60, v103, v56
	v_fma_f32 v60, v60, v102, v132
	v_mul_f32_e32 v133, v57, v107
	v_mul_f32_e32 v57, v57, v106
	v_fma_f32 v57, -v61, v107, v57
	v_fma_f32 v61, v61, v106, v133
	v_mul_f32_e32 v132, v58, v111
	v_mul_f32_e32 v58, v58, v110
	v_fma_f32 v58, -v62, v111, v58
	v_fma_f32 v62, v62, v110, v132
	v_mul_f32_e32 v133, v59, v115
	v_mul_f32_e32 v59, v59, v114
	v_fma_f32 v59, -v63, v115, v59
	v_fma_f32 v63, v63, v114, v133
	v_add_f32_e32 v88, v88, v178
	v_add_f32_e32 v92, v92, v179
	v_mul_f32_e32 v132, v92, v117
	v_mul_f32_e32 v179, v88, v117
	v_fma_f32 v178, v88, v116, -v132
	v_fma_f32 v179, v92, v116, v179
	v_add_f32_e32 v89, v89, v180
	v_add_f32_e32 v93, v93, v181
	v_mul_f32_e32 v133, v93, v121
	v_mul_f32_e32 v181, v89, v121
	v_fma_f32 v180, v89, v120, -v133
	v_fma_f32 v181, v93, v120, v181
	v_add_f32_e32 v90, v90, v182
	v_add_f32_e32 v94, v94, v183
	v_mul_f32_e32 v132, v94, v125
	v_mul_f32_e32 v183, v90, v125
	v_fma_f32 v182, v90, v124, -v132
	v_fma_f32 v183, v94, v124, v183
	v_add_f32_e32 v91, v91, v184
	v_add_f32_e32 v95, v95, v185
	v_mul_f32_e32 v133, v95, v129
	v_mul_f32_e32 v185, v91, v129
	v_fma_f32 v184, v91, v128, -v133
	v_fma_f32 v185, v95, v128, v185
	v_mul_f32_e32 v132, v48, v101
	v_mul_f32_e32 v48, v48, v100
	v_fma_f32 v48, -v52, v101, v48
	v_fma_f32 v52, v52, v100, v132
	v_mul_f32_e32 v133, v49, v105
	v_mul_f32_e32 v49, v49, v104
	v_fma_f32 v49, -v53, v105, v49
	v_fma_f32 v53, v53, v104, v133
	v_mul_f32_e32 v132, v50, v109
	v_mul_f32_e32 v50, v50, v108
	v_fma_f32 v50, -v54, v109, v50
	v_fma_f32 v54, v54, v108, v132
	v_mul_f32_e32 v133, v51, v113
	v_mul_f32_e32 v51, v51, v112
	v_fma_f32 v51, -v55, v113, v51
	v_fma_f32 v55, v55, v112, v133
	v_mov_b32_e32 v88, v48
	v_mov_b32_e32 v89, v49
	v_mov_b32_e32 v90, v50
	v_mov_b32_e32 v91, v51
	v_mov_b32_e32 v92, v52
	v_mov_b32_e32 v93, v53
	v_mov_b32_e32 v94, v54
	v_mov_b32_e32 v95, v55
	v_add_f32_dpp v48, v48, v48 row_shl:1 row_mask:0xf bank_mask:0xf bound_ctrl:1
	v_add_f32_dpp v49, v49, v49 row_shl:1 row_mask:0xf bank_mask:0xf bound_ctrl:1
	v_add_f32_dpp v50, v50, v50 row_shl:1 row_mask:0xf bank_mask:0xf bound_ctrl:1
	v_add_f32_dpp v51, v51, v51 row_shl:1 row_mask:0xf bank_mask:0xf bound_ctrl:1
	v_add_f32_dpp v52, v52, v52 row_shl:1 row_mask:0xf bank_mask:0xf bound_ctrl:1
	v_add_f32_dpp v53, v53, v53 row_shl:1 row_mask:0xf bank_mask:0xf bound_ctrl:1
	v_add_f32_dpp v54, v54, v54 row_shl:1 row_mask:0xf bank_mask:0xf bound_ctrl:1
	v_add_f32_dpp v55, v55, v55 row_shl:1 row_mask:0xf bank_mask:0xf bound_ctrl:1
	v_add_f32_dpp v88, v88, v88 row_ror:8 row_mask:0xf bank_mask:0xf
	v_add_f32_dpp v89, v89, v89 row_ror:8 row_mask:0xf bank_mask:0xf
	v_add_f32_dpp v90, v90, v90 row_ror:8 row_mask:0xf bank_mask:0xf
	v_add_f32_dpp v91, v91, v91 row_ror:8 row_mask:0xf bank_mask:0xf
	v_add_f32_dpp v92, v92, v92 row_ror:8 row_mask:0xf bank_mask:0xf
	v_add_f32_dpp v93, v93, v93 row_ror:8 row_mask:0xf bank_mask:0xf
	v_add_f32_dpp v94, v94, v94 row_ror:8 row_mask:0xf bank_mask:0xf
	v_add_f32_dpp v95, v95, v95 row_ror:8 row_mask:0xf bank_mask:0xf
	v_add_f32_dpp v48, v48, v48 row_shl:2 row_mask:0xf bank_mask:0xf bound_ctrl:1
	v_add_f32_dpp v49, v49, v49 row_shl:2 row_mask:0xf bank_mask:0xf bound_ctrl:1
	v_add_f32_dpp v50, v50, v50 row_shl:2 row_mask:0xf bank_mask:0xf bound_ctrl:1
	v_add_f32_dpp v51, v51, v51 row_shl:2 row_mask:0xf bank_mask:0xf bound_ctrl:1
	v_add_f32_dpp v52, v52, v52 row_shl:2 row_mask:0xf bank_mask:0xf bound_ctrl:1
	v_add_f32_dpp v53, v53, v53 row_shl:2 row_mask:0xf bank_mask:0xf bound_ctrl:1
	v_add_f32_dpp v54, v54, v54 row_shl:2 row_mask:0xf bank_mask:0xf bound_ctrl:1
	v_add_f32_dpp v55, v55, v55 row_shl:2 row_mask:0xf bank_mask:0xf bound_ctrl:1
	v_add_f32_dpp v88, v88, v88 row_ror:4 row_mask:0xf bank_mask:0xf
	v_add_f32_dpp v89, v89, v89 row_ror:4 row_mask:0xf bank_mask:0xf
	v_add_f32_dpp v90, v90, v90 row_ror:4 row_mask:0xf bank_mask:0xf
	v_add_f32_dpp v91, v91, v91 row_ror:4 row_mask:0xf bank_mask:0xf
	v_add_f32_dpp v92, v92, v92 row_ror:4 row_mask:0xf bank_mask:0xf
	v_add_f32_dpp v93, v93, v93 row_ror:4 row_mask:0xf bank_mask:0xf
	v_add_f32_dpp v94, v94, v94 row_ror:4 row_mask:0xf bank_mask:0xf
	v_add_f32_dpp v95, v95, v95 row_ror:4 row_mask:0xf bank_mask:0xf
	v_add_f32_dpp v48, v48, v48 row_shl:4 row_mask:0xf bank_mask:0xf bound_ctrl:1
	v_add_f32_dpp v49, v49, v49 row_shl:4 row_mask:0xf bank_mask:0xf bound_ctrl:1
	v_add_f32_dpp v50, v50, v50 row_shl:4 row_mask:0xf bank_mask:0xf bound_ctrl:1
	v_add_f32_dpp v51, v51, v51 row_shl:4 row_mask:0xf bank_mask:0xf bound_ctrl:1
	v_add_f32_dpp v52, v52, v52 row_shl:4 row_mask:0xf bank_mask:0xf bound_ctrl:1
	v_add_f32_dpp v53, v53, v53 row_shl:4 row_mask:0xf bank_mask:0xf bound_ctrl:1
	v_add_f32_dpp v54, v54, v54 row_shl:4 row_mask:0xf bank_mask:0xf bound_ctrl:1
	v_add_f32_dpp v55, v55, v55 row_shl:4 row_mask:0xf bank_mask:0xf bound_ctrl:1
	v_add_f32_dpp v88, v88, v88 row_ror:2 row_mask:0xf bank_mask:0xf
	v_add_f32_dpp v89, v89, v89 row_ror:2 row_mask:0xf bank_mask:0xf
	v_add_f32_dpp v90, v90, v90 row_ror:2 row_mask:0xf bank_mask:0xf
	v_add_f32_dpp v91, v91, v91 row_ror:2 row_mask:0xf bank_mask:0xf
	v_add_f32_dpp v92, v92, v92 row_ror:2 row_mask:0xf bank_mask:0xf
	v_add_f32_dpp v93, v93, v93 row_ror:2 row_mask:0xf bank_mask:0xf
	v_add_f32_dpp v94, v94, v94 row_ror:2 row_mask:0xf bank_mask:0xf
	v_add_f32_dpp v95, v95, v95 row_ror:2 row_mask:0xf bank_mask:0xf
	v_add_f32_dpp v48, v48, v48 row_shl:8 row_mask:0xf bank_mask:0xf bound_ctrl:1
	v_add_f32_dpp v49, v49, v49 row_shl:8 row_mask:0xf bank_mask:0xf bound_ctrl:1
	v_add_f32_dpp v50, v50, v50 row_shl:8 row_mask:0xf bank_mask:0xf bound_ctrl:1
	v_add_f32_dpp v51, v51, v51 row_shl:8 row_mask:0xf bank_mask:0xf bound_ctrl:1
	v_add_f32_dpp v52, v52, v52 row_shl:8 row_mask:0xf bank_mask:0xf bound_ctrl:1
	v_add_f32_dpp v53, v53, v53 row_shl:8 row_mask:0xf bank_mask:0xf bound_ctrl:1
	v_add_f32_dpp v54, v54, v54 row_shl:8 row_mask:0xf bank_mask:0xf bound_ctrl:1
	v_add_f32_dpp v55, v55, v55 row_shl:8 row_mask:0xf bank_mask:0xf bound_ctrl:1
	v_add_f32_dpp v88, v88, v88 row_ror:1 row_mask:0xf bank_mask:0xf
	v_add_f32_dpp v89, v89, v89 row_ror:1 row_mask:0xf bank_mask:0xf
	v_add_f32_dpp v90, v90, v90 row_ror:1 row_mask:0xf bank_mask:0xf
	v_add_f32_dpp v91, v91, v91 row_ror:1 row_mask:0xf bank_mask:0xf
	v_add_f32_dpp v92, v92, v92 row_ror:1 row_mask:0xf bank_mask:0xf
	v_add_f32_dpp v93, v93, v93 row_ror:1 row_mask:0xf bank_mask:0xf
	v_add_f32_dpp v94, v94, v94 row_ror:1 row_mask:0xf bank_mask:0xf
	v_add_f32_dpp v95, v95, v95 row_ror:1 row_mask:0xf bank_mask:0xf
	v_add_f32_e32 v48, v48, v178
	v_add_f32_e32 v52, v52, v179
	v_add_f32_e32 v49, v49, v180
	v_add_f32_e32 v53, v53, v181
	v_add_f32_e32 v50, v50, v182
	v_add_f32_e32 v54, v54, v183
	v_add_f32_e32 v51, v51, v184
	v_add_f32_e32 v55, v55, v185
	v_mul_f32_e32 v132, v48, v103
	v_mul_f32_e32 v48, v48, v102
	v_fma_f32 v48, -v52, v103, v48
	v_fma_f32 v52, v52, v102, v132
	v_mul_f32_e32 v133, v49, v107
	v_mul_f32_e32 v49, v49, v106
	v_fma_f32 v49, -v53, v107, v49
	v_fma_f32 v53, v53, v106, v133
	v_mul_f32_e32 v132, v50, v111
	v_mul_f32_e32 v50, v50, v110
	v_fma_f32 v50, -v54, v111, v50
	v_fma_f32 v54, v54, v110, v132
	v_mul_f32_e32 v133, v51, v115
	v_mul_f32_e32 v51, v51, v114
	v_fma_f32 v51, -v55, v115, v51
	v_fma_f32 v55, v55, v114, v133
	v_add_f32_e32 v88, v88, v178
	v_add_f32_e32 v92, v92, v179
	v_mul_f32_e32 v132, v92, v117
	v_mul_f32_e32 v179, v88, v117
	v_fma_f32 v178, v88, v116, -v132
	v_fma_f32 v179, v92, v116, v179
	v_add_f32_e32 v89, v89, v180
	v_add_f32_e32 v93, v93, v181
	v_mul_f32_e32 v133, v93, v121
	v_mul_f32_e32 v181, v89, v121
	v_fma_f32 v180, v89, v120, -v133
	v_fma_f32 v181, v93, v120, v181
	v_add_f32_e32 v90, v90, v182
	v_add_f32_e32 v94, v94, v183
	v_mul_f32_e32 v132, v94, v125
	v_mul_f32_e32 v183, v90, v125
	v_fma_f32 v182, v90, v124, -v132
	v_fma_f32 v183, v94, v124, v183
	v_add_f32_e32 v91, v91, v184
	v_add_f32_e32 v95, v95, v185
	v_mul_f32_e32 v133, v95, v129
	v_mul_f32_e32 v185, v91, v129
	v_fma_f32 v184, v91, v128, -v133
	v_fma_f32 v185, v95, v128, v185
	v_mul_f32_e32 v132, v40, v101
	v_mul_f32_e32 v40, v40, v100
	v_fma_f32 v40, -v44, v101, v40
	v_fma_f32 v44, v44, v100, v132
	v_mul_f32_e32 v133, v41, v105
	v_mul_f32_e32 v41, v41, v104
	v_fma_f32 v41, -v45, v105, v41
	v_fma_f32 v45, v45, v104, v133
	v_mul_f32_e32 v132, v42, v109
	v_mul_f32_e32 v42, v42, v108
	v_fma_f32 v42, -v46, v109, v42
	v_fma_f32 v46, v46, v108, v132
	v_mul_f32_e32 v133, v43, v113
	v_mul_f32_e32 v43, v43, v112
	v_fma_f32 v43, -v47, v113, v43
	v_fma_f32 v47, v47, v112, v133
	v_mov_b32_e32 v88, v40
	v_mov_b32_e32 v89, v41
	v_mov_b32_e32 v90, v42
	v_mov_b32_e32 v91, v43
	v_mov_b32_e32 v92, v44
	v_mov_b32_e32 v93, v45
	v_mov_b32_e32 v94, v46
	v_mov_b32_e32 v95, v47
	v_add_f32_dpp v40, v40, v40 row_shl:1 row_mask:0xf bank_mask:0xf bound_ctrl:1
	v_add_f32_dpp v41, v41, v41 row_shl:1 row_mask:0xf bank_mask:0xf bound_ctrl:1
	v_add_f32_dpp v42, v42, v42 row_shl:1 row_mask:0xf bank_mask:0xf bound_ctrl:1
	v_add_f32_dpp v43, v43, v43 row_shl:1 row_mask:0xf bank_mask:0xf bound_ctrl:1
	v_add_f32_dpp v44, v44, v44 row_shl:1 row_mask:0xf bank_mask:0xf bound_ctrl:1
	v_add_f32_dpp v45, v45, v45 row_shl:1 row_mask:0xf bank_mask:0xf bound_ctrl:1
	v_add_f32_dpp v46, v46, v46 row_shl:1 row_mask:0xf bank_mask:0xf bound_ctrl:1
	v_add_f32_dpp v47, v47, v47 row_shl:1 row_mask:0xf bank_mask:0xf bound_ctrl:1
	v_add_f32_dpp v88, v88, v88 row_ror:8 row_mask:0xf bank_mask:0xf
	v_add_f32_dpp v89, v89, v89 row_ror:8 row_mask:0xf bank_mask:0xf
	v_add_f32_dpp v90, v90, v90 row_ror:8 row_mask:0xf bank_mask:0xf
	v_add_f32_dpp v91, v91, v91 row_ror:8 row_mask:0xf bank_mask:0xf
	v_add_f32_dpp v92, v92, v92 row_ror:8 row_mask:0xf bank_mask:0xf
	v_add_f32_dpp v93, v93, v93 row_ror:8 row_mask:0xf bank_mask:0xf
	v_add_f32_dpp v94, v94, v94 row_ror:8 row_mask:0xf bank_mask:0xf
	v_add_f32_dpp v95, v95, v95 row_ror:8 row_mask:0xf bank_mask:0xf
	v_add_f32_dpp v40, v40, v40 row_shl:2 row_mask:0xf bank_mask:0xf bound_ctrl:1
	v_add_f32_dpp v41, v41, v41 row_shl:2 row_mask:0xf bank_mask:0xf bound_ctrl:1
	v_add_f32_dpp v42, v42, v42 row_shl:2 row_mask:0xf bank_mask:0xf bound_ctrl:1
	v_add_f32_dpp v43, v43, v43 row_shl:2 row_mask:0xf bank_mask:0xf bound_ctrl:1
	v_add_f32_dpp v44, v44, v44 row_shl:2 row_mask:0xf bank_mask:0xf bound_ctrl:1
	v_add_f32_dpp v45, v45, v45 row_shl:2 row_mask:0xf bank_mask:0xf bound_ctrl:1
	v_add_f32_dpp v46, v46, v46 row_shl:2 row_mask:0xf bank_mask:0xf bound_ctrl:1
	v_add_f32_dpp v47, v47, v47 row_shl:2 row_mask:0xf bank_mask:0xf bound_ctrl:1
	v_add_f32_dpp v88, v88, v88 row_ror:4 row_mask:0xf bank_mask:0xf
	v_add_f32_dpp v89, v89, v89 row_ror:4 row_mask:0xf bank_mask:0xf
	v_add_f32_dpp v90, v90, v90 row_ror:4 row_mask:0xf bank_mask:0xf
	v_add_f32_dpp v91, v91, v91 row_ror:4 row_mask:0xf bank_mask:0xf
	v_add_f32_dpp v92, v92, v92 row_ror:4 row_mask:0xf bank_mask:0xf
	v_add_f32_dpp v93, v93, v93 row_ror:4 row_mask:0xf bank_mask:0xf
	v_add_f32_dpp v94, v94, v94 row_ror:4 row_mask:0xf bank_mask:0xf
	v_add_f32_dpp v95, v95, v95 row_ror:4 row_mask:0xf bank_mask:0xf
	v_add_f32_dpp v40, v40, v40 row_shl:4 row_mask:0xf bank_mask:0xf bound_ctrl:1
	v_add_f32_dpp v41, v41, v41 row_shl:4 row_mask:0xf bank_mask:0xf bound_ctrl:1
	v_add_f32_dpp v42, v42, v42 row_shl:4 row_mask:0xf bank_mask:0xf bound_ctrl:1
	v_add_f32_dpp v43, v43, v43 row_shl:4 row_mask:0xf bank_mask:0xf bound_ctrl:1
	v_add_f32_dpp v44, v44, v44 row_shl:4 row_mask:0xf bank_mask:0xf bound_ctrl:1
	v_add_f32_dpp v45, v45, v45 row_shl:4 row_mask:0xf bank_mask:0xf bound_ctrl:1
	v_add_f32_dpp v46, v46, v46 row_shl:4 row_mask:0xf bank_mask:0xf bound_ctrl:1
	v_add_f32_dpp v47, v47, v47 row_shl:4 row_mask:0xf bank_mask:0xf bound_ctrl:1
	v_add_f32_dpp v88, v88, v88 row_ror:2 row_mask:0xf bank_mask:0xf
	v_add_f32_dpp v89, v89, v89 row_ror:2 row_mask:0xf bank_mask:0xf
	v_add_f32_dpp v90, v90, v90 row_ror:2 row_mask:0xf bank_mask:0xf
	v_add_f32_dpp v91, v91, v91 row_ror:2 row_mask:0xf bank_mask:0xf
	v_add_f32_dpp v92, v92, v92 row_ror:2 row_mask:0xf bank_mask:0xf
	v_add_f32_dpp v93, v93, v93 row_ror:2 row_mask:0xf bank_mask:0xf
	v_add_f32_dpp v94, v94, v94 row_ror:2 row_mask:0xf bank_mask:0xf
	v_add_f32_dpp v95, v95, v95 row_ror:2 row_mask:0xf bank_mask:0xf
	v_add_f32_dpp v40, v40, v40 row_shl:8 row_mask:0xf bank_mask:0xf bound_ctrl:1
	v_add_f32_dpp v41, v41, v41 row_shl:8 row_mask:0xf bank_mask:0xf bound_ctrl:1
	v_add_f32_dpp v42, v42, v42 row_shl:8 row_mask:0xf bank_mask:0xf bound_ctrl:1
	v_add_f32_dpp v43, v43, v43 row_shl:8 row_mask:0xf bank_mask:0xf bound_ctrl:1
	v_add_f32_dpp v44, v44, v44 row_shl:8 row_mask:0xf bank_mask:0xf bound_ctrl:1
	v_add_f32_dpp v45, v45, v45 row_shl:8 row_mask:0xf bank_mask:0xf bound_ctrl:1
	v_add_f32_dpp v46, v46, v46 row_shl:8 row_mask:0xf bank_mask:0xf bound_ctrl:1
	v_add_f32_dpp v47, v47, v47 row_shl:8 row_mask:0xf bank_mask:0xf bound_ctrl:1
	v_add_f32_dpp v88, v88, v88 row_ror:1 row_mask:0xf bank_mask:0xf
	v_add_f32_dpp v89, v89, v89 row_ror:1 row_mask:0xf bank_mask:0xf
	v_add_f32_dpp v90, v90, v90 row_ror:1 row_mask:0xf bank_mask:0xf
	v_add_f32_dpp v91, v91, v91 row_ror:1 row_mask:0xf bank_mask:0xf
	v_add_f32_dpp v92, v92, v92 row_ror:1 row_mask:0xf bank_mask:0xf
	v_add_f32_dpp v93, v93, v93 row_ror:1 row_mask:0xf bank_mask:0xf
	v_add_f32_dpp v94, v94, v94 row_ror:1 row_mask:0xf bank_mask:0xf
	v_add_f32_dpp v95, v95, v95 row_ror:1 row_mask:0xf bank_mask:0xf
	v_add_f32_e32 v40, v40, v178
	v_add_f32_e32 v44, v44, v179
	v_add_f32_e32 v41, v41, v180
	v_add_f32_e32 v45, v45, v181
	v_add_f32_e32 v42, v42, v182
	v_add_f32_e32 v46, v46, v183
	v_add_f32_e32 v43, v43, v184
	v_add_f32_e32 v47, v47, v185
	v_mul_f32_e32 v132, v40, v103
	v_mul_f32_e32 v40, v40, v102
	v_fma_f32 v40, -v44, v103, v40
	v_fma_f32 v44, v44, v102, v132
	v_mul_f32_e32 v133, v41, v107
	v_mul_f32_e32 v41, v41, v106
	v_fma_f32 v41, -v45, v107, v41
	v_fma_f32 v45, v45, v106, v133
	v_mul_f32_e32 v132, v42, v111
	v_mul_f32_e32 v42, v42, v110
	v_fma_f32 v42, -v46, v111, v42
	v_fma_f32 v46, v46, v110, v132
	v_mul_f32_e32 v133, v43, v115
	v_mul_f32_e32 v43, v43, v114
	v_fma_f32 v43, -v47, v115, v43
	v_fma_f32 v47, v47, v114, v133
	v_add_f32_e32 v88, v88, v178
	v_add_f32_e32 v92, v92, v179
	v_mul_f32_e32 v132, v92, v117
	v_mul_f32_e32 v179, v88, v117
	v_fma_f32 v178, v88, v116, -v132
	v_fma_f32 v179, v92, v116, v179
	v_add_f32_e32 v89, v89, v180
	v_add_f32_e32 v93, v93, v181
	v_mul_f32_e32 v133, v93, v121
	v_mul_f32_e32 v181, v89, v121
	v_fma_f32 v180, v89, v120, -v133
	v_fma_f32 v181, v93, v120, v181
	v_add_f32_e32 v90, v90, v182
	v_add_f32_e32 v94, v94, v183
	v_mul_f32_e32 v132, v94, v125
	v_mul_f32_e32 v183, v90, v125
	v_fma_f32 v182, v90, v124, -v132
	v_fma_f32 v183, v94, v124, v183
	v_add_f32_e32 v91, v91, v184
	v_add_f32_e32 v95, v95, v185
	v_mul_f32_e32 v133, v95, v129
	v_mul_f32_e32 v185, v91, v129
	v_fma_f32 v184, v91, v128, -v133
	v_fma_f32 v185, v95, v128, v185
	v_mul_f32_e32 v132, v32, v101
	v_mul_f32_e32 v32, v32, v100
	v_fma_f32 v32, -v36, v101, v32
	v_fma_f32 v36, v36, v100, v132
	v_mul_f32_e32 v133, v33, v105
	v_mul_f32_e32 v33, v33, v104
	v_fma_f32 v33, -v37, v105, v33
	v_fma_f32 v37, v37, v104, v133
	v_mul_f32_e32 v132, v34, v109
	v_mul_f32_e32 v34, v34, v108
	v_fma_f32 v34, -v38, v109, v34
	v_fma_f32 v38, v38, v108, v132
	v_mul_f32_e32 v133, v35, v113
	v_mul_f32_e32 v35, v35, v112
	v_fma_f32 v35, -v39, v113, v35
	v_fma_f32 v39, v39, v112, v133
	v_mov_b32_e32 v88, v32
	v_mov_b32_e32 v89, v33
	v_mov_b32_e32 v90, v34
	v_mov_b32_e32 v91, v35
	v_mov_b32_e32 v92, v36
	v_mov_b32_e32 v93, v37
	v_mov_b32_e32 v94, v38
	v_mov_b32_e32 v95, v39
	v_add_f32_dpp v32, v32, v32 row_shl:1 row_mask:0xf bank_mask:0xf bound_ctrl:1
	v_add_f32_dpp v33, v33, v33 row_shl:1 row_mask:0xf bank_mask:0xf bound_ctrl:1
	v_add_f32_dpp v34, v34, v34 row_shl:1 row_mask:0xf bank_mask:0xf bound_ctrl:1
	v_add_f32_dpp v35, v35, v35 row_shl:1 row_mask:0xf bank_mask:0xf bound_ctrl:1
	v_add_f32_dpp v36, v36, v36 row_shl:1 row_mask:0xf bank_mask:0xf bound_ctrl:1
	v_add_f32_dpp v37, v37, v37 row_shl:1 row_mask:0xf bank_mask:0xf bound_ctrl:1
	v_add_f32_dpp v38, v38, v38 row_shl:1 row_mask:0xf bank_mask:0xf bound_ctrl:1
	v_add_f32_dpp v39, v39, v39 row_shl:1 row_mask:0xf bank_mask:0xf bound_ctrl:1
	v_add_f32_dpp v88, v88, v88 row_ror:8 row_mask:0xf bank_mask:0xf
	v_add_f32_dpp v89, v89, v89 row_ror:8 row_mask:0xf bank_mask:0xf
	v_add_f32_dpp v90, v90, v90 row_ror:8 row_mask:0xf bank_mask:0xf
	v_add_f32_dpp v91, v91, v91 row_ror:8 row_mask:0xf bank_mask:0xf
	v_add_f32_dpp v92, v92, v92 row_ror:8 row_mask:0xf bank_mask:0xf
	v_add_f32_dpp v93, v93, v93 row_ror:8 row_mask:0xf bank_mask:0xf
	v_add_f32_dpp v94, v94, v94 row_ror:8 row_mask:0xf bank_mask:0xf
	v_add_f32_dpp v95, v95, v95 row_ror:8 row_mask:0xf bank_mask:0xf
	v_add_f32_dpp v32, v32, v32 row_shl:2 row_mask:0xf bank_mask:0xf bound_ctrl:1
	v_add_f32_dpp v33, v33, v33 row_shl:2 row_mask:0xf bank_mask:0xf bound_ctrl:1
	v_add_f32_dpp v34, v34, v34 row_shl:2 row_mask:0xf bank_mask:0xf bound_ctrl:1
	v_add_f32_dpp v35, v35, v35 row_shl:2 row_mask:0xf bank_mask:0xf bound_ctrl:1
	v_add_f32_dpp v36, v36, v36 row_shl:2 row_mask:0xf bank_mask:0xf bound_ctrl:1
	v_add_f32_dpp v37, v37, v37 row_shl:2 row_mask:0xf bank_mask:0xf bound_ctrl:1
	v_add_f32_dpp v38, v38, v38 row_shl:2 row_mask:0xf bank_mask:0xf bound_ctrl:1
	v_add_f32_dpp v39, v39, v39 row_shl:2 row_mask:0xf bank_mask:0xf bound_ctrl:1
	v_add_f32_dpp v88, v88, v88 row_ror:4 row_mask:0xf bank_mask:0xf
	v_add_f32_dpp v89, v89, v89 row_ror:4 row_mask:0xf bank_mask:0xf
	v_add_f32_dpp v90, v90, v90 row_ror:4 row_mask:0xf bank_mask:0xf
	v_add_f32_dpp v91, v91, v91 row_ror:4 row_mask:0xf bank_mask:0xf
	v_add_f32_dpp v92, v92, v92 row_ror:4 row_mask:0xf bank_mask:0xf
	v_add_f32_dpp v93, v93, v93 row_ror:4 row_mask:0xf bank_mask:0xf
	v_add_f32_dpp v94, v94, v94 row_ror:4 row_mask:0xf bank_mask:0xf
	v_add_f32_dpp v95, v95, v95 row_ror:4 row_mask:0xf bank_mask:0xf
	v_add_f32_dpp v32, v32, v32 row_shl:4 row_mask:0xf bank_mask:0xf bound_ctrl:1
	v_add_f32_dpp v33, v33, v33 row_shl:4 row_mask:0xf bank_mask:0xf bound_ctrl:1
	v_add_f32_dpp v34, v34, v34 row_shl:4 row_mask:0xf bank_mask:0xf bound_ctrl:1
	v_add_f32_dpp v35, v35, v35 row_shl:4 row_mask:0xf bank_mask:0xf bound_ctrl:1
	v_add_f32_dpp v36, v36, v36 row_shl:4 row_mask:0xf bank_mask:0xf bound_ctrl:1
	v_add_f32_dpp v37, v37, v37 row_shl:4 row_mask:0xf bank_mask:0xf bound_ctrl:1
	v_add_f32_dpp v38, v38, v38 row_shl:4 row_mask:0xf bank_mask:0xf bound_ctrl:1
	v_add_f32_dpp v39, v39, v39 row_shl:4 row_mask:0xf bank_mask:0xf bound_ctrl:1
	v_add_f32_dpp v88, v88, v88 row_ror:2 row_mask:0xf bank_mask:0xf
	v_add_f32_dpp v89, v89, v89 row_ror:2 row_mask:0xf bank_mask:0xf
	v_add_f32_dpp v90, v90, v90 row_ror:2 row_mask:0xf bank_mask:0xf
	v_add_f32_dpp v91, v91, v91 row_ror:2 row_mask:0xf bank_mask:0xf
	v_add_f32_dpp v92, v92, v92 row_ror:2 row_mask:0xf bank_mask:0xf
	v_add_f32_dpp v93, v93, v93 row_ror:2 row_mask:0xf bank_mask:0xf
	v_add_f32_dpp v94, v94, v94 row_ror:2 row_mask:0xf bank_mask:0xf
	v_add_f32_dpp v95, v95, v95 row_ror:2 row_mask:0xf bank_mask:0xf
	v_add_f32_dpp v32, v32, v32 row_shl:8 row_mask:0xf bank_mask:0xf bound_ctrl:1
	v_add_f32_dpp v33, v33, v33 row_shl:8 row_mask:0xf bank_mask:0xf bound_ctrl:1
	v_add_f32_dpp v34, v34, v34 row_shl:8 row_mask:0xf bank_mask:0xf bound_ctrl:1
	v_add_f32_dpp v35, v35, v35 row_shl:8 row_mask:0xf bank_mask:0xf bound_ctrl:1
	v_add_f32_dpp v36, v36, v36 row_shl:8 row_mask:0xf bank_mask:0xf bound_ctrl:1
	v_add_f32_dpp v37, v37, v37 row_shl:8 row_mask:0xf bank_mask:0xf bound_ctrl:1
	v_add_f32_dpp v38, v38, v38 row_shl:8 row_mask:0xf bank_mask:0xf bound_ctrl:1
	v_add_f32_dpp v39, v39, v39 row_shl:8 row_mask:0xf bank_mask:0xf bound_ctrl:1
	v_add_f32_dpp v88, v88, v88 row_ror:1 row_mask:0xf bank_mask:0xf
	v_add_f32_dpp v89, v89, v89 row_ror:1 row_mask:0xf bank_mask:0xf
	v_add_f32_dpp v90, v90, v90 row_ror:1 row_mask:0xf bank_mask:0xf
	v_add_f32_dpp v91, v91, v91 row_ror:1 row_mask:0xf bank_mask:0xf
	v_add_f32_dpp v92, v92, v92 row_ror:1 row_mask:0xf bank_mask:0xf
	v_add_f32_dpp v93, v93, v93 row_ror:1 row_mask:0xf bank_mask:0xf
	v_add_f32_dpp v94, v94, v94 row_ror:1 row_mask:0xf bank_mask:0xf
	v_add_f32_dpp v95, v95, v95 row_ror:1 row_mask:0xf bank_mask:0xf
	v_add_f32_e32 v32, v32, v178
	v_add_f32_e32 v36, v36, v179
	v_add_f32_e32 v33, v33, v180
	v_add_f32_e32 v37, v37, v181
	v_add_f32_e32 v34, v34, v182
	v_add_f32_e32 v38, v38, v183
	v_add_f32_e32 v35, v35, v184
	v_add_f32_e32 v39, v39, v185
	v_mul_f32_e32 v132, v32, v103
	v_mul_f32_e32 v32, v32, v102
	v_fma_f32 v32, -v36, v103, v32
	v_fma_f32 v36, v36, v102, v132
	v_mul_f32_e32 v133, v33, v107
	v_mul_f32_e32 v33, v33, v106
	v_fma_f32 v33, -v37, v107, v33
	v_fma_f32 v37, v37, v106, v133
	v_mul_f32_e32 v132, v34, v111
	v_mul_f32_e32 v34, v34, v110
	v_fma_f32 v34, -v38, v111, v34
	v_fma_f32 v38, v38, v110, v132
	v_mul_f32_e32 v133, v35, v115
	v_mul_f32_e32 v35, v35, v114
	v_fma_f32 v35, -v39, v115, v35
	v_fma_f32 v39, v39, v114, v133
	v_add_f32_e32 v88, v88, v178
	v_add_f32_e32 v92, v92, v179
	v_mul_f32_e32 v132, v92, v117
	v_mul_f32_e32 v179, v88, v117
	v_fma_f32 v178, v88, v116, -v132
	v_fma_f32 v179, v92, v116, v179
	v_add_f32_e32 v89, v89, v180
	v_add_f32_e32 v93, v93, v181
	v_mul_f32_e32 v133, v93, v121
	v_mul_f32_e32 v181, v89, v121
	v_fma_f32 v180, v89, v120, -v133
	v_fma_f32 v181, v93, v120, v181
	v_add_f32_e32 v90, v90, v182
	v_add_f32_e32 v94, v94, v183
	v_mul_f32_e32 v132, v94, v125
	v_mul_f32_e32 v183, v90, v125
	v_fma_f32 v182, v90, v124, -v132
	v_fma_f32 v183, v94, v124, v183
	v_add_f32_e32 v91, v91, v184
	v_add_f32_e32 v95, v95, v185
	v_mul_f32_e32 v133, v95, v129
	v_mul_f32_e32 v185, v91, v129
	v_fma_f32 v184, v91, v128, -v133
	v_fma_f32 v185, v95, v128, v185
	s_waitcnt vmcnt(14)
	v_cvt_pk_bf16_f32 v80, v80, v81
	v_cvt_pk_bf16_f32 v81, v82, v83
	v_cvt_pk_bf16_f32 v82, -v84, -v85
	v_cvt_pk_bf16_f32 v83, -v86, -v87
	v_cvt_pk_bf16_f32 v96, v32, v33
	v_cvt_pk_bf16_f32 v97, v34, v35
	v_cvt_pk_bf16_f32 v98, v36, v37
	v_cvt_pk_bf16_f32 v99, v38, v39
	s_nop 1
	v_mfma_f32_16x16x32_bf16 v[16:19], v[80:83], v[96:99], v[16:19]
	v_cvt_pk_bf16_f32 v96, v40, v41
	v_cvt_pk_bf16_f32 v97, v42, v43
	v_cvt_pk_bf16_f32 v98, v44, v45
	v_cvt_pk_bf16_f32 v99, v46, v47
	s_nop 1
	v_mfma_f32_16x16x32_bf16 v[20:23], v[80:83], v[96:99], v[20:23]
	v_cvt_pk_bf16_f32 v96, v48, v49
	v_cvt_pk_bf16_f32 v97, v50, v51
	v_cvt_pk_bf16_f32 v98, v52, v53
	v_cvt_pk_bf16_f32 v99, v54, v55
	s_nop 1
	v_mfma_f32_16x16x32_bf16 v[24:27], v[80:83], v[96:99], v[24:27]
	v_cvt_pk_bf16_f32 v96, v56, v57
	v_cvt_pk_bf16_f32 v97, v58, v59
	v_cvt_pk_bf16_f32 v98, v60, v61
	v_cvt_pk_bf16_f32 v99, v62, v63
	s_nop 1
	v_mfma_f32_16x16x32_bf16 v[28:31], v[80:83], v[96:99], v[28:31]
	s_waitcnt vmcnt(10)
	v_cvt_pk_bf16_f32 v64, v64, v65
	v_cvt_pk_bf16_f32 v65, v66, v67
	v_cvt_pk_bf16_f32 v66, v68, v69
	v_cvt_pk_bf16_f32 v67, v70, v71
	v_cvt_pk_bf16_f32 v72, v72, v73
	v_cvt_pk_bf16_f32 v73, v74, v75
	v_cvt_pk_bf16_f32 v74, v76, v77
	v_cvt_pk_bf16_f32 v75, v78, v79
	global_load_dwordx4 v[80:83], v136, s[38:39]
	global_load_dwordx4 v[84:87], v136, s[40:41]
	s_add_u32 s38, s38, 0x40
	s_addc_u32 s39, s39, 0
	s_add_u32 s40, s40, 0x40
	s_addc_u32 s41, s41, 0
	s_nop 0
	v_mfma_f32_16x16x32_bf16 v[32:35], v[64:67], v[0:3], 0
	v_mfma_f32_16x16x32_bf16 v[36:39], v[72:75], v[0:3], 0
	v_mfma_f32_16x16x32_bf16 v[40:43], v[64:67], v[4:7], 0
	v_mfma_f32_16x16x32_bf16 v[44:47], v[72:75], v[4:7], 0
	v_mfma_f32_16x16x32_bf16 v[48:51], v[64:67], v[8:11], 0
	v_mfma_f32_16x16x32_bf16 v[52:55], v[72:75], v[8:11], 0
	v_mfma_f32_16x16x32_bf16 v[56:59], v[64:67], v[12:15], 0
	v_mfma_f32_16x16x32_bf16 v[60:63], v[72:75], v[12:15], 0
	s_mov_b32 exec_hi, 0
	global_load_dwordx4 v[64:67], v135, s[20:21]
	global_load_dwordx4 v[68:71], v135, s[20:21] offset:16
	global_load_dwordx4 v[72:75], v135, s[22:23]
	global_load_dwordx4 v[76:79], v135, s[22:23] offset:16
	s_mov_b64 exec, -1
	global_load_dwordx4 v[100:103], v134, s[42:43] offset:0
	global_load_dwordx4 v[104:107], v134, s[42:43] offset:16
	global_load_dwordx4 v[108:111], v134, s[42:43] offset:32
	global_load_dwordx4 v[112:115], v134, s[42:43] offset:48
	global_load_dwordx4 v[116:119], v134, s[42:43] offset:64
	global_load_dwordx4 v[120:123], v134, s[42:43] offset:80
	global_load_dwordx4 v[124:127], v134, s[42:43] offset:96
	global_load_dwordx4 v[128:131], v134, s[42:43] offset:112
	global_load_dwordx4 v[178:181], v206, s[44:45]
	global_load_dwordx4 v[182:185], v206, s[44:45] offset:16
	s_waitcnt vmcnt(16)
	v_mul_f32_e32 v132, v171, v157
	v_mul_f32_e32 v133, v170, v157
	v_fma_f32 v170, v170, v156, -v132
	v_fma_f32 v171, v171, v156, v133
	v_mul_f32_e32 v132, v173, v161
	v_mul_f32_e32 v133, v172, v161
	v_fma_f32 v172, v172, v160, -v132
	v_fma_f32 v173, v173, v160, v133
	v_mul_f32_e32 v132, v175, v165
	v_mul_f32_e32 v133, v174, v165
	v_fma_f32 v174, v174, v164, -v132
	v_fma_f32 v175, v175, v164, v133
	v_mul_f32_e32 v132, v177, v169
	v_mul_f32_e32 v133, v176, v169
	v_fma_f32 v176, v176, v168, -v132
	v_fma_f32 v177, v177, v168, v133
	v_mul_f32_e32 v132, v56, v139
	v_mul_f32_e32 v56, v56, v138
	v_fma_f32 v56, -v60, v139, v56
	v_fma_f32 v60, v60, v138, v132
	v_mul_f32_e32 v133, v57, v143
	v_mul_f32_e32 v57, v57, v142
	v_fma_f32 v57, -v61, v143, v57
	v_fma_f32 v61, v61, v142, v133
	v_mul_f32_e32 v132, v58, v147
	v_mul_f32_e32 v58, v58, v146
	v_fma_f32 v58, -v62, v147, v58
	v_fma_f32 v62, v62, v146, v132
	v_mul_f32_e32 v133, v59, v151
	v_mul_f32_e32 v59, v59, v150
	v_fma_f32 v59, -v63, v151, v59
	v_fma_f32 v63, v63, v150, v133
	v_mov_b32_e32 v88, v56
	v_mov_b32_e32 v89, v57
	v_mov_b32_e32 v90, v58
	v_mov_b32_e32 v91, v59
	v_mov_b32_e32 v92, v60
	v_mov_b32_e32 v93, v61
	v_mov_b32_e32 v94, v62
	v_mov_b32_e32 v95, v63
	v_add_f32_dpp v56, v56, v56 row_shl:1 row_mask:0xf bank_mask:0xf bound_ctrl:1
	v_add_f32_dpp v57, v57, v57 row_shl:1 row_mask:0xf bank_mask:0xf bound_ctrl:1
	v_add_f32_dpp v58, v58, v58 row_shl:1 row_mask:0xf bank_mask:0xf bound_ctrl:1
	v_add_f32_dpp v59, v59, v59 row_shl:1 row_mask:0xf bank_mask:0xf bound_ctrl:1
	v_add_f32_dpp v60, v60, v60 row_shl:1 row_mask:0xf bank_mask:0xf bound_ctrl:1
	v_add_f32_dpp v61, v61, v61 row_shl:1 row_mask:0xf bank_mask:0xf bound_ctrl:1
	v_add_f32_dpp v62, v62, v62 row_shl:1 row_mask:0xf bank_mask:0xf bound_ctrl:1
	v_add_f32_dpp v63, v63, v63 row_shl:1 row_mask:0xf bank_mask:0xf bound_ctrl:1
	v_add_f32_dpp v88, v88, v88 row_ror:8 row_mask:0xf bank_mask:0xf
	v_add_f32_dpp v89, v89, v89 row_ror:8 row_mask:0xf bank_mask:0xf
	v_add_f32_dpp v90, v90, v90 row_ror:8 row_mask:0xf bank_mask:0xf
	v_add_f32_dpp v91, v91, v91 row_ror:8 row_mask:0xf bank_mask:0xf
	v_add_f32_dpp v92, v92, v92 row_ror:8 row_mask:0xf bank_mask:0xf
	v_add_f32_dpp v93, v93, v93 row_ror:8 row_mask:0xf bank_mask:0xf
	v_add_f32_dpp v94, v94, v94 row_ror:8 row_mask:0xf bank_mask:0xf
	v_add_f32_dpp v95, v95, v95 row_ror:8 row_mask:0xf bank_mask:0xf
	v_add_f32_dpp v56, v56, v56 row_shl:2 row_mask:0xf bank_mask:0xf bound_ctrl:1
	v_add_f32_dpp v57, v57, v57 row_shl:2 row_mask:0xf bank_mask:0xf bound_ctrl:1
	v_add_f32_dpp v58, v58, v58 row_shl:2 row_mask:0xf bank_mask:0xf bound_ctrl:1
	v_add_f32_dpp v59, v59, v59 row_shl:2 row_mask:0xf bank_mask:0xf bound_ctrl:1
	v_add_f32_dpp v60, v60, v60 row_shl:2 row_mask:0xf bank_mask:0xf bound_ctrl:1
	v_add_f32_dpp v61, v61, v61 row_shl:2 row_mask:0xf bank_mask:0xf bound_ctrl:1
	v_add_f32_dpp v62, v62, v62 row_shl:2 row_mask:0xf bank_mask:0xf bound_ctrl:1
	v_add_f32_dpp v63, v63, v63 row_shl:2 row_mask:0xf bank_mask:0xf bound_ctrl:1
	v_add_f32_dpp v88, v88, v88 row_ror:4 row_mask:0xf bank_mask:0xf
	v_add_f32_dpp v89, v89, v89 row_ror:4 row_mask:0xf bank_mask:0xf
	v_add_f32_dpp v90, v90, v90 row_ror:4 row_mask:0xf bank_mask:0xf
	v_add_f32_dpp v91, v91, v91 row_ror:4 row_mask:0xf bank_mask:0xf
	v_add_f32_dpp v92, v92, v92 row_ror:4 row_mask:0xf bank_mask:0xf
	v_add_f32_dpp v93, v93, v93 row_ror:4 row_mask:0xf bank_mask:0xf
	v_add_f32_dpp v94, v94, v94 row_ror:4 row_mask:0xf bank_mask:0xf
	v_add_f32_dpp v95, v95, v95 row_ror:4 row_mask:0xf bank_mask:0xf
	v_add_f32_dpp v56, v56, v56 row_shl:4 row_mask:0xf bank_mask:0xf bound_ctrl:1
	v_add_f32_dpp v57, v57, v57 row_shl:4 row_mask:0xf bank_mask:0xf bound_ctrl:1
	v_add_f32_dpp v58, v58, v58 row_shl:4 row_mask:0xf bank_mask:0xf bound_ctrl:1
	v_add_f32_dpp v59, v59, v59 row_shl:4 row_mask:0xf bank_mask:0xf bound_ctrl:1
	v_add_f32_dpp v60, v60, v60 row_shl:4 row_mask:0xf bank_mask:0xf bound_ctrl:1
	v_add_f32_dpp v61, v61, v61 row_shl:4 row_mask:0xf bank_mask:0xf bound_ctrl:1
	v_add_f32_dpp v62, v62, v62 row_shl:4 row_mask:0xf bank_mask:0xf bound_ctrl:1
	v_add_f32_dpp v63, v63, v63 row_shl:4 row_mask:0xf bank_mask:0xf bound_ctrl:1
	v_add_f32_dpp v88, v88, v88 row_ror:2 row_mask:0xf bank_mask:0xf
	v_add_f32_dpp v89, v89, v89 row_ror:2 row_mask:0xf bank_mask:0xf
	v_add_f32_dpp v90, v90, v90 row_ror:2 row_mask:0xf bank_mask:0xf
	v_add_f32_dpp v91, v91, v91 row_ror:2 row_mask:0xf bank_mask:0xf
	v_add_f32_dpp v92, v92, v92 row_ror:2 row_mask:0xf bank_mask:0xf
	v_add_f32_dpp v93, v93, v93 row_ror:2 row_mask:0xf bank_mask:0xf
	v_add_f32_dpp v94, v94, v94 row_ror:2 row_mask:0xf bank_mask:0xf
	v_add_f32_dpp v95, v95, v95 row_ror:2 row_mask:0xf bank_mask:0xf
	v_add_f32_dpp v56, v56, v56 row_shl:8 row_mask:0xf bank_mask:0xf bound_ctrl:1
	v_add_f32_dpp v57, v57, v57 row_shl:8 row_mask:0xf bank_mask:0xf bound_ctrl:1
	v_add_f32_dpp v58, v58, v58 row_shl:8 row_mask:0xf bank_mask:0xf bound_ctrl:1
	v_add_f32_dpp v59, v59, v59 row_shl:8 row_mask:0xf bank_mask:0xf bound_ctrl:1
	v_add_f32_dpp v60, v60, v60 row_shl:8 row_mask:0xf bank_mask:0xf bound_ctrl:1
	v_add_f32_dpp v61, v61, v61 row_shl:8 row_mask:0xf bank_mask:0xf bound_ctrl:1
	v_add_f32_dpp v62, v62, v62 row_shl:8 row_mask:0xf bank_mask:0xf bound_ctrl:1
	v_add_f32_dpp v63, v63, v63 row_shl:8 row_mask:0xf bank_mask:0xf bound_ctrl:1
	v_add_f32_dpp v88, v88, v88 row_ror:1 row_mask:0xf bank_mask:0xf
	v_add_f32_dpp v89, v89, v89 row_ror:1 row_mask:0xf bank_mask:0xf
	v_add_f32_dpp v90, v90, v90 row_ror:1 row_mask:0xf bank_mask:0xf
	v_add_f32_dpp v91, v91, v91 row_ror:1 row_mask:0xf bank_mask:0xf
	v_add_f32_dpp v92, v92, v92 row_ror:1 row_mask:0xf bank_mask:0xf
	v_add_f32_dpp v93, v93, v93 row_ror:1 row_mask:0xf bank_mask:0xf
	v_add_f32_dpp v94, v94, v94 row_ror:1 row_mask:0xf bank_mask:0xf
	v_add_f32_dpp v95, v95, v95 row_ror:1 row_mask:0xf bank_mask:0xf
	v_add_f32_e32 v56, v56, v170
	v_add_f32_e32 v60, v60, v171
	v_add_f32_e32 v57, v57, v172
	v_add_f32_e32 v61, v61, v173
	v_add_f32_e32 v58, v58, v174
	v_add_f32_e32 v62, v62, v175
	v_add_f32_e32 v59, v59, v176
	v_add_f32_e32 v63, v63, v177
	v_mul_f32_e32 v132, v56, v141
	v_mul_f32_e32 v56, v56, v140
	v_fma_f32 v56, -v60, v141, v56
	v_fma_f32 v60, v60, v140, v132
	v_mul_f32_e32 v133, v57, v145
	v_mul_f32_e32 v57, v57, v144
	v_fma_f32 v57, -v61, v145, v57
	v_fma_f32 v61, v61, v144, v133
	v_mul_f32_e32 v132, v58, v149
	v_mul_f32_e32 v58, v58, v148
	v_fma_f32 v58, -v62, v149, v58
	v_fma_f32 v62, v62, v148, v132
	v_mul_f32_e32 v133, v59, v153
	v_mul_f32_e32 v59, v59, v152
	v_fma_f32 v59, -v63, v153, v59
	v_fma_f32 v63, v63, v152, v133
	v_add_f32_e32 v88, v88, v170
	v_add_f32_e32 v92, v92, v171
	v_mul_f32_e32 v132, v92, v155
	v_mul_f32_e32 v171, v88, v155
	v_fma_f32 v170, v88, v154, -v132
	v_fma_f32 v171, v92, v154, v171
	v_add_f32_e32 v89, v89, v172
	v_add_f32_e32 v93, v93, v173
	v_mul_f32_e32 v133, v93, v159
	v_mul_f32_e32 v173, v89, v159
	v_fma_f32 v172, v89, v158, -v133
	v_fma_f32 v173, v93, v158, v173
	v_add_f32_e32 v90, v90, v174
	v_add_f32_e32 v94, v94, v175
	v_mul_f32_e32 v132, v94, v163
	v_mul_f32_e32 v175, v90, v163
	v_fma_f32 v174, v90, v162, -v132
	v_fma_f32 v175, v94, v162, v175
	v_add_f32_e32 v91, v91, v176
	v_add_f32_e32 v95, v95, v177
	v_mul_f32_e32 v133, v95, v167
	v_mul_f32_e32 v177, v91, v167
	v_fma_f32 v176, v91, v166, -v133
	v_fma_f32 v177, v95, v166, v177
	v_mul_f32_e32 v132, v48, v139
	v_mul_f32_e32 v48, v48, v138
	v_fma_f32 v48, -v52, v139, v48
	v_fma_f32 v52, v52, v138, v132
	v_mul_f32_e32 v133, v49, v143
	v_mul_f32_e32 v49, v49, v142
	v_fma_f32 v49, -v53, v143, v49
	v_fma_f32 v53, v53, v142, v133
	v_mul_f32_e32 v132, v50, v147
	v_mul_f32_e32 v50, v50, v146
	v_fma_f32 v50, -v54, v147, v50
	v_fma_f32 v54, v54, v146, v132
	v_mul_f32_e32 v133, v51, v151
	v_mul_f32_e32 v51, v51, v150
	v_fma_f32 v51, -v55, v151, v51
	v_fma_f32 v55, v55, v150, v133
	v_mov_b32_e32 v88, v48
	v_mov_b32_e32 v89, v49
	v_mov_b32_e32 v90, v50
	v_mov_b32_e32 v91, v51
	v_mov_b32_e32 v92, v52
	v_mov_b32_e32 v93, v53
	v_mov_b32_e32 v94, v54
	v_mov_b32_e32 v95, v55
	v_add_f32_dpp v48, v48, v48 row_shl:1 row_mask:0xf bank_mask:0xf bound_ctrl:1
	v_add_f32_dpp v49, v49, v49 row_shl:1 row_mask:0xf bank_mask:0xf bound_ctrl:1
	v_add_f32_dpp v50, v50, v50 row_shl:1 row_mask:0xf bank_mask:0xf bound_ctrl:1
	v_add_f32_dpp v51, v51, v51 row_shl:1 row_mask:0xf bank_mask:0xf bound_ctrl:1
	v_add_f32_dpp v52, v52, v52 row_shl:1 row_mask:0xf bank_mask:0xf bound_ctrl:1
	v_add_f32_dpp v53, v53, v53 row_shl:1 row_mask:0xf bank_mask:0xf bound_ctrl:1
	v_add_f32_dpp v54, v54, v54 row_shl:1 row_mask:0xf bank_mask:0xf bound_ctrl:1
	v_add_f32_dpp v55, v55, v55 row_shl:1 row_mask:0xf bank_mask:0xf bound_ctrl:1
	v_add_f32_dpp v88, v88, v88 row_ror:8 row_mask:0xf bank_mask:0xf
	v_add_f32_dpp v89, v89, v89 row_ror:8 row_mask:0xf bank_mask:0xf
	v_add_f32_dpp v90, v90, v90 row_ror:8 row_mask:0xf bank_mask:0xf
	v_add_f32_dpp v91, v91, v91 row_ror:8 row_mask:0xf bank_mask:0xf
	v_add_f32_dpp v92, v92, v92 row_ror:8 row_mask:0xf bank_mask:0xf
	v_add_f32_dpp v93, v93, v93 row_ror:8 row_mask:0xf bank_mask:0xf
	v_add_f32_dpp v94, v94, v94 row_ror:8 row_mask:0xf bank_mask:0xf
	v_add_f32_dpp v95, v95, v95 row_ror:8 row_mask:0xf bank_mask:0xf
	v_add_f32_dpp v48, v48, v48 row_shl:2 row_mask:0xf bank_mask:0xf bound_ctrl:1
	v_add_f32_dpp v49, v49, v49 row_shl:2 row_mask:0xf bank_mask:0xf bound_ctrl:1
	v_add_f32_dpp v50, v50, v50 row_shl:2 row_mask:0xf bank_mask:0xf bound_ctrl:1
	v_add_f32_dpp v51, v51, v51 row_shl:2 row_mask:0xf bank_mask:0xf bound_ctrl:1
	v_add_f32_dpp v52, v52, v52 row_shl:2 row_mask:0xf bank_mask:0xf bound_ctrl:1
	v_add_f32_dpp v53, v53, v53 row_shl:2 row_mask:0xf bank_mask:0xf bound_ctrl:1
	v_add_f32_dpp v54, v54, v54 row_shl:2 row_mask:0xf bank_mask:0xf bound_ctrl:1
	v_add_f32_dpp v55, v55, v55 row_shl:2 row_mask:0xf bank_mask:0xf bound_ctrl:1
	v_add_f32_dpp v88, v88, v88 row_ror:4 row_mask:0xf bank_mask:0xf
	v_add_f32_dpp v89, v89, v89 row_ror:4 row_mask:0xf bank_mask:0xf
	v_add_f32_dpp v90, v90, v90 row_ror:4 row_mask:0xf bank_mask:0xf
	v_add_f32_dpp v91, v91, v91 row_ror:4 row_mask:0xf bank_mask:0xf
	v_add_f32_dpp v92, v92, v92 row_ror:4 row_mask:0xf bank_mask:0xf
	v_add_f32_dpp v93, v93, v93 row_ror:4 row_mask:0xf bank_mask:0xf
	v_add_f32_dpp v94, v94, v94 row_ror:4 row_mask:0xf bank_mask:0xf
	v_add_f32_dpp v95, v95, v95 row_ror:4 row_mask:0xf bank_mask:0xf
	v_add_f32_dpp v48, v48, v48 row_shl:4 row_mask:0xf bank_mask:0xf bound_ctrl:1
	v_add_f32_dpp v49, v49, v49 row_shl:4 row_mask:0xf bank_mask:0xf bound_ctrl:1
	v_add_f32_dpp v50, v50, v50 row_shl:4 row_mask:0xf bank_mask:0xf bound_ctrl:1
	v_add_f32_dpp v51, v51, v51 row_shl:4 row_mask:0xf bank_mask:0xf bound_ctrl:1
	v_add_f32_dpp v52, v52, v52 row_shl:4 row_mask:0xf bank_mask:0xf bound_ctrl:1
	v_add_f32_dpp v53, v53, v53 row_shl:4 row_mask:0xf bank_mask:0xf bound_ctrl:1
	v_add_f32_dpp v54, v54, v54 row_shl:4 row_mask:0xf bank_mask:0xf bound_ctrl:1
	v_add_f32_dpp v55, v55, v55 row_shl:4 row_mask:0xf bank_mask:0xf bound_ctrl:1
	v_add_f32_dpp v88, v88, v88 row_ror:2 row_mask:0xf bank_mask:0xf
	v_add_f32_dpp v89, v89, v89 row_ror:2 row_mask:0xf bank_mask:0xf
	v_add_f32_dpp v90, v90, v90 row_ror:2 row_mask:0xf bank_mask:0xf
	v_add_f32_dpp v91, v91, v91 row_ror:2 row_mask:0xf bank_mask:0xf
	v_add_f32_dpp v92, v92, v92 row_ror:2 row_mask:0xf bank_mask:0xf
	v_add_f32_dpp v93, v93, v93 row_ror:2 row_mask:0xf bank_mask:0xf
	v_add_f32_dpp v94, v94, v94 row_ror:2 row_mask:0xf bank_mask:0xf
	v_add_f32_dpp v95, v95, v95 row_ror:2 row_mask:0xf bank_mask:0xf
	v_add_f32_dpp v48, v48, v48 row_shl:8 row_mask:0xf bank_mask:0xf bound_ctrl:1
	v_add_f32_dpp v49, v49, v49 row_shl:8 row_mask:0xf bank_mask:0xf bound_ctrl:1
	v_add_f32_dpp v50, v50, v50 row_shl:8 row_mask:0xf bank_mask:0xf bound_ctrl:1
	v_add_f32_dpp v51, v51, v51 row_shl:8 row_mask:0xf bank_mask:0xf bound_ctrl:1
	v_add_f32_dpp v52, v52, v52 row_shl:8 row_mask:0xf bank_mask:0xf bound_ctrl:1
	v_add_f32_dpp v53, v53, v53 row_shl:8 row_mask:0xf bank_mask:0xf bound_ctrl:1
	v_add_f32_dpp v54, v54, v54 row_shl:8 row_mask:0xf bank_mask:0xf bound_ctrl:1
	v_add_f32_dpp v55, v55, v55 row_shl:8 row_mask:0xf bank_mask:0xf bound_ctrl:1
	v_add_f32_dpp v88, v88, v88 row_ror:1 row_mask:0xf bank_mask:0xf
	v_add_f32_dpp v89, v89, v89 row_ror:1 row_mask:0xf bank_mask:0xf
	v_add_f32_dpp v90, v90, v90 row_ror:1 row_mask:0xf bank_mask:0xf
	v_add_f32_dpp v91, v91, v91 row_ror:1 row_mask:0xf bank_mask:0xf
	v_add_f32_dpp v92, v92, v92 row_ror:1 row_mask:0xf bank_mask:0xf
	v_add_f32_dpp v93, v93, v93 row_ror:1 row_mask:0xf bank_mask:0xf
	v_add_f32_dpp v94, v94, v94 row_ror:1 row_mask:0xf bank_mask:0xf
	v_add_f32_dpp v95, v95, v95 row_ror:1 row_mask:0xf bank_mask:0xf
	v_add_f32_e32 v48, v48, v170
	v_add_f32_e32 v52, v52, v171
	v_add_f32_e32 v49, v49, v172
	v_add_f32_e32 v53, v53, v173
	v_add_f32_e32 v50, v50, v174
	v_add_f32_e32 v54, v54, v175
	v_add_f32_e32 v51, v51, v176
	v_add_f32_e32 v55, v55, v177
	v_mul_f32_e32 v132, v48, v141
	v_mul_f32_e32 v48, v48, v140
	v_fma_f32 v48, -v52, v141, v48
	v_fma_f32 v52, v52, v140, v132
	v_mul_f32_e32 v133, v49, v145
	v_mul_f32_e32 v49, v49, v144
	v_fma_f32 v49, -v53, v145, v49
	v_fma_f32 v53, v53, v144, v133
	v_mul_f32_e32 v132, v50, v149
	v_mul_f32_e32 v50, v50, v148
	v_fma_f32 v50, -v54, v149, v50
	v_fma_f32 v54, v54, v148, v132
	v_mul_f32_e32 v133, v51, v153
	v_mul_f32_e32 v51, v51, v152
	v_fma_f32 v51, -v55, v153, v51
	v_fma_f32 v55, v55, v152, v133
	v_add_f32_e32 v88, v88, v170
	v_add_f32_e32 v92, v92, v171
	v_mul_f32_e32 v132, v92, v155
	v_mul_f32_e32 v171, v88, v155
	v_fma_f32 v170, v88, v154, -v132
	v_fma_f32 v171, v92, v154, v171
	v_add_f32_e32 v89, v89, v172
	v_add_f32_e32 v93, v93, v173
	v_mul_f32_e32 v133, v93, v159
	v_mul_f32_e32 v173, v89, v159
	v_fma_f32 v172, v89, v158, -v133
	v_fma_f32 v173, v93, v158, v173
	v_add_f32_e32 v90, v90, v174
	v_add_f32_e32 v94, v94, v175
	v_mul_f32_e32 v132, v94, v163
	v_mul_f32_e32 v175, v90, v163
	v_fma_f32 v174, v90, v162, -v132
	v_fma_f32 v175, v94, v162, v175
	v_add_f32_e32 v91, v91, v176
	v_add_f32_e32 v95, v95, v177
	v_mul_f32_e32 v133, v95, v167
	v_mul_f32_e32 v177, v91, v167
	v_fma_f32 v176, v91, v166, -v133
	v_fma_f32 v177, v95, v166, v177
	v_mul_f32_e32 v132, v40, v139
	v_mul_f32_e32 v40, v40, v138
	v_fma_f32 v40, -v44, v139, v40
	v_fma_f32 v44, v44, v138, v132
	v_mul_f32_e32 v133, v41, v143
	v_mul_f32_e32 v41, v41, v142
	v_fma_f32 v41, -v45, v143, v41
	v_fma_f32 v45, v45, v142, v133
	v_mul_f32_e32 v132, v42, v147
	v_mul_f32_e32 v42, v42, v146
	v_fma_f32 v42, -v46, v147, v42
	v_fma_f32 v46, v46, v146, v132
	v_mul_f32_e32 v133, v43, v151
	v_mul_f32_e32 v43, v43, v150
	v_fma_f32 v43, -v47, v151, v43
	v_fma_f32 v47, v47, v150, v133
	v_mov_b32_e32 v88, v40
	v_mov_b32_e32 v89, v41
	v_mov_b32_e32 v90, v42
	v_mov_b32_e32 v91, v43
	v_mov_b32_e32 v92, v44
	v_mov_b32_e32 v93, v45
	v_mov_b32_e32 v94, v46
	v_mov_b32_e32 v95, v47
	v_add_f32_dpp v40, v40, v40 row_shl:1 row_mask:0xf bank_mask:0xf bound_ctrl:1
	v_add_f32_dpp v41, v41, v41 row_shl:1 row_mask:0xf bank_mask:0xf bound_ctrl:1
	v_add_f32_dpp v42, v42, v42 row_shl:1 row_mask:0xf bank_mask:0xf bound_ctrl:1
	v_add_f32_dpp v43, v43, v43 row_shl:1 row_mask:0xf bank_mask:0xf bound_ctrl:1
	v_add_f32_dpp v44, v44, v44 row_shl:1 row_mask:0xf bank_mask:0xf bound_ctrl:1
	v_add_f32_dpp v45, v45, v45 row_shl:1 row_mask:0xf bank_mask:0xf bound_ctrl:1
	v_add_f32_dpp v46, v46, v46 row_shl:1 row_mask:0xf bank_mask:0xf bound_ctrl:1
	v_add_f32_dpp v47, v47, v47 row_shl:1 row_mask:0xf bank_mask:0xf bound_ctrl:1
	v_add_f32_dpp v88, v88, v88 row_ror:8 row_mask:0xf bank_mask:0xf
	v_add_f32_dpp v89, v89, v89 row_ror:8 row_mask:0xf bank_mask:0xf
	v_add_f32_dpp v90, v90, v90 row_ror:8 row_mask:0xf bank_mask:0xf
	v_add_f32_dpp v91, v91, v91 row_ror:8 row_mask:0xf bank_mask:0xf
	v_add_f32_dpp v92, v92, v92 row_ror:8 row_mask:0xf bank_mask:0xf
	v_add_f32_dpp v93, v93, v93 row_ror:8 row_mask:0xf bank_mask:0xf
	v_add_f32_dpp v94, v94, v94 row_ror:8 row_mask:0xf bank_mask:0xf
	v_add_f32_dpp v95, v95, v95 row_ror:8 row_mask:0xf bank_mask:0xf
	v_add_f32_dpp v40, v40, v40 row_shl:2 row_mask:0xf bank_mask:0xf bound_ctrl:1
	v_add_f32_dpp v41, v41, v41 row_shl:2 row_mask:0xf bank_mask:0xf bound_ctrl:1
	v_add_f32_dpp v42, v42, v42 row_shl:2 row_mask:0xf bank_mask:0xf bound_ctrl:1
	v_add_f32_dpp v43, v43, v43 row_shl:2 row_mask:0xf bank_mask:0xf bound_ctrl:1
	v_add_f32_dpp v44, v44, v44 row_shl:2 row_mask:0xf bank_mask:0xf bound_ctrl:1
	v_add_f32_dpp v45, v45, v45 row_shl:2 row_mask:0xf bank_mask:0xf bound_ctrl:1
	v_add_f32_dpp v46, v46, v46 row_shl:2 row_mask:0xf bank_mask:0xf bound_ctrl:1
	v_add_f32_dpp v47, v47, v47 row_shl:2 row_mask:0xf bank_mask:0xf bound_ctrl:1
	v_add_f32_dpp v88, v88, v88 row_ror:4 row_mask:0xf bank_mask:0xf
	v_add_f32_dpp v89, v89, v89 row_ror:4 row_mask:0xf bank_mask:0xf
	v_add_f32_dpp v90, v90, v90 row_ror:4 row_mask:0xf bank_mask:0xf
	v_add_f32_dpp v91, v91, v91 row_ror:4 row_mask:0xf bank_mask:0xf
	v_add_f32_dpp v92, v92, v92 row_ror:4 row_mask:0xf bank_mask:0xf
	v_add_f32_dpp v93, v93, v93 row_ror:4 row_mask:0xf bank_mask:0xf
	v_add_f32_dpp v94, v94, v94 row_ror:4 row_mask:0xf bank_mask:0xf
	v_add_f32_dpp v95, v95, v95 row_ror:4 row_mask:0xf bank_mask:0xf
	v_add_f32_dpp v40, v40, v40 row_shl:4 row_mask:0xf bank_mask:0xf bound_ctrl:1
	v_add_f32_dpp v41, v41, v41 row_shl:4 row_mask:0xf bank_mask:0xf bound_ctrl:1
	v_add_f32_dpp v42, v42, v42 row_shl:4 row_mask:0xf bank_mask:0xf bound_ctrl:1
	v_add_f32_dpp v43, v43, v43 row_shl:4 row_mask:0xf bank_mask:0xf bound_ctrl:1
	v_add_f32_dpp v44, v44, v44 row_shl:4 row_mask:0xf bank_mask:0xf bound_ctrl:1
	v_add_f32_dpp v45, v45, v45 row_shl:4 row_mask:0xf bank_mask:0xf bound_ctrl:1
	v_add_f32_dpp v46, v46, v46 row_shl:4 row_mask:0xf bank_mask:0xf bound_ctrl:1
	v_add_f32_dpp v47, v47, v47 row_shl:4 row_mask:0xf bank_mask:0xf bound_ctrl:1
	v_add_f32_dpp v88, v88, v88 row_ror:2 row_mask:0xf bank_mask:0xf
	v_add_f32_dpp v89, v89, v89 row_ror:2 row_mask:0xf bank_mask:0xf
	v_add_f32_dpp v90, v90, v90 row_ror:2 row_mask:0xf bank_mask:0xf
	v_add_f32_dpp v91, v91, v91 row_ror:2 row_mask:0xf bank_mask:0xf
	v_add_f32_dpp v92, v92, v92 row_ror:2 row_mask:0xf bank_mask:0xf
	v_add_f32_dpp v93, v93, v93 row_ror:2 row_mask:0xf bank_mask:0xf
	v_add_f32_dpp v94, v94, v94 row_ror:2 row_mask:0xf bank_mask:0xf
	v_add_f32_dpp v95, v95, v95 row_ror:2 row_mask:0xf bank_mask:0xf
	v_add_f32_dpp v40, v40, v40 row_shl:8 row_mask:0xf bank_mask:0xf bound_ctrl:1
	v_add_f32_dpp v41, v41, v41 row_shl:8 row_mask:0xf bank_mask:0xf bound_ctrl:1
	v_add_f32_dpp v42, v42, v42 row_shl:8 row_mask:0xf bank_mask:0xf bound_ctrl:1
	v_add_f32_dpp v43, v43, v43 row_shl:8 row_mask:0xf bank_mask:0xf bound_ctrl:1
	v_add_f32_dpp v44, v44, v44 row_shl:8 row_mask:0xf bank_mask:0xf bound_ctrl:1
	v_add_f32_dpp v45, v45, v45 row_shl:8 row_mask:0xf bank_mask:0xf bound_ctrl:1
	v_add_f32_dpp v46, v46, v46 row_shl:8 row_mask:0xf bank_mask:0xf bound_ctrl:1
	v_add_f32_dpp v47, v47, v47 row_shl:8 row_mask:0xf bank_mask:0xf bound_ctrl:1
	v_add_f32_dpp v88, v88, v88 row_ror:1 row_mask:0xf bank_mask:0xf
	v_add_f32_dpp v89, v89, v89 row_ror:1 row_mask:0xf bank_mask:0xf
	v_add_f32_dpp v90, v90, v90 row_ror:1 row_mask:0xf bank_mask:0xf
	v_add_f32_dpp v91, v91, v91 row_ror:1 row_mask:0xf bank_mask:0xf
	v_add_f32_dpp v92, v92, v92 row_ror:1 row_mask:0xf bank_mask:0xf
	v_add_f32_dpp v93, v93, v93 row_ror:1 row_mask:0xf bank_mask:0xf
	v_add_f32_dpp v94, v94, v94 row_ror:1 row_mask:0xf bank_mask:0xf
	v_add_f32_dpp v95, v95, v95 row_ror:1 row_mask:0xf bank_mask:0xf
	v_add_f32_e32 v40, v40, v170
	v_add_f32_e32 v44, v44, v171
	v_add_f32_e32 v41, v41, v172
	v_add_f32_e32 v45, v45, v173
	v_add_f32_e32 v42, v42, v174
	v_add_f32_e32 v46, v46, v175
	v_add_f32_e32 v43, v43, v176
	v_add_f32_e32 v47, v47, v177
	v_mul_f32_e32 v132, v40, v141
	v_mul_f32_e32 v40, v40, v140
	v_fma_f32 v40, -v44, v141, v40
	v_fma_f32 v44, v44, v140, v132
	v_mul_f32_e32 v133, v41, v145
	v_mul_f32_e32 v41, v41, v144
	v_fma_f32 v41, -v45, v145, v41
	v_fma_f32 v45, v45, v144, v133
	v_mul_f32_e32 v132, v42, v149
	v_mul_f32_e32 v42, v42, v148
	v_fma_f32 v42, -v46, v149, v42
	v_fma_f32 v46, v46, v148, v132
	v_mul_f32_e32 v133, v43, v153
	v_mul_f32_e32 v43, v43, v152
	v_fma_f32 v43, -v47, v153, v43
	v_fma_f32 v47, v47, v152, v133
	v_add_f32_e32 v88, v88, v170
	v_add_f32_e32 v92, v92, v171
	v_mul_f32_e32 v132, v92, v155
	v_mul_f32_e32 v171, v88, v155
	v_fma_f32 v170, v88, v154, -v132
	v_fma_f32 v171, v92, v154, v171
	v_add_f32_e32 v89, v89, v172
	v_add_f32_e32 v93, v93, v173
	v_mul_f32_e32 v133, v93, v159
	v_mul_f32_e32 v173, v89, v159
	v_fma_f32 v172, v89, v158, -v133
	v_fma_f32 v173, v93, v158, v173
	v_add_f32_e32 v90, v90, v174
	v_add_f32_e32 v94, v94, v175
	v_mul_f32_e32 v132, v94, v163
	v_mul_f32_e32 v175, v90, v163
	v_fma_f32 v174, v90, v162, -v132
	v_fma_f32 v175, v94, v162, v175
	v_add_f32_e32 v91, v91, v176
	v_add_f32_e32 v95, v95, v177
	v_mul_f32_e32 v133, v95, v167
	v_mul_f32_e32 v177, v91, v167
	v_fma_f32 v176, v91, v166, -v133
	v_fma_f32 v177, v95, v166, v177
	v_mul_f32_e32 v132, v32, v139
	v_mul_f32_e32 v32, v32, v138
	v_fma_f32 v32, -v36, v139, v32
	v_fma_f32 v36, v36, v138, v132
	v_mul_f32_e32 v133, v33, v143
	v_mul_f32_e32 v33, v33, v142
	v_fma_f32 v33, -v37, v143, v33
	v_fma_f32 v37, v37, v142, v133
	v_mul_f32_e32 v132, v34, v147
	v_mul_f32_e32 v34, v34, v146
	v_fma_f32 v34, -v38, v147, v34
	v_fma_f32 v38, v38, v146, v132
	v_mul_f32_e32 v133, v35, v151
	v_mul_f32_e32 v35, v35, v150
	v_fma_f32 v35, -v39, v151, v35
	v_fma_f32 v39, v39, v150, v133
	v_mov_b32_e32 v88, v32
	v_mov_b32_e32 v89, v33
	v_mov_b32_e32 v90, v34
	v_mov_b32_e32 v91, v35
	v_mov_b32_e32 v92, v36
	v_mov_b32_e32 v93, v37
	v_mov_b32_e32 v94, v38
	v_mov_b32_e32 v95, v39
	v_add_f32_dpp v32, v32, v32 row_shl:1 row_mask:0xf bank_mask:0xf bound_ctrl:1
	v_add_f32_dpp v33, v33, v33 row_shl:1 row_mask:0xf bank_mask:0xf bound_ctrl:1
	v_add_f32_dpp v34, v34, v34 row_shl:1 row_mask:0xf bank_mask:0xf bound_ctrl:1
	v_add_f32_dpp v35, v35, v35 row_shl:1 row_mask:0xf bank_mask:0xf bound_ctrl:1
	v_add_f32_dpp v36, v36, v36 row_shl:1 row_mask:0xf bank_mask:0xf bound_ctrl:1
	v_add_f32_dpp v37, v37, v37 row_shl:1 row_mask:0xf bank_mask:0xf bound_ctrl:1
	v_add_f32_dpp v38, v38, v38 row_shl:1 row_mask:0xf bank_mask:0xf bound_ctrl:1
	v_add_f32_dpp v39, v39, v39 row_shl:1 row_mask:0xf bank_mask:0xf bound_ctrl:1
	v_add_f32_dpp v88, v88, v88 row_ror:8 row_mask:0xf bank_mask:0xf
	v_add_f32_dpp v89, v89, v89 row_ror:8 row_mask:0xf bank_mask:0xf
	v_add_f32_dpp v90, v90, v90 row_ror:8 row_mask:0xf bank_mask:0xf
	v_add_f32_dpp v91, v91, v91 row_ror:8 row_mask:0xf bank_mask:0xf
	v_add_f32_dpp v92, v92, v92 row_ror:8 row_mask:0xf bank_mask:0xf
	v_add_f32_dpp v93, v93, v93 row_ror:8 row_mask:0xf bank_mask:0xf
	v_add_f32_dpp v94, v94, v94 row_ror:8 row_mask:0xf bank_mask:0xf
	v_add_f32_dpp v95, v95, v95 row_ror:8 row_mask:0xf bank_mask:0xf
	v_add_f32_dpp v32, v32, v32 row_shl:2 row_mask:0xf bank_mask:0xf bound_ctrl:1
	v_add_f32_dpp v33, v33, v33 row_shl:2 row_mask:0xf bank_mask:0xf bound_ctrl:1
	v_add_f32_dpp v34, v34, v34 row_shl:2 row_mask:0xf bank_mask:0xf bound_ctrl:1
	v_add_f32_dpp v35, v35, v35 row_shl:2 row_mask:0xf bank_mask:0xf bound_ctrl:1
	v_add_f32_dpp v36, v36, v36 row_shl:2 row_mask:0xf bank_mask:0xf bound_ctrl:1
	v_add_f32_dpp v37, v37, v37 row_shl:2 row_mask:0xf bank_mask:0xf bound_ctrl:1
	v_add_f32_dpp v38, v38, v38 row_shl:2 row_mask:0xf bank_mask:0xf bound_ctrl:1
	v_add_f32_dpp v39, v39, v39 row_shl:2 row_mask:0xf bank_mask:0xf bound_ctrl:1
	v_add_f32_dpp v88, v88, v88 row_ror:4 row_mask:0xf bank_mask:0xf
	v_add_f32_dpp v89, v89, v89 row_ror:4 row_mask:0xf bank_mask:0xf
	v_add_f32_dpp v90, v90, v90 row_ror:4 row_mask:0xf bank_mask:0xf
	v_add_f32_dpp v91, v91, v91 row_ror:4 row_mask:0xf bank_mask:0xf
	v_add_f32_dpp v92, v92, v92 row_ror:4 row_mask:0xf bank_mask:0xf
	v_add_f32_dpp v93, v93, v93 row_ror:4 row_mask:0xf bank_mask:0xf
	v_add_f32_dpp v94, v94, v94 row_ror:4 row_mask:0xf bank_mask:0xf
	v_add_f32_dpp v95, v95, v95 row_ror:4 row_mask:0xf bank_mask:0xf
	v_add_f32_dpp v32, v32, v32 row_shl:4 row_mask:0xf bank_mask:0xf bound_ctrl:1
	v_add_f32_dpp v33, v33, v33 row_shl:4 row_mask:0xf bank_mask:0xf bound_ctrl:1
	v_add_f32_dpp v34, v34, v34 row_shl:4 row_mask:0xf bank_mask:0xf bound_ctrl:1
	v_add_f32_dpp v35, v35, v35 row_shl:4 row_mask:0xf bank_mask:0xf bound_ctrl:1
	v_add_f32_dpp v36, v36, v36 row_shl:4 row_mask:0xf bank_mask:0xf bound_ctrl:1
	v_add_f32_dpp v37, v37, v37 row_shl:4 row_mask:0xf bank_mask:0xf bound_ctrl:1
	v_add_f32_dpp v38, v38, v38 row_shl:4 row_mask:0xf bank_mask:0xf bound_ctrl:1
	v_add_f32_dpp v39, v39, v39 row_shl:4 row_mask:0xf bank_mask:0xf bound_ctrl:1
	v_add_f32_dpp v88, v88, v88 row_ror:2 row_mask:0xf bank_mask:0xf
	v_add_f32_dpp v89, v89, v89 row_ror:2 row_mask:0xf bank_mask:0xf
	v_add_f32_dpp v90, v90, v90 row_ror:2 row_mask:0xf bank_mask:0xf
	v_add_f32_dpp v91, v91, v91 row_ror:2 row_mask:0xf bank_mask:0xf
	v_add_f32_dpp v92, v92, v92 row_ror:2 row_mask:0xf bank_mask:0xf
	v_add_f32_dpp v93, v93, v93 row_ror:2 row_mask:0xf bank_mask:0xf
	v_add_f32_dpp v94, v94, v94 row_ror:2 row_mask:0xf bank_mask:0xf
	v_add_f32_dpp v95, v95, v95 row_ror:2 row_mask:0xf bank_mask:0xf
	v_add_f32_dpp v32, v32, v32 row_shl:8 row_mask:0xf bank_mask:0xf bound_ctrl:1
	v_add_f32_dpp v33, v33, v33 row_shl:8 row_mask:0xf bank_mask:0xf bound_ctrl:1
	v_add_f32_dpp v34, v34, v34 row_shl:8 row_mask:0xf bank_mask:0xf bound_ctrl:1
	v_add_f32_dpp v35, v35, v35 row_shl:8 row_mask:0xf bank_mask:0xf bound_ctrl:1
	v_add_f32_dpp v36, v36, v36 row_shl:8 row_mask:0xf bank_mask:0xf bound_ctrl:1
	v_add_f32_dpp v37, v37, v37 row_shl:8 row_mask:0xf bank_mask:0xf bound_ctrl:1
	v_add_f32_dpp v38, v38, v38 row_shl:8 row_mask:0xf bank_mask:0xf bound_ctrl:1
	v_add_f32_dpp v39, v39, v39 row_shl:8 row_mask:0xf bank_mask:0xf bound_ctrl:1
	v_add_f32_dpp v88, v88, v88 row_ror:1 row_mask:0xf bank_mask:0xf
	v_add_f32_dpp v89, v89, v89 row_ror:1 row_mask:0xf bank_mask:0xf
	v_add_f32_dpp v90, v90, v90 row_ror:1 row_mask:0xf bank_mask:0xf
	v_add_f32_dpp v91, v91, v91 row_ror:1 row_mask:0xf bank_mask:0xf
	v_add_f32_dpp v92, v92, v92 row_ror:1 row_mask:0xf bank_mask:0xf
	v_add_f32_dpp v93, v93, v93 row_ror:1 row_mask:0xf bank_mask:0xf
	v_add_f32_dpp v94, v94, v94 row_ror:1 row_mask:0xf bank_mask:0xf
	v_add_f32_dpp v95, v95, v95 row_ror:1 row_mask:0xf bank_mask:0xf
	v_add_f32_e32 v32, v32, v170
	v_add_f32_e32 v36, v36, v171
	v_add_f32_e32 v33, v33, v172
	v_add_f32_e32 v37, v37, v173
	v_add_f32_e32 v34, v34, v174
	v_add_f32_e32 v38, v38, v175
	v_add_f32_e32 v35, v35, v176
	v_add_f32_e32 v39, v39, v177
	v_mul_f32_e32 v132, v32, v141
	v_mul_f32_e32 v32, v32, v140
	v_fma_f32 v32, -v36, v141, v32
	v_fma_f32 v36, v36, v140, v132
	v_mul_f32_e32 v133, v33, v145
	v_mul_f32_e32 v33, v33, v144
	v_fma_f32 v33, -v37, v145, v33
	v_fma_f32 v37, v37, v144, v133
	v_mul_f32_e32 v132, v34, v149
	v_mul_f32_e32 v34, v34, v148
	v_fma_f32 v34, -v38, v149, v34
	v_fma_f32 v38, v38, v148, v132
	v_mul_f32_e32 v133, v35, v153
	v_mul_f32_e32 v35, v35, v152
	v_fma_f32 v35, -v39, v153, v35
	v_fma_f32 v39, v39, v152, v133
	v_add_f32_e32 v88, v88, v170
	v_add_f32_e32 v92, v92, v171
	v_mul_f32_e32 v132, v92, v155
	v_mul_f32_e32 v171, v88, v155
	v_fma_f32 v170, v88, v154, -v132
	v_fma_f32 v171, v92, v154, v171
	v_add_f32_e32 v89, v89, v172
	v_add_f32_e32 v93, v93, v173
	v_mul_f32_e32 v133, v93, v159
	v_mul_f32_e32 v173, v89, v159
	v_fma_f32 v172, v89, v158, -v133
	v_fma_f32 v173, v93, v158, v173
	v_add_f32_e32 v90, v90, v174
	v_add_f32_e32 v94, v94, v175
	v_mul_f32_e32 v132, v94, v163
	v_mul_f32_e32 v175, v90, v163
	v_fma_f32 v174, v90, v162, -v132
	v_fma_f32 v175, v94, v162, v175
	v_add_f32_e32 v91, v91, v176
	v_add_f32_e32 v95, v95, v177
	v_mul_f32_e32 v133, v95, v167
	v_mul_f32_e32 v177, v91, v167
	v_fma_f32 v176, v91, v166, -v133
	v_fma_f32 v177, v95, v166, v177
	s_waitcnt vmcnt(14)
	v_cvt_pk_bf16_f32 v80, v80, v81
	v_cvt_pk_bf16_f32 v81, v82, v83
	v_cvt_pk_bf16_f32 v82, -v84, -v85
	v_cvt_pk_bf16_f32 v83, -v86, -v87
	v_cvt_pk_bf16_f32 v96, v32, v33
	v_cvt_pk_bf16_f32 v97, v34, v35
	v_cvt_pk_bf16_f32 v98, v36, v37
	v_cvt_pk_bf16_f32 v99, v38, v39
	s_nop 1
	v_mfma_f32_16x16x32_bf16 v[16:19], v[80:83], v[96:99], v[16:19]
	v_cvt_pk_bf16_f32 v96, v40, v41
	v_cvt_pk_bf16_f32 v97, v42, v43
	v_cvt_pk_bf16_f32 v98, v44, v45
	v_cvt_pk_bf16_f32 v99, v46, v47
	s_nop 1
	v_mfma_f32_16x16x32_bf16 v[20:23], v[80:83], v[96:99], v[20:23]
	v_cvt_pk_bf16_f32 v96, v48, v49
	v_cvt_pk_bf16_f32 v97, v50, v51
	v_cvt_pk_bf16_f32 v98, v52, v53
	v_cvt_pk_bf16_f32 v99, v54, v55
	s_nop 1
	v_mfma_f32_16x16x32_bf16 v[24:27], v[80:83], v[96:99], v[24:27]
	v_cvt_pk_bf16_f32 v96, v56, v57
	v_cvt_pk_bf16_f32 v97, v58, v59
	v_cvt_pk_bf16_f32 v98, v60, v61
	v_cvt_pk_bf16_f32 v99, v62, v63
	s_nop 1
	v_mfma_f32_16x16x32_bf16 v[28:31], v[80:83], v[96:99], v[28:31]
	s_waitcnt vmcnt(10)
	v_cvt_pk_bf16_f32 v64, v64, v65
	v_cvt_pk_bf16_f32 v65, v66, v67
	v_cvt_pk_bf16_f32 v66, v68, v69
	v_cvt_pk_bf16_f32 v67, v70, v71
	v_cvt_pk_bf16_f32 v72, v72, v73
	v_cvt_pk_bf16_f32 v73, v74, v75
	v_cvt_pk_bf16_f32 v74, v76, v77
	v_cvt_pk_bf16_f32 v75, v78, v79
	global_load_dwordx4 v[80:83], v136, s[38:39]
	global_load_dwordx4 v[84:87], v136, s[40:41]
	s_nop 0
	v_mfma_f32_16x16x32_bf16 v[32:35], v[64:67], v[0:3], 0
	v_mfma_f32_16x16x32_bf16 v[36:39], v[72:75], v[0:3], 0
	v_mfma_f32_16x16x32_bf16 v[40:43], v[64:67], v[4:7], 0
	v_mfma_f32_16x16x32_bf16 v[44:47], v[72:75], v[4:7], 0
	v_mfma_f32_16x16x32_bf16 v[48:51], v[64:67], v[8:11], 0
	v_mfma_f32_16x16x32_bf16 v[52:55], v[72:75], v[8:11], 0
	v_mfma_f32_16x16x32_bf16 v[56:59], v[64:67], v[12:15], 0
	v_mfma_f32_16x16x32_bf16 v[60:63], v[72:75], v[12:15], 0
	s_waitcnt vmcnt(2)
	v_mul_f32_e32 v132, v179, v119
	v_mul_f32_e32 v133, v178, v119
	v_fma_f32 v178, v178, v118, -v132
	v_fma_f32 v179, v179, v118, v133
	v_mul_f32_e32 v132, v181, v123
	v_mul_f32_e32 v133, v180, v123
	v_fma_f32 v180, v180, v122, -v132
	v_fma_f32 v181, v181, v122, v133
	v_mul_f32_e32 v132, v183, v127
	v_mul_f32_e32 v133, v182, v127
	v_fma_f32 v182, v182, v126, -v132
	v_fma_f32 v183, v183, v126, v133
	v_mul_f32_e32 v132, v185, v131
	v_mul_f32_e32 v133, v184, v131
	v_fma_f32 v184, v184, v130, -v132
	v_fma_f32 v185, v185, v130, v133
	v_mul_f32_e32 v132, v56, v101
	v_mul_f32_e32 v56, v56, v100
	v_fma_f32 v56, -v60, v101, v56
	v_fma_f32 v60, v60, v100, v132
	v_mul_f32_e32 v133, v57, v105
	v_mul_f32_e32 v57, v57, v104
	v_fma_f32 v57, -v61, v105, v57
	v_fma_f32 v61, v61, v104, v133
	v_mul_f32_e32 v132, v58, v109
	v_mul_f32_e32 v58, v58, v108
	v_fma_f32 v58, -v62, v109, v58
	v_fma_f32 v62, v62, v108, v132
	v_mul_f32_e32 v133, v59, v113
	v_mul_f32_e32 v59, v59, v112
	v_fma_f32 v59, -v63, v113, v59
	v_fma_f32 v63, v63, v112, v133
	v_mov_b32_e32 v88, v56
	v_mov_b32_e32 v89, v57
	v_mov_b32_e32 v90, v58
	v_mov_b32_e32 v91, v59
	v_mov_b32_e32 v92, v60
	v_mov_b32_e32 v93, v61
	v_mov_b32_e32 v94, v62
	v_mov_b32_e32 v95, v63
	v_add_f32_dpp v56, v56, v56 row_shl:1 row_mask:0xf bank_mask:0xf bound_ctrl:1
	v_add_f32_dpp v57, v57, v57 row_shl:1 row_mask:0xf bank_mask:0xf bound_ctrl:1
	v_add_f32_dpp v58, v58, v58 row_shl:1 row_mask:0xf bank_mask:0xf bound_ctrl:1
	v_add_f32_dpp v59, v59, v59 row_shl:1 row_mask:0xf bank_mask:0xf bound_ctrl:1
	v_add_f32_dpp v60, v60, v60 row_shl:1 row_mask:0xf bank_mask:0xf bound_ctrl:1
	v_add_f32_dpp v61, v61, v61 row_shl:1 row_mask:0xf bank_mask:0xf bound_ctrl:1
	v_add_f32_dpp v62, v62, v62 row_shl:1 row_mask:0xf bank_mask:0xf bound_ctrl:1
	v_add_f32_dpp v63, v63, v63 row_shl:1 row_mask:0xf bank_mask:0xf bound_ctrl:1
	v_add_f32_dpp v88, v88, v88 row_ror:8 row_mask:0xf bank_mask:0xf
	v_add_f32_dpp v89, v89, v89 row_ror:8 row_mask:0xf bank_mask:0xf
	v_add_f32_dpp v90, v90, v90 row_ror:8 row_mask:0xf bank_mask:0xf
	v_add_f32_dpp v91, v91, v91 row_ror:8 row_mask:0xf bank_mask:0xf
	v_add_f32_dpp v92, v92, v92 row_ror:8 row_mask:0xf bank_mask:0xf
	v_add_f32_dpp v93, v93, v93 row_ror:8 row_mask:0xf bank_mask:0xf
	v_add_f32_dpp v94, v94, v94 row_ror:8 row_mask:0xf bank_mask:0xf
	v_add_f32_dpp v95, v95, v95 row_ror:8 row_mask:0xf bank_mask:0xf
	v_add_f32_dpp v56, v56, v56 row_shl:2 row_mask:0xf bank_mask:0xf bound_ctrl:1
	v_add_f32_dpp v57, v57, v57 row_shl:2 row_mask:0xf bank_mask:0xf bound_ctrl:1
	v_add_f32_dpp v58, v58, v58 row_shl:2 row_mask:0xf bank_mask:0xf bound_ctrl:1
	v_add_f32_dpp v59, v59, v59 row_shl:2 row_mask:0xf bank_mask:0xf bound_ctrl:1
	v_add_f32_dpp v60, v60, v60 row_shl:2 row_mask:0xf bank_mask:0xf bound_ctrl:1
	v_add_f32_dpp v61, v61, v61 row_shl:2 row_mask:0xf bank_mask:0xf bound_ctrl:1
	v_add_f32_dpp v62, v62, v62 row_shl:2 row_mask:0xf bank_mask:0xf bound_ctrl:1
	v_add_f32_dpp v63, v63, v63 row_shl:2 row_mask:0xf bank_mask:0xf bound_ctrl:1
	v_add_f32_dpp v88, v88, v88 row_ror:4 row_mask:0xf bank_mask:0xf
	v_add_f32_dpp v89, v89, v89 row_ror:4 row_mask:0xf bank_mask:0xf
	v_add_f32_dpp v90, v90, v90 row_ror:4 row_mask:0xf bank_mask:0xf
	v_add_f32_dpp v91, v91, v91 row_ror:4 row_mask:0xf bank_mask:0xf
	v_add_f32_dpp v92, v92, v92 row_ror:4 row_mask:0xf bank_mask:0xf
	v_add_f32_dpp v93, v93, v93 row_ror:4 row_mask:0xf bank_mask:0xf
	v_add_f32_dpp v94, v94, v94 row_ror:4 row_mask:0xf bank_mask:0xf
	v_add_f32_dpp v95, v95, v95 row_ror:4 row_mask:0xf bank_mask:0xf
	v_add_f32_dpp v56, v56, v56 row_shl:4 row_mask:0xf bank_mask:0xf bound_ctrl:1
	v_add_f32_dpp v57, v57, v57 row_shl:4 row_mask:0xf bank_mask:0xf bound_ctrl:1
	v_add_f32_dpp v58, v58, v58 row_shl:4 row_mask:0xf bank_mask:0xf bound_ctrl:1
	v_add_f32_dpp v59, v59, v59 row_shl:4 row_mask:0xf bank_mask:0xf bound_ctrl:1
	v_add_f32_dpp v60, v60, v60 row_shl:4 row_mask:0xf bank_mask:0xf bound_ctrl:1
	v_add_f32_dpp v61, v61, v61 row_shl:4 row_mask:0xf bank_mask:0xf bound_ctrl:1
	v_add_f32_dpp v62, v62, v62 row_shl:4 row_mask:0xf bank_mask:0xf bound_ctrl:1
	v_add_f32_dpp v63, v63, v63 row_shl:4 row_mask:0xf bank_mask:0xf bound_ctrl:1
	v_add_f32_dpp v88, v88, v88 row_ror:2 row_mask:0xf bank_mask:0xf
	v_add_f32_dpp v89, v89, v89 row_ror:2 row_mask:0xf bank_mask:0xf
	v_add_f32_dpp v90, v90, v90 row_ror:2 row_mask:0xf bank_mask:0xf
	v_add_f32_dpp v91, v91, v91 row_ror:2 row_mask:0xf bank_mask:0xf
	v_add_f32_dpp v92, v92, v92 row_ror:2 row_mask:0xf bank_mask:0xf
	v_add_f32_dpp v93, v93, v93 row_ror:2 row_mask:0xf bank_mask:0xf
	v_add_f32_dpp v94, v94, v94 row_ror:2 row_mask:0xf bank_mask:0xf
	v_add_f32_dpp v95, v95, v95 row_ror:2 row_mask:0xf bank_mask:0xf
	v_add_f32_dpp v56, v56, v56 row_shl:8 row_mask:0xf bank_mask:0xf bound_ctrl:1
	v_add_f32_dpp v57, v57, v57 row_shl:8 row_mask:0xf bank_mask:0xf bound_ctrl:1
	v_add_f32_dpp v58, v58, v58 row_shl:8 row_mask:0xf bank_mask:0xf bound_ctrl:1
	v_add_f32_dpp v59, v59, v59 row_shl:8 row_mask:0xf bank_mask:0xf bound_ctrl:1
	v_add_f32_dpp v60, v60, v60 row_shl:8 row_mask:0xf bank_mask:0xf bound_ctrl:1
	v_add_f32_dpp v61, v61, v61 row_shl:8 row_mask:0xf bank_mask:0xf bound_ctrl:1
	v_add_f32_dpp v62, v62, v62 row_shl:8 row_mask:0xf bank_mask:0xf bound_ctrl:1
	v_add_f32_dpp v63, v63, v63 row_shl:8 row_mask:0xf bank_mask:0xf bound_ctrl:1
	v_add_f32_dpp v88, v88, v88 row_ror:1 row_mask:0xf bank_mask:0xf
	v_add_f32_dpp v89, v89, v89 row_ror:1 row_mask:0xf bank_mask:0xf
	v_add_f32_dpp v90, v90, v90 row_ror:1 row_mask:0xf bank_mask:0xf
	v_add_f32_dpp v91, v91, v91 row_ror:1 row_mask:0xf bank_mask:0xf
	v_add_f32_dpp v92, v92, v92 row_ror:1 row_mask:0xf bank_mask:0xf
	v_add_f32_dpp v93, v93, v93 row_ror:1 row_mask:0xf bank_mask:0xf
	v_add_f32_dpp v94, v94, v94 row_ror:1 row_mask:0xf bank_mask:0xf
	v_add_f32_dpp v95, v95, v95 row_ror:1 row_mask:0xf bank_mask:0xf
	v_add_f32_e32 v56, v56, v178
	v_add_f32_e32 v60, v60, v179
	v_add_f32_e32 v57, v57, v180
	v_add_f32_e32 v61, v61, v181
	v_add_f32_e32 v58, v58, v182
	v_add_f32_e32 v62, v62, v183
	v_add_f32_e32 v59, v59, v184
	v_add_f32_e32 v63, v63, v185
	v_mul_f32_e32 v132, v56, v103
	v_mul_f32_e32 v56, v56, v102
	v_fma_f32 v56, -v60, v103, v56
	v_fma_f32 v60, v60, v102, v132
	v_mul_f32_e32 v133, v57, v107
	v_mul_f32_e32 v57, v57, v106
	v_fma_f32 v57, -v61, v107, v57
	v_fma_f32 v61, v61, v106, v133
	v_mul_f32_e32 v132, v58, v111
	v_mul_f32_e32 v58, v58, v110
	v_fma_f32 v58, -v62, v111, v58
	v_fma_f32 v62, v62, v110, v132
	v_mul_f32_e32 v133, v59, v115
	v_mul_f32_e32 v59, v59, v114
	v_fma_f32 v59, -v63, v115, v59
	v_fma_f32 v63, v63, v114, v133
	v_add_f32_e32 v88, v88, v178
	v_add_f32_e32 v92, v92, v179
	v_mul_f32_e32 v132, v92, v117
	v_mul_f32_e32 v179, v88, v117
	v_fma_f32 v178, v88, v116, -v132
	v_fma_f32 v179, v92, v116, v179
	v_add_f32_e32 v89, v89, v180
	v_add_f32_e32 v93, v93, v181
	v_mul_f32_e32 v133, v93, v121
	v_mul_f32_e32 v181, v89, v121
	v_fma_f32 v180, v89, v120, -v133
	v_fma_f32 v181, v93, v120, v181
	v_add_f32_e32 v90, v90, v182
	v_add_f32_e32 v94, v94, v183
	v_mul_f32_e32 v132, v94, v125
	v_mul_f32_e32 v183, v90, v125
	v_fma_f32 v182, v90, v124, -v132
	v_fma_f32 v183, v94, v124, v183
	v_add_f32_e32 v91, v91, v184
	v_add_f32_e32 v95, v95, v185
	v_mul_f32_e32 v133, v95, v129
	v_mul_f32_e32 v185, v91, v129
	v_fma_f32 v184, v91, v128, -v133
	v_fma_f32 v185, v95, v128, v185
	v_mul_f32_e32 v132, v48, v101
	v_mul_f32_e32 v48, v48, v100
	v_fma_f32 v48, -v52, v101, v48
	v_fma_f32 v52, v52, v100, v132
	v_mul_f32_e32 v133, v49, v105
	v_mul_f32_e32 v49, v49, v104
	v_fma_f32 v49, -v53, v105, v49
	v_fma_f32 v53, v53, v104, v133
	v_mul_f32_e32 v132, v50, v109
	v_mul_f32_e32 v50, v50, v108
	v_fma_f32 v50, -v54, v109, v50
	v_fma_f32 v54, v54, v108, v132
	v_mul_f32_e32 v133, v51, v113
	v_mul_f32_e32 v51, v51, v112
	v_fma_f32 v51, -v55, v113, v51
	v_fma_f32 v55, v55, v112, v133
	v_mov_b32_e32 v88, v48
	v_mov_b32_e32 v89, v49
	v_mov_b32_e32 v90, v50
	v_mov_b32_e32 v91, v51
	v_mov_b32_e32 v92, v52
	v_mov_b32_e32 v93, v53
	v_mov_b32_e32 v94, v54
	v_mov_b32_e32 v95, v55
	v_add_f32_dpp v48, v48, v48 row_shl:1 row_mask:0xf bank_mask:0xf bound_ctrl:1
	v_add_f32_dpp v49, v49, v49 row_shl:1 row_mask:0xf bank_mask:0xf bound_ctrl:1
	v_add_f32_dpp v50, v50, v50 row_shl:1 row_mask:0xf bank_mask:0xf bound_ctrl:1
	v_add_f32_dpp v51, v51, v51 row_shl:1 row_mask:0xf bank_mask:0xf bound_ctrl:1
	v_add_f32_dpp v52, v52, v52 row_shl:1 row_mask:0xf bank_mask:0xf bound_ctrl:1
	v_add_f32_dpp v53, v53, v53 row_shl:1 row_mask:0xf bank_mask:0xf bound_ctrl:1
	v_add_f32_dpp v54, v54, v54 row_shl:1 row_mask:0xf bank_mask:0xf bound_ctrl:1
	v_add_f32_dpp v55, v55, v55 row_shl:1 row_mask:0xf bank_mask:0xf bound_ctrl:1
	v_add_f32_dpp v88, v88, v88 row_ror:8 row_mask:0xf bank_mask:0xf
	v_add_f32_dpp v89, v89, v89 row_ror:8 row_mask:0xf bank_mask:0xf
	v_add_f32_dpp v90, v90, v90 row_ror:8 row_mask:0xf bank_mask:0xf
	v_add_f32_dpp v91, v91, v91 row_ror:8 row_mask:0xf bank_mask:0xf
	v_add_f32_dpp v92, v92, v92 row_ror:8 row_mask:0xf bank_mask:0xf
	v_add_f32_dpp v93, v93, v93 row_ror:8 row_mask:0xf bank_mask:0xf
	v_add_f32_dpp v94, v94, v94 row_ror:8 row_mask:0xf bank_mask:0xf
	v_add_f32_dpp v95, v95, v95 row_ror:8 row_mask:0xf bank_mask:0xf
	v_add_f32_dpp v48, v48, v48 row_shl:2 row_mask:0xf bank_mask:0xf bound_ctrl:1
	v_add_f32_dpp v49, v49, v49 row_shl:2 row_mask:0xf bank_mask:0xf bound_ctrl:1
	v_add_f32_dpp v50, v50, v50 row_shl:2 row_mask:0xf bank_mask:0xf bound_ctrl:1
	v_add_f32_dpp v51, v51, v51 row_shl:2 row_mask:0xf bank_mask:0xf bound_ctrl:1
	v_add_f32_dpp v52, v52, v52 row_shl:2 row_mask:0xf bank_mask:0xf bound_ctrl:1
	v_add_f32_dpp v53, v53, v53 row_shl:2 row_mask:0xf bank_mask:0xf bound_ctrl:1
	v_add_f32_dpp v54, v54, v54 row_shl:2 row_mask:0xf bank_mask:0xf bound_ctrl:1
	v_add_f32_dpp v55, v55, v55 row_shl:2 row_mask:0xf bank_mask:0xf bound_ctrl:1
	v_add_f32_dpp v88, v88, v88 row_ror:4 row_mask:0xf bank_mask:0xf
	v_add_f32_dpp v89, v89, v89 row_ror:4 row_mask:0xf bank_mask:0xf
	v_add_f32_dpp v90, v90, v90 row_ror:4 row_mask:0xf bank_mask:0xf
	v_add_f32_dpp v91, v91, v91 row_ror:4 row_mask:0xf bank_mask:0xf
	v_add_f32_dpp v92, v92, v92 row_ror:4 row_mask:0xf bank_mask:0xf
	v_add_f32_dpp v93, v93, v93 row_ror:4 row_mask:0xf bank_mask:0xf
	v_add_f32_dpp v94, v94, v94 row_ror:4 row_mask:0xf bank_mask:0xf
	v_add_f32_dpp v95, v95, v95 row_ror:4 row_mask:0xf bank_mask:0xf
	v_add_f32_dpp v48, v48, v48 row_shl:4 row_mask:0xf bank_mask:0xf bound_ctrl:1
	v_add_f32_dpp v49, v49, v49 row_shl:4 row_mask:0xf bank_mask:0xf bound_ctrl:1
	v_add_f32_dpp v50, v50, v50 row_shl:4 row_mask:0xf bank_mask:0xf bound_ctrl:1
	v_add_f32_dpp v51, v51, v51 row_shl:4 row_mask:0xf bank_mask:0xf bound_ctrl:1
	v_add_f32_dpp v52, v52, v52 row_shl:4 row_mask:0xf bank_mask:0xf bound_ctrl:1
	v_add_f32_dpp v53, v53, v53 row_shl:4 row_mask:0xf bank_mask:0xf bound_ctrl:1
	v_add_f32_dpp v54, v54, v54 row_shl:4 row_mask:0xf bank_mask:0xf bound_ctrl:1
	v_add_f32_dpp v55, v55, v55 row_shl:4 row_mask:0xf bank_mask:0xf bound_ctrl:1
	v_add_f32_dpp v88, v88, v88 row_ror:2 row_mask:0xf bank_mask:0xf
	v_add_f32_dpp v89, v89, v89 row_ror:2 row_mask:0xf bank_mask:0xf
	v_add_f32_dpp v90, v90, v90 row_ror:2 row_mask:0xf bank_mask:0xf
	v_add_f32_dpp v91, v91, v91 row_ror:2 row_mask:0xf bank_mask:0xf
	v_add_f32_dpp v92, v92, v92 row_ror:2 row_mask:0xf bank_mask:0xf
	v_add_f32_dpp v93, v93, v93 row_ror:2 row_mask:0xf bank_mask:0xf
	v_add_f32_dpp v94, v94, v94 row_ror:2 row_mask:0xf bank_mask:0xf
	v_add_f32_dpp v95, v95, v95 row_ror:2 row_mask:0xf bank_mask:0xf
	v_add_f32_dpp v48, v48, v48 row_shl:8 row_mask:0xf bank_mask:0xf bound_ctrl:1
	v_add_f32_dpp v49, v49, v49 row_shl:8 row_mask:0xf bank_mask:0xf bound_ctrl:1
	v_add_f32_dpp v50, v50, v50 row_shl:8 row_mask:0xf bank_mask:0xf bound_ctrl:1
	v_add_f32_dpp v51, v51, v51 row_shl:8 row_mask:0xf bank_mask:0xf bound_ctrl:1
	v_add_f32_dpp v52, v52, v52 row_shl:8 row_mask:0xf bank_mask:0xf bound_ctrl:1
	v_add_f32_dpp v53, v53, v53 row_shl:8 row_mask:0xf bank_mask:0xf bound_ctrl:1
	v_add_f32_dpp v54, v54, v54 row_shl:8 row_mask:0xf bank_mask:0xf bound_ctrl:1
	v_add_f32_dpp v55, v55, v55 row_shl:8 row_mask:0xf bank_mask:0xf bound_ctrl:1
	v_add_f32_dpp v88, v88, v88 row_ror:1 row_mask:0xf bank_mask:0xf
	v_add_f32_dpp v89, v89, v89 row_ror:1 row_mask:0xf bank_mask:0xf
	v_add_f32_dpp v90, v90, v90 row_ror:1 row_mask:0xf bank_mask:0xf
	v_add_f32_dpp v91, v91, v91 row_ror:1 row_mask:0xf bank_mask:0xf
	v_add_f32_dpp v92, v92, v92 row_ror:1 row_mask:0xf bank_mask:0xf
	v_add_f32_dpp v93, v93, v93 row_ror:1 row_mask:0xf bank_mask:0xf
	v_add_f32_dpp v94, v94, v94 row_ror:1 row_mask:0xf bank_mask:0xf
	v_add_f32_dpp v95, v95, v95 row_ror:1 row_mask:0xf bank_mask:0xf
	v_add_f32_e32 v48, v48, v178
	v_add_f32_e32 v52, v52, v179
	v_add_f32_e32 v49, v49, v180
	v_add_f32_e32 v53, v53, v181
	v_add_f32_e32 v50, v50, v182
	v_add_f32_e32 v54, v54, v183
	v_add_f32_e32 v51, v51, v184
	v_add_f32_e32 v55, v55, v185
	v_mul_f32_e32 v132, v48, v103
	v_mul_f32_e32 v48, v48, v102
	v_fma_f32 v48, -v52, v103, v48
	v_fma_f32 v52, v52, v102, v132
	v_mul_f32_e32 v133, v49, v107
	v_mul_f32_e32 v49, v49, v106
	v_fma_f32 v49, -v53, v107, v49
	v_fma_f32 v53, v53, v106, v133
	v_mul_f32_e32 v132, v50, v111
	v_mul_f32_e32 v50, v50, v110
	v_fma_f32 v50, -v54, v111, v50
	v_fma_f32 v54, v54, v110, v132
	v_mul_f32_e32 v133, v51, v115
	v_mul_f32_e32 v51, v51, v114
	v_fma_f32 v51, -v55, v115, v51
	v_fma_f32 v55, v55, v114, v133
	v_add_f32_e32 v88, v88, v178
	v_add_f32_e32 v92, v92, v179
	v_mul_f32_e32 v132, v92, v117
	v_mul_f32_e32 v179, v88, v117
	v_fma_f32 v178, v88, v116, -v132
	v_fma_f32 v179, v92, v116, v179
	v_add_f32_e32 v89, v89, v180
	v_add_f32_e32 v93, v93, v181
	v_mul_f32_e32 v133, v93, v121
	v_mul_f32_e32 v181, v89, v121
	v_fma_f32 v180, v89, v120, -v133
	v_fma_f32 v181, v93, v120, v181
	v_add_f32_e32 v90, v90, v182
	v_add_f32_e32 v94, v94, v183
	v_mul_f32_e32 v132, v94, v125
	v_mul_f32_e32 v183, v90, v125
	v_fma_f32 v182, v90, v124, -v132
	v_fma_f32 v183, v94, v124, v183
	v_add_f32_e32 v91, v91, v184
	v_add_f32_e32 v95, v95, v185
	v_mul_f32_e32 v133, v95, v129
	v_mul_f32_e32 v185, v91, v129
	v_fma_f32 v184, v91, v128, -v133
	v_fma_f32 v185, v95, v128, v185
	v_mul_f32_e32 v132, v40, v101
	v_mul_f32_e32 v40, v40, v100
	v_fma_f32 v40, -v44, v101, v40
	v_fma_f32 v44, v44, v100, v132
	v_mul_f32_e32 v133, v41, v105
	v_mul_f32_e32 v41, v41, v104
	v_fma_f32 v41, -v45, v105, v41
	v_fma_f32 v45, v45, v104, v133
	v_mul_f32_e32 v132, v42, v109
	v_mul_f32_e32 v42, v42, v108
	v_fma_f32 v42, -v46, v109, v42
	v_fma_f32 v46, v46, v108, v132
	v_mul_f32_e32 v133, v43, v113
	v_mul_f32_e32 v43, v43, v112
	v_fma_f32 v43, -v47, v113, v43
	v_fma_f32 v47, v47, v112, v133
	v_mov_b32_e32 v88, v40
	v_mov_b32_e32 v89, v41
	v_mov_b32_e32 v90, v42
	v_mov_b32_e32 v91, v43
	v_mov_b32_e32 v92, v44
	v_mov_b32_e32 v93, v45
	v_mov_b32_e32 v94, v46
	v_mov_b32_e32 v95, v47
	v_add_f32_dpp v40, v40, v40 row_shl:1 row_mask:0xf bank_mask:0xf bound_ctrl:1
	v_add_f32_dpp v41, v41, v41 row_shl:1 row_mask:0xf bank_mask:0xf bound_ctrl:1
	v_add_f32_dpp v42, v42, v42 row_shl:1 row_mask:0xf bank_mask:0xf bound_ctrl:1
	v_add_f32_dpp v43, v43, v43 row_shl:1 row_mask:0xf bank_mask:0xf bound_ctrl:1
	v_add_f32_dpp v44, v44, v44 row_shl:1 row_mask:0xf bank_mask:0xf bound_ctrl:1
	v_add_f32_dpp v45, v45, v45 row_shl:1 row_mask:0xf bank_mask:0xf bound_ctrl:1
	v_add_f32_dpp v46, v46, v46 row_shl:1 row_mask:0xf bank_mask:0xf bound_ctrl:1
	v_add_f32_dpp v47, v47, v47 row_shl:1 row_mask:0xf bank_mask:0xf bound_ctrl:1
	v_add_f32_dpp v88, v88, v88 row_ror:8 row_mask:0xf bank_mask:0xf
	v_add_f32_dpp v89, v89, v89 row_ror:8 row_mask:0xf bank_mask:0xf
	v_add_f32_dpp v90, v90, v90 row_ror:8 row_mask:0xf bank_mask:0xf
	v_add_f32_dpp v91, v91, v91 row_ror:8 row_mask:0xf bank_mask:0xf
	v_add_f32_dpp v92, v92, v92 row_ror:8 row_mask:0xf bank_mask:0xf
	v_add_f32_dpp v93, v93, v93 row_ror:8 row_mask:0xf bank_mask:0xf
	v_add_f32_dpp v94, v94, v94 row_ror:8 row_mask:0xf bank_mask:0xf
	v_add_f32_dpp v95, v95, v95 row_ror:8 row_mask:0xf bank_mask:0xf
	v_add_f32_dpp v40, v40, v40 row_shl:2 row_mask:0xf bank_mask:0xf bound_ctrl:1
	v_add_f32_dpp v41, v41, v41 row_shl:2 row_mask:0xf bank_mask:0xf bound_ctrl:1
	v_add_f32_dpp v42, v42, v42 row_shl:2 row_mask:0xf bank_mask:0xf bound_ctrl:1
	v_add_f32_dpp v43, v43, v43 row_shl:2 row_mask:0xf bank_mask:0xf bound_ctrl:1
	v_add_f32_dpp v44, v44, v44 row_shl:2 row_mask:0xf bank_mask:0xf bound_ctrl:1
	v_add_f32_dpp v45, v45, v45 row_shl:2 row_mask:0xf bank_mask:0xf bound_ctrl:1
	v_add_f32_dpp v46, v46, v46 row_shl:2 row_mask:0xf bank_mask:0xf bound_ctrl:1
	v_add_f32_dpp v47, v47, v47 row_shl:2 row_mask:0xf bank_mask:0xf bound_ctrl:1
	v_add_f32_dpp v88, v88, v88 row_ror:4 row_mask:0xf bank_mask:0xf
	v_add_f32_dpp v89, v89, v89 row_ror:4 row_mask:0xf bank_mask:0xf
	v_add_f32_dpp v90, v90, v90 row_ror:4 row_mask:0xf bank_mask:0xf
	v_add_f32_dpp v91, v91, v91 row_ror:4 row_mask:0xf bank_mask:0xf
	v_add_f32_dpp v92, v92, v92 row_ror:4 row_mask:0xf bank_mask:0xf
	v_add_f32_dpp v93, v93, v93 row_ror:4 row_mask:0xf bank_mask:0xf
	v_add_f32_dpp v94, v94, v94 row_ror:4 row_mask:0xf bank_mask:0xf
	v_add_f32_dpp v95, v95, v95 row_ror:4 row_mask:0xf bank_mask:0xf
	v_add_f32_dpp v40, v40, v40 row_shl:4 row_mask:0xf bank_mask:0xf bound_ctrl:1
	v_add_f32_dpp v41, v41, v41 row_shl:4 row_mask:0xf bank_mask:0xf bound_ctrl:1
	v_add_f32_dpp v42, v42, v42 row_shl:4 row_mask:0xf bank_mask:0xf bound_ctrl:1
	v_add_f32_dpp v43, v43, v43 row_shl:4 row_mask:0xf bank_mask:0xf bound_ctrl:1
	v_add_f32_dpp v44, v44, v44 row_shl:4 row_mask:0xf bank_mask:0xf bound_ctrl:1
	v_add_f32_dpp v45, v45, v45 row_shl:4 row_mask:0xf bank_mask:0xf bound_ctrl:1
	v_add_f32_dpp v46, v46, v46 row_shl:4 row_mask:0xf bank_mask:0xf bound_ctrl:1
	v_add_f32_dpp v47, v47, v47 row_shl:4 row_mask:0xf bank_mask:0xf bound_ctrl:1
	v_add_f32_dpp v88, v88, v88 row_ror:2 row_mask:0xf bank_mask:0xf
	v_add_f32_dpp v89, v89, v89 row_ror:2 row_mask:0xf bank_mask:0xf
	v_add_f32_dpp v90, v90, v90 row_ror:2 row_mask:0xf bank_mask:0xf
	v_add_f32_dpp v91, v91, v91 row_ror:2 row_mask:0xf bank_mask:0xf
	v_add_f32_dpp v92, v92, v92 row_ror:2 row_mask:0xf bank_mask:0xf
	v_add_f32_dpp v93, v93, v93 row_ror:2 row_mask:0xf bank_mask:0xf
	v_add_f32_dpp v94, v94, v94 row_ror:2 row_mask:0xf bank_mask:0xf
	v_add_f32_dpp v95, v95, v95 row_ror:2 row_mask:0xf bank_mask:0xf
	v_add_f32_dpp v40, v40, v40 row_shl:8 row_mask:0xf bank_mask:0xf bound_ctrl:1
	v_add_f32_dpp v41, v41, v41 row_shl:8 row_mask:0xf bank_mask:0xf bound_ctrl:1
	v_add_f32_dpp v42, v42, v42 row_shl:8 row_mask:0xf bank_mask:0xf bound_ctrl:1
	v_add_f32_dpp v43, v43, v43 row_shl:8 row_mask:0xf bank_mask:0xf bound_ctrl:1
	v_add_f32_dpp v44, v44, v44 row_shl:8 row_mask:0xf bank_mask:0xf bound_ctrl:1
	v_add_f32_dpp v45, v45, v45 row_shl:8 row_mask:0xf bank_mask:0xf bound_ctrl:1
	v_add_f32_dpp v46, v46, v46 row_shl:8 row_mask:0xf bank_mask:0xf bound_ctrl:1
	v_add_f32_dpp v47, v47, v47 row_shl:8 row_mask:0xf bank_mask:0xf bound_ctrl:1
	v_add_f32_dpp v88, v88, v88 row_ror:1 row_mask:0xf bank_mask:0xf
	v_add_f32_dpp v89, v89, v89 row_ror:1 row_mask:0xf bank_mask:0xf
	v_add_f32_dpp v90, v90, v90 row_ror:1 row_mask:0xf bank_mask:0xf
	v_add_f32_dpp v91, v91, v91 row_ror:1 row_mask:0xf bank_mask:0xf
	v_add_f32_dpp v92, v92, v92 row_ror:1 row_mask:0xf bank_mask:0xf
	v_add_f32_dpp v93, v93, v93 row_ror:1 row_mask:0xf bank_mask:0xf
	v_add_f32_dpp v94, v94, v94 row_ror:1 row_mask:0xf bank_mask:0xf
	v_add_f32_dpp v95, v95, v95 row_ror:1 row_mask:0xf bank_mask:0xf
	v_add_f32_e32 v40, v40, v178
	v_add_f32_e32 v44, v44, v179
	v_add_f32_e32 v41, v41, v180
	v_add_f32_e32 v45, v45, v181
	v_add_f32_e32 v42, v42, v182
	v_add_f32_e32 v46, v46, v183
	v_add_f32_e32 v43, v43, v184
	v_add_f32_e32 v47, v47, v185
	v_mul_f32_e32 v132, v40, v103
	v_mul_f32_e32 v40, v40, v102
	v_fma_f32 v40, -v44, v103, v40
	v_fma_f32 v44, v44, v102, v132
	v_mul_f32_e32 v133, v41, v107
	v_mul_f32_e32 v41, v41, v106
	v_fma_f32 v41, -v45, v107, v41
	v_fma_f32 v45, v45, v106, v133
	v_mul_f32_e32 v132, v42, v111
	v_mul_f32_e32 v42, v42, v110
	v_fma_f32 v42, -v46, v111, v42
	v_fma_f32 v46, v46, v110, v132
	v_mul_f32_e32 v133, v43, v115
	v_mul_f32_e32 v43, v43, v114
	v_fma_f32 v43, -v47, v115, v43
	v_fma_f32 v47, v47, v114, v133
	v_add_f32_e32 v88, v88, v178
	v_add_f32_e32 v92, v92, v179
	v_mul_f32_e32 v132, v92, v117
	v_mul_f32_e32 v179, v88, v117
	v_fma_f32 v178, v88, v116, -v132
	v_fma_f32 v179, v92, v116, v179
	v_add_f32_e32 v89, v89, v180
	v_add_f32_e32 v93, v93, v181
	v_mul_f32_e32 v133, v93, v121
	v_mul_f32_e32 v181, v89, v121
	v_fma_f32 v180, v89, v120, -v133
	v_fma_f32 v181, v93, v120, v181
	v_add_f32_e32 v90, v90, v182
	v_add_f32_e32 v94, v94, v183
	v_mul_f32_e32 v132, v94, v125
	v_mul_f32_e32 v183, v90, v125
	v_fma_f32 v182, v90, v124, -v132
	v_fma_f32 v183, v94, v124, v183
	v_add_f32_e32 v91, v91, v184
	v_add_f32_e32 v95, v95, v185
	v_mul_f32_e32 v133, v95, v129
	v_mul_f32_e32 v185, v91, v129
	v_fma_f32 v184, v91, v128, -v133
	v_fma_f32 v185, v95, v128, v185
	v_mul_f32_e32 v132, v32, v101
	v_mul_f32_e32 v32, v32, v100
	v_fma_f32 v32, -v36, v101, v32
	v_fma_f32 v36, v36, v100, v132
	v_mul_f32_e32 v133, v33, v105
	v_mul_f32_e32 v33, v33, v104
	v_fma_f32 v33, -v37, v105, v33
	v_fma_f32 v37, v37, v104, v133
	v_mul_f32_e32 v132, v34, v109
	v_mul_f32_e32 v34, v34, v108
	v_fma_f32 v34, -v38, v109, v34
	v_fma_f32 v38, v38, v108, v132
	v_mul_f32_e32 v133, v35, v113
	v_mul_f32_e32 v35, v35, v112
	v_fma_f32 v35, -v39, v113, v35
	v_fma_f32 v39, v39, v112, v133
	v_mov_b32_e32 v88, v32
	v_mov_b32_e32 v89, v33
	v_mov_b32_e32 v90, v34
	v_mov_b32_e32 v91, v35
	v_mov_b32_e32 v92, v36
	v_mov_b32_e32 v93, v37
	v_mov_b32_e32 v94, v38
	v_mov_b32_e32 v95, v39
	v_add_f32_dpp v32, v32, v32 row_shl:1 row_mask:0xf bank_mask:0xf bound_ctrl:1
	v_add_f32_dpp v33, v33, v33 row_shl:1 row_mask:0xf bank_mask:0xf bound_ctrl:1
	v_add_f32_dpp v34, v34, v34 row_shl:1 row_mask:0xf bank_mask:0xf bound_ctrl:1
	v_add_f32_dpp v35, v35, v35 row_shl:1 row_mask:0xf bank_mask:0xf bound_ctrl:1
	v_add_f32_dpp v36, v36, v36 row_shl:1 row_mask:0xf bank_mask:0xf bound_ctrl:1
	v_add_f32_dpp v37, v37, v37 row_shl:1 row_mask:0xf bank_mask:0xf bound_ctrl:1
	v_add_f32_dpp v38, v38, v38 row_shl:1 row_mask:0xf bank_mask:0xf bound_ctrl:1
	v_add_f32_dpp v39, v39, v39 row_shl:1 row_mask:0xf bank_mask:0xf bound_ctrl:1
	v_add_f32_dpp v88, v88, v88 row_ror:8 row_mask:0xf bank_mask:0xf
	v_add_f32_dpp v89, v89, v89 row_ror:8 row_mask:0xf bank_mask:0xf
	v_add_f32_dpp v90, v90, v90 row_ror:8 row_mask:0xf bank_mask:0xf
	v_add_f32_dpp v91, v91, v91 row_ror:8 row_mask:0xf bank_mask:0xf
	v_add_f32_dpp v92, v92, v92 row_ror:8 row_mask:0xf bank_mask:0xf
	v_add_f32_dpp v93, v93, v93 row_ror:8 row_mask:0xf bank_mask:0xf
	v_add_f32_dpp v94, v94, v94 row_ror:8 row_mask:0xf bank_mask:0xf
	v_add_f32_dpp v95, v95, v95 row_ror:8 row_mask:0xf bank_mask:0xf
	v_add_f32_dpp v32, v32, v32 row_shl:2 row_mask:0xf bank_mask:0xf bound_ctrl:1
	v_add_f32_dpp v33, v33, v33 row_shl:2 row_mask:0xf bank_mask:0xf bound_ctrl:1
	v_add_f32_dpp v34, v34, v34 row_shl:2 row_mask:0xf bank_mask:0xf bound_ctrl:1
	v_add_f32_dpp v35, v35, v35 row_shl:2 row_mask:0xf bank_mask:0xf bound_ctrl:1
	v_add_f32_dpp v36, v36, v36 row_shl:2 row_mask:0xf bank_mask:0xf bound_ctrl:1
	v_add_f32_dpp v37, v37, v37 row_shl:2 row_mask:0xf bank_mask:0xf bound_ctrl:1
	v_add_f32_dpp v38, v38, v38 row_shl:2 row_mask:0xf bank_mask:0xf bound_ctrl:1
	v_add_f32_dpp v39, v39, v39 row_shl:2 row_mask:0xf bank_mask:0xf bound_ctrl:1
	v_add_f32_dpp v88, v88, v88 row_ror:4 row_mask:0xf bank_mask:0xf
	v_add_f32_dpp v89, v89, v89 row_ror:4 row_mask:0xf bank_mask:0xf
	v_add_f32_dpp v90, v90, v90 row_ror:4 row_mask:0xf bank_mask:0xf
	v_add_f32_dpp v91, v91, v91 row_ror:4 row_mask:0xf bank_mask:0xf
	v_add_f32_dpp v92, v92, v92 row_ror:4 row_mask:0xf bank_mask:0xf
	v_add_f32_dpp v93, v93, v93 row_ror:4 row_mask:0xf bank_mask:0xf
	v_add_f32_dpp v94, v94, v94 row_ror:4 row_mask:0xf bank_mask:0xf
	v_add_f32_dpp v95, v95, v95 row_ror:4 row_mask:0xf bank_mask:0xf
	v_add_f32_dpp v32, v32, v32 row_shl:4 row_mask:0xf bank_mask:0xf bound_ctrl:1
	v_add_f32_dpp v33, v33, v33 row_shl:4 row_mask:0xf bank_mask:0xf bound_ctrl:1
	v_add_f32_dpp v34, v34, v34 row_shl:4 row_mask:0xf bank_mask:0xf bound_ctrl:1
	v_add_f32_dpp v35, v35, v35 row_shl:4 row_mask:0xf bank_mask:0xf bound_ctrl:1
	v_add_f32_dpp v36, v36, v36 row_shl:4 row_mask:0xf bank_mask:0xf bound_ctrl:1
	v_add_f32_dpp v37, v37, v37 row_shl:4 row_mask:0xf bank_mask:0xf bound_ctrl:1
	v_add_f32_dpp v38, v38, v38 row_shl:4 row_mask:0xf bank_mask:0xf bound_ctrl:1
	v_add_f32_dpp v39, v39, v39 row_shl:4 row_mask:0xf bank_mask:0xf bound_ctrl:1
	v_add_f32_dpp v88, v88, v88 row_ror:2 row_mask:0xf bank_mask:0xf
	v_add_f32_dpp v89, v89, v89 row_ror:2 row_mask:0xf bank_mask:0xf
	v_add_f32_dpp v90, v90, v90 row_ror:2 row_mask:0xf bank_mask:0xf
	v_add_f32_dpp v91, v91, v91 row_ror:2 row_mask:0xf bank_mask:0xf
	v_add_f32_dpp v92, v92, v92 row_ror:2 row_mask:0xf bank_mask:0xf
	v_add_f32_dpp v93, v93, v93 row_ror:2 row_mask:0xf bank_mask:0xf
	v_add_f32_dpp v94, v94, v94 row_ror:2 row_mask:0xf bank_mask:0xf
	v_add_f32_dpp v95, v95, v95 row_ror:2 row_mask:0xf bank_mask:0xf
	v_add_f32_dpp v32, v32, v32 row_shl:8 row_mask:0xf bank_mask:0xf bound_ctrl:1
	v_add_f32_dpp v33, v33, v33 row_shl:8 row_mask:0xf bank_mask:0xf bound_ctrl:1
	v_add_f32_dpp v34, v34, v34 row_shl:8 row_mask:0xf bank_mask:0xf bound_ctrl:1
	v_add_f32_dpp v35, v35, v35 row_shl:8 row_mask:0xf bank_mask:0xf bound_ctrl:1
	v_add_f32_dpp v36, v36, v36 row_shl:8 row_mask:0xf bank_mask:0xf bound_ctrl:1
	v_add_f32_dpp v37, v37, v37 row_shl:8 row_mask:0xf bank_mask:0xf bound_ctrl:1
	v_add_f32_dpp v38, v38, v38 row_shl:8 row_mask:0xf bank_mask:0xf bound_ctrl:1
	v_add_f32_dpp v39, v39, v39 row_shl:8 row_mask:0xf bank_mask:0xf bound_ctrl:1
	v_add_f32_dpp v88, v88, v88 row_ror:1 row_mask:0xf bank_mask:0xf
	v_add_f32_dpp v89, v89, v89 row_ror:1 row_mask:0xf bank_mask:0xf
	v_add_f32_dpp v90, v90, v90 row_ror:1 row_mask:0xf bank_mask:0xf
	v_add_f32_dpp v91, v91, v91 row_ror:1 row_mask:0xf bank_mask:0xf
	v_add_f32_dpp v92, v92, v92 row_ror:1 row_mask:0xf bank_mask:0xf
	v_add_f32_dpp v93, v93, v93 row_ror:1 row_mask:0xf bank_mask:0xf
	v_add_f32_dpp v94, v94, v94 row_ror:1 row_mask:0xf bank_mask:0xf
	v_add_f32_dpp v95, v95, v95 row_ror:1 row_mask:0xf bank_mask:0xf
	v_add_f32_e32 v32, v32, v178
	v_add_f32_e32 v36, v36, v179
	v_add_f32_e32 v33, v33, v180
	v_add_f32_e32 v37, v37, v181
	v_add_f32_e32 v34, v34, v182
	v_add_f32_e32 v38, v38, v183
	v_add_f32_e32 v35, v35, v184
	v_add_f32_e32 v39, v39, v185
	v_mul_f32_e32 v132, v32, v103
	v_mul_f32_e32 v32, v32, v102
	v_fma_f32 v32, -v36, v103, v32
	v_fma_f32 v36, v36, v102, v132
	v_mul_f32_e32 v133, v33, v107
	v_mul_f32_e32 v33, v33, v106
	v_fma_f32 v33, -v37, v107, v33
	v_fma_f32 v37, v37, v106, v133
	v_mul_f32_e32 v132, v34, v111
	v_mul_f32_e32 v34, v34, v110
	v_fma_f32 v34, -v38, v111, v34
	v_fma_f32 v38, v38, v110, v132
	v_mul_f32_e32 v133, v35, v115
	v_mul_f32_e32 v35, v35, v114
	v_fma_f32 v35, -v39, v115, v35
	v_fma_f32 v39, v39, v114, v133
	v_add_f32_e32 v88, v88, v178
	v_add_f32_e32 v92, v92, v179
	v_mul_f32_e32 v132, v92, v117
	v_mul_f32_e32 v179, v88, v117
	v_fma_f32 v178, v88, v116, -v132
	v_fma_f32 v179, v92, v116, v179
	v_add_f32_e32 v89, v89, v180
	v_add_f32_e32 v93, v93, v181
	v_mul_f32_e32 v133, v93, v121
	v_mul_f32_e32 v181, v89, v121
	v_fma_f32 v180, v89, v120, -v133
	v_fma_f32 v181, v93, v120, v181
	v_add_f32_e32 v90, v90, v182
	v_add_f32_e32 v94, v94, v183
	v_mul_f32_e32 v132, v94, v125
	v_mul_f32_e32 v183, v90, v125
	v_fma_f32 v182, v90, v124, -v132
	v_fma_f32 v183, v94, v124, v183
	v_add_f32_e32 v91, v91, v184
	v_add_f32_e32 v95, v95, v185
	v_mul_f32_e32 v133, v95, v129
	v_mul_f32_e32 v185, v91, v129
	v_fma_f32 v184, v91, v128, -v133
	v_fma_f32 v185, v95, v128, v185
	s_waitcnt vmcnt(0)
	v_cvt_pk_bf16_f32 v80, v80, v81
	v_cvt_pk_bf16_f32 v81, v82, v83
	v_cvt_pk_bf16_f32 v82, -v84, -v85
	v_cvt_pk_bf16_f32 v83, -v86, -v87
	v_cvt_pk_bf16_f32 v96, v32, v33
	v_cvt_pk_bf16_f32 v97, v34, v35
	v_cvt_pk_bf16_f32 v98, v36, v37
	v_cvt_pk_bf16_f32 v99, v38, v39
	s_nop 1
	v_mfma_f32_16x16x32_bf16 v[16:19], v[80:83], v[96:99], v[16:19]
	v_cvt_pk_bf16_f32 v96, v40, v41
	v_cvt_pk_bf16_f32 v97, v42, v43
	v_cvt_pk_bf16_f32 v98, v44, v45
	v_cvt_pk_bf16_f32 v99, v46, v47
	s_nop 1
	v_mfma_f32_16x16x32_bf16 v[20:23], v[80:83], v[96:99], v[20:23]
	v_cvt_pk_bf16_f32 v96, v48, v49
	v_cvt_pk_bf16_f32 v97, v50, v51
	v_cvt_pk_bf16_f32 v98, v52, v53
	v_cvt_pk_bf16_f32 v99, v54, v55
	s_nop 1
	v_mfma_f32_16x16x32_bf16 v[24:27], v[80:83], v[96:99], v[24:27]
	v_cvt_pk_bf16_f32 v96, v56, v57
	v_cvt_pk_bf16_f32 v97, v58, v59
	v_cvt_pk_bf16_f32 v98, v60, v61
	v_cvt_pk_bf16_f32 v99, v62, v63
	s_nop 1
	v_mfma_f32_16x16x32_bf16 v[28:31], v[80:83], v[96:99], v[28:31]
	v_and_b32_e32 v100, 15, v205
	v_lshrrev_b32_e32 v101, 4, v205
	v_mul_u32_u24_e32 v102, 0xe00, v100
	v_lshl_add_u32 v102, v101, 3, v102
	v_lshlrev_b32_e32 v103, 9, v100
	v_lshl_add_u32 v103, v101, 3, v103
	v_lshlrev_b32_e32 v104, 4, v101
	s_mul_i32 s18, s9, 0xe00
	s_lshl_b32 s19, s7, 5
	s_add_i32 s18, s18, s19
	s_add_u32 s18, s18, 0x5e00c00
	s_add_u32 s18, s4, s18
	s_addc_u32 s19, s5, 0
	global_load_dwordx2 v[108:109], v102, s[18:19]
	s_add_u32 s18, s18, 0xe000
	s_addc_u32 s19, s19, 0
	global_load_dwordx2 v[110:111], v102, s[18:19]
	s_add_u32 s18, s18, 0xe000
	s_addc_u32 s19, s19, 0
	global_load_dwordx2 v[112:113], v102, s[18:19]
	s_add_u32 s18, s18, 0xe000
	s_addc_u32 s19, s19, 0
	global_load_dwordx2 v[114:115], v102, s[18:19]
	v_readlane_b32 s10, v247, 28
	s_lshl_b32 s10, s10, 10
	s_lshl_b32 s11, s7, 6
	s_add_i32 s10, s10, s11
	s_add_u32 s10, s10, 0x21fb20
	s_add_u32 s20, s4, s10
	s_addc_u32 s21, s5, 0
	global_load_dwordx4 v[116:119], v104, s[20:21]
	s_lshl_b32 s10, s9, 9
	s_add_i32 s10, s10, s11
	s_lshr_b32 s11, s11, 1
	s_sub_i32 s10, s10, s11
	s_add_u32 s10, s10, 0xc500000
	s_add_u32 s22, s4, s10
	s_addc_u32 s23, s5, 0
	s_waitcnt vmcnt(0)
	s_nop 4
	v_lshlrev_b32_e32 v120, 16, v108
	v_and_b32_e32 v121, 0xffff0000, v108
	v_lshlrev_b32_e32 v122, 16, v109
	v_and_b32_e32 v123, 0xffff0000, v109
	v_fmac_f32_e32 v16, v116, v120
	v_fmac_f32_e32 v17, v117, v121
	v_fmac_f32_e32 v18, v118, v122
	v_fmac_f32_e32 v19, v119, v123
	v_cvt_pk_bf16_f32 v124, v16, v17
	v_cvt_pk_bf16_f32 v125, v18, v19
	global_store_dwordx2 v103, v[124:125], s[22:23] offset:0
	s_add_u32 s22, s22, 0x2000
	s_addc_u32 s23, s23, 0
	v_lshlrev_b32_e32 v120, 16, v110
	v_and_b32_e32 v121, 0xffff0000, v110
	v_lshlrev_b32_e32 v122, 16, v111
	v_and_b32_e32 v123, 0xffff0000, v111
	v_fmac_f32_e32 v20, v116, v120
	v_fmac_f32_e32 v21, v117, v121
	v_fmac_f32_e32 v22, v118, v122
	v_fmac_f32_e32 v23, v119, v123
	v_cvt_pk_bf16_f32 v124, v20, v21
	v_cvt_pk_bf16_f32 v125, v22, v23
	global_store_dwordx2 v103, v[124:125], s[22:23] offset:0
	s_add_u32 s22, s22, 0x2000
	s_addc_u32 s23, s23, 0
	v_lshlrev_b32_e32 v120, 16, v112
	v_and_b32_e32 v121, 0xffff0000, v112
	v_lshlrev_b32_e32 v122, 16, v113
	v_and_b32_e32 v123, 0xffff0000, v113
	v_fmac_f32_e32 v24, v116, v120
	v_fmac_f32_e32 v25, v117, v121
	v_fmac_f32_e32 v26, v118, v122
	v_fmac_f32_e32 v27, v119, v123
	v_cvt_pk_bf16_f32 v124, v24, v25
	v_cvt_pk_bf16_f32 v125, v26, v27
	global_store_dwordx2 v103, v[124:125], s[22:23] offset:0
	s_add_u32 s22, s22, 0x2000
	s_addc_u32 s23, s23, 0
	v_lshlrev_b32_e32 v120, 16, v114
	v_and_b32_e32 v121, 0xffff0000, v114
	v_lshlrev_b32_e32 v122, 16, v115
	v_and_b32_e32 v123, 0xffff0000, v115
	v_fmac_f32_e32 v28, v116, v120
	v_fmac_f32_e32 v29, v117, v121
	v_fmac_f32_e32 v30, v118, v122
	v_fmac_f32_e32 v31, v119, v123
	v_cvt_pk_bf16_f32 v124, v28, v29
	v_cvt_pk_bf16_f32 v125, v30, v31
	global_store_dwordx2 v103, v[124:125], s[22:23] offset:0
	s_cmp_eq_u32 s37, 1
	s_cbranch_scc1 .Lss3_done
	s_add_i32 s36, s36, s30
	s_branch .Lss3_top
.Lss3_done:
.LBB0_436:
	s_and_b32 s0, s94, 0x4c0
	s_cmp_eq_u32 s0, 0
	s_cbranch_scc1 .LBB0_612
	s_bitcmp1_b32 s94, 6
	s_cselect_b64 s[0:1], -1, 0
	s_and_b32 s8, s94, 0x400
	s_and_b64 vcc, exec, s[0:1]
	s_mov_b64 s[6:7], s[0:1]
	s_cbranch_vccnz .LBB0_439
	s_cmp_lg_u32 s8, 0
	v_readlane_b32 s9, v245, 37
	s_cselect_b64 s[6:7], -1, 0
	s_add_i32 s9, s9, -12
	s_cmp_lt_u32 s9, 11
	s_cselect_b64 s[10:11], -1, 0
	s_and_b64 s[6:7], s[6:7], s[10:11]

.LBB0_449:
	s_andn2_b64 vcc, exec, s[0:1]
	s_cbranch_vccnz .LBB0_478
	s_sub_i32 s86, s12, s60
	s_mul_i32 s10, s86, 0xf0f1
	s_lshr_b32 s10, s10, 22
	s_mul_i32 s11, s10, 68
	s_sub_i32 s8, s86, s11
	s_and_b32 s7, s10, 15
	s_lshr_b32 s6, s10, 4
	s_lshl_b32 s10, s8, 6
	s_lshl_b32 s11, s6, 8
	s_add_i32 s9, s10, s11
	s_lshl_b32 s11, s6, 12
	s_add_i32 s11, s11, s10
	s_add_i32 s11, s11, 0x300
	s_cmp_lt_u32 s8, 4
	s_cselect_b32 s9, s9, s11
	v_mov_b32_e32 v0, 0
	v_mov_b32_e32 v1, 0
	v_mov_b32_e32 v2, 0
	v_mov_b32_e32 v3, 0
	v_mov_b32_e32 v4, 0
	v_mov_b32_e32 v5, 0
	v_mov_b32_e32 v6, 0
	v_mov_b32_e32 v7, 0
	v_mov_b32_e32 v8, 0
	v_mov_b32_e32 v9, 0
	v_mov_b32_e32 v10, 0
	v_mov_b32_e32 v11, 0
	v_mov_b32_e32 v12, 0
	v_mov_b32_e32 v13, 0
	v_mov_b32_e32 v14, 0
	v_mov_b32_e32 v15, 0
	v_and_b32_e32 v100, 15, v205
	v_mul_u32_u24_e32 v100, 0xe00, v100
	v_and_b32_e32 v101, 16, v205
	v_add_u32_e32 v100, v100, v101
	s_mul_i32 s18, s9, 0xe00
	s_lshl_b32 s19, s7, 5
	s_add_i32 s18, s18, s19
	s_add_u32 s18, s18, 0x5e00c00
	s_add_u32 s18, s4, s18
	s_addc_u32 s19, s5, 0
	s_mov_b32 exec_hi, 0
	global_load_dwordx4 v[0:3], v100, s[18:19]
	s_add_u32 s18, s18, 0xe000
	s_addc_u32 s19, s19, 0
	global_load_dwordx4 v[4:7], v100, s[18:19]
	s_add_u32 s18, s18, 0xe000
	s_addc_u32 s19, s19, 0
	global_load_dwordx4 v[8:11], v100, s[18:19]
	s_add_u32 s18, s18, 0xe000
	s_addc_u32 s19, s19, 0
	global_load_dwordx4 v[12:15], v100, s[18:19]
	s_mov_b64 exec, -1
	v_mov_b32_e32 v48, 0
	v_mov_b32_e32 v49, 0
	v_mov_b32_e32 v50, 0
	v_mov_b32_e32 v51, 0
	v_mov_b32_e32 v52, 0
	v_mov_b32_e32 v53, 0
	v_mov_b32_e32 v54, 0
	v_mov_b32_e32 v55, 0
	v_mov_b32_e32 v56, 0
	v_mov_b32_e32 v57, 0
	v_mov_b32_e32 v58, 0
	v_mov_b32_e32 v59, 0
	v_mov_b32_e32 v60, 0
	v_mov_b32_e32 v61, 0
	v_mov_b32_e32 v62, 0
	v_mov_b32_e32 v63, 0
	v_mov_b32_e32 v64, 0
	v_mov_b32_e32 v65, 0
	v_mov_b32_e32 v66, 0
	v_mov_b32_e32 v67, 0
	v_mov_b32_e32 v68, 0
	v_mov_b32_e32 v69, 0
	v_mov_b32_e32 v70, 0
	v_mov_b32_e32 v71, 0
	v_mov_b32_e32 v72, 0
	v_mov_b32_e32 v73, 0
	v_mov_b32_e32 v74, 0
	v_mov_b32_e32 v75, 0
	v_mov_b32_e32 v76, 0
	v_mov_b32_e32 v77, 0
	v_mov_b32_e32 v78, 0
	v_mov_b32_e32 v79, 0
	v_and_b32_e32 v112, 15, v205
	v_lshlrev_b32_e32 v112, 6, v112
	v_and_b32_e32 v113, 16, v205
	v_lshl_add_u32 v112, v113, 1, v112
	v_lshlrev_b32_e32 v113, 6, v205
	v_lshrrev_b32_e32 v114, 4, v205
	v_lshlrev_b32_e32 v114, 5, v114
	v_readlane_b32 s10, v247, 28
	s_mov_b32 s11, s8
	s_lshl_b32 s16, s10, 1
	s_add_i32 s16, s16, 0
	s_lshl_b32 s16, s16, 4
	s_add_i32 s16, s16, s7
	s_lshl_b32 s17, s6, 1
	s_add_i32 s17, s17, 0
	s_lshl_b32 s17, s17, 4
	s_add_i32 s17, s17, s7
	s_mul_i32 s17, s17, 68
	s_add_i32 s17, s17, s11
	s_lshl_b32 s17, s17, 6
	s_lshl_b32 s20, s16, 12
	s_add_u32 s20, s20, 0x11fb20
	s_add_u32 s20, s4, s20
	s_addc_u32 s21, s5, 0
	s_add_u32 s22, s20, 0x40000
	s_addc_u32 s23, s21, 0
	s_lshl_b32 s24, s16, 14
	s_add_u32 s24, s24, 0xfc00000
	s_add_u32 s24, s4, s24
	s_addc_u32 s25, s5, 0
	s_lshl_b32 s26, s17, 3
	s_add_u32 s26, s26, 0x300000
	s_add_u32 s26, s4, s26
	s_addc_u32 s27, s5, 0
	s_mov_b32 exec_hi, 0
	global_load_dwordx4 v[48:51], v112, s[20:21]
	global_load_dwordx4 v[52:55], v112, s[20:21] offset:16
	global_load_dwordx4 v[56:59], v112, s[22:23]
	global_load_dwordx4 v[60:63], v112, s[22:23] offset:16
	s_mov_b64 exec, -1
	global_load_dwordx4 v[80:83], v113, s[24:25] offset:0
	global_load_dwordx4 v[84:87], v113, s[24:25] offset:16
	global_load_dwordx4 v[88:91], v113, s[24:25] offset:32
	global_load_dwordx4 v[92:95], v113, s[24:25] offset:48
	s_add_u32 s20, s20, 0x400
	s_addc_u32 s21, s21, 0
	s_add_u32 s22, s22, 0x400
	s_addc_u32 s23, s23, 0
	s_add_u32 s24, s24, 0x1000
	s_addc_u32 s25, s25, 0
	s_waitcnt vmcnt(8)
	s_waitcnt vmcnt(4)
	v_cvt_pk_bf16_f32 v48, v48, v49
	v_cvt_pk_bf16_f32 v49, v50, v51
	v_cvt_pk_bf16_f32 v50, v52, v53
	v_cvt_pk_bf16_f32 v51, v54, v55
	v_cvt_pk_bf16_f32 v56, v56, v57
	v_cvt_pk_bf16_f32 v57, v58, v59
	v_cvt_pk_bf16_f32 v58, v60, v61
	v_cvt_pk_bf16_f32 v59, v62, v63
	s_mov_b32 exec_hi, 0
	global_load_dwordx4 v[64:67], v112, s[20:21]
	global_load_dwordx4 v[68:71], v112, s[20:21] offset:16
	global_load_dwordx4 v[72:75], v112, s[22:23]
	global_load_dwordx4 v[76:79], v112, s[22:23] offset:16
	s_mov_b64 exec, -1
	global_load_dwordx4 v[96:99], v113, s[24:25] offset:0
	global_load_dwordx4 v[100:103], v113, s[24:25] offset:16
	global_load_dwordx4 v[104:107], v113, s[24:25] offset:32
	global_load_dwordx4 v[108:111], v113, s[24:25] offset:48
	s_add_u32 s20, s20, 0x400
	s_addc_u32 s21, s21, 0
	s_add_u32 s22, s22, 0x400
	s_addc_u32 s23, s23, 0
	s_add_u32 s24, s24, 0x1000
	s_addc_u32 s25, s25, 0
	v_mfma_f32_16x16x32_bf16 v[16:19], v[48:51], v[0:3], 0
	v_mfma_f32_16x16x32_bf16 v[20:23], v[56:59], v[0:3], 0
	v_mfma_f32_16x16x32_bf16 v[24:27], v[48:51], v[4:7], 0
	v_mfma_f32_16x16x32_bf16 v[28:31], v[56:59], v[4:7], 0
	v_mfma_f32_16x16x32_bf16 v[32:35], v[48:51], v[8:11], 0
	v_mfma_f32_16x16x32_bf16 v[36:39], v[56:59], v[8:11], 0
	v_mfma_f32_16x16x32_bf16 v[40:43], v[48:51], v[12:15], 0
	v_mfma_f32_16x16x32_bf16 v[44:47], v[56:59], v[12:15], 0
	s_waitcnt vmcnt(8)
	s_nop 7
	v_mul_f32_e32 v116, v81, v20
	v_fma_f32 v120, v80, v16, -v116
	v_mul_f32_e32 v116, v80, v20
	v_fma_f32 v124, v81, v16, v116
	v_mul_f32_e32 v116, v85, v21
	v_fma_f32 v121, v84, v17, -v116
	v_mul_f32_e32 v116, v84, v21
	v_fma_f32 v125, v85, v17, v116
	v_mul_f32_e32 v116, v89, v22
	v_fma_f32 v122, v88, v18, -v116
	v_mul_f32_e32 v116, v88, v22
	v_fma_f32 v126, v89, v18, v116
	v_mul_f32_e32 v116, v93, v23
	v_fma_f32 v123, v92, v19, -v116
	v_mul_f32_e32 v116, v92, v23
	v_fma_f32 v127, v93, v19, v116
	v_mul_f32_e32 v116, v81, v28
	v_fma_f32 v117, v80, v24, -v116
	v_mul_f32_e32 v116, v80, v28
	v_fma_f32 v118, v81, v24, v116
	v_fma_f32 v117, v120, v82, v117
	v_fma_f32 v118, v120, v83, v118
	v_fma_f32 v117, -v124, v83, v117
	v_fma_f32 v124, v124, v82, v118
	v_mov_b32_e32 v120, v117
	v_mul_f32_e32 v116, v85, v29
	v_fma_f32 v117, v84, v25, -v116
	v_mul_f32_e32 v116, v84, v29
	v_fma_f32 v118, v85, v25, v116
	v_fma_f32 v117, v121, v86, v117
	v_fma_f32 v118, v121, v87, v118
	v_fma_f32 v117, -v125, v87, v117
	v_fma_f32 v125, v125, v86, v118
	v_mov_b32_e32 v121, v117
	v_mul_f32_e32 v116, v89, v30
	v_fma_f32 v117, v88, v26, -v116
	v_mul_f32_e32 v116, v88, v30
	v_fma_f32 v118, v89, v26, v116
	v_fma_f32 v117, v122, v90, v117
	v_fma_f32 v118, v122, v91, v118
	v_fma_f32 v117, -v126, v91, v117
	v_fma_f32 v126, v126, v90, v118
	v_mov_b32_e32 v122, v117
	v_mul_f32_e32 v116, v93, v31
	v_fma_f32 v117, v92, v27, -v116
	v_mul_f32_e32 v116, v92, v31
	v_fma_f32 v118, v93, v27, v116
	v_fma_f32 v117, v123, v94, v117
	v_fma_f32 v118, v123, v95, v118
	v_fma_f32 v117, -v127, v95, v117
	v_fma_f32 v127, v127, v94, v118
	v_mov_b32_e32 v123, v117
	v_mul_f32_e32 v116, v81, v36
	v_fma_f32 v117, v80, v32, -v116
	v_mul_f32_e32 v116, v80, v36
	v_fma_f32 v118, v81, v32, v116
	v_fma_f32 v117, v120, v82, v117
	v_fma_f32 v118, v120, v83, v118
	v_fma_f32 v117, -v124, v83, v117
	v_fma_f32 v124, v124, v82, v118
	v_mov_b32_e32 v120, v117
	v_mul_f32_e32 v116, v85, v37
	v_fma_f32 v117, v84, v33, -v116
	v_mul_f32_e32 v116, v84, v37
	v_fma_f32 v118, v85, v33, v116
	v_fma_f32 v117, v121, v86, v117
	v_fma_f32 v118, v121, v87, v118
	v_fma_f32 v117, -v125, v87, v117
	v_fma_f32 v125, v125, v86, v118
	v_mov_b32_e32 v121, v117
	v_mul_f32_e32 v116, v89, v38
	v_fma_f32 v117, v88, v34, -v116
	v_mul_f32_e32 v116, v88, v38
	v_fma_f32 v118, v89, v34, v116
	v_fma_f32 v117, v122, v90, v117
	v_fma_f32 v118, v122, v91, v118
	v_fma_f32 v117, -v126, v91, v117
	v_fma_f32 v126, v126, v90, v118
	v_mov_b32_e32 v122, v117
	v_mul_f32_e32 v116, v93, v39
	v_fma_f32 v117, v92, v35, -v116
	v_mul_f32_e32 v116, v92, v39
	v_fma_f32 v118, v93, v35, v116
	v_fma_f32 v117, v123, v94, v117
	v_fma_f32 v118, v123, v95, v118
	v_fma_f32 v117, -v127, v95, v117
	v_fma_f32 v127, v127, v94, v118
	v_mov_b32_e32 v123, v117
	v_mul_f32_e32 v116, v81, v44
	v_fma_f32 v117, v80, v40, -v116
	v_mul_f32_e32 v116, v80, v44
	v_fma_f32 v118, v81, v40, v116
	v_fma_f32 v117, v120, v82, v117
	v_fma_f32 v118, v120, v83, v118
	v_fma_f32 v117, -v124, v83, v117
	v_fma_f32 v124, v124, v82, v118
	v_mov_b32_e32 v120, v117
	v_mul_f32_e32 v116, v85, v45
	v_fma_f32 v117, v84, v41, -v116
	v_mul_f32_e32 v116, v84, v45
	v_fma_f32 v118, v85, v41, v116
	v_fma_f32 v117, v121, v86, v117
	v_fma_f32 v118, v121, v87, v118
	v_fma_f32 v117, -v125, v87, v117
	v_fma_f32 v125, v125, v86, v118
	v_mov_b32_e32 v121, v117
	v_mul_f32_e32 v116, v89, v46
	v_fma_f32 v117, v88, v42, -v116
	v_mul_f32_e32 v116, v88, v46
	v_fma_f32 v118, v89, v42, v116
	v_fma_f32 v117, v122, v90, v117
	v_fma_f32 v118, v122, v91, v118
	v_fma_f32 v117, -v126, v91, v117
	v_fma_f32 v126, v126, v90, v118
	v_mov_b32_e32 v122, v117
	v_mul_f32_e32 v116, v93, v47
	v_fma_f32 v117, v92, v43, -v116
	v_mul_f32_e32 v116, v92, v47
	v_fma_f32 v118, v93, v43, v116
	v_fma_f32 v117, v123, v94, v117
	v_fma_f32 v118, v123, v95, v118
	v_fma_f32 v117, -v127, v95, v117
	v_fma_f32 v127, v127, v94, v118
	v_mov_b32_e32 v123, v117
	v_add_f32_dpp v120, v120, v120 row_ror:8 row_mask:0xf bank_mask:0xf
	v_add_f32_dpp v121, v121, v121 row_ror:8 row_mask:0xf bank_mask:0xf
	v_add_f32_dpp v122, v122, v122 row_ror:8 row_mask:0xf bank_mask:0xf
	v_add_f32_dpp v123, v123, v123 row_ror:8 row_mask:0xf bank_mask:0xf
	v_add_f32_dpp v124, v124, v124 row_ror:8 row_mask:0xf bank_mask:0xf
	v_add_f32_dpp v125, v125, v125 row_ror:8 row_mask:0xf bank_mask:0xf
	v_add_f32_dpp v126, v126, v126 row_ror:8 row_mask:0xf bank_mask:0xf
	v_add_f32_dpp v127, v127, v127 row_ror:8 row_mask:0xf bank_mask:0xf
	v_add_f32_dpp v120, v120, v120 row_ror:4 row_mask:0xf bank_mask:0xf
	v_add_f32_dpp v121, v121, v121 row_ror:4 row_mask:0xf bank_mask:0xf
	v_add_f32_dpp v122, v122, v122 row_ror:4 row_mask:0xf bank_mask:0xf
	v_add_f32_dpp v123, v123, v123 row_ror:4 row_mask:0xf bank_mask:0xf
	v_add_f32_dpp v124, v124, v124 row_ror:4 row_mask:0xf bank_mask:0xf
	v_add_f32_dpp v125, v125, v125 row_ror:4 row_mask:0xf bank_mask:0xf
	v_add_f32_dpp v126, v126, v126 row_ror:4 row_mask:0xf bank_mask:0xf
	v_add_f32_dpp v127, v127, v127 row_ror:4 row_mask:0xf bank_mask:0xf
	v_add_f32_dpp v120, v120, v120 row_ror:2 row_mask:0xf bank_mask:0xf
	v_add_f32_dpp v121, v121, v121 row_ror:2 row_mask:0xf bank_mask:0xf
	v_add_f32_dpp v122, v122, v122 row_ror:2 row_mask:0xf bank_mask:0xf
	v_add_f32_dpp v123, v123, v123 row_ror:2 row_mask:0xf bank_mask:0xf
	v_add_f32_dpp v124, v124, v124 row_ror:2 row_mask:0xf bank_mask:0xf
	v_add_f32_dpp v125, v125, v125 row_ror:2 row_mask:0xf bank_mask:0xf
	v_add_f32_dpp v126, v126, v126 row_ror:2 row_mask:0xf bank_mask:0xf
	v_add_f32_dpp v127, v127, v127 row_ror:2 row_mask:0xf bank_mask:0xf
	v_add_f32_dpp v120, v120, v120 row_ror:1 row_mask:0xf bank_mask:0xf
	v_add_f32_dpp v121, v121, v121 row_ror:1 row_mask:0xf bank_mask:0xf
	v_add_f32_dpp v122, v122, v122 row_ror:1 row_mask:0xf bank_mask:0xf
	v_add_f32_dpp v123, v123, v123 row_ror:1 row_mask:0xf bank_mask:0xf
	v_add_f32_dpp v124, v124, v124 row_ror:1 row_mask:0xf bank_mask:0xf
	v_add_f32_dpp v125, v125, v125 row_ror:1 row_mask:0xf bank_mask:0xf
	v_add_f32_dpp v126, v126, v126 row_ror:1 row_mask:0xf bank_mask:0xf
	v_add_f32_dpp v127, v127, v127 row_ror:1 row_mask:0xf bank_mask:0xf
	s_add_u32 s18, s26, 0
	s_addc_u32 s19, s27, 0
	v_mov_b32_e32 v128, v120
	v_mov_b32_e32 v129, v124
	v_mov_b32_e32 v130, v121
	v_mov_b32_e32 v131, v125
	v_mov_b32_e32 v132, v122
	v_mov_b32_e32 v133, v126
	v_mov_b32_e32 v134, v123
	v_mov_b32_e32 v135, v127
	s_mov_b32 exec_lo, 0x10001
	s_mov_b32 exec_hi, 0x10001
	global_store_dwordx4 v114, v[128:131], s[18:19]
	global_store_dwordx4 v114, v[132:135], s[18:19] offset:16
	s_mov_b64 exec, -1
	s_nop 1
	s_waitcnt vmcnt(4)
	v_cvt_pk_bf16_f32 v64, v64, v65
	v_cvt_pk_bf16_f32 v65, v66, v67
	v_cvt_pk_bf16_f32 v66, v68, v69
	v_cvt_pk_bf16_f32 v67, v70, v71
	v_cvt_pk_bf16_f32 v72, v72, v73
	v_cvt_pk_bf16_f32 v73, v74, v75
	v_cvt_pk_bf16_f32 v74, v76, v77
	v_cvt_pk_bf16_f32 v75, v78, v79
	s_mov_b32 exec_hi, 0
	global_load_dwordx4 v[48:51], v112, s[20:21]
	global_load_dwordx4 v[52:55], v112, s[20:21] offset:16
	global_load_dwordx4 v[56:59], v112, s[22:23]
	global_load_dwordx4 v[60:63], v112, s[22:23] offset:16
	s_mov_b64 exec, -1
	global_load_dwordx4 v[80:83], v113, s[24:25] offset:0
	global_load_dwordx4 v[84:87], v113, s[24:25] offset:16
	global_load_dwordx4 v[88:91], v113, s[24:25] offset:32
	global_load_dwordx4 v[92:95], v113, s[24:25] offset:48
	s_add_u32 s20, s20, 0x400
	s_addc_u32 s21, s21, 0
	s_add_u32 s22, s22, 0x400
	s_addc_u32 s23, s23, 0
	s_add_u32 s24, s24, 0x1000
	s_addc_u32 s25, s25, 0
	v_mfma_f32_16x16x32_bf16 v[16:19], v[64:67], v[0:3], 0
	v_mfma_f32_16x16x32_bf16 v[20:23], v[72:75], v[0:3], 0
	v_mfma_f32_16x16x32_bf16 v[24:27], v[64:67], v[4:7], 0
	v_mfma_f32_16x16x32_bf16 v[28:31], v[72:75], v[4:7], 0
	v_mfma_f32_16x16x32_bf16 v[32:35], v[64:67], v[8:11], 0
	v_mfma_f32_16x16x32_bf16 v[36:39], v[72:75], v[8:11], 0
	v_mfma_f32_16x16x32_bf16 v[40:43], v[64:67], v[12:15], 0
	v_mfma_f32_16x16x32_bf16 v[44:47], v[72:75], v[12:15], 0
	s_waitcnt vmcnt(8)
	s_nop 7
	v_mul_f32_e32 v116, v97, v20
	v_fma_f32 v120, v96, v16, -v116
	v_mul_f32_e32 v116, v96, v20
	v_fma_f32 v124, v97, v16, v116
	v_mul_f32_e32 v116, v101, v21
	v_fma_f32 v121, v100, v17, -v116
	v_mul_f32_e32 v116, v100, v21
	v_fma_f32 v125, v101, v17, v116
	v_mul_f32_e32 v116, v105, v22
	v_fma_f32 v122, v104, v18, -v116
	v_mul_f32_e32 v116, v104, v22
	v_fma_f32 v126, v105, v18, v116
	v_mul_f32_e32 v116, v109, v23
	v_fma_f32 v123, v108, v19, -v116
	v_mul_f32_e32 v116, v108, v23
	v_fma_f32 v127, v109, v19, v116
	v_mul_f32_e32 v116, v97, v28
	v_fma_f32 v117, v96, v24, -v116
	v_mul_f32_e32 v116, v96, v28
	v_fma_f32 v118, v97, v24, v116
	v_fma_f32 v117, v120, v98, v117
	v_fma_f32 v118, v120, v99, v118
	v_fma_f32 v117, -v124, v99, v117
	v_fma_f32 v124, v124, v98, v118
	v_mov_b32_e32 v120, v117
	v_mul_f32_e32 v116, v101, v29
	v_fma_f32 v117, v100, v25, -v116
	v_mul_f32_e32 v116, v100, v29
	v_fma_f32 v118, v101, v25, v116
	v_fma_f32 v117, v121, v102, v117
	v_fma_f32 v118, v121, v103, v118
	v_fma_f32 v117, -v125, v103, v117
	v_fma_f32 v125, v125, v102, v118
	v_mov_b32_e32 v121, v117
	v_mul_f32_e32 v116, v105, v30
	v_fma_f32 v117, v104, v26, -v116
	v_mul_f32_e32 v116, v104, v30
	v_fma_f32 v118, v105, v26, v116
	v_fma_f32 v117, v122, v106, v117
	v_fma_f32 v118, v122, v107, v118
	v_fma_f32 v117, -v126, v107, v117
	v_fma_f32 v126, v126, v106, v118
	v_mov_b32_e32 v122, v117
	v_mul_f32_e32 v116, v109, v31
	v_fma_f32 v117, v108, v27, -v116
	v_mul_f32_e32 v116, v108, v31
	v_fma_f32 v118, v109, v27, v116
	v_fma_f32 v117, v123, v110, v117
	v_fma_f32 v118, v123, v111, v118
	v_fma_f32 v117, -v127, v111, v117
	v_fma_f32 v127, v127, v110, v118
	v_mov_b32_e32 v123, v117
	v_mul_f32_e32 v116, v97, v36
	v_fma_f32 v117, v96, v32, -v116
	v_mul_f32_e32 v116, v96, v36
	v_fma_f32 v118, v97, v32, v116
	v_fma_f32 v117, v120, v98, v117
	v_fma_f32 v118, v120, v99, v118
	v_fma_f32 v117, -v124, v99, v117
	v_fma_f32 v124, v124, v98, v118
	v_mov_b32_e32 v120, v117
	v_mul_f32_e32 v116, v101, v37
	v_fma_f32 v117, v100, v33, -v116
	v_mul_f32_e32 v116, v100, v37
	v_fma_f32 v118, v101, v33, v116
	v_fma_f32 v117, v121, v102, v117
	v_fma_f32 v118, v121, v103, v118
	v_fma_f32 v117, -v125, v103, v117
	v_fma_f32 v125, v125, v102, v118
	v_mov_b32_e32 v121, v117
	v_mul_f32_e32 v116, v105, v38
	v_fma_f32 v117, v104, v34, -v116
	v_mul_f32_e32 v116, v104, v38
	v_fma_f32 v118, v105, v34, v116
	v_fma_f32 v117, v122, v106, v117
	v_fma_f32 v118, v122, v107, v118
	v_fma_f32 v117, -v126, v107, v117
	v_fma_f32 v126, v126, v106, v118
	v_mov_b32_e32 v122, v117
	v_mul_f32_e32 v116, v109, v39
	v_fma_f32 v117, v108, v35, -v116
	v_mul_f32_e32 v116, v108, v39
	v_fma_f32 v118, v109, v35, v116
	v_fma_f32 v117, v123, v110, v117
	v_fma_f32 v118, v123, v111, v118
	v_fma_f32 v117, -v127, v111, v117
	v_fma_f32 v127, v127, v110, v118
	v_mov_b32_e32 v123, v117
	v_mul_f32_e32 v116, v97, v44
	v_fma_f32 v117, v96, v40, -v116
	v_mul_f32_e32 v116, v96, v44
	v_fma_f32 v118, v97, v40, v116
	v_fma_f32 v117, v120, v98, v117
	v_fma_f32 v118, v120, v99, v118
	v_fma_f32 v117, -v124, v99, v117
	v_fma_f32 v124, v124, v98, v118
	v_mov_b32_e32 v120, v117
	v_mul_f32_e32 v116, v101, v45
	v_fma_f32 v117, v100, v41, -v116
	v_mul_f32_e32 v116, v100, v45
	v_fma_f32 v118, v101, v41, v116
	v_fma_f32 v117, v121, v102, v117
	v_fma_f32 v118, v121, v103, v118
	v_fma_f32 v117, -v125, v103, v117
	v_fma_f32 v125, v125, v102, v118
	v_mov_b32_e32 v121, v117
	v_mul_f32_e32 v116, v105, v46
	v_fma_f32 v117, v104, v42, -v116
	v_mul_f32_e32 v116, v104, v46
	v_fma_f32 v118, v105, v42, v116
	v_fma_f32 v117, v122, v106, v117
	v_fma_f32 v118, v122, v107, v118
	v_fma_f32 v117, -v126, v107, v117
	v_fma_f32 v126, v126, v106, v118
	v_mov_b32_e32 v122, v117
	v_mul_f32_e32 v116, v109, v47
	v_fma_f32 v117, v108, v43, -v116
	v_mul_f32_e32 v116, v108, v47
	v_fma_f32 v118, v109, v43, v116
	v_fma_f32 v117, v123, v110, v117
	v_fma_f32 v118, v123, v111, v118
	v_fma_f32 v117, -v127, v111, v117
	v_fma_f32 v127, v127, v110, v118
	v_mov_b32_e32 v123, v117
	v_add_f32_dpp v120, v120, v120 row_ror:8 row_mask:0xf bank_mask:0xf
	v_add_f32_dpp v121, v121, v121 row_ror:8 row_mask:0xf bank_mask:0xf
	v_add_f32_dpp v122, v122, v122 row_ror:8 row_mask:0xf bank_mask:0xf
	v_add_f32_dpp v123, v123, v123 row_ror:8 row_mask:0xf bank_mask:0xf
	v_add_f32_dpp v124, v124, v124 row_ror:8 row_mask:0xf bank_mask:0xf
	v_add_f32_dpp v125, v125, v125 row_ror:8 row_mask:0xf bank_mask:0xf
	v_add_f32_dpp v126, v126, v126 row_ror:8 row_mask:0xf bank_mask:0xf
	v_add_f32_dpp v127, v127, v127 row_ror:8 row_mask:0xf bank_mask:0xf
	v_add_f32_dpp v120, v120, v120 row_ror:4 row_mask:0xf bank_mask:0xf
	v_add_f32_dpp v121, v121, v121 row_ror:4 row_mask:0xf bank_mask:0xf
	v_add_f32_dpp v122, v122, v122 row_ror:4 row_mask:0xf bank_mask:0xf
	v_add_f32_dpp v123, v123, v123 row_ror:4 row_mask:0xf bank_mask:0xf
	v_add_f32_dpp v124, v124, v124 row_ror:4 row_mask:0xf bank_mask:0xf
	v_add_f32_dpp v125, v125, v125 row_ror:4 row_mask:0xf bank_mask:0xf
	v_add_f32_dpp v126, v126, v126 row_ror:4 row_mask:0xf bank_mask:0xf
	v_add_f32_dpp v127, v127, v127 row_ror:4 row_mask:0xf bank_mask:0xf
	v_add_f32_dpp v120, v120, v120 row_ror:2 row_mask:0xf bank_mask:0xf
	v_add_f32_dpp v121, v121, v121 row_ror:2 row_mask:0xf bank_mask:0xf
	v_add_f32_dpp v122, v122, v122 row_ror:2 row_mask:0xf bank_mask:0xf
	v_add_f32_dpp v123, v123, v123 row_ror:2 row_mask:0xf bank_mask:0xf
	v_add_f32_dpp v124, v124, v124 row_ror:2 row_mask:0xf bank_mask:0xf
	v_add_f32_dpp v125, v125, v125 row_ror:2 row_mask:0xf bank_mask:0xf
	v_add_f32_dpp v126, v126, v126 row_ror:2 row_mask:0xf bank_mask:0xf
	v_add_f32_dpp v127, v127, v127 row_ror:2 row_mask:0xf bank_mask:0xf
	v_add_f32_dpp v120, v120, v120 row_ror:1 row_mask:0xf bank_mask:0xf
	v_add_f32_dpp v121, v121, v121 row_ror:1 row_mask:0xf bank_mask:0xf
	v_add_f32_dpp v122, v122, v122 row_ror:1 row_mask:0xf bank_mask:0xf
	v_add_f32_dpp v123, v123, v123 row_ror:1 row_mask:0xf bank_mask:0xf
	v_add_f32_dpp v124, v124, v124 row_ror:1 row_mask:0xf bank_mask:0xf
	v_add_f32_dpp v125, v125, v125 row_ror:1 row_mask:0xf bank_mask:0xf
	v_add_f32_dpp v126, v126, v126 row_ror:1 row_mask:0xf bank_mask:0xf
	v_add_f32_dpp v127, v127, v127 row_ror:1 row_mask:0xf bank_mask:0xf
	s_add_u32 s18, s26, 128
	s_addc_u32 s19, s27, 0
	v_mov_b32_e32 v128, v120
	v_mov_b32_e32 v129, v124
	v_mov_b32_e32 v130, v121
	v_mov_b32_e32 v131, v125
	v_mov_b32_e32 v132, v122
	v_mov_b32_e32 v133, v126
	v_mov_b32_e32 v134, v123
	v_mov_b32_e32 v135, v127
	s_mov_b32 exec_lo, 0x10001
	s_mov_b32 exec_hi, 0x10001
	global_store_dwordx4 v114, v[128:131], s[18:19]
	global_store_dwordx4 v114, v[132:135], s[18:19] offset:16
	s_mov_b64 exec, -1
	s_nop 1
	s_waitcnt vmcnt(4)
	v_cvt_pk_bf16_f32 v48, v48, v49
	v_cvt_pk_bf16_f32 v49, v50, v51
	v_cvt_pk_bf16_f32 v50, v52, v53
	v_cvt_pk_bf16_f32 v51, v54, v55
	v_cvt_pk_bf16_f32 v56, v56, v57
	v_cvt_pk_bf16_f32 v57, v58, v59
	v_cvt_pk_bf16_f32 v58, v60, v61
	v_cvt_pk_bf16_f32 v59, v62, v63
	s_mov_b32 exec_hi, 0
	global_load_dwordx4 v[64:67], v112, s[20:21]
	global_load_dwordx4 v[68:71], v112, s[20:21] offset:16
	global_load_dwordx4 v[72:75], v112, s[22:23]
	global_load_dwordx4 v[76:79], v112, s[22:23] offset:16
	s_mov_b64 exec, -1
	global_load_dwordx4 v[96:99], v113, s[24:25] offset:0
	global_load_dwordx4 v[100:103], v113, s[24:25] offset:16
	global_load_dwordx4 v[104:107], v113, s[24:25] offset:32
	global_load_dwordx4 v[108:111], v113, s[24:25] offset:48
	v_mfma_f32_16x16x32_bf16 v[16:19], v[48:51], v[0:3], 0
	v_mfma_f32_16x16x32_bf16 v[20:23], v[56:59], v[0:3], 0
	v_mfma_f32_16x16x32_bf16 v[24:27], v[48:51], v[4:7], 0
	v_mfma_f32_16x16x32_bf16 v[28:31], v[56:59], v[4:7], 0
	v_mfma_f32_16x16x32_bf16 v[32:35], v[48:51], v[8:11], 0
	v_mfma_f32_16x16x32_bf16 v[36:39], v[56:59], v[8:11], 0
	v_mfma_f32_16x16x32_bf16 v[40:43], v[48:51], v[12:15], 0
	v_mfma_f32_16x16x32_bf16 v[44:47], v[56:59], v[12:15], 0
	s_waitcnt vmcnt(8)
	s_nop 7
	v_mul_f32_e32 v116, v81, v20
	v_fma_f32 v120, v80, v16, -v116
	v_mul_f32_e32 v116, v80, v20
	v_fma_f32 v124, v81, v16, v116
	v_mul_f32_e32 v116, v85, v21
	v_fma_f32 v121, v84, v17, -v116
	v_mul_f32_e32 v116, v84, v21
	v_fma_f32 v125, v85, v17, v116
	v_mul_f32_e32 v116, v89, v22
	v_fma_f32 v122, v88, v18, -v116
	v_mul_f32_e32 v116, v88, v22
	v_fma_f32 v126, v89, v18, v116
	v_mul_f32_e32 v116, v93, v23
	v_fma_f32 v123, v92, v19, -v116
	v_mul_f32_e32 v116, v92, v23
	v_fma_f32 v127, v93, v19, v116
	v_mul_f32_e32 v116, v81, v28
	v_fma_f32 v117, v80, v24, -v116
	v_mul_f32_e32 v116, v80, v28
	v_fma_f32 v118, v81, v24, v116
	v_fma_f32 v117, v120, v82, v117
	v_fma_f32 v118, v120, v83, v118
	v_fma_f32 v117, -v124, v83, v117
	v_fma_f32 v124, v124, v82, v118
	v_mov_b32_e32 v120, v117
	v_mul_f32_e32 v116, v85, v29
	v_fma_f32 v117, v84, v25, -v116
	v_mul_f32_e32 v116, v84, v29
	v_fma_f32 v118, v85, v25, v116
	v_fma_f32 v117, v121, v86, v117
	v_fma_f32 v118, v121, v87, v118
	v_fma_f32 v117, -v125, v87, v117
	v_fma_f32 v125, v125, v86, v118
	v_mov_b32_e32 v121, v117
	v_mul_f32_e32 v116, v89, v30
	v_fma_f32 v117, v88, v26, -v116
	v_mul_f32_e32 v116, v88, v30
	v_fma_f32 v118, v89, v26, v116
	v_fma_f32 v117, v122, v90, v117
	v_fma_f32 v118, v122, v91, v118
	v_fma_f32 v117, -v126, v91, v117
	v_fma_f32 v126, v126, v90, v118
	v_mov_b32_e32 v122, v117
	v_mul_f32_e32 v116, v93, v31
	v_fma_f32 v117, v92, v27, -v116
	v_mul_f32_e32 v116, v92, v31
	v_fma_f32 v118, v93, v27, v116
	v_fma_f32 v117, v123, v94, v117
	v_fma_f32 v118, v123, v95, v118
	v_fma_f32 v117, -v127, v95, v117
	v_fma_f32 v127, v127, v94, v118
	v_mov_b32_e32 v123, v117
	v_mul_f32_e32 v116, v81, v36
	v_fma_f32 v117, v80, v32, -v116
	v_mul_f32_e32 v116, v80, v36
	v_fma_f32 v118, v81, v32, v116
	v_fma_f32 v117, v120, v82, v117
	v_fma_f32 v118, v120, v83, v118
	v_fma_f32 v117, -v124, v83, v117
	v_fma_f32 v124, v124, v82, v118
	v_mov_b32_e32 v120, v117
	v_mul_f32_e32 v116, v85, v37
	v_fma_f32 v117, v84, v33, -v116
	v_mul_f32_e32 v116, v84, v37
	v_fma_f32 v118, v85, v33, v116
	v_fma_f32 v117, v121, v86, v117
	v_fma_f32 v118, v121, v87, v118
	v_fma_f32 v117, -v125, v87, v117
	v_fma_f32 v125, v125, v86, v118
	v_mov_b32_e32 v121, v117
	v_mul_f32_e32 v116, v89, v38
	v_fma_f32 v117, v88, v34, -v116
	v_mul_f32_e32 v116, v88, v38
	v_fma_f32 v118, v89, v34, v116
	v_fma_f32 v117, v122, v90, v117
	v_fma_f32 v118, v122, v91, v118
	v_fma_f32 v117, -v126, v91, v117
	v_fma_f32 v126, v126, v90, v118
	v_mov_b32_e32 v122, v117
	v_mul_f32_e32 v116, v93, v39
	v_fma_f32 v117, v92, v35, -v116
	v_mul_f32_e32 v116, v92, v39
	v_fma_f32 v118, v93, v35, v116
	v_fma_f32 v117, v123, v94, v117
	v_fma_f32 v118, v123, v95, v118
	v_fma_f32 v117, -v127, v95, v117
	v_fma_f32 v127, v127, v94, v118
	v_mov_b32_e32 v123, v117
	v_mul_f32_e32 v116, v81, v44
	v_fma_f32 v117, v80, v40, -v116
	v_mul_f32_e32 v116, v80, v44
	v_fma_f32 v118, v81, v40, v116
	v_fma_f32 v117, v120, v82, v117
	v_fma_f32 v118, v120, v83, v118
	v_fma_f32 v117, -v124, v83, v117
	v_fma_f32 v124, v124, v82, v118
	v_mov_b32_e32 v120, v117
	v_mul_f32_e32 v116, v85, v45
	v_fma_f32 v117, v84, v41, -v116
	v_mul_f32_e32 v116, v84, v45
	v_fma_f32 v118, v85, v41, v116
	v_fma_f32 v117, v121, v86, v117
	v_fma_f32 v118, v121, v87, v118
	v_fma_f32 v117, -v125, v87, v117
	v_fma_f32 v125, v125, v86, v118
	v_mov_b32_e32 v121, v117
	v_mul_f32_e32 v116, v89, v46
	v_fma_f32 v117, v88, v42, -v116
	v_mul_f32_e32 v116, v88, v46
	v_fma_f32 v118, v89, v42, v116
	v_fma_f32 v117, v122, v90, v117
	v_fma_f32 v118, v122, v91, v118
	v_fma_f32 v117, -v126, v91, v117
	v_fma_f32 v126, v126, v90, v118
	v_mov_b32_e32 v122, v117
	v_mul_f32_e32 v116, v93, v47
	v_fma_f32 v117, v92, v43, -v116
	v_mul_f32_e32 v116, v92, v47
	v_fma_f32 v118, v93, v43, v116
	v_fma_f32 v117, v123, v94, v117
	v_fma_f32 v118, v123, v95, v118
	v_fma_f32 v117, -v127, v95, v117
	v_fma_f32 v127, v127, v94, v118
	v_mov_b32_e32 v123, v117
	v_add_f32_dpp v120, v120, v120 row_ror:8 row_mask:0xf bank_mask:0xf
	v_add_f32_dpp v121, v121, v121 row_ror:8 row_mask:0xf bank_mask:0xf
	v_add_f32_dpp v122, v122, v122 row_ror:8 row_mask:0xf bank_mask:0xf
	v_add_f32_dpp v123, v123, v123 row_ror:8 row_mask:0xf bank_mask:0xf
	v_add_f32_dpp v124, v124, v124 row_ror:8 row_mask:0xf bank_mask:0xf
	v_add_f32_dpp v125, v125, v125 row_ror:8 row_mask:0xf bank_mask:0xf
	v_add_f32_dpp v126, v126, v126 row_ror:8 row_mask:0xf bank_mask:0xf
	v_add_f32_dpp v127, v127, v127 row_ror:8 row_mask:0xf bank_mask:0xf
	v_add_f32_dpp v120, v120, v120 row_ror:4 row_mask:0xf bank_mask:0xf
	v_add_f32_dpp v121, v121, v121 row_ror:4 row_mask:0xf bank_mask:0xf
	v_add_f32_dpp v122, v122, v122 row_ror:4 row_mask:0xf bank_mask:0xf
	v_add_f32_dpp v123, v123, v123 row_ror:4 row_mask:0xf bank_mask:0xf
	v_add_f32_dpp v124, v124, v124 row_ror:4 row_mask:0xf bank_mask:0xf
	v_add_f32_dpp v125, v125, v125 row_ror:4 row_mask:0xf bank_mask:0xf
	v_add_f32_dpp v126, v126, v126 row_ror:4 row_mask:0xf bank_mask:0xf
	v_add_f32_dpp v127, v127, v127 row_ror:4 row_mask:0xf bank_mask:0xf
	v_add_f32_dpp v120, v120, v120 row_ror:2 row_mask:0xf bank_mask:0xf
	v_add_f32_dpp v121, v121, v121 row_ror:2 row_mask:0xf bank_mask:0xf
	v_add_f32_dpp v122, v122, v122 row_ror:2 row_mask:0xf bank_mask:0xf
	v_add_f32_dpp v123, v123, v123 row_ror:2 row_mask:0xf bank_mask:0xf
	v_add_f32_dpp v124, v124, v124 row_ror:2 row_mask:0xf bank_mask:0xf
	v_add_f32_dpp v125, v125, v125 row_ror:2 row_mask:0xf bank_mask:0xf
	v_add_f32_dpp v126, v126, v126 row_ror:2 row_mask:0xf bank_mask:0xf
	v_add_f32_dpp v127, v127, v127 row_ror:2 row_mask:0xf bank_mask:0xf
	v_add_f32_dpp v120, v120, v120 row_ror:1 row_mask:0xf bank_mask:0xf
	v_add_f32_dpp v121, v121, v121 row_ror:1 row_mask:0xf bank_mask:0xf
	v_add_f32_dpp v122, v122, v122 row_ror:1 row_mask:0xf bank_mask:0xf
	v_add_f32_dpp v123, v123, v123 row_ror:1 row_mask:0xf bank_mask:0xf
	v_add_f32_dpp v124, v124, v124 row_ror:1 row_mask:0xf bank_mask:0xf
	v_add_f32_dpp v125, v125, v125 row_ror:1 row_mask:0xf bank_mask:0xf
	v_add_f32_dpp v126, v126, v126 row_ror:1 row_mask:0xf bank_mask:0xf
	v_add_f32_dpp v127, v127, v127 row_ror:1 row_mask:0xf bank_mask:0xf
	s_add_u32 s18, s26, 256
	s_addc_u32 s19, s27, 0
	v_mov_b32_e32 v128, v120
	v_mov_b32_e32 v129, v124
	v_mov_b32_e32 v130, v121
	v_mov_b32_e32 v131, v125
	v_mov_b32_e32 v132, v122
	v_mov_b32_e32 v133, v126
	v_mov_b32_e32 v134, v123
	v_mov_b32_e32 v135, v127
	s_mov_b32 exec_lo, 0x10001
	s_mov_b32 exec_hi, 0x10001
	global_store_dwordx4 v114, v[128:131], s[18:19]
	global_store_dwordx4 v114, v[132:135], s[18:19] offset:16
	s_mov_b64 exec, -1
	s_nop 1
	s_waitcnt vmcnt(4)
	v_cvt_pk_bf16_f32 v64, v64, v65
	v_cvt_pk_bf16_f32 v65, v66, v67
	v_cvt_pk_bf16_f32 v66, v68, v69
	v_cvt_pk_bf16_f32 v67, v70, v71
	v_cvt_pk_bf16_f32 v72, v72, v73
	v_cvt_pk_bf16_f32 v73, v74, v75
	v_cvt_pk_bf16_f32 v74, v76, v77
	v_cvt_pk_bf16_f32 v75, v78, v79
	v_readlane_b32 s10, v247, 28
	s_sub_i32 s11, 3, s8
	s_sub_i32 s17, 71, s8
	s_cmp_lt_u32 s8, 4
	s_cselect_b32 s11, s11, s17
	s_lshl_b32 s16, s10, 1
	s_add_i32 s16, s16, 1
	s_lshl_b32 s16, s16, 4
	s_add_i32 s16, s16, s7
	s_lshl_b32 s17, s6, 1
	s_add_i32 s17, s17, 1
	s_lshl_b32 s17, s17, 4
	s_add_i32 s17, s17, s7
	s_mul_i32 s17, s17, 68
	s_add_i32 s17, s17, s11
	s_lshl_b32 s17, s17, 6
	s_lshl_b32 s20, s16, 12
	s_add_u32 s20, s20, 0x11fb20
	s_add_u32 s20, s4, s20
	s_addc_u32 s21, s5, 0
	s_add_u32 s22, s20, 0x40000
	s_addc_u32 s23, s21, 0
	s_lshl_b32 s24, s16, 14
	s_add_u32 s24, s24, 0xfc00000
	s_add_u32 s24, s4, s24
	s_addc_u32 s25, s5, 0
	s_lshl_b32 s36, s17, 3
	s_add_u32 s36, s36, 0x300000
	s_add_u32 s36, s4, s36
	s_addc_u32 s37, s5, 0
	s_mov_b32 exec_hi, 0
	global_load_dwordx4 v[48:51], v112, s[20:21]
	global_load_dwordx4 v[52:55], v112, s[20:21] offset:16
	global_load_dwordx4 v[56:59], v112, s[22:23]
	global_load_dwordx4 v[60:63], v112, s[22:23] offset:16
	s_mov_b64 exec, -1
	global_load_dwordx4 v[80:83], v113, s[24:25] offset:0
	global_load_dwordx4 v[84:87], v113, s[24:25] offset:16
	global_load_dwordx4 v[88:91], v113, s[24:25] offset:32
	global_load_dwordx4 v[92:95], v113, s[24:25] offset:48
	s_add_u32 s20, s20, 0x400
	s_addc_u32 s21, s21, 0
	s_add_u32 s22, s22, 0x400
	s_addc_u32 s23, s23, 0
	s_add_u32 s24, s24, 0x1000
	s_addc_u32 s25, s25, 0
	v_mfma_f32_16x16x32_bf16 v[16:19], v[64:67], v[0:3], 0
	v_mfma_f32_16x16x32_bf16 v[20:23], v[72:75], v[0:3], 0
	v_mfma_f32_16x16x32_bf16 v[24:27], v[64:67], v[4:7], 0
	v_mfma_f32_16x16x32_bf16 v[28:31], v[72:75], v[4:7], 0
	v_mfma_f32_16x16x32_bf16 v[32:35], v[64:67], v[8:11], 0
	v_mfma_f32_16x16x32_bf16 v[36:39], v[72:75], v[8:11], 0
	v_mfma_f32_16x16x32_bf16 v[40:43], v[64:67], v[12:15], 0
	v_mfma_f32_16x16x32_bf16 v[44:47], v[72:75], v[12:15], 0
	s_waitcnt vmcnt(8)
	s_nop 7
	v_mul_f32_e32 v116, v97, v20
	v_fma_f32 v120, v96, v16, -v116
	v_mul_f32_e32 v116, v96, v20
	v_fma_f32 v124, v97, v16, v116
	v_mul_f32_e32 v116, v101, v21
	v_fma_f32 v121, v100, v17, -v116
	v_mul_f32_e32 v116, v100, v21
	v_fma_f32 v125, v101, v17, v116
	v_mul_f32_e32 v116, v105, v22
	v_fma_f32 v122, v104, v18, -v116
	v_mul_f32_e32 v116, v104, v22
	v_fma_f32 v126, v105, v18, v116
	v_mul_f32_e32 v116, v109, v23
	v_fma_f32 v123, v108, v19, -v116
	v_mul_f32_e32 v116, v108, v23
	v_fma_f32 v127, v109, v19, v116
	v_mul_f32_e32 v116, v97, v28
	v_fma_f32 v117, v96, v24, -v116
	v_mul_f32_e32 v116, v96, v28
	v_fma_f32 v118, v97, v24, v116
	v_fma_f32 v117, v120, v98, v117
	v_fma_f32 v118, v120, v99, v118
	v_fma_f32 v117, -v124, v99, v117
	v_fma_f32 v124, v124, v98, v118
	v_mov_b32_e32 v120, v117
	v_mul_f32_e32 v116, v101, v29
	v_fma_f32 v117, v100, v25, -v116
	v_mul_f32_e32 v116, v100, v29
	v_fma_f32 v118, v101, v25, v116
	v_fma_f32 v117, v121, v102, v117
	v_fma_f32 v118, v121, v103, v118
	v_fma_f32 v117, -v125, v103, v117
	v_fma_f32 v125, v125, v102, v118
	v_mov_b32_e32 v121, v117
	v_mul_f32_e32 v116, v105, v30
	v_fma_f32 v117, v104, v26, -v116
	v_mul_f32_e32 v116, v104, v30
	v_fma_f32 v118, v105, v26, v116
	v_fma_f32 v117, v122, v106, v117
	v_fma_f32 v118, v122, v107, v118
	v_fma_f32 v117, -v126, v107, v117
	v_fma_f32 v126, v126, v106, v118
	v_mov_b32_e32 v122, v117
	v_mul_f32_e32 v116, v109, v31
	v_fma_f32 v117, v108, v27, -v116
	v_mul_f32_e32 v116, v108, v31
	v_fma_f32 v118, v109, v27, v116
	v_fma_f32 v117, v123, v110, v117
	v_fma_f32 v118, v123, v111, v118
	v_fma_f32 v117, -v127, v111, v117
	v_fma_f32 v127, v127, v110, v118
	v_mov_b32_e32 v123, v117
	v_mul_f32_e32 v116, v97, v36
	v_fma_f32 v117, v96, v32, -v116
	v_mul_f32_e32 v116, v96, v36
	v_fma_f32 v118, v97, v32, v116
	v_fma_f32 v117, v120, v98, v117
	v_fma_f32 v118, v120, v99, v118
	v_fma_f32 v117, -v124, v99, v117
	v_fma_f32 v124, v124, v98, v118
	v_mov_b32_e32 v120, v117
	v_mul_f32_e32 v116, v101, v37
	v_fma_f32 v117, v100, v33, -v116
	v_mul_f32_e32 v116, v100, v37
	v_fma_f32 v118, v101, v33, v116
	v_fma_f32 v117, v121, v102, v117
	v_fma_f32 v118, v121, v103, v118
	v_fma_f32 v117, -v125, v103, v117
	v_fma_f32 v125, v125, v102, v118
	v_mov_b32_e32 v121, v117
	v_mul_f32_e32 v116, v105, v38
	v_fma_f32 v117, v104, v34, -v116
	v_mul_f32_e32 v116, v104, v38
	v_fma_f32 v118, v105, v34, v116
	v_fma_f32 v117, v122, v106, v117
	v_fma_f32 v118, v122, v107, v118
	v_fma_f32 v117, -v126, v107, v117
	v_fma_f32 v126, v126, v106, v118
	v_mov_b32_e32 v122, v117
	v_mul_f32_e32 v116, v109, v39
	v_fma_f32 v117, v108, v35, -v116
	v_mul_f32_e32 v116, v108, v39
	v_fma_f32 v118, v109, v35, v116
	v_fma_f32 v117, v123, v110, v117
	v_fma_f32 v118, v123, v111, v118
	v_fma_f32 v117, -v127, v111, v117
	v_fma_f32 v127, v127, v110, v118
	v_mov_b32_e32 v123, v117
	v_mul_f32_e32 v116, v97, v44
	v_fma_f32 v117, v96, v40, -v116
	v_mul_f32_e32 v116, v96, v44
	v_fma_f32 v118, v97, v40, v116
	v_fma_f32 v117, v120, v98, v117
	v_fma_f32 v118, v120, v99, v118
	v_fma_f32 v117, -v124, v99, v117
	v_fma_f32 v124, v124, v98, v118
	v_mov_b32_e32 v120, v117
	v_mul_f32_e32 v116, v101, v45
	v_fma_f32 v117, v100, v41, -v116
	v_mul_f32_e32 v116, v100, v45
	v_fma_f32 v118, v101, v41, v116
	v_fma_f32 v117, v121, v102, v117
	v_fma_f32 v118, v121, v103, v118
	v_fma_f32 v117, -v125, v103, v117
	v_fma_f32 v125, v125, v102, v118
	v_mov_b32_e32 v121, v117
	v_mul_f32_e32 v116, v105, v46
	v_fma_f32 v117, v104, v42, -v116
	v_mul_f32_e32 v116, v104, v46
	v_fma_f32 v118, v105, v42, v116
	v_fma_f32 v117, v122, v106, v117
	v_fma_f32 v118, v122, v107, v118
	v_fma_f32 v117, -v126, v107, v117
	v_fma_f32 v126, v126, v106, v118
	v_mov_b32_e32 v122, v117
	v_mul_f32_e32 v116, v109, v47
	v_fma_f32 v117, v108, v43, -v116
	v_mul_f32_e32 v116, v108, v47
	v_fma_f32 v118, v109, v43, v116
	v_fma_f32 v117, v123, v110, v117
	v_fma_f32 v118, v123, v111, v118
	v_fma_f32 v117, -v127, v111, v117
	v_fma_f32 v127, v127, v110, v118
	v_mov_b32_e32 v123, v117
	v_add_f32_dpp v120, v120, v120 row_ror:8 row_mask:0xf bank_mask:0xf
	v_add_f32_dpp v121, v121, v121 row_ror:8 row_mask:0xf bank_mask:0xf
	v_add_f32_dpp v122, v122, v122 row_ror:8 row_mask:0xf bank_mask:0xf
	v_add_f32_dpp v123, v123, v123 row_ror:8 row_mask:0xf bank_mask:0xf
	v_add_f32_dpp v124, v124, v124 row_ror:8 row_mask:0xf bank_mask:0xf
	v_add_f32_dpp v125, v125, v125 row_ror:8 row_mask:0xf bank_mask:0xf
	v_add_f32_dpp v126, v126, v126 row_ror:8 row_mask:0xf bank_mask:0xf
	v_add_f32_dpp v127, v127, v127 row_ror:8 row_mask:0xf bank_mask:0xf
	v_add_f32_dpp v120, v120, v120 row_ror:4 row_mask:0xf bank_mask:0xf
	v_add_f32_dpp v121, v121, v121 row_ror:4 row_mask:0xf bank_mask:0xf
	v_add_f32_dpp v122, v122, v122 row_ror:4 row_mask:0xf bank_mask:0xf
	v_add_f32_dpp v123, v123, v123 row_ror:4 row_mask:0xf bank_mask:0xf
	v_add_f32_dpp v124, v124, v124 row_ror:4 row_mask:0xf bank_mask:0xf
	v_add_f32_dpp v125, v125, v125 row_ror:4 row_mask:0xf bank_mask:0xf
	v_add_f32_dpp v126, v126, v126 row_ror:4 row_mask:0xf bank_mask:0xf
	v_add_f32_dpp v127, v127, v127 row_ror:4 row_mask:0xf bank_mask:0xf
	v_add_f32_dpp v120, v120, v120 row_ror:2 row_mask:0xf bank_mask:0xf
	v_add_f32_dpp v121, v121, v121 row_ror:2 row_mask:0xf bank_mask:0xf
	v_add_f32_dpp v122, v122, v122 row_ror:2 row_mask:0xf bank_mask:0xf
	v_add_f32_dpp v123, v123, v123 row_ror:2 row_mask:0xf bank_mask:0xf
	v_add_f32_dpp v124, v124, v124 row_ror:2 row_mask:0xf bank_mask:0xf
	v_add_f32_dpp v125, v125, v125 row_ror:2 row_mask:0xf bank_mask:0xf
	v_add_f32_dpp v126, v126, v126 row_ror:2 row_mask:0xf bank_mask:0xf
	v_add_f32_dpp v127, v127, v127 row_ror:2 row_mask:0xf bank_mask:0xf
	v_add_f32_dpp v120, v120, v120 row_ror:1 row_mask:0xf bank_mask:0xf
	v_add_f32_dpp v121, v121, v121 row_ror:1 row_mask:0xf bank_mask:0xf
	v_add_f32_dpp v122, v122, v122 row_ror:1 row_mask:0xf bank_mask:0xf
	v_add_f32_dpp v123, v123, v123 row_ror:1 row_mask:0xf bank_mask:0xf
	v_add_f32_dpp v124, v124, v124 row_ror:1 row_mask:0xf bank_mask:0xf
	v_add_f32_dpp v125, v125, v125 row_ror:1 row_mask:0xf bank_mask:0xf
	v_add_f32_dpp v126, v126, v126 row_ror:1 row_mask:0xf bank_mask:0xf
	v_add_f32_dpp v127, v127, v127 row_ror:1 row_mask:0xf bank_mask:0xf
	s_add_u32 s18, s26, 384
	s_addc_u32 s19, s27, 0
	v_mov_b32_e32 v128, v120
	v_mov_b32_e32 v129, v124
	v_mov_b32_e32 v130, v121
	v_mov_b32_e32 v131, v125
	v_mov_b32_e32 v132, v122
	v_mov_b32_e32 v133, v126
	v_mov_b32_e32 v134, v123
	v_mov_b32_e32 v135, v127
	s_mov_b32 exec_lo, 0x10001
	s_mov_b32 exec_hi, 0x10001
	global_store_dwordx4 v114, v[128:131], s[18:19]
	global_store_dwordx4 v114, v[132:135], s[18:19] offset:16
	s_mov_b64 exec, -1
	s_nop 1
	s_waitcnt vmcnt(4)
	v_cvt_pk_bf16_f32 v48, v48, v49
	v_cvt_pk_bf16_f32 v49, v50, v51
	v_cvt_pk_bf16_f32 v50, v52, v53
	v_cvt_pk_bf16_f32 v51, v54, v55
	v_cvt_pk_bf16_f32 v56, v56, v57
	v_cvt_pk_bf16_f32 v57, v58, v59
	v_cvt_pk_bf16_f32 v58, v60, v61
	v_cvt_pk_bf16_f32 v59, v62, v63
	s_mov_b32 exec_hi, 0
	global_load_dwordx4 v[64:67], v112, s[20:21]
	global_load_dwordx4 v[68:71], v112, s[20:21] offset:16
	global_load_dwordx4 v[72:75], v112, s[22:23]
	global_load_dwordx4 v[76:79], v112, s[22:23] offset:16
	s_mov_b64 exec, -1
	global_load_dwordx4 v[96:99], v113, s[24:25] offset:0
	global_load_dwordx4 v[100:103], v113, s[24:25] offset:16
	global_load_dwordx4 v[104:107], v113, s[24:25] offset:32
	global_load_dwordx4 v[108:111], v113, s[24:25] offset:48
	s_add_u32 s20, s20, 0x400
	s_addc_u32 s21, s21, 0
	s_add_u32 s22, s22, 0x400
	s_addc_u32 s23, s23, 0
	s_add_u32 s24, s24, 0x1000
	s_addc_u32 s25, s25, 0
	v_mfma_f32_16x16x32_bf16 v[16:19], v[48:51], v[0:3], 0
	v_mfma_f32_16x16x32_bf16 v[20:23], v[56:59], v[0:3], 0
	v_mfma_f32_16x16x32_bf16 v[24:27], v[48:51], v[4:7], 0
	v_mfma_f32_16x16x32_bf16 v[28:31], v[56:59], v[4:7], 0
	v_mfma_f32_16x16x32_bf16 v[32:35], v[48:51], v[8:11], 0
	v_mfma_f32_16x16x32_bf16 v[36:39], v[56:59], v[8:11], 0
	v_mfma_f32_16x16x32_bf16 v[40:43], v[48:51], v[12:15], 0
	v_mfma_f32_16x16x32_bf16 v[44:47], v[56:59], v[12:15], 0
	s_waitcnt vmcnt(8)
	s_nop 7
	v_mul_f32_e32 v116, v81, v44
	v_fma_f32 v120, v80, v40, -v116
	v_mul_f32_e32 v116, v80, v44
	v_fma_f32 v124, v81, v40, v116
	v_mul_f32_e32 v116, v85, v45
	v_fma_f32 v121, v84, v41, -v116
	v_mul_f32_e32 v116, v84, v45
	v_fma_f32 v125, v85, v41, v116
	v_mul_f32_e32 v116, v89, v46
	v_fma_f32 v122, v88, v42, -v116
	v_mul_f32_e32 v116, v88, v46
	v_fma_f32 v126, v89, v42, v116
	v_mul_f32_e32 v116, v93, v47
	v_fma_f32 v123, v92, v43, -v116
	v_mul_f32_e32 v116, v92, v47
	v_fma_f32 v127, v93, v43, v116
	v_mul_f32_e32 v116, v81, v36
	v_fma_f32 v117, v80, v32, -v116
	v_mul_f32_e32 v116, v80, v36
	v_fma_f32 v118, v81, v32, v116
	v_fma_f32 v117, v120, v82, v117
	v_fma_f32 v118, v120, v83, v118
	v_fma_f32 v117, -v124, v83, v117
	v_fma_f32 v124, v124, v82, v118
	v_mov_b32_e32 v120, v117
	v_mul_f32_e32 v116, v85, v37
	v_fma_f32 v117, v84, v33, -v116
	v_mul_f32_e32 v116, v84, v37
	v_fma_f32 v118, v85, v33, v116
	v_fma_f32 v117, v121, v86, v117
	v_fma_f32 v118, v121, v87, v118
	v_fma_f32 v117, -v125, v87, v117
	v_fma_f32 v125, v125, v86, v118
	v_mov_b32_e32 v121, v117
	v_mul_f32_e32 v116, v89, v38
	v_fma_f32 v117, v88, v34, -v116
	v_mul_f32_e32 v116, v88, v38
	v_fma_f32 v118, v89, v34, v116
	v_fma_f32 v117, v122, v90, v117
	v_fma_f32 v118, v122, v91, v118
	v_fma_f32 v117, -v126, v91, v117
	v_fma_f32 v126, v126, v90, v118
	v_mov_b32_e32 v122, v117
	v_mul_f32_e32 v116, v93, v39
	v_fma_f32 v117, v92, v35, -v116
	v_mul_f32_e32 v116, v92, v39
	v_fma_f32 v118, v93, v35, v116
	v_fma_f32 v117, v123, v94, v117
	v_fma_f32 v118, v123, v95, v118
	v_fma_f32 v117, -v127, v95, v117
	v_fma_f32 v127, v127, v94, v118
	v_mov_b32_e32 v123, v117
	v_mul_f32_e32 v116, v81, v28
	v_fma_f32 v117, v80, v24, -v116
	v_mul_f32_e32 v116, v80, v28
	v_fma_f32 v118, v81, v24, v116
	v_fma_f32 v117, v120, v82, v117
	v_fma_f32 v118, v120, v83, v118
	v_fma_f32 v117, -v124, v83, v117
	v_fma_f32 v124, v124, v82, v118
	v_mov_b32_e32 v120, v117
	v_mul_f32_e32 v116, v85, v29
	v_fma_f32 v117, v84, v25, -v116
	v_mul_f32_e32 v116, v84, v29
	v_fma_f32 v118, v85, v25, v116
	v_fma_f32 v117, v121, v86, v117
	v_fma_f32 v118, v121, v87, v118
	v_fma_f32 v117, -v125, v87, v117
	v_fma_f32 v125, v125, v86, v118
	v_mov_b32_e32 v121, v117
	v_mul_f32_e32 v116, v89, v30
	v_fma_f32 v117, v88, v26, -v116
	v_mul_f32_e32 v116, v88, v30
	v_fma_f32 v118, v89, v26, v116
	v_fma_f32 v117, v122, v90, v117
	v_fma_f32 v118, v122, v91, v118
	v_fma_f32 v117, -v126, v91, v117
	v_fma_f32 v126, v126, v90, v118
	v_mov_b32_e32 v122, v117
	v_mul_f32_e32 v116, v93, v31
	v_fma_f32 v117, v92, v27, -v116
	v_mul_f32_e32 v116, v92, v31
	v_fma_f32 v118, v93, v27, v116
	v_fma_f32 v117, v123, v94, v117
	v_fma_f32 v118, v123, v95, v118
	v_fma_f32 v117, -v127, v95, v117
	v_fma_f32 v127, v127, v94, v118
	v_mov_b32_e32 v123, v117
	v_mul_f32_e32 v116, v81, v20
	v_fma_f32 v117, v80, v16, -v116
	v_mul_f32_e32 v116, v80, v20
	v_fma_f32 v118, v81, v16, v116
	v_fma_f32 v117, v120, v82, v117
	v_fma_f32 v118, v120, v83, v118
	v_fma_f32 v117, -v124, v83, v117
	v_fma_f32 v124, v124, v82, v118
	v_mov_b32_e32 v120, v117
	v_mul_f32_e32 v116, v85, v21
	v_fma_f32 v117, v84, v17, -v116
	v_mul_f32_e32 v116, v84, v21
	v_fma_f32 v118, v85, v17, v116
	v_fma_f32 v117, v121, v86, v117
	v_fma_f32 v118, v121, v87, v118
	v_fma_f32 v117, -v125, v87, v117
	v_fma_f32 v125, v125, v86, v118
	v_mov_b32_e32 v121, v117
	v_mul_f32_e32 v116, v89, v22
	v_fma_f32 v117, v88, v18, -v116
	v_mul_f32_e32 v116, v88, v22
	v_fma_f32 v118, v89, v18, v116
	v_fma_f32 v117, v122, v90, v117
	v_fma_f32 v118, v122, v91, v118
	v_fma_f32 v117, -v126, v91, v117
	v_fma_f32 v126, v126, v90, v118
	v_mov_b32_e32 v122, v117
	v_mul_f32_e32 v116, v93, v23
	v_fma_f32 v117, v92, v19, -v116
	v_mul_f32_e32 v116, v92, v23
	v_fma_f32 v118, v93, v19, v116
	v_fma_f32 v117, v123, v94, v117
	v_fma_f32 v118, v123, v95, v118
	v_fma_f32 v117, -v127, v95, v117
	v_fma_f32 v127, v127, v94, v118
	v_mov_b32_e32 v123, v117
	v_add_f32_dpp v120, v120, v120 row_ror:8 row_mask:0xf bank_mask:0xf
	v_add_f32_dpp v121, v121, v121 row_ror:8 row_mask:0xf bank_mask:0xf
	v_add_f32_dpp v122, v122, v122 row_ror:8 row_mask:0xf bank_mask:0xf
	v_add_f32_dpp v123, v123, v123 row_ror:8 row_mask:0xf bank_mask:0xf
	v_add_f32_dpp v124, v124, v124 row_ror:8 row_mask:0xf bank_mask:0xf
	v_add_f32_dpp v125, v125, v125 row_ror:8 row_mask:0xf bank_mask:0xf
	v_add_f32_dpp v126, v126, v126 row_ror:8 row_mask:0xf bank_mask:0xf
	v_add_f32_dpp v127, v127, v127 row_ror:8 row_mask:0xf bank_mask:0xf
	v_add_f32_dpp v120, v120, v120 row_ror:4 row_mask:0xf bank_mask:0xf
	v_add_f32_dpp v121, v121, v121 row_ror:4 row_mask:0xf bank_mask:0xf
	v_add_f32_dpp v122, v122, v122 row_ror:4 row_mask:0xf bank_mask:0xf
	v_add_f32_dpp v123, v123, v123 row_ror:4 row_mask:0xf bank_mask:0xf
	v_add_f32_dpp v124, v124, v124 row_ror:4 row_mask:0xf bank_mask:0xf
	v_add_f32_dpp v125, v125, v125 row_ror:4 row_mask:0xf bank_mask:0xf
	v_add_f32_dpp v126, v126, v126 row_ror:4 row_mask:0xf bank_mask:0xf
	v_add_f32_dpp v127, v127, v127 row_ror:4 row_mask:0xf bank_mask:0xf
	v_add_f32_dpp v120, v120, v120 row_ror:2 row_mask:0xf bank_mask:0xf
	v_add_f32_dpp v121, v121, v121 row_ror:2 row_mask:0xf bank_mask:0xf
	v_add_f32_dpp v122, v122, v122 row_ror:2 row_mask:0xf bank_mask:0xf
	v_add_f32_dpp v123, v123, v123 row_ror:2 row_mask:0xf bank_mask:0xf
	v_add_f32_dpp v124, v124, v124 row_ror:2 row_mask:0xf bank_mask:0xf
	v_add_f32_dpp v125, v125, v125 row_ror:2 row_mask:0xf bank_mask:0xf
	v_add_f32_dpp v126, v126, v126 row_ror:2 row_mask:0xf bank_mask:0xf
	v_add_f32_dpp v127, v127, v127 row_ror:2 row_mask:0xf bank_mask:0xf
	v_add_f32_dpp v120, v120, v120 row_ror:1 row_mask:0xf bank_mask:0xf
	v_add_f32_dpp v121, v121, v121 row_ror:1 row_mask:0xf bank_mask:0xf
	v_add_f32_dpp v122, v122, v122 row_ror:1 row_mask:0xf bank_mask:0xf
	v_add_f32_dpp v123, v123, v123 row_ror:1 row_mask:0xf bank_mask:0xf
	v_add_f32_dpp v124, v124, v124 row_ror:1 row_mask:0xf bank_mask:0xf
	v_add_f32_dpp v125, v125, v125 row_ror:1 row_mask:0xf bank_mask:0xf
	v_add_f32_dpp v126, v126, v126 row_ror:1 row_mask:0xf bank_mask:0xf
	v_add_f32_dpp v127, v127, v127 row_ror:1 row_mask:0xf bank_mask:0xf
	s_add_u32 s18, s36, 0
	s_addc_u32 s19, s37, 0
	v_mov_b32_e32 v128, v120
	v_mov_b32_e32 v129, v124
	v_mov_b32_e32 v130, v121
	v_mov_b32_e32 v131, v125
	v_mov_b32_e32 v132, v122
	v_mov_b32_e32 v133, v126
	v_mov_b32_e32 v134, v123
	v_mov_b32_e32 v135, v127
	s_mov_b32 exec_lo, 0x10001
	s_mov_b32 exec_hi, 0x10001
	global_store_dwordx4 v114, v[128:131], s[18:19]
	global_store_dwordx4 v114, v[132:135], s[18:19] offset:16
	s_mov_b64 exec, -1
	s_nop 1
	s_waitcnt vmcnt(4)
	v_cvt_pk_bf16_f32 v64, v64, v65
	v_cvt_pk_bf16_f32 v65, v66, v67
	v_cvt_pk_bf16_f32 v66, v68, v69
	v_cvt_pk_bf16_f32 v67, v70, v71
	v_cvt_pk_bf16_f32 v72, v72, v73
	v_cvt_pk_bf16_f32 v73, v74, v75
	v_cvt_pk_bf16_f32 v74, v76, v77
	v_cvt_pk_bf16_f32 v75, v78, v79
	s_mov_b32 exec_hi, 0
	global_load_dwordx4 v[48:51], v112, s[20:21]
	global_load_dwordx4 v[52:55], v112, s[20:21] offset:16
	global_load_dwordx4 v[56:59], v112, s[22:23]
	global_load_dwordx4 v[60:63], v112, s[22:23] offset:16
	s_mov_b64 exec, -1
	global_load_dwordx4 v[80:83], v113, s[24:25] offset:0
	global_load_dwordx4 v[84:87], v113, s[24:25] offset:16
	global_load_dwordx4 v[88:91], v113, s[24:25] offset:32
	global_load_dwordx4 v[92:95], v113, s[24:25] offset:48
	s_add_u32 s20, s20, 0x400
	s_addc_u32 s21, s21, 0
	s_add_u32 s22, s22, 0x400
	s_addc_u32 s23, s23, 0
	s_add_u32 s24, s24, 0x1000
	s_addc_u32 s25, s25, 0
	v_mfma_f32_16x16x32_bf16 v[16:19], v[64:67], v[0:3], 0
	v_mfma_f32_16x16x32_bf16 v[20:23], v[72:75], v[0:3], 0
	v_mfma_f32_16x16x32_bf16 v[24:27], v[64:67], v[4:7], 0
	v_mfma_f32_16x16x32_bf16 v[28:31], v[72:75], v[4:7], 0
	v_mfma_f32_16x16x32_bf16 v[32:35], v[64:67], v[8:11], 0
	v_mfma_f32_16x16x32_bf16 v[36:39], v[72:75], v[8:11], 0
	v_mfma_f32_16x16x32_bf16 v[40:43], v[64:67], v[12:15], 0
	v_mfma_f32_16x16x32_bf16 v[44:47], v[72:75], v[12:15], 0
	s_waitcnt vmcnt(8)
	s_nop 7
	v_mul_f32_e32 v116, v97, v44
	v_fma_f32 v120, v96, v40, -v116
	v_mul_f32_e32 v116, v96, v44
	v_fma_f32 v124, v97, v40, v116
	v_mul_f32_e32 v116, v101, v45
	v_fma_f32 v121, v100, v41, -v116
	v_mul_f32_e32 v116, v100, v45
	v_fma_f32 v125, v101, v41, v116
	v_mul_f32_e32 v116, v105, v46
	v_fma_f32 v122, v104, v42, -v116
	v_mul_f32_e32 v116, v104, v46
	v_fma_f32 v126, v105, v42, v116
	v_mul_f32_e32 v116, v109, v47
	v_fma_f32 v123, v108, v43, -v116
	v_mul_f32_e32 v116, v108, v47
	v_fma_f32 v127, v109, v43, v116
	v_mul_f32_e32 v116, v97, v36
	v_fma_f32 v117, v96, v32, -v116
	v_mul_f32_e32 v116, v96, v36
	v_fma_f32 v118, v97, v32, v116
	v_fma_f32 v117, v120, v98, v117
	v_fma_f32 v118, v120, v99, v118
	v_fma_f32 v117, -v124, v99, v117
	v_fma_f32 v124, v124, v98, v118
	v_mov_b32_e32 v120, v117
	v_mul_f32_e32 v116, v101, v37
	v_fma_f32 v117, v100, v33, -v116
	v_mul_f32_e32 v116, v100, v37
	v_fma_f32 v118, v101, v33, v116
	v_fma_f32 v117, v121, v102, v117
	v_fma_f32 v118, v121, v103, v118
	v_fma_f32 v117, -v125, v103, v117
	v_fma_f32 v125, v125, v102, v118
	v_mov_b32_e32 v121, v117
	v_mul_f32_e32 v116, v105, v38
	v_fma_f32 v117, v104, v34, -v116
	v_mul_f32_e32 v116, v104, v38
	v_fma_f32 v118, v105, v34, v116
	v_fma_f32 v117, v122, v106, v117
	v_fma_f32 v118, v122, v107, v118
	v_fma_f32 v117, -v126, v107, v117
	v_fma_f32 v126, v126, v106, v118
	v_mov_b32_e32 v122, v117
	v_mul_f32_e32 v116, v109, v39
	v_fma_f32 v117, v108, v35, -v116
	v_mul_f32_e32 v116, v108, v39
	v_fma_f32 v118, v109, v35, v116
	v_fma_f32 v117, v123, v110, v117
	v_fma_f32 v118, v123, v111, v118
	v_fma_f32 v117, -v127, v111, v117
	v_fma_f32 v127, v127, v110, v118
	v_mov_b32_e32 v123, v117
	v_mul_f32_e32 v116, v97, v28
	v_fma_f32 v117, v96, v24, -v116
	v_mul_f32_e32 v116, v96, v28
	v_fma_f32 v118, v97, v24, v116
	v_fma_f32 v117, v120, v98, v117
	v_fma_f32 v118, v120, v99, v118
	v_fma_f32 v117, -v124, v99, v117
	v_fma_f32 v124, v124, v98, v118
	v_mov_b32_e32 v120, v117
	v_mul_f32_e32 v116, v101, v29
	v_fma_f32 v117, v100, v25, -v116
	v_mul_f32_e32 v116, v100, v29
	v_fma_f32 v118, v101, v25, v116
	v_fma_f32 v117, v121, v102, v117
	v_fma_f32 v118, v121, v103, v118
	v_fma_f32 v117, -v125, v103, v117
	v_fma_f32 v125, v125, v102, v118
	v_mov_b32_e32 v121, v117
	v_mul_f32_e32 v116, v105, v30
	v_fma_f32 v117, v104, v26, -v116
	v_mul_f32_e32 v116, v104, v30
	v_fma_f32 v118, v105, v26, v116
	v_fma_f32 v117, v122, v106, v117
	v_fma_f32 v118, v122, v107, v118
	v_fma_f32 v117, -v126, v107, v117
	v_fma_f32 v126, v126, v106, v118
	v_mov_b32_e32 v122, v117
	v_mul_f32_e32 v116, v109, v31
	v_fma_f32 v117, v108, v27, -v116
	v_mul_f32_e32 v116, v108, v31
	v_fma_f32 v118, v109, v27, v116
	v_fma_f32 v117, v123, v110, v117
	v_fma_f32 v118, v123, v111, v118
	v_fma_f32 v117, -v127, v111, v117
	v_fma_f32 v127, v127, v110, v118
	v_mov_b32_e32 v123, v117
	v_mul_f32_e32 v116, v97, v20
	v_fma_f32 v117, v96, v16, -v116
	v_mul_f32_e32 v116, v96, v20
	v_fma_f32 v118, v97, v16, v116
	v_fma_f32 v117, v120, v98, v117
	v_fma_f32 v118, v120, v99, v118
	v_fma_f32 v117, -v124, v99, v117
	v_fma_f32 v124, v124, v98, v118
	v_mov_b32_e32 v120, v117
	v_mul_f32_e32 v116, v101, v21
	v_fma_f32 v117, v100, v17, -v116
	v_mul_f32_e32 v116, v100, v21
	v_fma_f32 v118, v101, v17, v116
	v_fma_f32 v117, v121, v102, v117
	v_fma_f32 v118, v121, v103, v118
	v_fma_f32 v117, -v125, v103, v117
	v_fma_f32 v125, v125, v102, v118
	v_mov_b32_e32 v121, v117
	v_mul_f32_e32 v116, v105, v22
	v_fma_f32 v117, v104, v18, -v116
	v_mul_f32_e32 v116, v104, v22
	v_fma_f32 v118, v105, v18, v116
	v_fma_f32 v117, v122, v106, v117
	v_fma_f32 v118, v122, v107, v118
	v_fma_f32 v117, -v126, v107, v117
	v_fma_f32 v126, v126, v106, v118
	v_mov_b32_e32 v122, v117
	v_mul_f32_e32 v116, v109, v23
	v_fma_f32 v117, v108, v19, -v116
	v_mul_f32_e32 v116, v108, v23
	v_fma_f32 v118, v109, v19, v116
	v_fma_f32 v117, v123, v110, v117
	v_fma_f32 v118, v123, v111, v118
	v_fma_f32 v117, -v127, v111, v117
	v_fma_f32 v127, v127, v110, v118
	v_mov_b32_e32 v123, v117
	v_add_f32_dpp v120, v120, v120 row_ror:8 row_mask:0xf bank_mask:0xf
	v_add_f32_dpp v121, v121, v121 row_ror:8 row_mask:0xf bank_mask:0xf
	v_add_f32_dpp v122, v122, v122 row_ror:8 row_mask:0xf bank_mask:0xf
	v_add_f32_dpp v123, v123, v123 row_ror:8 row_mask:0xf bank_mask:0xf
	v_add_f32_dpp v124, v124, v124 row_ror:8 row_mask:0xf bank_mask:0xf
	v_add_f32_dpp v125, v125, v125 row_ror:8 row_mask:0xf bank_mask:0xf
	v_add_f32_dpp v126, v126, v126 row_ror:8 row_mask:0xf bank_mask:0xf
	v_add_f32_dpp v127, v127, v127 row_ror:8 row_mask:0xf bank_mask:0xf
	v_add_f32_dpp v120, v120, v120 row_ror:4 row_mask:0xf bank_mask:0xf
	v_add_f32_dpp v121, v121, v121 row_ror:4 row_mask:0xf bank_mask:0xf
	v_add_f32_dpp v122, v122, v122 row_ror:4 row_mask:0xf bank_mask:0xf
	v_add_f32_dpp v123, v123, v123 row_ror:4 row_mask:0xf bank_mask:0xf
	v_add_f32_dpp v124, v124, v124 row_ror:4 row_mask:0xf bank_mask:0xf
	v_add_f32_dpp v125, v125, v125 row_ror:4 row_mask:0xf bank_mask:0xf
	v_add_f32_dpp v126, v126, v126 row_ror:4 row_mask:0xf bank_mask:0xf
	v_add_f32_dpp v127, v127, v127 row_ror:4 row_mask:0xf bank_mask:0xf
	v_add_f32_dpp v120, v120, v120 row_ror:2 row_mask:0xf bank_mask:0xf
	v_add_f32_dpp v121, v121, v121 row_ror:2 row_mask:0xf bank_mask:0xf
	v_add_f32_dpp v122, v122, v122 row_ror:2 row_mask:0xf bank_mask:0xf
	v_add_f32_dpp v123, v123, v123 row_ror:2 row_mask:0xf bank_mask:0xf
	v_add_f32_dpp v124, v124, v124 row_ror:2 row_mask:0xf bank_mask:0xf
	v_add_f32_dpp v125, v125, v125 row_ror:2 row_mask:0xf bank_mask:0xf
	v_add_f32_dpp v126, v126, v126 row_ror:2 row_mask:0xf bank_mask:0xf
	v_add_f32_dpp v127, v127, v127 row_ror:2 row_mask:0xf bank_mask:0xf
	v_add_f32_dpp v120, v120, v120 row_ror:1 row_mask:0xf bank_mask:0xf
	v_add_f32_dpp v121, v121, v121 row_ror:1 row_mask:0xf bank_mask:0xf
	v_add_f32_dpp v122, v122, v122 row_ror:1 row_mask:0xf bank_mask:0xf
	v_add_f32_dpp v123, v123, v123 row_ror:1 row_mask:0xf bank_mask:0xf
	v_add_f32_dpp v124, v124, v124 row_ror:1 row_mask:0xf bank_mask:0xf
	v_add_f32_dpp v125, v125, v125 row_ror:1 row_mask:0xf bank_mask:0xf
	v_add_f32_dpp v126, v126, v126 row_ror:1 row_mask:0xf bank_mask:0xf
	v_add_f32_dpp v127, v127, v127 row_ror:1 row_mask:0xf bank_mask:0xf
	s_add_u32 s18, s36, 128
	s_addc_u32 s19, s37, 0
	v_mov_b32_e32 v128, v120
	v_mov_b32_e32 v129, v124
	v_mov_b32_e32 v130, v121
	v_mov_b32_e32 v131, v125
	v_mov_b32_e32 v132, v122
	v_mov_b32_e32 v133, v126
	v_mov_b32_e32 v134, v123
	v_mov_b32_e32 v135, v127
	s_mov_b32 exec_lo, 0x10001
	s_mov_b32 exec_hi, 0x10001
	global_store_dwordx4 v114, v[128:131], s[18:19]
	global_store_dwordx4 v114, v[132:135], s[18:19] offset:16
	s_mov_b64 exec, -1
	s_nop 1
	s_waitcnt vmcnt(4)
	v_cvt_pk_bf16_f32 v48, v48, v49
	v_cvt_pk_bf16_f32 v49, v50, v51
	v_cvt_pk_bf16_f32 v50, v52, v53
	v_cvt_pk_bf16_f32 v51, v54, v55
	v_cvt_pk_bf16_f32 v56, v56, v57
	v_cvt_pk_bf16_f32 v57, v58, v59
	v_cvt_pk_bf16_f32 v58, v60, v61
	v_cvt_pk_bf16_f32 v59, v62, v63
	s_mov_b32 exec_hi, 0
	global_load_dwordx4 v[64:67], v112, s[20:21]
	global_load_dwordx4 v[68:71], v112, s[20:21] offset:16
	global_load_dwordx4 v[72:75], v112, s[22:23]
	global_load_dwordx4 v[76:79], v112, s[22:23] offset:16
	s_mov_b64 exec, -1
	global_load_dwordx4 v[96:99], v113, s[24:25] offset:0
	global_load_dwordx4 v[100:103], v113, s[24:25] offset:16
	global_load_dwordx4 v[104:107], v113, s[24:25] offset:32
	global_load_dwordx4 v[108:111], v113, s[24:25] offset:48
	v_mfma_f32_16x16x32_bf16 v[16:19], v[48:51], v[0:3], 0
	v_mfma_f32_16x16x32_bf16 v[20:23], v[56:59], v[0:3], 0
	v_mfma_f32_16x16x32_bf16 v[24:27], v[48:51], v[4:7], 0
	v_mfma_f32_16x16x32_bf16 v[28:31], v[56:59], v[4:7], 0
	v_mfma_f32_16x16x32_bf16 v[32:35], v[48:51], v[8:11], 0
	v_mfma_f32_16x16x32_bf16 v[36:39], v[56:59], v[8:11], 0
	v_mfma_f32_16x16x32_bf16 v[40:43], v[48:51], v[12:15], 0
	v_mfma_f32_16x16x32_bf16 v[44:47], v[56:59], v[12:15], 0
	s_waitcnt vmcnt(8)
	s_nop 7
	v_mul_f32_e32 v116, v81, v44
	v_fma_f32 v120, v80, v40, -v116
	v_mul_f32_e32 v116, v80, v44
	v_fma_f32 v124, v81, v40, v116
	v_mul_f32_e32 v116, v85, v45
	v_fma_f32 v121, v84, v41, -v116
	v_mul_f32_e32 v116, v84, v45
	v_fma_f32 v125, v85, v41, v116
	v_mul_f32_e32 v116, v89, v46
	v_fma_f32 v122, v88, v42, -v116
	v_mul_f32_e32 v116, v88, v46
	v_fma_f32 v126, v89, v42, v116
	v_mul_f32_e32 v116, v93, v47
	v_fma_f32 v123, v92, v43, -v116
	v_mul_f32_e32 v116, v92, v47
	v_fma_f32 v127, v93, v43, v116
	v_mul_f32_e32 v116, v81, v36
	v_fma_f32 v117, v80, v32, -v116
	v_mul_f32_e32 v116, v80, v36
	v_fma_f32 v118, v81, v32, v116
	v_fma_f32 v117, v120, v82, v117
	v_fma_f32 v118, v120, v83, v118
	v_fma_f32 v117, -v124, v83, v117
	v_fma_f32 v124, v124, v82, v118
	v_mov_b32_e32 v120, v117
	v_mul_f32_e32 v116, v85, v37
	v_fma_f32 v117, v84, v33, -v116
	v_mul_f32_e32 v116, v84, v37
	v_fma_f32 v118, v85, v33, v116
	v_fma_f32 v117, v121, v86, v117
	v_fma_f32 v118, v121, v87, v118
	v_fma_f32 v117, -v125, v87, v117
	v_fma_f32 v125, v125, v86, v118
	v_mov_b32_e32 v121, v117
	v_mul_f32_e32 v116, v89, v38
	v_fma_f32 v117, v88, v34, -v116
	v_mul_f32_e32 v116, v88, v38
	v_fma_f32 v118, v89, v34, v116
	v_fma_f32 v117, v122, v90, v117
	v_fma_f32 v118, v122, v91, v118
	v_fma_f32 v117, -v126, v91, v117
	v_fma_f32 v126, v126, v90, v118
	v_mov_b32_e32 v122, v117
	v_mul_f32_e32 v116, v93, v39
	v_fma_f32 v117, v92, v35, -v116
	v_mul_f32_e32 v116, v92, v39
	v_fma_f32 v118, v93, v35, v116
	v_fma_f32 v117, v123, v94, v117
	v_fma_f32 v118, v123, v95, v118
	v_fma_f32 v117, -v127, v95, v117
	v_fma_f32 v127, v127, v94, v118
	v_mov_b32_e32 v123, v117
	v_mul_f32_e32 v116, v81, v28
	v_fma_f32 v117, v80, v24, -v116
	v_mul_f32_e32 v116, v80, v28
	v_fma_f32 v118, v81, v24, v116
	v_fma_f32 v117, v120, v82, v117
	v_fma_f32 v118, v120, v83, v118
	v_fma_f32 v117, -v124, v83, v117
	v_fma_f32 v124, v124, v82, v118
	v_mov_b32_e32 v120, v117
	v_mul_f32_e32 v116, v85, v29
	v_fma_f32 v117, v84, v25, -v116
	v_mul_f32_e32 v116, v84, v29
	v_fma_f32 v118, v85, v25, v116
	v_fma_f32 v117, v121, v86, v117
	v_fma_f32 v118, v121, v87, v118
	v_fma_f32 v117, -v125, v87, v117
	v_fma_f32 v125, v125, v86, v118
	v_mov_b32_e32 v121, v117
	v_mul_f32_e32 v116, v89, v30
	v_fma_f32 v117, v88, v26, -v116
	v_mul_f32_e32 v116, v88, v30
	v_fma_f32 v118, v89, v26, v116
	v_fma_f32 v117, v122, v90, v117
	v_fma_f32 v118, v122, v91, v118
	v_fma_f32 v117, -v126, v91, v117
	v_fma_f32 v126, v126, v90, v118
	v_mov_b32_e32 v122, v117
	v_mul_f32_e32 v116, v93, v31
	v_fma_f32 v117, v92, v27, -v116
	v_mul_f32_e32 v116, v92, v31
	v_fma_f32 v118, v93, v27, v116
	v_fma_f32 v117, v123, v94, v117
	v_fma_f32 v118, v123, v95, v118
	v_fma_f32 v117, -v127, v95, v117
	v_fma_f32 v127, v127, v94, v118
	v_mov_b32_e32 v123, v117
	v_mul_f32_e32 v116, v81, v20
	v_fma_f32 v117, v80, v16, -v116
	v_mul_f32_e32 v116, v80, v20
	v_fma_f32 v118, v81, v16, v116
	v_fma_f32 v117, v120, v82, v117
	v_fma_f32 v118, v120, v83, v118
	v_fma_f32 v117, -v124, v83, v117
	v_fma_f32 v124, v124, v82, v118
	v_mov_b32_e32 v120, v117
	v_mul_f32_e32 v116, v85, v21
	v_fma_f32 v117, v84, v17, -v116
	v_mul_f32_e32 v116, v84, v21
	v_fma_f32 v118, v85, v17, v116
	v_fma_f32 v117, v121, v86, v117
	v_fma_f32 v118, v121, v87, v118
	v_fma_f32 v117, -v125, v87, v117
	v_fma_f32 v125, v125, v86, v118
	v_mov_b32_e32 v121, v117
	v_mul_f32_e32 v116, v89, v22
	v_fma_f32 v117, v88, v18, -v116
	v_mul_f32_e32 v116, v88, v22
	v_fma_f32 v118, v89, v18, v116
	v_fma_f32 v117, v122, v90, v117
	v_fma_f32 v118, v122, v91, v118
	v_fma_f32 v117, -v126, v91, v117
	v_fma_f32 v126, v126, v90, v118
	v_mov_b32_e32 v122, v117
	v_mul_f32_e32 v116, v93, v23
	v_fma_f32 v117, v92, v19, -v116
	v_mul_f32_e32 v116, v92, v23
	v_fma_f32 v118, v93, v19, v116
	v_fma_f32 v117, v123, v94, v117
	v_fma_f32 v118, v123, v95, v118
	v_fma_f32 v117, -v127, v95, v117
	v_fma_f32 v127, v127, v94, v118
	v_mov_b32_e32 v123, v117
	v_add_f32_dpp v120, v120, v120 row_ror:8 row_mask:0xf bank_mask:0xf
	v_add_f32_dpp v121, v121, v121 row_ror:8 row_mask:0xf bank_mask:0xf
	v_add_f32_dpp v122, v122, v122 row_ror:8 row_mask:0xf bank_mask:0xf
	v_add_f32_dpp v123, v123, v123 row_ror:8 row_mask:0xf bank_mask:0xf
	v_add_f32_dpp v124, v124, v124 row_ror:8 row_mask:0xf bank_mask:0xf
	v_add_f32_dpp v125, v125, v125 row_ror:8 row_mask:0xf bank_mask:0xf
	v_add_f32_dpp v126, v126, v126 row_ror:8 row_mask:0xf bank_mask:0xf
	v_add_f32_dpp v127, v127, v127 row_ror:8 row_mask:0xf bank_mask:0xf
	v_add_f32_dpp v120, v120, v120 row_ror:4 row_mask:0xf bank_mask:0xf
	v_add_f32_dpp v121, v121, v121 row_ror:4 row_mask:0xf bank_mask:0xf
	v_add_f32_dpp v122, v122, v122 row_ror:4 row_mask:0xf bank_mask:0xf
	v_add_f32_dpp v123, v123, v123 row_ror:4 row_mask:0xf bank_mask:0xf
	v_add_f32_dpp v124, v124, v124 row_ror:4 row_mask:0xf bank_mask:0xf
	v_add_f32_dpp v125, v125, v125 row_ror:4 row_mask:0xf bank_mask:0xf
	v_add_f32_dpp v126, v126, v126 row_ror:4 row_mask:0xf bank_mask:0xf
	v_add_f32_dpp v127, v127, v127 row_ror:4 row_mask:0xf bank_mask:0xf
	v_add_f32_dpp v120, v120, v120 row_ror:2 row_mask:0xf bank_mask:0xf
	v_add_f32_dpp v121, v121, v121 row_ror:2 row_mask:0xf bank_mask:0xf
	v_add_f32_dpp v122, v122, v122 row_ror:2 row_mask:0xf bank_mask:0xf
	v_add_f32_dpp v123, v123, v123 row_ror:2 row_mask:0xf bank_mask:0xf
	v_add_f32_dpp v124, v124, v124 row_ror:2 row_mask:0xf bank_mask:0xf
	v_add_f32_dpp v125, v125, v125 row_ror:2 row_mask:0xf bank_mask:0xf
	v_add_f32_dpp v126, v126, v126 row_ror:2 row_mask:0xf bank_mask:0xf
	v_add_f32_dpp v127, v127, v127 row_ror:2 row_mask:0xf bank_mask:0xf
	v_add_f32_dpp v120, v120, v120 row_ror:1 row_mask:0xf bank_mask:0xf
	v_add_f32_dpp v121, v121, v121 row_ror:1 row_mask:0xf bank_mask:0xf
	v_add_f32_dpp v122, v122, v122 row_ror:1 row_mask:0xf bank_mask:0xf
	v_add_f32_dpp v123, v123, v123 row_ror:1 row_mask:0xf bank_mask:0xf
	v_add_f32_dpp v124, v124, v124 row_ror:1 row_mask:0xf bank_mask:0xf
	v_add_f32_dpp v125, v125, v125 row_ror:1 row_mask:0xf bank_mask:0xf
	v_add_f32_dpp v126, v126, v126 row_ror:1 row_mask:0xf bank_mask:0xf
	v_add_f32_dpp v127, v127, v127 row_ror:1 row_mask:0xf bank_mask:0xf
	s_add_u32 s18, s36, 256
	s_addc_u32 s19, s37, 0
	v_mov_b32_e32 v128, v120
	v_mov_b32_e32 v129, v124
	v_mov_b32_e32 v130, v121
	v_mov_b32_e32 v131, v125
	v_mov_b32_e32 v132, v122
	v_mov_b32_e32 v133, v126
	v_mov_b32_e32 v134, v123
	v_mov_b32_e32 v135, v127
	s_mov_b32 exec_lo, 0x10001
	s_mov_b32 exec_hi, 0x10001
	global_store_dwordx4 v114, v[128:131], s[18:19]
	global_store_dwordx4 v114, v[132:135], s[18:19] offset:16
	s_mov_b64 exec, -1
	s_nop 1
	s_waitcnt vmcnt(4)
	v_cvt_pk_bf16_f32 v64, v64, v65
	v_cvt_pk_bf16_f32 v65, v66, v67
	v_cvt_pk_bf16_f32 v66, v68, v69
	v_cvt_pk_bf16_f32 v67, v70, v71
	v_cvt_pk_bf16_f32 v72, v72, v73
	v_cvt_pk_bf16_f32 v73, v74, v75
	v_cvt_pk_bf16_f32 v74, v76, v77
	v_cvt_pk_bf16_f32 v75, v78, v79
	s_nop 1
	v_mfma_f32_16x16x32_bf16 v[16:19], v[64:67], v[0:3], 0
	v_mfma_f32_16x16x32_bf16 v[20:23], v[72:75], v[0:3], 0
	v_mfma_f32_16x16x32_bf16 v[24:27], v[64:67], v[4:7], 0
	v_mfma_f32_16x16x32_bf16 v[28:31], v[72:75], v[4:7], 0
	v_mfma_f32_16x16x32_bf16 v[32:35], v[64:67], v[8:11], 0
	v_mfma_f32_16x16x32_bf16 v[36:39], v[72:75], v[8:11], 0
	v_mfma_f32_16x16x32_bf16 v[40:43], v[64:67], v[12:15], 0
	v_mfma_f32_16x16x32_bf16 v[44:47], v[72:75], v[12:15], 0
	s_waitcnt vmcnt(0)
	s_nop 7
	v_mul_f32_e32 v116, v97, v44
	v_fma_f32 v120, v96, v40, -v116
	v_mul_f32_e32 v116, v96, v44
	v_fma_f32 v124, v97, v40, v116
	v_mul_f32_e32 v116, v101, v45
	v_fma_f32 v121, v100, v41, -v116
	v_mul_f32_e32 v116, v100, v45
	v_fma_f32 v125, v101, v41, v116
	v_mul_f32_e32 v116, v105, v46
	v_fma_f32 v122, v104, v42, -v116
	v_mul_f32_e32 v116, v104, v46
	v_fma_f32 v126, v105, v42, v116
	v_mul_f32_e32 v116, v109, v47
	v_fma_f32 v123, v108, v43, -v116
	v_mul_f32_e32 v116, v108, v47
	v_fma_f32 v127, v109, v43, v116
	v_mul_f32_e32 v116, v97, v36
	v_fma_f32 v117, v96, v32, -v116
	v_mul_f32_e32 v116, v96, v36
	v_fma_f32 v118, v97, v32, v116
	v_fma_f32 v117, v120, v98, v117
	v_fma_f32 v118, v120, v99, v118
	v_fma_f32 v117, -v124, v99, v117
	v_fma_f32 v124, v124, v98, v118
	v_mov_b32_e32 v120, v117
	v_mul_f32_e32 v116, v101, v37
	v_fma_f32 v117, v100, v33, -v116
	v_mul_f32_e32 v116, v100, v37
	v_fma_f32 v118, v101, v33, v116
	v_fma_f32 v117, v121, v102, v117
	v_fma_f32 v118, v121, v103, v118
	v_fma_f32 v117, -v125, v103, v117
	v_fma_f32 v125, v125, v102, v118
	v_mov_b32_e32 v121, v117
	v_mul_f32_e32 v116, v105, v38
	v_fma_f32 v117, v104, v34, -v116
	v_mul_f32_e32 v116, v104, v38
	v_fma_f32 v118, v105, v34, v116
	v_fma_f32 v117, v122, v106, v117
	v_fma_f32 v118, v122, v107, v118
	v_fma_f32 v117, -v126, v107, v117
	v_fma_f32 v126, v126, v106, v118
	v_mov_b32_e32 v122, v117
	v_mul_f32_e32 v116, v109, v39
	v_fma_f32 v117, v108, v35, -v116
	v_mul_f32_e32 v116, v108, v39
	v_fma_f32 v118, v109, v35, v116
	v_fma_f32 v117, v123, v110, v117
	v_fma_f32 v118, v123, v111, v118
	v_fma_f32 v117, -v127, v111, v117
	v_fma_f32 v127, v127, v110, v118
	v_mov_b32_e32 v123, v117
	v_mul_f32_e32 v116, v97, v28
	v_fma_f32 v117, v96, v24, -v116
	v_mul_f32_e32 v116, v96, v28
	v_fma_f32 v118, v97, v24, v116
	v_fma_f32 v117, v120, v98, v117
	v_fma_f32 v118, v120, v99, v118
	v_fma_f32 v117, -v124, v99, v117
	v_fma_f32 v124, v124, v98, v118
	v_mov_b32_e32 v120, v117
	v_mul_f32_e32 v116, v101, v29
	v_fma_f32 v117, v100, v25, -v116
	v_mul_f32_e32 v116, v100, v29
	v_fma_f32 v118, v101, v25, v116
	v_fma_f32 v117, v121, v102, v117
	v_fma_f32 v118, v121, v103, v118
	v_fma_f32 v117, -v125, v103, v117
	v_fma_f32 v125, v125, v102, v118
	v_mov_b32_e32 v121, v117
	v_mul_f32_e32 v116, v105, v30
	v_fma_f32 v117, v104, v26, -v116
	v_mul_f32_e32 v116, v104, v30
	v_fma_f32 v118, v105, v26, v116
	v_fma_f32 v117, v122, v106, v117
	v_fma_f32 v118, v122, v107, v118
	v_fma_f32 v117, -v126, v107, v117
	v_fma_f32 v126, v126, v106, v118
	v_mov_b32_e32 v122, v117
	v_mul_f32_e32 v116, v109, v31
	v_fma_f32 v117, v108, v27, -v116
	v_mul_f32_e32 v116, v108, v31
	v_fma_f32 v118, v109, v27, v116
	v_fma_f32 v117, v123, v110, v117
	v_fma_f32 v118, v123, v111, v118
	v_fma_f32 v117, -v127, v111, v117
	v_fma_f32 v127, v127, v110, v118
	v_mov_b32_e32 v123, v117
	v_mul_f32_e32 v116, v97, v20
	v_fma_f32 v117, v96, v16, -v116
	v_mul_f32_e32 v116, v96, v20
	v_fma_f32 v118, v97, v16, v116
	v_fma_f32 v117, v120, v98, v117
	v_fma_f32 v118, v120, v99, v118
	v_fma_f32 v117, -v124, v99, v117
	v_fma_f32 v124, v124, v98, v118
	v_mov_b32_e32 v120, v117
	v_mul_f32_e32 v116, v101, v21
	v_fma_f32 v117, v100, v17, -v116
	v_mul_f32_e32 v116, v100, v21
	v_fma_f32 v118, v101, v17, v116
	v_fma_f32 v117, v121, v102, v117
	v_fma_f32 v118, v121, v103, v118
	v_fma_f32 v117, -v125, v103, v117
	v_fma_f32 v125, v125, v102, v118
	v_mov_b32_e32 v121, v117
	v_mul_f32_e32 v116, v105, v22
	v_fma_f32 v117, v104, v18, -v116
	v_mul_f32_e32 v116, v104, v22
	v_fma_f32 v118, v105, v18, v116
	v_fma_f32 v117, v122, v106, v117
	v_fma_f32 v118, v122, v107, v118
	v_fma_f32 v117, -v126, v107, v117
	v_fma_f32 v126, v126, v106, v118
	v_mov_b32_e32 v122, v117
	v_mul_f32_e32 v116, v109, v23
	v_fma_f32 v117, v108, v19, -v116
	v_mul_f32_e32 v116, v108, v23
	v_fma_f32 v118, v109, v19, v116
	v_fma_f32 v117, v123, v110, v117
	v_fma_f32 v118, v123, v111, v118
	v_fma_f32 v117, -v127, v111, v117
	v_fma_f32 v127, v127, v110, v118
	v_mov_b32_e32 v123, v117
	v_add_f32_dpp v120, v120, v120 row_ror:8 row_mask:0xf bank_mask:0xf
	v_add_f32_dpp v121, v121, v121 row_ror:8 row_mask:0xf bank_mask:0xf
	v_add_f32_dpp v122, v122, v122 row_ror:8 row_mask:0xf bank_mask:0xf
	v_add_f32_dpp v123, v123, v123 row_ror:8 row_mask:0xf bank_mask:0xf
	v_add_f32_dpp v124, v124, v124 row_ror:8 row_mask:0xf bank_mask:0xf
	v_add_f32_dpp v125, v125, v125 row_ror:8 row_mask:0xf bank_mask:0xf
	v_add_f32_dpp v126, v126, v126 row_ror:8 row_mask:0xf bank_mask:0xf
	v_add_f32_dpp v127, v127, v127 row_ror:8 row_mask:0xf bank_mask:0xf
	v_add_f32_dpp v120, v120, v120 row_ror:4 row_mask:0xf bank_mask:0xf
	v_add_f32_dpp v121, v121, v121 row_ror:4 row_mask:0xf bank_mask:0xf
	v_add_f32_dpp v122, v122, v122 row_ror:4 row_mask:0xf bank_mask:0xf
	v_add_f32_dpp v123, v123, v123 row_ror:4 row_mask:0xf bank_mask:0xf
	v_add_f32_dpp v124, v124, v124 row_ror:4 row_mask:0xf bank_mask:0xf
	v_add_f32_dpp v125, v125, v125 row_ror:4 row_mask:0xf bank_mask:0xf
	v_add_f32_dpp v126, v126, v126 row_ror:4 row_mask:0xf bank_mask:0xf
	v_add_f32_dpp v127, v127, v127 row_ror:4 row_mask:0xf bank_mask:0xf
	v_add_f32_dpp v120, v120, v120 row_ror:2 row_mask:0xf bank_mask:0xf
	v_add_f32_dpp v121, v121, v121 row_ror:2 row_mask:0xf bank_mask:0xf
	v_add_f32_dpp v122, v122, v122 row_ror:2 row_mask:0xf bank_mask:0xf
	v_add_f32_dpp v123, v123, v123 row_ror:2 row_mask:0xf bank_mask:0xf
	v_add_f32_dpp v124, v124, v124 row_ror:2 row_mask:0xf bank_mask:0xf
	v_add_f32_dpp v125, v125, v125 row_ror:2 row_mask:0xf bank_mask:0xf
	v_add_f32_dpp v126, v126, v126 row_ror:2 row_mask:0xf bank_mask:0xf
	v_add_f32_dpp v127, v127, v127 row_ror:2 row_mask:0xf bank_mask:0xf
	v_add_f32_dpp v120, v120, v120 row_ror:1 row_mask:0xf bank_mask:0xf
	v_add_f32_dpp v121, v121, v121 row_ror:1 row_mask:0xf bank_mask:0xf
	v_add_f32_dpp v122, v122, v122 row_ror:1 row_mask:0xf bank_mask:0xf
	v_add_f32_dpp v123, v123, v123 row_ror:1 row_mask:0xf bank_mask:0xf
	v_add_f32_dpp v124, v124, v124 row_ror:1 row_mask:0xf bank_mask:0xf
	v_add_f32_dpp v125, v125, v125 row_ror:1 row_mask:0xf bank_mask:0xf
	v_add_f32_dpp v126, v126, v126 row_ror:1 row_mask:0xf bank_mask:0xf
	v_add_f32_dpp v127, v127, v127 row_ror:1 row_mask:0xf bank_mask:0xf
	s_add_u32 s18, s36, 384
	s_addc_u32 s19, s37, 0
	v_mov_b32_e32 v128, v120
	v_mov_b32_e32 v129, v124
	v_mov_b32_e32 v130, v121
	v_mov_b32_e32 v131, v125
	v_mov_b32_e32 v132, v122
	v_mov_b32_e32 v133, v126
	v_mov_b32_e32 v134, v123
	v_mov_b32_e32 v135, v127
	s_mov_b32 exec_lo, 0x10001
	s_mov_b32 exec_hi, 0x10001
	global_store_dwordx4 v114, v[128:131], s[18:19]
	global_store_dwordx4 v114, v[132:135], s[18:19] offset:16
	s_mov_b64 exec, -1
	s_nop 1

.LBB0_479:
	s_andn2_b64 vcc, exec, s[0:1]
	s_cbranch_vccnz .LBB0_609
	s_sub_i32 s86, s12, s13
	s_and_b32 s0, s86, 3
	s_bfe_u32 s1, s86, 0x10002
	s_bfe_u32 s6, s86, 0x20003
	s_bfe_u32 s7, s86, 0x50005
	s_lshr_b32 s8, s86, 10
	s_lshl_b32 s7, s7, 1
	s_or_b32 s1, s1, s7
	s_sub_i32 s7, s1, 4
	s_max_i32 s7, s7, 0
	s_min_i32 s7, s7, 56
	s_lshl_b32 s9, s0, 4
	s_sub_i32 s9, s9, 8
	s_max_i32 s9, s9, 0
	s_min_i32 s9, s9, 32
	v_and_b32_e32 v206, 15, v205
	v_lshrrev_b32_e32 v207, 4, v205
	s_mul_i32 s10, s6, 15
	s_add_i32 s10, s10, s7
	s_sub_i32 s10, s10, s1
	s_add_i32 s10, s10, 7
	s_mul_i32 s10, s10, 31
	s_add_i32 s10, s10, s9
	s_lshl_b32 s11, s0, 4
	s_sub_i32 s10, s10, s11
	s_add_i32 s10, s10, 15
	v_lshlrev_b32_e32 v214, 3, v207
	v_sub_u32_e32 v214, v214, v206
	v_add_u32_e32 v214, s10, v214
	v_ashrrev_i32_e32 v215, 31, v214
	v_lshl_add_u64 v[212:213], v[214:215], 2, s[56:57]
	global_load_dword v0, v[212:213], off offset:0
	global_load_dword v1, v[212:213], off offset:4
	global_load_dword v2, v[212:213], off offset:8
	global_load_dword v3, v[212:213], off offset:12
	global_load_dword v4, v[212:213], off offset:16
	global_load_dword v5, v[212:213], off offset:20
	global_load_dword v6, v[212:213], off offset:24
	global_load_dword v7, v[212:213], off offset:28
	global_load_dword v8, v[212:213], off offset:124
	global_load_dword v9, v[212:213], off offset:128
	global_load_dword v10, v[212:213], off offset:132
	global_load_dword v11, v[212:213], off offset:136
	global_load_dword v12, v[212:213], off offset:140
	global_load_dword v13, v[212:213], off offset:144
	global_load_dword v14, v[212:213], off offset:148
	global_load_dword v15, v[212:213], off offset:152
	global_load_dword v16, v[212:213], off offset:248
	global_load_dword v17, v[212:213], off offset:252
	global_load_dword v18, v[212:213], off offset:256
	global_load_dword v19, v[212:213], off offset:260
	global_load_dword v20, v[212:213], off offset:264
	global_load_dword v21, v[212:213], off offset:268
	global_load_dword v22, v[212:213], off offset:272
	global_load_dword v23, v[212:213], off offset:276
	global_load_dword v24, v[212:213], off offset:372
	global_load_dword v25, v[212:213], off offset:376
	global_load_dword v26, v[212:213], off offset:380
	global_load_dword v27, v[212:213], off offset:384
	global_load_dword v28, v[212:213], off offset:388
	global_load_dword v29, v[212:213], off offset:392
	global_load_dword v30, v[212:213], off offset:396
	global_load_dword v31, v[212:213], off offset:400
	s_lshl_b32 s10, s8, 12
	s_lshl_b32 s11, s1, 6
	s_add_i32 s10, s10, s11
	s_lshl_b32 s11, s0, 4
	s_add_i32 s10, s10, s11
	s_addk_i32 s10, 0x400
	s_mul_i32 s11, s10, 0xe00
	s_lshl_b32 s16, s6, 7
	s_add_u32 s16, s16, 0x5e00000
	s_add_u32 s18, s4, s16
	s_addc_u32 s19, s5, 0
	s_add_u32 s20, s18, s11
	s_addc_u32 s21, s19, 0
	v_mul_u32_u24_e32 v208, 0xe00, v206
	v_lshl_add_u32 v208, v207, 4, v208
	global_load_dwordx4 v[128:131], v208, s[20:21] offset:1536
	global_load_dwordx4 v[132:135], v208, s[20:21] offset:1600
	v_lshrrev_b32_e32 v209, 2, v206
	v_and_b32_e32 v210, 3, v206
	v_lshl_add_u32 v209, v209, 3, v210
	v_mul_u32_u24_e32 v209, 0xe00, v209
	v_lshl_add_u32 v209, v207, 4, v209
	s_lshl_b32 s10, s8, 12
	s_lshl_b32 s11, s7, 6
	s_add_i32 s10, s10, s11
	s_add_i32 s10, s10, s9
	s_addk_i32 s10, 0x400
	s_mul_i32 s10, s10, 0xe00
	s_add_u32 s22, s18, s10
	s_addc_u32 s23, s19, 0
	s_lshl_b32 s10, s8, 8
	s_mul_i32 s10, s10, 0xe00
	s_add_u32 s24, s18, s10
	s_addc_u32 s25, s19, 0
	global_load_dwordx4 v[138:141], v209, s[22:23] offset:2048
	global_load_dwordx4 v[142:145], v209, s[22:23] offset:2112
	s_add_u32 s22, s22, 0x3800
	s_addc_u32 s23, s23, 0
	global_load_dwordx4 v[146:149], v209, s[22:23] offset:2048
	global_load_dwordx4 v[150:153], v209, s[22:23] offset:2112
	s_add_u32 s22, s22, 0x34800
	s_addc_u32 s23, s23, 0
	global_load_dwordx4 v[154:157], v209, s[22:23] offset:2048
	global_load_dwordx4 v[158:161], v209, s[22:23] offset:2112
	s_add_u32 s22, s22, 0x3800
	s_addc_u32 s23, s23, 0
	global_load_dwordx4 v[162:165], v209, s[22:23] offset:2048
	global_load_dwordx4 v[166:169], v209, s[22:23] offset:2112
	s_add_u32 s22, s22, 0x34800
	s_addc_u32 s23, s23, 0
	global_load_dwordx4 v[170:173], v209, s[22:23] offset:2048
	global_load_dwordx4 v[174:177], v209, s[22:23] offset:2112
	s_add_u32 s22, s22, 0x3800
	s_addc_u32 s23, s23, 0
	global_load_dwordx4 v[178:181], v209, s[22:23] offset:2048
	global_load_dwordx4 v[182:185], v209, s[22:23] offset:2112
	s_add_u32 s22, s22, 0x34800
	s_addc_u32 s23, s23, 0
	s_lshl_b32 s10, s0, 4
	s_sub_i32 s10, s10, 8
	v_add_u32_e32 v210, s10, v206
	v_med3_i32 v210, v210, 0, 48
	v_lshl_add_u32 v211, v207, 3, s9
	v_sub_u32_e32 v210, v211, v210
	v_writelane_b32 v136, s0, 0
	v_writelane_b32 v136, s1, 1
	v_writelane_b32 v136, s6, 2
	v_writelane_b32 v136, s7, 3
	v_writelane_b32 v136, s8, 4
	v_writelane_b32 v136, s9, 5
	v_add_u32_e32 v211, 0, v210
	v_cmp_gt_u32_e64 s[26:27], 16, v211
	v_add_u32_e32 v211, 1, v210
	v_cmp_gt_u32_e64 s[36:37], 16, v211
	v_add_u32_e32 v211, 2, v210
	v_cmp_gt_u32_e64 s[10:11], 16, v211
	v_add_u32_e32 v211, 3, v210
	v_cmp_gt_u32_e64 s[0:1], 16, v211
	v_add_u32_e32 v211, 4, v210
	v_cmp_gt_u32_e64 s[6:7], 16, v211
	v_add_u32_e32 v211, 5, v210
	v_cmp_gt_u32_e64 s[8:9], 16, v211
	v_add_u32_e32 v211, 6, v210
	v_cmp_gt_u32_e64 s[16:17], 16, v211
	v_add_u32_e32 v211, 7, v210
	v_cmp_gt_u32_e64 s[20:21], 16, v211
	v_mov_b32_e32 v216, 0xf2c9f2ca
	s_waitcnt vmcnt(14)
	v_mul_f32_e32 v0, 0x41000000, v0
	v_mul_f32_e32 v1, 0x41000000, v1
	v_mul_f32_e32 v2, 0x41000000, v2
	v_mul_f32_e32 v3, 0x41000000, v3
	v_mul_f32_e32 v4, 0x41000000, v4
	v_mul_f32_e32 v5, 0x41000000, v5
	v_mul_f32_e32 v6, 0x41000000, v6
	v_mul_f32_e32 v7, 0x41000000, v7
	v_cndmask_b32_e64 v0, v216, v0, s[26:27]
	v_cndmask_b32_e64 v1, v216, v1, s[36:37]
	v_cndmask_b32_e64 v2, v216, v2, s[10:11]
	v_cndmask_b32_e64 v3, v216, v3, s[0:1]
	v_cndmask_b32_e64 v4, v216, v4, s[6:7]
	v_cndmask_b32_e64 v5, v216, v5, s[8:9]
	v_cndmask_b32_e64 v6, v216, v6, s[16:17]
	v_cndmask_b32_e64 v7, v216, v7, s[20:21]
	v_mul_f32_e32 v8, 0x41000000, v8
	v_mul_f32_e32 v9, 0x41000000, v9
	v_mul_f32_e32 v10, 0x41000000, v10
	v_mul_f32_e32 v11, 0x41000000, v11
	v_mul_f32_e32 v12, 0x41000000, v12
	v_mul_f32_e32 v13, 0x41000000, v13
	v_mul_f32_e32 v14, 0x41000000, v14
	v_mul_f32_e32 v15, 0x41000000, v15
	v_cndmask_b32_e64 v8, v216, v8, s[26:27]
	v_cndmask_b32_e64 v9, v216, v9, s[36:37]
	v_cndmask_b32_e64 v10, v216, v10, s[10:11]
	v_cndmask_b32_e64 v11, v216, v11, s[0:1]
	v_cndmask_b32_e64 v12, v216, v12, s[6:7]
	v_cndmask_b32_e64 v13, v216, v13, s[8:9]
	v_cndmask_b32_e64 v14, v216, v14, s[16:17]
	v_cndmask_b32_e64 v15, v216, v15, s[20:21]
	v_mul_f32_e32 v16, 0x41000000, v16
	v_mul_f32_e32 v17, 0x41000000, v17
	v_mul_f32_e32 v18, 0x41000000, v18
	v_mul_f32_e32 v19, 0x41000000, v19
	v_mul_f32_e32 v20, 0x41000000, v20
	v_mul_f32_e32 v21, 0x41000000, v21
	v_mul_f32_e32 v22, 0x41000000, v22
	v_mul_f32_e32 v23, 0x41000000, v23
	v_cndmask_b32_e64 v16, v216, v16, s[26:27]
	v_cndmask_b32_e64 v17, v216, v17, s[36:37]
	v_cndmask_b32_e64 v18, v216, v18, s[10:11]
	v_cndmask_b32_e64 v19, v216, v19, s[0:1]
	v_cndmask_b32_e64 v20, v216, v20, s[6:7]
	v_cndmask_b32_e64 v21, v216, v21, s[8:9]
	v_cndmask_b32_e64 v22, v216, v22, s[16:17]
	v_cndmask_b32_e64 v23, v216, v23, s[20:21]
	v_mul_f32_e32 v24, 0x41000000, v24
	v_mul_f32_e32 v25, 0x41000000, v25
	v_mul_f32_e32 v26, 0x41000000, v26
	v_mul_f32_e32 v27, 0x41000000, v27
	v_mul_f32_e32 v28, 0x41000000, v28
	v_mul_f32_e32 v29, 0x41000000, v29
	v_mul_f32_e32 v30, 0x41000000, v30
	v_mul_f32_e32 v31, 0x41000000, v31
	v_cndmask_b32_e64 v24, v216, v24, s[26:27]
	v_cndmask_b32_e64 v25, v216, v25, s[36:37]
	v_cndmask_b32_e64 v26, v216, v26, s[10:11]
	v_cndmask_b32_e64 v27, v216, v27, s[0:1]
	v_cndmask_b32_e64 v28, v216, v28, s[6:7]
	v_cndmask_b32_e64 v29, v216, v29, s[8:9]
	v_cndmask_b32_e64 v30, v216, v30, s[16:17]
	v_cndmask_b32_e64 v31, v216, v31, s[20:21]
	global_load_dword v32, v[212:213], off offset:496
	global_load_dword v33, v[212:213], off offset:500
	global_load_dword v34, v[212:213], off offset:504
	global_load_dword v35, v[212:213], off offset:508
	global_load_dword v36, v[212:213], off offset:512
	global_load_dword v37, v[212:213], off offset:516
	global_load_dword v38, v[212:213], off offset:520
	global_load_dword v39, v[212:213], off offset:524
	global_load_dword v40, v[212:213], off offset:620
	global_load_dword v41, v[212:213], off offset:624
	global_load_dword v42, v[212:213], off offset:628
	global_load_dword v43, v[212:213], off offset:632
	global_load_dword v44, v[212:213], off offset:636
	global_load_dword v45, v[212:213], off offset:640
	global_load_dword v46, v[212:213], off offset:644
	global_load_dword v47, v[212:213], off offset:648
	global_load_dword v48, v[212:213], off offset:744
	global_load_dword v49, v[212:213], off offset:748
	global_load_dword v50, v[212:213], off offset:752
	global_load_dword v51, v[212:213], off offset:756
	global_load_dword v52, v[212:213], off offset:760
	global_load_dword v53, v[212:213], off offset:764
	global_load_dword v54, v[212:213], off offset:768
	global_load_dword v55, v[212:213], off offset:772
	global_load_dword v56, v[212:213], off offset:868
	global_load_dword v57, v[212:213], off offset:872
	global_load_dword v58, v[212:213], off offset:876
	global_load_dword v59, v[212:213], off offset:880
	global_load_dword v60, v[212:213], off offset:884
	global_load_dword v61, v[212:213], off offset:888
	global_load_dword v62, v[212:213], off offset:892
	global_load_dword v63, v[212:213], off offset:896
	s_waitcnt vmcnt(0)
	v_mul_f32_e32 v32, 0x41000000, v32
	v_mul_f32_e32 v33, 0x41000000, v33
	v_mul_f32_e32 v34, 0x41000000, v34
	v_mul_f32_e32 v35, 0x41000000, v35
	v_mul_f32_e32 v36, 0x41000000, v36
	v_mul_f32_e32 v37, 0x41000000, v37
	v_mul_f32_e32 v38, 0x41000000, v38
	v_mul_f32_e32 v39, 0x41000000, v39
	v_cndmask_b32_e64 v32, v216, v32, s[26:27]
	v_cndmask_b32_e64 v33, v216, v33, s[36:37]
	v_cndmask_b32_e64 v34, v216, v34, s[10:11]
	v_cndmask_b32_e64 v35, v216, v35, s[0:1]
	v_cndmask_b32_e64 v36, v216, v36, s[6:7]
	v_cndmask_b32_e64 v37, v216, v37, s[8:9]
	v_cndmask_b32_e64 v38, v216, v38, s[16:17]
	v_cndmask_b32_e64 v39, v216, v39, s[20:21]
	v_mul_f32_e32 v40, 0x41000000, v40
	v_mul_f32_e32 v41, 0x41000000, v41
	v_mul_f32_e32 v42, 0x41000000, v42
	v_mul_f32_e32 v43, 0x41000000, v43
	v_mul_f32_e32 v44, 0x41000000, v44
	v_mul_f32_e32 v45, 0x41000000, v45
	v_mul_f32_e32 v46, 0x41000000, v46
	v_mul_f32_e32 v47, 0x41000000, v47
	v_cndmask_b32_e64 v40, v216, v40, s[26:27]
	v_cndmask_b32_e64 v41, v216, v41, s[36:37]
	v_cndmask_b32_e64 v42, v216, v42, s[10:11]
	v_cndmask_b32_e64 v43, v216, v43, s[0:1]
	v_cndmask_b32_e64 v44, v216, v44, s[6:7]
	v_cndmask_b32_e64 v45, v216, v45, s[8:9]
	v_cndmask_b32_e64 v46, v216, v46, s[16:17]
	v_cndmask_b32_e64 v47, v216, v47, s[20:21]
	v_mul_f32_e32 v48, 0x41000000, v48
	v_mul_f32_e32 v49, 0x41000000, v49
	v_mul_f32_e32 v50, 0x41000000, v50
	v_mul_f32_e32 v51, 0x41000000, v51
	v_mul_f32_e32 v52, 0x41000000, v52
	v_mul_f32_e32 v53, 0x41000000, v53
	v_mul_f32_e32 v54, 0x41000000, v54
	v_mul_f32_e32 v55, 0x41000000, v55
	v_cndmask_b32_e64 v48, v216, v48, s[26:27]
	v_cndmask_b32_e64 v49, v216, v49, s[36:37]
	v_cndmask_b32_e64 v50, v216, v50, s[10:11]
	v_cndmask_b32_e64 v51, v216, v51, s[0:1]
	v_cndmask_b32_e64 v52, v216, v52, s[6:7]
	v_cndmask_b32_e64 v53, v216, v53, s[8:9]
	v_cndmask_b32_e64 v54, v216, v54, s[16:17]
	v_cndmask_b32_e64 v55, v216, v55, s[20:21]
	v_mul_f32_e32 v56, 0x41000000, v56
	v_mul_f32_e32 v57, 0x41000000, v57
	v_mul_f32_e32 v58, 0x41000000, v58
	v_mul_f32_e32 v59, 0x41000000, v59
	v_mul_f32_e32 v60, 0x41000000, v60
	v_mul_f32_e32 v61, 0x41000000, v61
	v_mul_f32_e32 v62, 0x41000000, v62
	v_mul_f32_e32 v63, 0x41000000, v63
	v_cndmask_b32_e64 v56, v216, v56, s[26:27]
	v_cndmask_b32_e64 v57, v216, v57, s[36:37]
	v_cndmask_b32_e64 v58, v216, v58, s[10:11]
	v_cndmask_b32_e64 v59, v216, v59, s[0:1]
	v_cndmask_b32_e64 v60, v216, v60, s[6:7]
	v_cndmask_b32_e64 v61, v216, v61, s[8:9]
	v_cndmask_b32_e64 v62, v216, v62, s[16:17]
	v_cndmask_b32_e64 v63, v216, v63, s[20:21]
	v_readlane_b32 s0, v136, 0
	v_readlane_b32 s1, v136, 1
	v_readlane_b32 s6, v136, 2
	v_readlane_b32 s7, v136, 3
	v_readlane_b32 s8, v136, 4
	v_readlane_b32 s9, v136, 5
	v_mfma_f32_16x16x32_bf16 v[0:3], v[138:141], v[128:131], v[0:3]
	v_mfma_f32_16x16x32_bf16 v[0:3], v[142:145], v[132:135], v[0:3]
	global_load_dwordx4 v[138:141], v209, s[22:23] offset:2048
	global_load_dwordx4 v[142:145], v209, s[22:23] offset:2112
	s_add_u32 s22, s22, 0x3800
	s_addc_u32 s23, s23, 0
	v_mfma_f32_16x16x32_bf16 v[4:7], v[146:149], v[128:131], v[4:7]
	v_mfma_f32_16x16x32_bf16 v[4:7], v[150:153], v[132:135], v[4:7]
	global_load_dwordx4 v[146:149], v209, s[22:23] offset:2048
	global_load_dwordx4 v[150:153], v209, s[22:23] offset:2112
	s_add_u32 s22, s22, 0x34800
	s_addc_u32 s23, s23, 0
	v_mfma_f32_16x16x32_bf16 v[8:11], v[154:157], v[128:131], v[8:11]
	v_mfma_f32_16x16x32_bf16 v[8:11], v[158:161], v[132:135], v[8:11]
	global_load_dwordx4 v[154:157], v209, s[22:23] offset:2048
	global_load_dwordx4 v[158:161], v209, s[22:23] offset:2112
	s_add_u32 s22, s22, 0x3800
	s_addc_u32 s23, s23, 0
	v_mfma_f32_16x16x32_bf16 v[12:15], v[162:165], v[128:131], v[12:15]
	v_mfma_f32_16x16x32_bf16 v[12:15], v[166:169], v[132:135], v[12:15]
	global_load_dwordx4 v[162:165], v209, s[22:23] offset:2048
	global_load_dwordx4 v[166:169], v209, s[22:23] offset:2112
	s_add_u32 s22, s22, 0x34800
	s_addc_u32 s23, s23, 0
	v_mfma_f32_16x16x32_bf16 v[16:19], v[170:173], v[128:131], v[16:19]
	v_mfma_f32_16x16x32_bf16 v[16:19], v[174:177], v[132:135], v[16:19]
	global_load_dwordx4 v[170:173], v209, s[22:23] offset:2048
	global_load_dwordx4 v[174:177], v209, s[22:23] offset:2112
	s_add_u32 s22, s22, 0x3800
	s_addc_u32 s23, s23, 0
	v_mfma_f32_16x16x32_bf16 v[20:23], v[178:181], v[128:131], v[20:23]
	v_mfma_f32_16x16x32_bf16 v[20:23], v[182:185], v[132:135], v[20:23]
	global_load_dwordx4 v[178:181], v209, s[22:23] offset:2048
	global_load_dwordx4 v[182:185], v209, s[22:23] offset:2112
	s_add_u32 s22, s22, 0x34800
	s_addc_u32 s23, s23, 0
	s_waitcnt vmcnt(11)
	v_mfma_f32_16x16x32_bf16 v[24:27], v[138:141], v[128:131], v[24:27]
	s_waitcnt vmcnt(10)
	v_mfma_f32_16x16x32_bf16 v[24:27], v[142:145], v[132:135], v[24:27]
	global_load_dwordx4 v[138:141], v209, s[22:23] offset:2048
	global_load_dwordx4 v[142:145], v209, s[22:23] offset:2112
	s_add_u32 s22, s22, 0x3800
	s_addc_u32 s23, s23, 0
	s_waitcnt vmcnt(11)
	v_mfma_f32_16x16x32_bf16 v[28:31], v[146:149], v[128:131], v[28:31]
	s_waitcnt vmcnt(10)
	v_mfma_f32_16x16x32_bf16 v[28:31], v[150:153], v[132:135], v[28:31]
	global_load_dwordx4 v[146:149], v209, s[22:23] offset:2048
	global_load_dwordx4 v[150:153], v209, s[22:23] offset:2112
	s_add_u32 s22, s22, 0x34800
	s_addc_u32 s23, s23, 0
	s_waitcnt vmcnt(11)
	v_mfma_f32_16x16x32_bf16 v[32:35], v[154:157], v[128:131], v[32:35]
	s_waitcnt vmcnt(10)
	v_mfma_f32_16x16x32_bf16 v[32:35], v[158:161], v[132:135], v[32:35]
	global_load_dwordx4 v[154:157], v209, s[22:23] offset:2048
	global_load_dwordx4 v[158:161], v209, s[22:23] offset:2112
	s_add_u32 s22, s22, 0x3800
	s_addc_u32 s23, s23, 0
	s_waitcnt vmcnt(11)
	v_mfma_f32_16x16x32_bf16 v[36:39], v[162:165], v[128:131], v[36:39]
	s_waitcnt vmcnt(10)
	v_mfma_f32_16x16x32_bf16 v[36:39], v[166:169], v[132:135], v[36:39]
	global_load_dwordx4 v[162:165], v209, s[22:23] offset:2048
	global_load_dwordx4 v[166:169], v209, s[22:23] offset:2112
	s_waitcnt vmcnt(11)
	v_mfma_f32_16x16x32_bf16 v[40:43], v[170:173], v[128:131], v[40:43]
	s_waitcnt vmcnt(10)
	v_mfma_f32_16x16x32_bf16 v[40:43], v[174:177], v[132:135], v[40:43]
	global_load_dwordx4 v[170:173], v209, s[24:25] offset:2048
	global_load_dwordx4 v[174:177], v209, s[24:25] offset:2112
	s_add_u32 s24, s24, 0x3800
	s_addc_u32 s25, s25, 0
	s_waitcnt vmcnt(11)
	v_mfma_f32_16x16x32_bf16 v[44:47], v[178:181], v[128:131], v[44:47]
	s_waitcnt vmcnt(10)
	v_mfma_f32_16x16x32_bf16 v[44:47], v[182:185], v[132:135], v[44:47]
	global_load_dwordx4 v[178:181], v209, s[24:25] offset:2048
	global_load_dwordx4 v[182:185], v209, s[24:25] offset:2112
	s_add_u32 s24, s24, 0x18800
	s_addc_u32 s25, s25, 0
	s_waitcnt vmcnt(11)
	v_mfma_f32_16x16x32_bf16 v[48:51], v[138:141], v[128:131], v[48:51]
	s_waitcnt vmcnt(10)
	v_mfma_f32_16x16x32_bf16 v[48:51], v[142:145], v[132:135], v[48:51]
	global_load_dwordx4 v[138:141], v209, s[24:25] offset:2048
	global_load_dwordx4 v[142:145], v209, s[24:25] offset:2112
	s_add_u32 s24, s24, 0x3800
	s_addc_u32 s25, s25, 0
	s_waitcnt vmcnt(11)
	v_mfma_f32_16x16x32_bf16 v[52:55], v[146:149], v[128:131], v[52:55]
	s_waitcnt vmcnt(10)
	v_mfma_f32_16x16x32_bf16 v[52:55], v[150:153], v[132:135], v[52:55]
	global_load_dwordx4 v[146:149], v209, s[24:25] offset:2048
	global_load_dwordx4 v[150:153], v209, s[24:25] offset:2112
	s_add_u32 s24, s24, 0x18800
	s_addc_u32 s25, s25, 0
	s_waitcnt vmcnt(11)
	v_mfma_f32_16x16x32_bf16 v[56:59], v[154:157], v[128:131], v[56:59]
	s_waitcnt vmcnt(10)
	v_mfma_f32_16x16x32_bf16 v[56:59], v[158:161], v[132:135], v[56:59]
	global_load_dwordx4 v[154:157], v209, s[24:25] offset:2048
	global_load_dwordx4 v[158:161], v209, s[24:25] offset:2112
	s_add_u32 s24, s24, 0x3800
	s_addc_u32 s25, s25, 0
	s_waitcnt vmcnt(11)
	v_mfma_f32_16x16x32_bf16 v[60:63], v[162:165], v[128:131], v[60:63]
	s_waitcnt vmcnt(10)
	v_mfma_f32_16x16x32_bf16 v[60:63], v[166:169], v[132:135], v[60:63]
	global_load_dwordx4 v[162:165], v209, s[24:25] offset:2048
	global_load_dwordx4 v[166:169], v209, s[24:25] offset:2112
	s_add_u32 s24, s24, 0x18800
	s_addc_u32 s25, s25, 0
	s_waitcnt vmcnt(11)
	v_mfma_f32_16x16x32_bf16 v[64:67], v[170:173], v[128:131], 0
	s_waitcnt vmcnt(10)
	v_mfma_f32_16x16x32_bf16 v[64:67], v[174:177], v[132:135], v[64:67]
	global_load_dwordx4 v[170:173], v209, s[24:25] offset:2048
	global_load_dwordx4 v[174:177], v209, s[24:25] offset:2112
	s_add_u32 s24, s24, 0x3800
	s_addc_u32 s25, s25, 0
	s_waitcnt vmcnt(11)
	v_mfma_f32_16x16x32_bf16 v[68:71], v[178:181], v[128:131], 0
	s_waitcnt vmcnt(10)
	v_mfma_f32_16x16x32_bf16 v[68:71], v[182:185], v[132:135], v[68:71]
	global_load_dwordx4 v[178:181], v209, s[24:25] offset:2048
	global_load_dwordx4 v[182:185], v209, s[24:25] offset:2112
	s_add_u32 s24, s24, 0x18800
	s_addc_u32 s25, s25, 0
	s_waitcnt vmcnt(11)
	v_mfma_f32_16x16x32_bf16 v[72:75], v[138:141], v[128:131], 0
	s_waitcnt vmcnt(10)
	v_mfma_f32_16x16x32_bf16 v[72:75], v[142:145], v[132:135], v[72:75]
	global_load_dwordx4 v[138:141], v209, s[24:25] offset:2048
	global_load_dwordx4 v[142:145], v209, s[24:25] offset:2112
	s_add_u32 s24, s24, 0x3800
	s_addc_u32 s25, s25, 0
	s_waitcnt vmcnt(11)
	v_mfma_f32_16x16x32_bf16 v[76:79], v[146:149], v[128:131], 0
	s_waitcnt vmcnt(10)
	v_mfma_f32_16x16x32_bf16 v[76:79], v[150:153], v[132:135], v[76:79]
	global_load_dwordx4 v[146:149], v209, s[24:25] offset:2048
	global_load_dwordx4 v[150:153], v209, s[24:25] offset:2112
	s_add_u32 s24, s24, 0x18800
	s_addc_u32 s25, s25, 0
	s_waitcnt vmcnt(11)
	v_mfma_f32_16x16x32_bf16 v[80:83], v[154:157], v[128:131], 0
	s_waitcnt vmcnt(10)
	v_mfma_f32_16x16x32_bf16 v[80:83], v[158:161], v[132:135], v[80:83]
	global_load_dwordx4 v[154:157], v209, s[24:25] offset:2048
	global_load_dwordx4 v[158:161], v209, s[24:25] offset:2112
	s_add_u32 s24, s24, 0x3800
	s_addc_u32 s25, s25, 0
	s_waitcnt vmcnt(11)
	v_mfma_f32_16x16x32_bf16 v[84:87], v[162:165], v[128:131], 0
	s_waitcnt vmcnt(10)
	v_mfma_f32_16x16x32_bf16 v[84:87], v[166:169], v[132:135], v[84:87]
	global_load_dwordx4 v[162:165], v209, s[24:25] offset:2048
	global_load_dwordx4 v[166:169], v209, s[24:25] offset:2112
	s_add_u32 s24, s24, 0x18800
	s_addc_u32 s25, s25, 0
	s_waitcnt vmcnt(11)
	v_mfma_f32_16x16x32_bf16 v[88:91], v[170:173], v[128:131], 0
	s_waitcnt vmcnt(10)
	v_mfma_f32_16x16x32_bf16 v[88:91], v[174:177], v[132:135], v[88:91]
	global_load_dwordx4 v[170:173], v209, s[24:25] offset:2048
	global_load_dwordx4 v[174:177], v209, s[24:25] offset:2112
	s_add_u32 s24, s24, 0x3800
	s_addc_u32 s25, s25, 0
	s_waitcnt vmcnt(11)
	v_mfma_f32_16x16x32_bf16 v[92:95], v[178:181], v[128:131], 0
	s_waitcnt vmcnt(10)
	v_mfma_f32_16x16x32_bf16 v[92:95], v[182:185], v[132:135], v[92:95]
	global_load_dwordx4 v[178:181], v209, s[24:25] offset:2048
	global_load_dwordx4 v[182:185], v209, s[24:25] offset:2112
	s_add_u32 s24, s24, 0x18800
	s_addc_u32 s25, s25, 0
	s_waitcnt vmcnt(11)
	v_mfma_f32_16x16x32_bf16 v[96:99], v[138:141], v[128:131], 0
	s_waitcnt vmcnt(10)
	v_mfma_f32_16x16x32_bf16 v[96:99], v[142:145], v[132:135], v[96:99]
	global_load_dwordx4 v[138:141], v209, s[24:25] offset:2048
	global_load_dwordx4 v[142:145], v209, s[24:25] offset:2112
	s_add_u32 s24, s24, 0x3800
	s_addc_u32 s25, s25, 0
	s_waitcnt vmcnt(11)
	v_mfma_f32_16x16x32_bf16 v[100:103], v[146:149], v[128:131], 0
	s_waitcnt vmcnt(10)
	v_mfma_f32_16x16x32_bf16 v[100:103], v[150:153], v[132:135], v[100:103]
	global_load_dwordx4 v[146:149], v209, s[24:25] offset:2048
	global_load_dwordx4 v[150:153], v209, s[24:25] offset:2112
	s_waitcnt vmcnt(11)
	v_mfma_f32_16x16x32_bf16 v[104:107], v[154:157], v[128:131], 0
	s_waitcnt vmcnt(10)
	v_mfma_f32_16x16x32_bf16 v[104:107], v[158:161], v[132:135], v[104:107]
	s_waitcnt vmcnt(9)
	v_mfma_f32_16x16x32_bf16 v[108:111], v[162:165], v[128:131], 0
	s_waitcnt vmcnt(8)
	v_mfma_f32_16x16x32_bf16 v[108:111], v[166:169], v[132:135], v[108:111]
	s_waitcnt vmcnt(7)
	v_mfma_f32_16x16x32_bf16 v[112:115], v[170:173], v[128:131], 0
	s_waitcnt vmcnt(6)
	v_mfma_f32_16x16x32_bf16 v[112:115], v[174:177], v[132:135], v[112:115]
	s_waitcnt vmcnt(5)
	v_mfma_f32_16x16x32_bf16 v[116:119], v[178:181], v[128:131], 0
	s_waitcnt vmcnt(4)
	v_mfma_f32_16x16x32_bf16 v[116:119], v[182:185], v[132:135], v[116:119]
	s_waitcnt vmcnt(3)
	v_mfma_f32_16x16x32_bf16 v[120:123], v[138:141], v[128:131], 0
	s_waitcnt vmcnt(2)
	v_mfma_f32_16x16x32_bf16 v[120:123], v[142:145], v[132:135], v[120:123]
	s_waitcnt vmcnt(1)
	v_mfma_f32_16x16x32_bf16 v[124:127], v[146:149], v[128:131], 0
	s_waitcnt vmcnt(0)
	v_mfma_f32_16x16x32_bf16 v[124:127], v[150:153], v[132:135], v[124:127]
	v_lshlrev_b32_e32 v210, 13, v206
	v_lshl_add_u32 v210, v207, 4, v210
	v_lshlrev_b32_e32 v211, 9, v206
	v_lshl_add_u32 v211, v207, 4, v211
	s_lshl_b32 s10, s8, 8
	s_lshl_b32 s11, s6, 6
	s_add_i32 s10, s10, s11
	s_lshl_b32 s11, s10, 13
	s_lshl_b32 s38, s7, 7
	s_add_i32 s11, s11, s38
	s_lshl_b32 s38, s9, 1
	s_add_i32 s11, s11, s38
	s_add_u32 s11, s11, 0x9a00000
	s_add_u32 s16, s4, s11
	s_addc_u32 s17, s5, 0
	s_add_u32 s18, s16, 0x20000
	s_addc_u32 s19, s17, 0
	s_add_u32 s20, s18, 0x20000
	s_addc_u32 s21, s19, 0
	s_add_u32 s22, s20, 0x20000
	s_addc_u32 s23, s21, 0
	s_lshl_b32 s11, s10, 9
	s_add_u32 s11, s11, 0xa200000
	s_add_u32 s24, s4, s11
	s_addc_u32 s25, s5, 0
	s_add_u32 s26, s24, 0x2000
	s_addc_u32 s27, s25, 0
	s_add_u32 s36, s26, 0x2000
	s_addc_u32 s37, s27, 0
	s_lshl_b32 s10, s8, 12
	s_lshl_b32 s11, s1, 6
	s_add_i32 s10, s10, s11
	s_lshl_b32 s11, s0, 4
	s_add_i32 s10, s10, s11
	s_addk_i32 s10, 0x400
	s_mul_i32 s10, s10, 0x600
	s_lshl_b32 s11, s6, 7
	s_add_i32 s10, s10, s11
	s_add_u32 s38, s10, 0xdf00400
	s_add_u32 s0, s36, 0x2000
	s_addc_u32 s1, s37, 0
	global_load_dwordx4 v[138:141], v210, s[16:17] offset:0
	global_load_dwordx4 v[142:145], v210, s[18:19] offset:0
	global_load_dwordx4 v[146:149], v210, s[20:21] offset:0
	global_load_dwordx4 v[150:153], v210, s[22:23] offset:0
	global_load_dwordx4 v[154:157], v210, s[16:17] offset:128
	global_load_dwordx4 v[158:161], v210, s[18:19] offset:128
	global_load_dwordx4 v[162:165], v210, s[20:21] offset:128
	global_load_dwordx4 v[166:169], v210, s[22:23] offset:128
	global_load_dwordx4 v[170:173], v210, s[16:17] offset:256
	global_load_dwordx4 v[174:177], v210, s[18:19] offset:256
	s_nop 7
	v_max3_f32 v214, v0, v1, v2
	v_max3_f32 v214, v214, v3, v4
	v_max3_f32 v214, v214, v5, v6
	v_max3_f32 v214, v214, v7, v8
	v_max3_f32 v214, v214, v9, v10
	v_max3_f32 v214, v214, v11, v12
	v_max3_f32 v214, v214, v13, v14
	v_max3_f32 v214, v214, v15, v16
	v_max3_f32 v214, v214, v17, v18
	v_max3_f32 v214, v214, v19, v20
	v_max3_f32 v214, v214, v21, v22
	v_max3_f32 v214, v214, v23, v24
	v_max3_f32 v214, v214, v25, v26
	v_max3_f32 v214, v214, v27, v28
	v_max3_f32 v214, v214, v29, v30
	v_max3_f32 v214, v214, v31, v32
	v_max3_f32 v214, v214, v33, v34
	v_max3_f32 v214, v214, v35, v36
	v_max3_f32 v214, v214, v37, v38
	v_max3_f32 v214, v214, v39, v40
	v_max3_f32 v214, v214, v41, v42
	v_max3_f32 v214, v214, v43, v44
	v_max3_f32 v214, v214, v45, v46
	v_max3_f32 v214, v214, v47, v48
	v_max3_f32 v214, v214, v49, v50
	v_max3_f32 v214, v214, v51, v52
	v_max3_f32 v214, v214, v53, v54
	v_max3_f32 v214, v214, v55, v56
	v_max3_f32 v214, v214, v57, v58
	v_max3_f32 v214, v214, v59, v60
	v_max3_f32 v214, v214, v61, v62
	v_max3_f32 v214, v214, v63, v64
	v_max3_f32 v214, v214, v65, v66
	v_max3_f32 v214, v214, v67, v68
	v_max3_f32 v214, v214, v69, v70
	v_max3_f32 v214, v214, v71, v72
	v_max3_f32 v214, v214, v73, v74
	v_max3_f32 v214, v214, v75, v76
	v_max3_f32 v214, v214, v77, v78
	v_max3_f32 v214, v214, v79, v80
	v_max3_f32 v214, v214, v81, v82
	v_max3_f32 v214, v214, v83, v84
	v_max3_f32 v214, v214, v85, v86
	v_max3_f32 v214, v214, v87, v88
	v_max3_f32 v214, v214, v89, v90
	v_max3_f32 v214, v214, v91, v92
	v_max3_f32 v214, v214, v93, v94
	v_max3_f32 v214, v214, v95, v96
	v_max3_f32 v214, v214, v97, v98
	v_max3_f32 v214, v214, v99, v100
	v_max3_f32 v214, v214, v101, v102
	v_max3_f32 v214, v214, v103, v104
	v_max3_f32 v214, v214, v105, v106
	v_max3_f32 v214, v214, v107, v108
	v_max3_f32 v214, v214, v109, v110
	v_max3_f32 v214, v214, v111, v112
	v_max3_f32 v214, v214, v113, v114
	v_max3_f32 v214, v214, v115, v116
	v_max3_f32 v214, v214, v117, v118
	v_max3_f32 v214, v214, v119, v120
	v_max3_f32 v214, v214, v121, v122
	v_max3_f32 v214, v214, v123, v124
	v_max3_f32 v214, v214, v125, v126
	v_max_f32_e32 v214, v214, v127
	v_xor_b32_e32 v215, 16, v205
	v_lshlrev_b32_e32 v215, 2, v215
	v_xor_b32_e32 v216, 32, v205
	v_lshlrev_b32_e32 v216, 2, v216
	ds_bpermute_b32 v136, v215, v214
	s_waitcnt lgkmcnt(0)
	v_max_f32_e32 v214, v214, v136
	ds_bpermute_b32 v136, v216, v214
	s_waitcnt lgkmcnt(0)
	v_max_f32_e32 v214, v214, v136
	v_mul_f32_e32 v214, 0xbe38aa3b, v214
	s_mov_b32 s10, 0x3e38aa3b
	v_mov_b32_e32 v212, 0
	v_mov_b32_e32 v213, 0
	v_fma_f32 v0, v0, s10, v214
	v_fma_f32 v1, v1, s10, v214
	v_fma_f32 v2, v2, s10, v214
	v_fma_f32 v3, v3, s10, v214
	v_fma_f32 v4, v4, s10, v214
	v_fma_f32 v5, v5, s10, v214
	v_fma_f32 v6, v6, s10, v214
	v_fma_f32 v7, v7, s10, v214
	v_exp_f32_e32 v0, v0
	v_exp_f32_e32 v1, v1
	v_exp_f32_e32 v2, v2
	v_exp_f32_e32 v3, v3
	v_exp_f32_e32 v4, v4
	v_exp_f32_e32 v5, v5
	v_exp_f32_e32 v6, v6
	v_exp_f32_e32 v7, v7
	s_nop 0
	v_add_f32_e32 v212, v212, v0
	v_add_f32_e32 v213, v213, v1
	v_add_f32_e32 v212, v212, v2
	v_add_f32_e32 v213, v213, v3
	v_add_f32_e32 v212, v212, v4
	v_add_f32_e32 v213, v213, v5
	v_add_f32_e32 v212, v212, v6
	v_add_f32_e32 v213, v213, v7
	v_cvt_pk_bf16_f32 v0, v0, v1
	v_cvt_pk_bf16_f32 v1, v2, v3
	v_cvt_pk_bf16_f32 v2, v4, v5
	v_cvt_pk_bf16_f32 v3, v6, v7
	v_fma_f32 v8, v8, s10, v214
	v_fma_f32 v9, v9, s10, v214
	v_fma_f32 v10, v10, s10, v214
	v_fma_f32 v11, v11, s10, v214
	v_fma_f32 v12, v12, s10, v214
	v_fma_f32 v13, v13, s10, v214
	v_fma_f32 v14, v14, s10, v214
	v_fma_f32 v15, v15, s10, v214
	v_exp_f32_e32 v8, v8
	v_exp_f32_e32 v9, v9
	v_exp_f32_e32 v10, v10
	v_exp_f32_e32 v11, v11
	v_exp_f32_e32 v12, v12
	v_exp_f32_e32 v13, v13
	v_exp_f32_e32 v14, v14
	v_exp_f32_e32 v15, v15
	s_nop 0
	v_add_f32_e32 v212, v212, v8
	v_add_f32_e32 v213, v213, v9
	v_add_f32_e32 v212, v212, v10
	v_add_f32_e32 v213, v213, v11
	v_add_f32_e32 v212, v212, v12
	v_add_f32_e32 v213, v213, v13
	v_add_f32_e32 v212, v212, v14
	v_add_f32_e32 v213, v213, v15
	v_cvt_pk_bf16_f32 v8, v8, v9
	v_cvt_pk_bf16_f32 v9, v10, v11
	v_cvt_pk_bf16_f32 v10, v12, v13
	v_cvt_pk_bf16_f32 v11, v14, v15
	v_fma_f32 v16, v16, s10, v214
	v_fma_f32 v17, v17, s10, v214
	v_fma_f32 v18, v18, s10, v214
	v_fma_f32 v19, v19, s10, v214
	v_fma_f32 v20, v20, s10, v214
	v_fma_f32 v21, v21, s10, v214
	v_fma_f32 v22, v22, s10, v214
	v_fma_f32 v23, v23, s10, v214
	v_exp_f32_e32 v16, v16
	v_exp_f32_e32 v17, v17
	v_exp_f32_e32 v18, v18
	v_exp_f32_e32 v19, v19
	v_exp_f32_e32 v20, v20
	v_exp_f32_e32 v21, v21
	v_exp_f32_e32 v22, v22
	v_exp_f32_e32 v23, v23
	s_nop 0
	v_add_f32_e32 v212, v212, v16
	v_add_f32_e32 v213, v213, v17
	v_add_f32_e32 v212, v212, v18
	v_add_f32_e32 v213, v213, v19
	v_add_f32_e32 v212, v212, v20
	v_add_f32_e32 v213, v213, v21
	v_add_f32_e32 v212, v212, v22
	v_add_f32_e32 v213, v213, v23
	v_cvt_pk_bf16_f32 v16, v16, v17
	v_cvt_pk_bf16_f32 v17, v18, v19
	v_cvt_pk_bf16_f32 v18, v20, v21
	v_cvt_pk_bf16_f32 v19, v22, v23
	v_fma_f32 v24, v24, s10, v214
	v_fma_f32 v25, v25, s10, v214
	v_fma_f32 v26, v26, s10, v214
	v_fma_f32 v27, v27, s10, v214
	v_fma_f32 v28, v28, s10, v214
	v_fma_f32 v29, v29, s10, v214
	v_fma_f32 v30, v30, s10, v214
	v_fma_f32 v31, v31, s10, v214
	v_exp_f32_e32 v24, v24
	v_exp_f32_e32 v25, v25
	v_exp_f32_e32 v26, v26
	v_exp_f32_e32 v27, v27
	v_exp_f32_e32 v28, v28
	v_exp_f32_e32 v29, v29
	v_exp_f32_e32 v30, v30
	v_exp_f32_e32 v31, v31
	s_nop 0
	v_add_f32_e32 v212, v212, v24
	v_add_f32_e32 v213, v213, v25
	v_add_f32_e32 v212, v212, v26
	v_add_f32_e32 v213, v213, v27
	v_add_f32_e32 v212, v212, v28
	v_add_f32_e32 v213, v213, v29
	v_add_f32_e32 v212, v212, v30
	v_add_f32_e32 v213, v213, v31
	v_cvt_pk_bf16_f32 v24, v24, v25
	v_cvt_pk_bf16_f32 v25, v26, v27
	v_cvt_pk_bf16_f32 v26, v28, v29
	v_cvt_pk_bf16_f32 v27, v30, v31
	v_fma_f32 v32, v32, s10, v214
	v_fma_f32 v33, v33, s10, v214
	v_fma_f32 v34, v34, s10, v214
	v_fma_f32 v35, v35, s10, v214
	v_fma_f32 v36, v36, s10, v214
	v_fma_f32 v37, v37, s10, v214
	v_fma_f32 v38, v38, s10, v214
	v_fma_f32 v39, v39, s10, v214
	v_exp_f32_e32 v32, v32
	v_exp_f32_e32 v33, v33
	v_exp_f32_e32 v34, v34
	v_exp_f32_e32 v35, v35
	v_exp_f32_e32 v36, v36
	v_exp_f32_e32 v37, v37
	v_exp_f32_e32 v38, v38
	v_exp_f32_e32 v39, v39
	s_nop 0
	v_add_f32_e32 v212, v212, v32
	v_add_f32_e32 v213, v213, v33
	v_add_f32_e32 v212, v212, v34
	v_add_f32_e32 v213, v213, v35
	v_add_f32_e32 v212, v212, v36
	v_add_f32_e32 v213, v213, v37
	v_add_f32_e32 v212, v212, v38
	v_add_f32_e32 v213, v213, v39
	v_cvt_pk_bf16_f32 v32, v32, v33
	v_cvt_pk_bf16_f32 v33, v34, v35
	v_cvt_pk_bf16_f32 v34, v36, v37
	v_cvt_pk_bf16_f32 v35, v38, v39
	v_fma_f32 v40, v40, s10, v214
	v_fma_f32 v41, v41, s10, v214
	v_fma_f32 v42, v42, s10, v214
	v_fma_f32 v43, v43, s10, v214
	v_fma_f32 v44, v44, s10, v214
	v_fma_f32 v45, v45, s10, v214
	v_fma_f32 v46, v46, s10, v214
	v_fma_f32 v47, v47, s10, v214
	v_exp_f32_e32 v40, v40
	v_exp_f32_e32 v41, v41
	v_exp_f32_e32 v42, v42
	v_exp_f32_e32 v43, v43
	v_exp_f32_e32 v44, v44
	v_exp_f32_e32 v45, v45
	v_exp_f32_e32 v46, v46
	v_exp_f32_e32 v47, v47
	s_nop 0
	v_add_f32_e32 v212, v212, v40
	v_add_f32_e32 v213, v213, v41
	v_add_f32_e32 v212, v212, v42
	v_add_f32_e32 v213, v213, v43
	v_add_f32_e32 v212, v212, v44
	v_add_f32_e32 v213, v213, v45
	v_add_f32_e32 v212, v212, v46
	v_add_f32_e32 v213, v213, v47
	v_cvt_pk_bf16_f32 v40, v40, v41
	v_cvt_pk_bf16_f32 v41, v42, v43
	v_cvt_pk_bf16_f32 v42, v44, v45
	v_cvt_pk_bf16_f32 v43, v46, v47
	v_fma_f32 v48, v48, s10, v214
	v_fma_f32 v49, v49, s10, v214
	v_fma_f32 v50, v50, s10, v214
	v_fma_f32 v51, v51, s10, v214
	v_fma_f32 v52, v52, s10, v214
	v_fma_f32 v53, v53, s10, v214
	v_fma_f32 v54, v54, s10, v214
	v_fma_f32 v55, v55, s10, v214
	v_exp_f32_e32 v48, v48
	v_exp_f32_e32 v49, v49
	v_exp_f32_e32 v50, v50
	v_exp_f32_e32 v51, v51
	v_exp_f32_e32 v52, v52
	v_exp_f32_e32 v53, v53
	v_exp_f32_e32 v54, v54
	v_exp_f32_e32 v55, v55
	s_nop 0
	v_add_f32_e32 v212, v212, v48
	v_add_f32_e32 v213, v213, v49
	v_add_f32_e32 v212, v212, v50
	v_add_f32_e32 v213, v213, v51
	v_add_f32_e32 v212, v212, v52
	v_add_f32_e32 v213, v213, v53
	v_add_f32_e32 v212, v212, v54
	v_add_f32_e32 v213, v213, v55
	v_cvt_pk_bf16_f32 v48, v48, v49
	v_cvt_pk_bf16_f32 v49, v50, v51
	v_cvt_pk_bf16_f32 v50, v52, v53
	v_cvt_pk_bf16_f32 v51, v54, v55
	v_fma_f32 v56, v56, s10, v214
	v_fma_f32 v57, v57, s10, v214
	v_fma_f32 v58, v58, s10, v214
	v_fma_f32 v59, v59, s10, v214
	v_fma_f32 v60, v60, s10, v214
	v_fma_f32 v61, v61, s10, v214
	v_fma_f32 v62, v62, s10, v214
	v_fma_f32 v63, v63, s10, v214
	v_exp_f32_e32 v56, v56
	v_exp_f32_e32 v57, v57
	v_exp_f32_e32 v58, v58
	v_exp_f32_e32 v59, v59
	v_exp_f32_e32 v60, v60
	v_exp_f32_e32 v61, v61
	v_exp_f32_e32 v62, v62
	v_exp_f32_e32 v63, v63
	s_nop 0
	v_add_f32_e32 v212, v212, v56
	v_add_f32_e32 v213, v213, v57
	v_add_f32_e32 v212, v212, v58
	v_add_f32_e32 v213, v213, v59
	v_add_f32_e32 v212, v212, v60
	v_add_f32_e32 v213, v213, v61
	v_add_f32_e32 v212, v212, v62
	v_add_f32_e32 v213, v213, v63
	v_cvt_pk_bf16_f32 v56, v56, v57
	v_cvt_pk_bf16_f32 v57, v58, v59
	v_cvt_pk_bf16_f32 v58, v60, v61
	v_cvt_pk_bf16_f32 v59, v62, v63
	v_fma_f32 v64, v64, s10, v214
	v_fma_f32 v65, v65, s10, v214
	v_fma_f32 v66, v66, s10, v214
	v_fma_f32 v67, v67, s10, v214
	v_fma_f32 v68, v68, s10, v214
	v_fma_f32 v69, v69, s10, v214
	v_fma_f32 v70, v70, s10, v214
	v_fma_f32 v71, v71, s10, v214
	v_exp_f32_e32 v64, v64
	v_exp_f32_e32 v65, v65
	v_exp_f32_e32 v66, v66
	v_exp_f32_e32 v67, v67
	v_exp_f32_e32 v68, v68
	v_exp_f32_e32 v69, v69
	v_exp_f32_e32 v70, v70
	v_exp_f32_e32 v71, v71
	s_nop 0
	v_add_f32_e32 v212, v212, v64
	v_add_f32_e32 v213, v213, v65
	v_add_f32_e32 v212, v212, v66
	v_add_f32_e32 v213, v213, v67
	v_add_f32_e32 v212, v212, v68
	v_add_f32_e32 v213, v213, v69
	v_add_f32_e32 v212, v212, v70
	v_add_f32_e32 v213, v213, v71
	v_cvt_pk_bf16_f32 v64, v64, v65
	v_cvt_pk_bf16_f32 v65, v66, v67
	v_cvt_pk_bf16_f32 v66, v68, v69
	v_cvt_pk_bf16_f32 v67, v70, v71
	v_fma_f32 v72, v72, s10, v214
	v_fma_f32 v73, v73, s10, v214
	v_fma_f32 v74, v74, s10, v214
	v_fma_f32 v75, v75, s10, v214
	v_fma_f32 v76, v76, s10, v214
	v_fma_f32 v77, v77, s10, v214
	v_fma_f32 v78, v78, s10, v214
	v_fma_f32 v79, v79, s10, v214
	v_exp_f32_e32 v72, v72
	v_exp_f32_e32 v73, v73
	v_exp_f32_e32 v74, v74
	v_exp_f32_e32 v75, v75
	v_exp_f32_e32 v76, v76
	v_exp_f32_e32 v77, v77
	v_exp_f32_e32 v78, v78
	v_exp_f32_e32 v79, v79
	s_nop 0
	v_add_f32_e32 v212, v212, v72
	v_add_f32_e32 v213, v213, v73
	v_add_f32_e32 v212, v212, v74
	v_add_f32_e32 v213, v213, v75
	v_add_f32_e32 v212, v212, v76
	v_add_f32_e32 v213, v213, v77
	v_add_f32_e32 v212, v212, v78
	v_add_f32_e32 v213, v213, v79
	v_cvt_pk_bf16_f32 v72, v72, v73
	v_cvt_pk_bf16_f32 v73, v74, v75
	v_cvt_pk_bf16_f32 v74, v76, v77
	v_cvt_pk_bf16_f32 v75, v78, v79
	v_fma_f32 v80, v80, s10, v214
	v_fma_f32 v81, v81, s10, v214
	v_fma_f32 v82, v82, s10, v214
	v_fma_f32 v83, v83, s10, v214
	v_fma_f32 v84, v84, s10, v214
	v_fma_f32 v85, v85, s10, v214
	v_fma_f32 v86, v86, s10, v214
	v_fma_f32 v87, v87, s10, v214
	v_exp_f32_e32 v80, v80
	v_exp_f32_e32 v81, v81
	v_exp_f32_e32 v82, v82
	v_exp_f32_e32 v83, v83
	v_exp_f32_e32 v84, v84
	v_exp_f32_e32 v85, v85
	v_exp_f32_e32 v86, v86
	v_exp_f32_e32 v87, v87
	s_nop 0
	v_add_f32_e32 v212, v212, v80
	v_add_f32_e32 v213, v213, v81
	v_add_f32_e32 v212, v212, v82
	v_add_f32_e32 v213, v213, v83
	v_add_f32_e32 v212, v212, v84
	v_add_f32_e32 v213, v213, v85
	v_add_f32_e32 v212, v212, v86
	v_add_f32_e32 v213, v213, v87
	v_cvt_pk_bf16_f32 v80, v80, v81
	v_cvt_pk_bf16_f32 v81, v82, v83
	v_cvt_pk_bf16_f32 v82, v84, v85
	v_cvt_pk_bf16_f32 v83, v86, v87
	v_fma_f32 v88, v88, s10, v214
	v_fma_f32 v89, v89, s10, v214
	v_fma_f32 v90, v90, s10, v214
	v_fma_f32 v91, v91, s10, v214
	v_fma_f32 v92, v92, s10, v214
	v_fma_f32 v93, v93, s10, v214
	v_fma_f32 v94, v94, s10, v214
	v_fma_f32 v95, v95, s10, v214
	v_exp_f32_e32 v88, v88
	v_exp_f32_e32 v89, v89
	v_exp_f32_e32 v90, v90
	v_exp_f32_e32 v91, v91
	v_exp_f32_e32 v92, v92
	v_exp_f32_e32 v93, v93
	v_exp_f32_e32 v94, v94
	v_exp_f32_e32 v95, v95
	s_nop 0
	v_add_f32_e32 v212, v212, v88
	v_add_f32_e32 v213, v213, v89
	v_add_f32_e32 v212, v212, v90
	v_add_f32_e32 v213, v213, v91
	v_add_f32_e32 v212, v212, v92
	v_add_f32_e32 v213, v213, v93
	v_add_f32_e32 v212, v212, v94
	v_add_f32_e32 v213, v213, v95
	v_cvt_pk_bf16_f32 v88, v88, v89
	v_cvt_pk_bf16_f32 v89, v90, v91
	v_cvt_pk_bf16_f32 v90, v92, v93
	v_cvt_pk_bf16_f32 v91, v94, v95
	v_fma_f32 v96, v96, s10, v214
	v_fma_f32 v97, v97, s10, v214
	v_fma_f32 v98, v98, s10, v214
	v_fma_f32 v99, v99, s10, v214
	v_fma_f32 v100, v100, s10, v214
	v_fma_f32 v101, v101, s10, v214
	v_fma_f32 v102, v102, s10, v214
	v_fma_f32 v103, v103, s10, v214
	v_exp_f32_e32 v96, v96
	v_exp_f32_e32 v97, v97
	v_exp_f32_e32 v98, v98
	v_exp_f32_e32 v99, v99
	v_exp_f32_e32 v100, v100
	v_exp_f32_e32 v101, v101
	v_exp_f32_e32 v102, v102
	v_exp_f32_e32 v103, v103
	s_nop 0
	v_add_f32_e32 v212, v212, v96
	v_add_f32_e32 v213, v213, v97
	v_add_f32_e32 v212, v212, v98
	v_add_f32_e32 v213, v213, v99
	v_add_f32_e32 v212, v212, v100
	v_add_f32_e32 v213, v213, v101
	v_add_f32_e32 v212, v212, v102
	v_add_f32_e32 v213, v213, v103
	v_cvt_pk_bf16_f32 v96, v96, v97
	v_cvt_pk_bf16_f32 v97, v98, v99
	v_cvt_pk_bf16_f32 v98, v100, v101
	v_cvt_pk_bf16_f32 v99, v102, v103
	v_fma_f32 v104, v104, s10, v214
	v_fma_f32 v105, v105, s10, v214
	v_fma_f32 v106, v106, s10, v214
	v_fma_f32 v107, v107, s10, v214
	v_fma_f32 v108, v108, s10, v214
	v_fma_f32 v109, v109, s10, v214
	v_fma_f32 v110, v110, s10, v214
	v_fma_f32 v111, v111, s10, v214
	v_exp_f32_e32 v104, v104
	v_exp_f32_e32 v105, v105
	v_exp_f32_e32 v106, v106
	v_exp_f32_e32 v107, v107
	v_exp_f32_e32 v108, v108
	v_exp_f32_e32 v109, v109
	v_exp_f32_e32 v110, v110
	v_exp_f32_e32 v111, v111
	s_nop 0
	v_add_f32_e32 v212, v212, v104
	v_add_f32_e32 v213, v213, v105
	v_add_f32_e32 v212, v212, v106
	v_add_f32_e32 v213, v213, v107
	v_add_f32_e32 v212, v212, v108
	v_add_f32_e32 v213, v213, v109
	v_add_f32_e32 v212, v212, v110
	v_add_f32_e32 v213, v213, v111
	v_cvt_pk_bf16_f32 v104, v104, v105
	v_cvt_pk_bf16_f32 v105, v106, v107
	v_cvt_pk_bf16_f32 v106, v108, v109
	v_cvt_pk_bf16_f32 v107, v110, v111
	v_fma_f32 v112, v112, s10, v214
	v_fma_f32 v113, v113, s10, v214
	v_fma_f32 v114, v114, s10, v214
	v_fma_f32 v115, v115, s10, v214
	v_fma_f32 v116, v116, s10, v214
	v_fma_f32 v117, v117, s10, v214
	v_fma_f32 v118, v118, s10, v214
	v_fma_f32 v119, v119, s10, v214
	v_exp_f32_e32 v112, v112
	v_exp_f32_e32 v113, v113
	v_exp_f32_e32 v114, v114
	v_exp_f32_e32 v115, v115
	v_exp_f32_e32 v116, v116
	v_exp_f32_e32 v117, v117
	v_exp_f32_e32 v118, v118
	v_exp_f32_e32 v119, v119
	s_nop 0
	v_add_f32_e32 v212, v212, v112
	v_add_f32_e32 v213, v213, v113
	v_add_f32_e32 v212, v212, v114
	v_add_f32_e32 v213, v213, v115
	v_add_f32_e32 v212, v212, v116
	v_add_f32_e32 v213, v213, v117
	v_add_f32_e32 v212, v212, v118
	v_add_f32_e32 v213, v213, v119
	v_cvt_pk_bf16_f32 v112, v112, v113
	v_cvt_pk_bf16_f32 v113, v114, v115
	v_cvt_pk_bf16_f32 v114, v116, v117
	v_cvt_pk_bf16_f32 v115, v118, v119
	v_fma_f32 v120, v120, s10, v214
	v_fma_f32 v121, v121, s10, v214
	v_fma_f32 v122, v122, s10, v214
	v_fma_f32 v123, v123, s10, v214
	v_fma_f32 v124, v124, s10, v214
	v_fma_f32 v125, v125, s10, v214
	v_fma_f32 v126, v126, s10, v214
	v_fma_f32 v127, v127, s10, v214
	v_exp_f32_e32 v120, v120
	v_exp_f32_e32 v121, v121
	v_exp_f32_e32 v122, v122
	v_exp_f32_e32 v123, v123
	v_exp_f32_e32 v124, v124
	v_exp_f32_e32 v125, v125
	v_exp_f32_e32 v126, v126
	v_exp_f32_e32 v127, v127
	s_nop 0
	v_add_f32_e32 v212, v212, v120
	v_add_f32_e32 v213, v213, v121
	v_add_f32_e32 v212, v212, v122
	v_add_f32_e32 v213, v213, v123
	v_add_f32_e32 v212, v212, v124
	v_add_f32_e32 v213, v213, v125
	v_add_f32_e32 v212, v212, v126
	v_add_f32_e32 v213, v213, v127
	v_cvt_pk_bf16_f32 v120, v120, v121
	v_cvt_pk_bf16_f32 v121, v122, v123
	v_cvt_pk_bf16_f32 v122, v124, v125
	v_cvt_pk_bf16_f32 v123, v126, v127
	v_add_f32_e32 v212, v212, v213
	global_load_dwordx4 v[4:7], v210, s[20:21] offset:256
	global_load_dwordx4 v[12:15], v210, s[22:23] offset:256
	global_load_dwordx4 v[20:23], v210, s[16:17] offset:384
	global_load_dwordx4 v[28:31], v210, s[18:19] offset:384
	global_load_dwordx4 v[36:39], v210, s[20:21] offset:384
	global_load_dwordx4 v[44:47], v210, s[22:23] offset:384
	global_load_dwordx4 v[52:55], v210, s[16:17] offset:512
	global_load_dwordx4 v[60:63], v210, s[18:19] offset:512
	global_load_dwordx4 v[68:71], v210, s[20:21] offset:512
	global_load_dwordx4 v[76:79], v210, s[22:23] offset:512
	global_load_dwordx4 v[84:87], v210, s[16:17] offset:640
	global_load_dwordx4 v[92:95], v210, s[18:19] offset:640
	global_load_dwordx4 v[100:103], v210, s[20:21] offset:640
	global_load_dwordx4 v[108:111], v210, s[22:23] offset:640
	global_load_dwordx4 v[116:119], v210, s[16:17] offset:768
	global_load_dwordx4 v[124:127], v210, s[18:19] offset:768
	s_waitcnt vmcnt(25)
	v_mfma_f32_16x16x32_bf16 v[128:131], v[138:141], v[0:3], 0
	global_load_dwordx4 v[138:141], v210, s[20:21] offset:768
	s_waitcnt vmcnt(25)
	v_mfma_f32_16x16x32_bf16 v[132:135], v[142:145], v[0:3], 0
	global_load_dwordx4 v[142:145], v210, s[22:23] offset:768
	s_waitcnt vmcnt(25)
	v_mfma_f32_16x16x32_bf16 v[178:181], v[146:149], v[0:3], 0
	global_load_dwordx4 v[146:149], v210, s[16:17] offset:896
	s_waitcnt vmcnt(25)
	v_mfma_f32_16x16x32_bf16 v[182:185], v[150:153], v[0:3], 0
	global_load_dwordx4 v[150:153], v210, s[18:19] offset:896
	s_waitcnt vmcnt(25)
	v_mfma_f32_16x16x32_bf16 v[128:131], v[154:157], v[8:11], v[128:131]
	global_load_dwordx4 v[154:157], v210, s[20:21] offset:896
	s_waitcnt vmcnt(25)
	v_mfma_f32_16x16x32_bf16 v[132:135], v[158:161], v[8:11], v[132:135]
	global_load_dwordx4 v[158:161], v210, s[22:23] offset:896
	s_waitcnt vmcnt(25)
	v_mfma_f32_16x16x32_bf16 v[178:181], v[162:165], v[8:11], v[178:181]
	global_load_dwordx4 v[162:165], v211, s[24:25] offset:0
	s_waitcnt vmcnt(25)
	v_mfma_f32_16x16x32_bf16 v[182:185], v[166:169], v[8:11], v[182:185]
	global_load_dwordx4 v[166:169], v211, s[26:27] offset:0
	s_waitcnt vmcnt(25)
	v_mfma_f32_16x16x32_bf16 v[128:131], v[170:173], v[16:19], v[128:131]
	global_load_dwordx4 v[170:173], v211, s[36:37] offset:0
	s_waitcnt vmcnt(25)
	v_mfma_f32_16x16x32_bf16 v[132:135], v[174:177], v[16:19], v[132:135]
	global_load_dwordx4 v[174:177], v211, s[0:1] offset:0
	s_waitcnt vmcnt(25)
	v_mfma_f32_16x16x32_bf16 v[178:181], v[4:7], v[16:19], v[178:181]
	global_load_dwordx4 v[4:7], v211, s[24:25] offset:64
	s_waitcnt vmcnt(25)
	v_mfma_f32_16x16x32_bf16 v[182:185], v[12:15], v[16:19], v[182:185]
	global_load_dwordx4 v[12:15], v211, s[26:27] offset:64
	s_waitcnt vmcnt(25)
	v_mfma_f32_16x16x32_bf16 v[128:131], v[20:23], v[24:27], v[128:131]
	global_load_dwordx4 v[20:23], v211, s[36:37] offset:64
	s_waitcnt vmcnt(25)
	v_mfma_f32_16x16x32_bf16 v[132:135], v[28:31], v[24:27], v[132:135]
	global_load_dwordx4 v[28:31], v211, s[0:1] offset:64
	s_waitcnt vmcnt(25)
	v_mfma_f32_16x16x32_bf16 v[178:181], v[36:39], v[24:27], v[178:181]
	global_load_dwordx4 v[36:39], v211, s[24:25] offset:128
	s_waitcnt vmcnt(25)
	v_mfma_f32_16x16x32_bf16 v[182:185], v[44:47], v[24:27], v[182:185]
	global_load_dwordx4 v[44:47], v211, s[26:27] offset:128
	s_waitcnt vmcnt(25)
	v_mfma_f32_16x16x32_bf16 v[128:131], v[52:55], v[32:35], v[128:131]
	global_load_dwordx4 v[52:55], v211, s[36:37] offset:128
	s_waitcnt vmcnt(25)
	v_mfma_f32_16x16x32_bf16 v[132:135], v[60:63], v[32:35], v[132:135]
	global_load_dwordx4 v[60:63], v211, s[0:1] offset:128
	s_waitcnt vmcnt(25)
	v_mfma_f32_16x16x32_bf16 v[178:181], v[68:71], v[32:35], v[178:181]
	global_load_dwordx4 v[68:71], v211, s[24:25] offset:192
	s_waitcnt vmcnt(25)
	v_mfma_f32_16x16x32_bf16 v[182:185], v[76:79], v[32:35], v[182:185]
	global_load_dwordx4 v[76:79], v211, s[26:27] offset:192
	s_waitcnt vmcnt(25)
	v_mfma_f32_16x16x32_bf16 v[128:131], v[84:87], v[40:43], v[128:131]
	global_load_dwordx4 v[84:87], v211, s[36:37] offset:192
	s_waitcnt vmcnt(25)
	v_mfma_f32_16x16x32_bf16 v[132:135], v[92:95], v[40:43], v[132:135]
	global_load_dwordx4 v[92:95], v211, s[0:1] offset:192
	s_waitcnt vmcnt(25)
	v_mfma_f32_16x16x32_bf16 v[178:181], v[100:103], v[40:43], v[178:181]
	global_load_dwordx4 v[100:103], v211, s[24:25] offset:256
	s_waitcnt vmcnt(25)
	v_mfma_f32_16x16x32_bf16 v[182:185], v[108:111], v[40:43], v[182:185]
	global_load_dwordx4 v[108:111], v211, s[26:27] offset:256
	s_waitcnt vmcnt(25)
	v_mfma_f32_16x16x32_bf16 v[128:131], v[116:119], v[48:51], v[128:131]
	global_load_dwordx4 v[116:119], v211, s[36:37] offset:256
	s_waitcnt vmcnt(25)
	v_mfma_f32_16x16x32_bf16 v[132:135], v[124:127], v[48:51], v[132:135]
	global_load_dwordx4 v[124:127], v211, s[0:1] offset:256
	s_waitcnt vmcnt(25)
	v_mfma_f32_16x16x32_bf16 v[178:181], v[138:141], v[48:51], v[178:181]
	global_load_dwordx4 v[138:141], v211, s[24:25] offset:320
	s_waitcnt vmcnt(25)
	v_mfma_f32_16x16x32_bf16 v[182:185], v[142:145], v[48:51], v[182:185]
	global_load_dwordx4 v[142:145], v211, s[26:27] offset:320
	s_waitcnt vmcnt(25)
	v_mfma_f32_16x16x32_bf16 v[128:131], v[146:149], v[56:59], v[128:131]
	global_load_dwordx4 v[146:149], v211, s[36:37] offset:320
	s_waitcnt vmcnt(25)
	v_mfma_f32_16x16x32_bf16 v[132:135], v[150:153], v[56:59], v[132:135]
	global_load_dwordx4 v[150:153], v211, s[0:1] offset:320
	s_waitcnt vmcnt(25)
	v_mfma_f32_16x16x32_bf16 v[178:181], v[154:157], v[56:59], v[178:181]
	global_load_dwordx4 v[154:157], v211, s[24:25] offset:384
	s_waitcnt vmcnt(25)
	v_mfma_f32_16x16x32_bf16 v[182:185], v[158:161], v[56:59], v[182:185]
	global_load_dwordx4 v[158:161], v211, s[26:27] offset:384
	s_waitcnt vmcnt(25)
	v_mfma_f32_16x16x32_bf16 v[128:131], v[162:165], v[64:67], v[128:131]
	global_load_dwordx4 v[162:165], v211, s[36:37] offset:384
	s_waitcnt vmcnt(25)
	v_mfma_f32_16x16x32_bf16 v[132:135], v[166:169], v[64:67], v[132:135]
	global_load_dwordx4 v[166:169], v211, s[0:1] offset:384
	s_waitcnt vmcnt(25)
	v_mfma_f32_16x16x32_bf16 v[178:181], v[170:173], v[64:67], v[178:181]
	global_load_dwordx4 v[170:173], v211, s[24:25] offset:448
	s_waitcnt vmcnt(25)
	v_mfma_f32_16x16x32_bf16 v[182:185], v[174:177], v[64:67], v[182:185]
	global_load_dwordx4 v[174:177], v211, s[26:27] offset:448
	s_waitcnt vmcnt(25)
	v_mfma_f32_16x16x32_bf16 v[128:131], v[4:7], v[72:75], v[128:131]
	global_load_dwordx4 v[4:7], v211, s[36:37] offset:448
	s_waitcnt vmcnt(25)
	v_mfma_f32_16x16x32_bf16 v[132:135], v[12:15], v[72:75], v[132:135]
	global_load_dwordx4 v[12:15], v211, s[0:1] offset:448
	s_waitcnt vmcnt(25)
	v_mfma_f32_16x16x32_bf16 v[178:181], v[20:23], v[72:75], v[178:181]
	s_waitcnt vmcnt(24)
	v_mfma_f32_16x16x32_bf16 v[182:185], v[28:31], v[72:75], v[182:185]
	s_waitcnt vmcnt(23)
	v_mfma_f32_16x16x32_bf16 v[128:131], v[36:39], v[80:83], v[128:131]
	s_waitcnt vmcnt(22)
	v_mfma_f32_16x16x32_bf16 v[132:135], v[44:47], v[80:83], v[132:135]
	s_waitcnt vmcnt(21)
	v_mfma_f32_16x16x32_bf16 v[178:181], v[52:55], v[80:83], v[178:181]
	s_waitcnt vmcnt(20)
	v_mfma_f32_16x16x32_bf16 v[182:185], v[60:63], v[80:83], v[182:185]
	s_waitcnt vmcnt(19)
	v_mfma_f32_16x16x32_bf16 v[128:131], v[68:71], v[88:91], v[128:131]
	s_waitcnt vmcnt(18)
	v_mfma_f32_16x16x32_bf16 v[132:135], v[76:79], v[88:91], v[132:135]
	s_waitcnt vmcnt(17)
	v_mfma_f32_16x16x32_bf16 v[178:181], v[84:87], v[88:91], v[178:181]
	s_waitcnt vmcnt(16)
	v_mfma_f32_16x16x32_bf16 v[182:185], v[92:95], v[88:91], v[182:185]
	s_waitcnt vmcnt(15)
	v_mfma_f32_16x16x32_bf16 v[128:131], v[100:103], v[96:99], v[128:131]
	s_waitcnt vmcnt(14)
	v_mfma_f32_16x16x32_bf16 v[132:135], v[108:111], v[96:99], v[132:135]
	s_waitcnt vmcnt(13)
	v_mfma_f32_16x16x32_bf16 v[178:181], v[116:119], v[96:99], v[178:181]
	s_waitcnt vmcnt(12)
	v_mfma_f32_16x16x32_bf16 v[182:185], v[124:127], v[96:99], v[182:185]
	s_waitcnt vmcnt(11)
	v_mfma_f32_16x16x32_bf16 v[128:131], v[138:141], v[104:107], v[128:131]
	s_waitcnt vmcnt(10)
	v_mfma_f32_16x16x32_bf16 v[132:135], v[142:145], v[104:107], v[132:135]
	s_waitcnt vmcnt(9)
	v_mfma_f32_16x16x32_bf16 v[178:181], v[146:149], v[104:107], v[178:181]
	s_waitcnt vmcnt(8)
	v_mfma_f32_16x16x32_bf16 v[182:185], v[150:153], v[104:107], v[182:185]
	s_waitcnt vmcnt(7)
	v_mfma_f32_16x16x32_bf16 v[128:131], v[154:157], v[112:115], v[128:131]
	s_waitcnt vmcnt(6)
	v_mfma_f32_16x16x32_bf16 v[132:135], v[158:161], v[112:115], v[132:135]
	s_waitcnt vmcnt(5)
	v_mfma_f32_16x16x32_bf16 v[178:181], v[162:165], v[112:115], v[178:181]
	s_waitcnt vmcnt(4)
	v_mfma_f32_16x16x32_bf16 v[182:185], v[166:169], v[112:115], v[182:185]
	s_waitcnt vmcnt(3)
	v_mfma_f32_16x16x32_bf16 v[128:131], v[170:173], v[120:123], v[128:131]
	s_waitcnt vmcnt(2)
	v_mfma_f32_16x16x32_bf16 v[132:135], v[174:177], v[120:123], v[132:135]
	s_waitcnt vmcnt(1)
	v_mfma_f32_16x16x32_bf16 v[178:181], v[4:7], v[120:123], v[178:181]
	s_waitcnt vmcnt(0)
	v_mfma_f32_16x16x32_bf16 v[182:185], v[12:15], v[120:123], v[182:185]
	ds_bpermute_b32 v136, v215, v212
	s_waitcnt lgkmcnt(0)
	v_add_f32_e32 v212, v212, v136
	ds_bpermute_b32 v136, v216, v212
	s_waitcnt lgkmcnt(0)
	v_add_f32_e32 v212, v212, v136
	v_rcp_f32_e32 v213, v212
	s_nop 0
	v_fma_f32 v136, -v212, v213, 1.0
	v_fma_f32 v213, v136, v213, v213
	v_mul_u32_u24_e32 v208, 0x600, v206
	v_lshl_add_u32 v208, v207, 3, v208
	s_add_u32 s10, s4, s38
	s_addc_u32 s11, s5, 0
	s_nop 2
	v_mul_f32_e32 v128, v128, v213
	v_mul_f32_e32 v129, v129, v213
	v_mul_f32_e32 v130, v130, v213
	v_mul_f32_e32 v131, v131, v213
	v_cvt_pk_bf16_f32 v128, v128, v129
	v_cvt_pk_bf16_f32 v129, v130, v131
	global_store_dwordx2 v208, v[128:129], s[10:11] offset:0
	v_mul_f32_e32 v132, v132, v213
	v_mul_f32_e32 v133, v133, v213
	v_mul_f32_e32 v134, v134, v213
	v_mul_f32_e32 v135, v135, v213
	v_cvt_pk_bf16_f32 v132, v132, v133
	v_cvt_pk_bf16_f32 v133, v134, v135
	global_store_dwordx2 v208, v[132:133], s[10:11] offset:32
	v_mul_f32_e32 v178, v178, v213
	v_mul_f32_e32 v179, v179, v213
	v_mul_f32_e32 v180, v180, v213
	v_mul_f32_e32 v181, v181, v213
	v_cvt_pk_bf16_f32 v178, v178, v179
	v_cvt_pk_bf16_f32 v179, v180, v181
	global_store_dwordx2 v208, v[178:179], s[10:11] offset:64
	v_mul_f32_e32 v182, v182, v213
	v_mul_f32_e32 v183, v183, v213
	v_mul_f32_e32 v184, v184, v213
	v_mul_f32_e32 v185, v185, v213
	v_cvt_pk_bf16_f32 v182, v182, v183
	v_cvt_pk_bf16_f32 v183, v184, v185
	global_store_dwordx2 v208, v[182:183], s[10:11] offset:96

.LBB0_612:
	v_readlane_b32 s78, v247, 22
	s_bitcmp0_b32 s94, 0
	v_readlane_b32 s79, v247, 23
	v_readlane_b32 s24, v247, 28
	v_readlane_b32 s25, v244, 30
	v_readlane_b32 s26, v244, 31
	v_readlane_b32 s27, v245, 40
	s_cbranch_scc1 .LBB0_620
	v_readlane_b32 s0, v246, 3
	v_readlane_b32 s1, v246, 4
	s_andn2_b64 vcc, exec, s[0:1]
	s_cbranch_vccnz .LBB0_620
	v_readlane_b32 s0, v245, 21
	s_nop 0
	s_cmp_ge_u32 s0, 0x80
	s_cbranch_scc1 .Lstab_end
	s_lshr_b32 s1, s0, 2
	s_and_b32 s6, s0, 3
	s_lshl_b32 s7, s24, 5
	s_add_i32 s7, s7, s1
	s_bfe_u32 s8, s1, 0x10004
	s_mul_i32 s9, s8, 15
	v_and_b32_e32 v0, 15, v205
	v_lshrrev_b32_e32 v1, 4, v205
	v_xor_b32_e32 v2, s9, v0
	v_and_b32_e32 v3, 1, v2
	v_cmp_ne_u32_e64 s[10:11], 0, v3
	v_and_b32_e32 v3, 2, v2
	v_cmp_ne_u32_e64 s[12:13], 0, v3
	v_and_b32_e32 v3, 4, v2
	v_cmp_ne_u32_e64 s[14:15], 0, v3
	v_and_b32_e32 v3, 8, v2
	v_cmp_ne_u32_e64 s[16:17], 0, v3
	s_lshl_b32 s18, s7, 6
	s_lshl_b32 s19, s6, 4
	s_add_i32 s18, s18, s19
	s_lshl_b32 s18, s18, 2
	s_add_u32 s18, s18, 0x117a20
	s_add_u32 s20, s4, s18
	s_addc_u32 s21, s5, 0
	s_add_u32 s22, s20, 0x4000
	s_addc_u32 s23, s21, 0
	v_lshlrev_b32_e32 v3, 4, v1
	global_load_dwordx4 v[4:7], v3, s[20:21]
	global_load_dwordx4 v[8:11], v3, s[22:23]
	s_lshl_b32 s19, s7, 2
	s_add_u32 s19, s19, 0x11fa20
	s_add_u32 s0, s4, s19
	s_addc_u32 s1, s5, 0
	global_load_dword v12, v137, s[0:1]
	s_lshl_b32 s18, s7, 2
	s_add_i32 s18, s18, s6
	s_lshl_b32 s19, s18, 13
	s_add_u32 s19, s19, 0xf900000
	s_add_u32 s20, s4, s19
	s_addc_u32 s21, s5, 0
	s_lshl_b32 s19, s18, 12
	s_add_u32 s19, s19, 0xfc00000
	s_add_u32 s22, s4, s19
	s_addc_u32 s23, s5, 0
	v_lshlrev_b32_e32 v13, 7, v205
	v_lshlrev_b32_e32 v14, 6, v205
	s_waitcnt vmcnt(0)
	v_mul_f32_e32 v12, 0x3fb8aa3b, v12
	v_exp_f32_e32 v12, v12
	s_nop 0
	v_mul_f32_e32 v15, v12, v4
	v_mul_f32_e32 v16, 0x3fb8aa3b, v15
	v_mul_f32_e32 v17, 0xbfb8aa3b, v15
	v_exp_f32_e32 v16, v16
	v_exp_f32_e32 v17, v17
	v_mul_f32_e32 v18, v12, v8
	v_mul_f32_e32 v19, 0.15915494, v18
	v_rndne_f32_e32 v19, v19
	v_fma_f32 v18, v18, 0.15915494, -v19
	v_cos_f32_e32 v19, v18
	v_sin_f32_e32 v20, v18
	s_nop 0
	v_mul_f32_e32 v22, v16, v19
	v_mul_f32_e32 v23, v16, v20
	v_mul_f32_e32 v24, v17, v19
	v_mul_f32_e64 v25, -v17, v20
	v_add_f32_e32 v26, -1.0, v22
	v_mul_f32_e32 v27, v8, v8
	v_fmac_f32_e32 v27, v4, v4
	v_rcp_f32_e32 v27, v27
	v_mul_f32_e32 v28, v26, v4
	v_fmac_f32_e32 v28, v23, v8
	v_mul_f32_e32 v29, v23, v4
	v_fma_f32 v29, -v26, v8, v29
	v_mul_f32_e32 v28, v28, v27
	v_mul_f32_e32 v29, v29, v27
	v_mul_f32_e32 v42, v23, v23
	v_mul_f32_e32 v43, v22, v23
	v_fma_f32 v30, v22, v22, -v42
	v_add_f32_e32 v31, v43, v43
	v_mul_f32_e32 v42, v31, v31
	v_mul_f32_e32 v43, v30, v31
	v_fma_f32 v32, v30, v30, -v42
	v_add_f32_e32 v33, v43, v43
	v_mul_f32_e32 v42, v33, v33
	v_mul_f32_e32 v43, v32, v33
	v_fma_f32 v34, v32, v32, -v42
	v_add_f32_e32 v35, v43, v43
	v_mul_f32_e32 v42, v35, v35
	v_mul_f32_e32 v43, v34, v35
	v_fma_f32 v36, v34, v34, -v42
	v_add_f32_e32 v37, v43, v43
	v_mov_b32_e32 v38, 1.0
	v_mov_b32_e32 v39, 0
	v_mov_b32_e32 v40, 1.0
	v_mov_b32_e32 v41, 0
	v_mul_f32_e32 v15, v39, v23
	v_fma_f32 v42, v38, v22, -v15
	v_mul_f32_e32 v15, v38, v23
	v_fma_f32 v43, v39, v22, v15
	v_cndmask_b32_e64 v38, v38, v42, s[10:11]
	v_cndmask_b32_e64 v39, v39, v43, s[10:11]
	v_mul_f32_e32 v15, v41, v23
	v_fma_f32 v42, v40, v22, -v15
	v_mul_f32_e32 v15, v40, v23
	v_fma_f32 v43, v41, v22, v15
	v_cndmask_b32_e64 v40, v42, v40, s[10:11]
	v_cndmask_b32_e64 v41, v43, v41, s[10:11]
	v_mul_f32_e32 v15, v39, v31
	v_fma_f32 v42, v38, v30, -v15
	v_mul_f32_e32 v15, v38, v31
	v_fma_f32 v43, v39, v30, v15
	v_cndmask_b32_e64 v38, v38, v42, s[12:13]
	v_cndmask_b32_e64 v39, v39, v43, s[12:13]
	v_mul_f32_e32 v15, v41, v31
	v_fma_f32 v42, v40, v30, -v15
	v_mul_f32_e32 v15, v40, v31
	v_fma_f32 v43, v41, v30, v15
	v_cndmask_b32_e64 v40, v42, v40, s[12:13]
	v_cndmask_b32_e64 v41, v43, v41, s[12:13]
	v_mul_f32_e32 v15, v39, v33
	v_fma_f32 v42, v38, v32, -v15
	v_mul_f32_e32 v15, v38, v33
	v_fma_f32 v43, v39, v32, v15
	v_cndmask_b32_e64 v38, v38, v42, s[14:15]
	v_cndmask_b32_e64 v39, v39, v43, s[14:15]
	v_mul_f32_e32 v15, v41, v33
	v_fma_f32 v42, v40, v32, -v15
	v_mul_f32_e32 v15, v40, v33
	v_fma_f32 v43, v41, v32, v15
	v_cndmask_b32_e64 v40, v42, v40, s[14:15]
	v_cndmask_b32_e64 v41, v43, v41, s[14:15]
	v_mul_f32_e32 v15, v39, v35
	v_fma_f32 v42, v38, v34, -v15
	v_mul_f32_e32 v15, v38, v35
	v_fma_f32 v43, v39, v34, v15
	v_cndmask_b32_e64 v38, v38, v42, s[16:17]
	v_cndmask_b32_e64 v39, v39, v43, s[16:17]
	v_mul_f32_e32 v15, v41, v35
	v_fma_f32 v42, v40, v34, -v15
	v_mul_f32_e32 v15, v40, v35
	v_fma_f32 v43, v41, v34, v15
	v_cndmask_b32_e64 v40, v42, v40, s[16:17]
	v_cndmask_b32_e64 v41, v43, v41, s[16:17]
	v_mul_f32_e32 v42, v25, v25
	v_mul_f32_e32 v43, v24, v25
	v_fma_f32 v30, v24, v24, -v42
	v_add_f32_e32 v31, v43, v43
	v_mul_f32_e32 v42, v31, v31
	v_mul_f32_e32 v43, v30, v31
	v_fma_f32 v32, v30, v30, -v42
	v_add_f32_e32 v33, v43, v43
	v_mul_f32_e32 v42, v33, v33
	v_mul_f32_e32 v43, v32, v33
	v_fma_f32 v34, v32, v32, -v42
	v_add_f32_e32 v35, v43, v43
	v_mov_b32_e32 v16, 1.0
	v_mov_b32_e32 v17, 0
	v_mul_f32_e32 v15, v17, v25
	v_fma_f32 v42, v16, v24, -v15
	v_mul_f32_e32 v15, v16, v25
	v_fma_f32 v43, v17, v24, v15
	v_cndmask_b32_e64 v16, v16, v42, s[10:11]
	v_cndmask_b32_e64 v17, v17, v43, s[10:11]
	v_mul_f32_e32 v15, v17, v31
	v_fma_f32 v42, v16, v30, -v15
	v_mul_f32_e32 v15, v16, v31
	v_fma_f32 v43, v17, v30, v15
	v_cndmask_b32_e64 v16, v16, v42, s[12:13]
	v_cndmask_b32_e64 v17, v17, v43, s[12:13]
	v_mul_f32_e32 v15, v17, v33
	v_fma_f32 v42, v16, v32, -v15
	v_mul_f32_e32 v15, v16, v33
	v_fma_f32 v43, v17, v32, v15
	v_cndmask_b32_e64 v16, v16, v42, s[14:15]
	v_cndmask_b32_e64 v17, v17, v43, s[14:15]
	v_mul_f32_e32 v15, v17, v35
	v_fma_f32 v42, v16, v34, -v15
	v_mul_f32_e32 v15, v16, v35
	v_fma_f32 v43, v17, v34, v15
	v_cndmask_b32_e64 v16, v16, v42, s[16:17]
	v_cndmask_b32_e64 v17, v17, v43, s[16:17]
	v_mul_f32_e32 v15, v29, v17
	v_fma_f32 v18, v28, v16, -v15
	v_mul_f32_e32 v15, v28, v17
	v_fma_f32 v19, v29, v16, v15
	v_mul_f32_e32 v15, v29, v41
	v_fma_f32 v20, v28, v40, -v15
	v_mul_f32_e32 v15, v28, v41
	v_fma_f32 v21, v29, v40, v15
	global_store_dwordx2 v13, v[18:19], s[20:21] offset:0
	global_store_dwordx2 v13, v[38:39], s[20:21] offset:8
	global_store_dwordx2 v13, v[36:37], s[20:21] offset:64
	global_store_dwordx2 v13, v[22:23], s[20:21] offset:72
	global_store_dwordx2 v14, v[20:21], s[22:23] offset:0
	global_store_dwordx2 v14, v[36:37], s[22:23] offset:8
	s_nop 1
	v_mul_f32_e32 v15, v12, v5
	v_mul_f32_e32 v16, 0x3fb8aa3b, v15
	v_mul_f32_e32 v17, 0xbfb8aa3b, v15
	v_exp_f32_e32 v16, v16
	v_exp_f32_e32 v17, v17
	v_mul_f32_e32 v18, v12, v9
	v_mul_f32_e32 v19, 0.15915494, v18
	v_rndne_f32_e32 v19, v19
	v_fma_f32 v18, v18, 0.15915494, -v19
	v_cos_f32_e32 v19, v18
	v_sin_f32_e32 v20, v18
	s_nop 0
	v_mul_f32_e32 v22, v16, v19
	v_mul_f32_e32 v23, v16, v20
	v_mul_f32_e32 v24, v17, v19
	v_mul_f32_e64 v25, -v17, v20
	v_add_f32_e32 v26, -1.0, v22
	v_mul_f32_e32 v27, v9, v9
	v_fmac_f32_e32 v27, v5, v5
	v_rcp_f32_e32 v27, v27
	v_mul_f32_e32 v28, v26, v5
	v_fmac_f32_e32 v28, v23, v9
	v_mul_f32_e32 v29, v23, v5
	v_fma_f32 v29, -v26, v9, v29
	v_mul_f32_e32 v28, v28, v27
	v_mul_f32_e32 v29, v29, v27
	v_mul_f32_e32 v42, v23, v23
	v_mul_f32_e32 v43, v22, v23
	v_fma_f32 v30, v22, v22, -v42
	v_add_f32_e32 v31, v43, v43
	v_mul_f32_e32 v42, v31, v31
	v_mul_f32_e32 v43, v30, v31
	v_fma_f32 v32, v30, v30, -v42
	v_add_f32_e32 v33, v43, v43
	v_mul_f32_e32 v42, v33, v33
	v_mul_f32_e32 v43, v32, v33
	v_fma_f32 v34, v32, v32, -v42
	v_add_f32_e32 v35, v43, v43
	v_mul_f32_e32 v42, v35, v35
	v_mul_f32_e32 v43, v34, v35
	v_fma_f32 v36, v34, v34, -v42
	v_add_f32_e32 v37, v43, v43
	v_mov_b32_e32 v38, 1.0
	v_mov_b32_e32 v39, 0
	v_mov_b32_e32 v40, 1.0
	v_mov_b32_e32 v41, 0
	v_mul_f32_e32 v15, v39, v23
	v_fma_f32 v42, v38, v22, -v15
	v_mul_f32_e32 v15, v38, v23
	v_fma_f32 v43, v39, v22, v15
	v_cndmask_b32_e64 v38, v38, v42, s[10:11]
	v_cndmask_b32_e64 v39, v39, v43, s[10:11]
	v_mul_f32_e32 v15, v41, v23
	v_fma_f32 v42, v40, v22, -v15
	v_mul_f32_e32 v15, v40, v23
	v_fma_f32 v43, v41, v22, v15
	v_cndmask_b32_e64 v40, v42, v40, s[10:11]
	v_cndmask_b32_e64 v41, v43, v41, s[10:11]
	v_mul_f32_e32 v15, v39, v31
	v_fma_f32 v42, v38, v30, -v15
	v_mul_f32_e32 v15, v38, v31
	v_fma_f32 v43, v39, v30, v15
	v_cndmask_b32_e64 v38, v38, v42, s[12:13]
	v_cndmask_b32_e64 v39, v39, v43, s[12:13]
	v_mul_f32_e32 v15, v41, v31
	v_fma_f32 v42, v40, v30, -v15
	v_mul_f32_e32 v15, v40, v31
	v_fma_f32 v43, v41, v30, v15
	v_cndmask_b32_e64 v40, v42, v40, s[12:13]
	v_cndmask_b32_e64 v41, v43, v41, s[12:13]
	v_mul_f32_e32 v15, v39, v33
	v_fma_f32 v42, v38, v32, -v15
	v_mul_f32_e32 v15, v38, v33
	v_fma_f32 v43, v39, v32, v15
	v_cndmask_b32_e64 v38, v38, v42, s[14:15]
	v_cndmask_b32_e64 v39, v39, v43, s[14:15]
	v_mul_f32_e32 v15, v41, v33
	v_fma_f32 v42, v40, v32, -v15
	v_mul_f32_e32 v15, v40, v33
	v_fma_f32 v43, v41, v32, v15
	v_cndmask_b32_e64 v40, v42, v40, s[14:15]
	v_cndmask_b32_e64 v41, v43, v41, s[14:15]
	v_mul_f32_e32 v15, v39, v35
	v_fma_f32 v42, v38, v34, -v15
	v_mul_f32_e32 v15, v38, v35
	v_fma_f32 v43, v39, v34, v15
	v_cndmask_b32_e64 v38, v38, v42, s[16:17]
	v_cndmask_b32_e64 v39, v39, v43, s[16:17]
	v_mul_f32_e32 v15, v41, v35
	v_fma_f32 v42, v40, v34, -v15
	v_mul_f32_e32 v15, v40, v35
	v_fma_f32 v43, v41, v34, v15
	v_cndmask_b32_e64 v40, v42, v40, s[16:17]
	v_cndmask_b32_e64 v41, v43, v41, s[16:17]
	v_mul_f32_e32 v42, v25, v25
	v_mul_f32_e32 v43, v24, v25
	v_fma_f32 v30, v24, v24, -v42
	v_add_f32_e32 v31, v43, v43
	v_mul_f32_e32 v42, v31, v31
	v_mul_f32_e32 v43, v30, v31
	v_fma_f32 v32, v30, v30, -v42
	v_add_f32_e32 v33, v43, v43
	v_mul_f32_e32 v42, v33, v33
	v_mul_f32_e32 v43, v32, v33
	v_fma_f32 v34, v32, v32, -v42
	v_add_f32_e32 v35, v43, v43
	v_mov_b32_e32 v16, 1.0
	v_mov_b32_e32 v17, 0
	v_mul_f32_e32 v15, v17, v25
	v_fma_f32 v42, v16, v24, -v15
	v_mul_f32_e32 v15, v16, v25
	v_fma_f32 v43, v17, v24, v15
	v_cndmask_b32_e64 v16, v16, v42, s[10:11]
	v_cndmask_b32_e64 v17, v17, v43, s[10:11]
	v_mul_f32_e32 v15, v17, v31
	v_fma_f32 v42, v16, v30, -v15
	v_mul_f32_e32 v15, v16, v31
	v_fma_f32 v43, v17, v30, v15
	v_cndmask_b32_e64 v16, v16, v42, s[12:13]
	v_cndmask_b32_e64 v17, v17, v43, s[12:13]
	v_mul_f32_e32 v15, v17, v33
	v_fma_f32 v42, v16, v32, -v15
	v_mul_f32_e32 v15, v16, v33
	v_fma_f32 v43, v17, v32, v15
	v_cndmask_b32_e64 v16, v16, v42, s[14:15]
	v_cndmask_b32_e64 v17, v17, v43, s[14:15]
	v_mul_f32_e32 v15, v17, v35
	v_fma_f32 v42, v16, v34, -v15
	v_mul_f32_e32 v15, v16, v35
	v_fma_f32 v43, v17, v34, v15
	v_cndmask_b32_e64 v16, v16, v42, s[16:17]
	v_cndmask_b32_e64 v17, v17, v43, s[16:17]
	v_mul_f32_e32 v15, v29, v17
	v_fma_f32 v18, v28, v16, -v15
	v_mul_f32_e32 v15, v28, v17
	v_fma_f32 v19, v29, v16, v15
	v_mul_f32_e32 v15, v29, v41
	v_fma_f32 v20, v28, v40, -v15
	v_mul_f32_e32 v15, v28, v41
	v_fma_f32 v21, v29, v40, v15
	global_store_dwordx2 v13, v[18:19], s[20:21] offset:16
	global_store_dwordx2 v13, v[38:39], s[20:21] offset:24
	global_store_dwordx2 v13, v[36:37], s[20:21] offset:80
	global_store_dwordx2 v13, v[22:23], s[20:21] offset:88
	global_store_dwordx2 v14, v[20:21], s[22:23] offset:16
	global_store_dwordx2 v14, v[36:37], s[22:23] offset:24
	s_nop 1
	v_mul_f32_e32 v15, v12, v6
	v_mul_f32_e32 v16, 0x3fb8aa3b, v15
	v_mul_f32_e32 v17, 0xbfb8aa3b, v15
	v_exp_f32_e32 v16, v16
	v_exp_f32_e32 v17, v17
	v_mul_f32_e32 v18, v12, v10
	v_mul_f32_e32 v19, 0.15915494, v18
	v_rndne_f32_e32 v19, v19
	v_fma_f32 v18, v18, 0.15915494, -v19
	v_cos_f32_e32 v19, v18
	v_sin_f32_e32 v20, v18
	s_nop 0
	v_mul_f32_e32 v22, v16, v19
	v_mul_f32_e32 v23, v16, v20
	v_mul_f32_e32 v24, v17, v19
	v_mul_f32_e64 v25, -v17, v20
	v_add_f32_e32 v26, -1.0, v22
	v_mul_f32_e32 v27, v10, v10
	v_fmac_f32_e32 v27, v6, v6
	v_rcp_f32_e32 v27, v27
	v_mul_f32_e32 v28, v26, v6
	v_fmac_f32_e32 v28, v23, v10
	v_mul_f32_e32 v29, v23, v6
	v_fma_f32 v29, -v26, v10, v29
	v_mul_f32_e32 v28, v28, v27
	v_mul_f32_e32 v29, v29, v27
	v_mul_f32_e32 v42, v23, v23
	v_mul_f32_e32 v43, v22, v23
	v_fma_f32 v30, v22, v22, -v42
	v_add_f32_e32 v31, v43, v43
	v_mul_f32_e32 v42, v31, v31
	v_mul_f32_e32 v43, v30, v31
	v_fma_f32 v32, v30, v30, -v42
	v_add_f32_e32 v33, v43, v43
	v_mul_f32_e32 v42, v33, v33
	v_mul_f32_e32 v43, v32, v33
	v_fma_f32 v34, v32, v32, -v42
	v_add_f32_e32 v35, v43, v43
	v_mul_f32_e32 v42, v35, v35
	v_mul_f32_e32 v43, v34, v35
	v_fma_f32 v36, v34, v34, -v42
	v_add_f32_e32 v37, v43, v43
	v_mov_b32_e32 v38, 1.0
	v_mov_b32_e32 v39, 0
	v_mov_b32_e32 v40, 1.0
	v_mov_b32_e32 v41, 0
	v_mul_f32_e32 v15, v39, v23
	v_fma_f32 v42, v38, v22, -v15
	v_mul_f32_e32 v15, v38, v23
	v_fma_f32 v43, v39, v22, v15
	v_cndmask_b32_e64 v38, v38, v42, s[10:11]
	v_cndmask_b32_e64 v39, v39, v43, s[10:11]
	v_mul_f32_e32 v15, v41, v23
	v_fma_f32 v42, v40, v22, -v15
	v_mul_f32_e32 v15, v40, v23
	v_fma_f32 v43, v41, v22, v15
	v_cndmask_b32_e64 v40, v42, v40, s[10:11]
	v_cndmask_b32_e64 v41, v43, v41, s[10:11]
	v_mul_f32_e32 v15, v39, v31
	v_fma_f32 v42, v38, v30, -v15
	v_mul_f32_e32 v15, v38, v31
	v_fma_f32 v43, v39, v30, v15
	v_cndmask_b32_e64 v38, v38, v42, s[12:13]
	v_cndmask_b32_e64 v39, v39, v43, s[12:13]
	v_mul_f32_e32 v15, v41, v31
	v_fma_f32 v42, v40, v30, -v15
	v_mul_f32_e32 v15, v40, v31
	v_fma_f32 v43, v41, v30, v15
	v_cndmask_b32_e64 v40, v42, v40, s[12:13]
	v_cndmask_b32_e64 v41, v43, v41, s[12:13]
	v_mul_f32_e32 v15, v39, v33
	v_fma_f32 v42, v38, v32, -v15
	v_mul_f32_e32 v15, v38, v33
	v_fma_f32 v43, v39, v32, v15
	v_cndmask_b32_e64 v38, v38, v42, s[14:15]
	v_cndmask_b32_e64 v39, v39, v43, s[14:15]
	v_mul_f32_e32 v15, v41, v33
	v_fma_f32 v42, v40, v32, -v15
	v_mul_f32_e32 v15, v40, v33
	v_fma_f32 v43, v41, v32, v15
	v_cndmask_b32_e64 v40, v42, v40, s[14:15]
	v_cndmask_b32_e64 v41, v43, v41, s[14:15]
	v_mul_f32_e32 v15, v39, v35
	v_fma_f32 v42, v38, v34, -v15
	v_mul_f32_e32 v15, v38, v35
	v_fma_f32 v43, v39, v34, v15
	v_cndmask_b32_e64 v38, v38, v42, s[16:17]
	v_cndmask_b32_e64 v39, v39, v43, s[16:17]
	v_mul_f32_e32 v15, v41, v35
	v_fma_f32 v42, v40, v34, -v15
	v_mul_f32_e32 v15, v40, v35
	v_fma_f32 v43, v41, v34, v15
	v_cndmask_b32_e64 v40, v42, v40, s[16:17]
	v_cndmask_b32_e64 v41, v43, v41, s[16:17]
	v_mul_f32_e32 v42, v25, v25
	v_mul_f32_e32 v43, v24, v25
	v_fma_f32 v30, v24, v24, -v42
	v_add_f32_e32 v31, v43, v43
	v_mul_f32_e32 v42, v31, v31
	v_mul_f32_e32 v43, v30, v31
	v_fma_f32 v32, v30, v30, -v42
	v_add_f32_e32 v33, v43, v43
	v_mul_f32_e32 v42, v33, v33
	v_mul_f32_e32 v43, v32, v33
	v_fma_f32 v34, v32, v32, -v42
	v_add_f32_e32 v35, v43, v43
	v_mov_b32_e32 v16, 1.0
	v_mov_b32_e32 v17, 0
	v_mul_f32_e32 v15, v17, v25
	v_fma_f32 v42, v16, v24, -v15
	v_mul_f32_e32 v15, v16, v25
	v_fma_f32 v43, v17, v24, v15
	v_cndmask_b32_e64 v16, v16, v42, s[10:11]
	v_cndmask_b32_e64 v17, v17, v43, s[10:11]
	v_mul_f32_e32 v15, v17, v31
	v_fma_f32 v42, v16, v30, -v15
	v_mul_f32_e32 v15, v16, v31
	v_fma_f32 v43, v17, v30, v15
	v_cndmask_b32_e64 v16, v16, v42, s[12:13]
	v_cndmask_b32_e64 v17, v17, v43, s[12:13]
	v_mul_f32_e32 v15, v17, v33
	v_fma_f32 v42, v16, v32, -v15
	v_mul_f32_e32 v15, v16, v33
	v_fma_f32 v43, v17, v32, v15
	v_cndmask_b32_e64 v16, v16, v42, s[14:15]
	v_cndmask_b32_e64 v17, v17, v43, s[14:15]
	v_mul_f32_e32 v15, v17, v35
	v_fma_f32 v42, v16, v34, -v15
	v_mul_f32_e32 v15, v16, v35
	v_fma_f32 v43, v17, v34, v15
	v_cndmask_b32_e64 v16, v16, v42, s[16:17]
	v_cndmask_b32_e64 v17, v17, v43, s[16:17]
	v_mul_f32_e32 v15, v29, v17
	v_fma_f32 v18, v28, v16, -v15
	v_mul_f32_e32 v15, v28, v17
	v_fma_f32 v19, v29, v16, v15
	v_mul_f32_e32 v15, v29, v41
	v_fma_f32 v20, v28, v40, -v15
	v_mul_f32_e32 v15, v28, v41
	v_fma_f32 v21, v29, v40, v15
	global_store_dwordx2 v13, v[18:19], s[20:21] offset:32
	global_store_dwordx2 v13, v[38:39], s[20:21] offset:40
	global_store_dwordx2 v13, v[36:37], s[20:21] offset:96
	global_store_dwordx2 v13, v[22:23], s[20:21] offset:104
	global_store_dwordx2 v14, v[20:21], s[22:23] offset:32
	global_store_dwordx2 v14, v[36:37], s[22:23] offset:40
	s_nop 1
	v_mul_f32_e32 v15, v12, v7
	v_mul_f32_e32 v16, 0x3fb8aa3b, v15
	v_mul_f32_e32 v17, 0xbfb8aa3b, v15
	v_exp_f32_e32 v16, v16
	v_exp_f32_e32 v17, v17
	v_mul_f32_e32 v18, v12, v11
	v_mul_f32_e32 v19, 0.15915494, v18
	v_rndne_f32_e32 v19, v19
	v_fma_f32 v18, v18, 0.15915494, -v19
	v_cos_f32_e32 v19, v18
	v_sin_f32_e32 v20, v18
	s_nop 0
	v_mul_f32_e32 v22, v16, v19
	v_mul_f32_e32 v23, v16, v20
	v_mul_f32_e32 v24, v17, v19
	v_mul_f32_e64 v25, -v17, v20
	v_add_f32_e32 v26, -1.0, v22
	v_mul_f32_e32 v27, v11, v11
	v_fmac_f32_e32 v27, v7, v7
	v_rcp_f32_e32 v27, v27
	v_mul_f32_e32 v28, v26, v7
	v_fmac_f32_e32 v28, v23, v11
	v_mul_f32_e32 v29, v23, v7
	v_fma_f32 v29, -v26, v11, v29
	v_mul_f32_e32 v28, v28, v27
	v_mul_f32_e32 v29, v29, v27
	v_mul_f32_e32 v42, v23, v23
	v_mul_f32_e32 v43, v22, v23
	v_fma_f32 v30, v22, v22, -v42
	v_add_f32_e32 v31, v43, v43
	v_mul_f32_e32 v42, v31, v31
	v_mul_f32_e32 v43, v30, v31
	v_fma_f32 v32, v30, v30, -v42
	v_add_f32_e32 v33, v43, v43
	v_mul_f32_e32 v42, v33, v33
	v_mul_f32_e32 v43, v32, v33
	v_fma_f32 v34, v32, v32, -v42
	v_add_f32_e32 v35, v43, v43
	v_mul_f32_e32 v42, v35, v35
	v_mul_f32_e32 v43, v34, v35
	v_fma_f32 v36, v34, v34, -v42
	v_add_f32_e32 v37, v43, v43
	v_mov_b32_e32 v38, 1.0
	v_mov_b32_e32 v39, 0
	v_mov_b32_e32 v40, 1.0
	v_mov_b32_e32 v41, 0
	v_mul_f32_e32 v15, v39, v23
	v_fma_f32 v42, v38, v22, -v15
	v_mul_f32_e32 v15, v38, v23
	v_fma_f32 v43, v39, v22, v15
	v_cndmask_b32_e64 v38, v38, v42, s[10:11]
	v_cndmask_b32_e64 v39, v39, v43, s[10:11]
	v_mul_f32_e32 v15, v41, v23
	v_fma_f32 v42, v40, v22, -v15
	v_mul_f32_e32 v15, v40, v23
	v_fma_f32 v43, v41, v22, v15
	v_cndmask_b32_e64 v40, v42, v40, s[10:11]
	v_cndmask_b32_e64 v41, v43, v41, s[10:11]
	v_mul_f32_e32 v15, v39, v31
	v_fma_f32 v42, v38, v30, -v15
	v_mul_f32_e32 v15, v38, v31
	v_fma_f32 v43, v39, v30, v15
	v_cndmask_b32_e64 v38, v38, v42, s[12:13]
	v_cndmask_b32_e64 v39, v39, v43, s[12:13]
	v_mul_f32_e32 v15, v41, v31
	v_fma_f32 v42, v40, v30, -v15
	v_mul_f32_e32 v15, v40, v31
	v_fma_f32 v43, v41, v30, v15
	v_cndmask_b32_e64 v40, v42, v40, s[12:13]
	v_cndmask_b32_e64 v41, v43, v41, s[12:13]
	v_mul_f32_e32 v15, v39, v33
	v_fma_f32 v42, v38, v32, -v15
	v_mul_f32_e32 v15, v38, v33
	v_fma_f32 v43, v39, v32, v15
	v_cndmask_b32_e64 v38, v38, v42, s[14:15]
	v_cndmask_b32_e64 v39, v39, v43, s[14:15]
	v_mul_f32_e32 v15, v41, v33
	v_fma_f32 v42, v40, v32, -v15
	v_mul_f32_e32 v15, v40, v33
	v_fma_f32 v43, v41, v32, v15
	v_cndmask_b32_e64 v40, v42, v40, s[14:15]
	v_cndmask_b32_e64 v41, v43, v41, s[14:15]
	v_mul_f32_e32 v15, v39, v35
	v_fma_f32 v42, v38, v34, -v15
	v_mul_f32_e32 v15, v38, v35
	v_fma_f32 v43, v39, v34, v15
	v_cndmask_b32_e64 v38, v38, v42, s[16:17]
	v_cndmask_b32_e64 v39, v39, v43, s[16:17]
	v_mul_f32_e32 v15, v41, v35
	v_fma_f32 v42, v40, v34, -v15
	v_mul_f32_e32 v15, v40, v35
	v_fma_f32 v43, v41, v34, v15
	v_cndmask_b32_e64 v40, v42, v40, s[16:17]
	v_cndmask_b32_e64 v41, v43, v41, s[16:17]
	v_mul_f32_e32 v42, v25, v25
	v_mul_f32_e32 v43, v24, v25
	v_fma_f32 v30, v24, v24, -v42
	v_add_f32_e32 v31, v43, v43
	v_mul_f32_e32 v42, v31, v31
	v_mul_f32_e32 v43, v30, v31
	v_fma_f32 v32, v30, v30, -v42
	v_add_f32_e32 v33, v43, v43
	v_mul_f32_e32 v42, v33, v33
	v_mul_f32_e32 v43, v32, v33
	v_fma_f32 v34, v32, v32, -v42
	v_add_f32_e32 v35, v43, v43
	v_mov_b32_e32 v16, 1.0
	v_mov_b32_e32 v17, 0
	v_mul_f32_e32 v15, v17, v25
	v_fma_f32 v42, v16, v24, -v15
	v_mul_f32_e32 v15, v16, v25
	v_fma_f32 v43, v17, v24, v15
	v_cndmask_b32_e64 v16, v16, v42, s[10:11]
	v_cndmask_b32_e64 v17, v17, v43, s[10:11]
	v_mul_f32_e32 v15, v17, v31
	v_fma_f32 v42, v16, v30, -v15
	v_mul_f32_e32 v15, v16, v31
	v_fma_f32 v43, v17, v30, v15
	v_cndmask_b32_e64 v16, v16, v42, s[12:13]
	v_cndmask_b32_e64 v17, v17, v43, s[12:13]
	v_mul_f32_e32 v15, v17, v33
	v_fma_f32 v42, v16, v32, -v15
	v_mul_f32_e32 v15, v16, v33
	v_fma_f32 v43, v17, v32, v15
	v_cndmask_b32_e64 v16, v16, v42, s[14:15]
	v_cndmask_b32_e64 v17, v17, v43, s[14:15]
	v_mul_f32_e32 v15, v17, v35
	v_fma_f32 v42, v16, v34, -v15
	v_mul_f32_e32 v15, v16, v35
	v_fma_f32 v43, v17, v34, v15
	v_cndmask_b32_e64 v16, v16, v42, s[16:17]
	v_cndmask_b32_e64 v17, v17, v43, s[16:17]
	v_mul_f32_e32 v15, v29, v17
	v_fma_f32 v18, v28, v16, -v15
	v_mul_f32_e32 v15, v28, v17
	v_fma_f32 v19, v29, v16, v15
	v_mul_f32_e32 v15, v29, v41
	v_fma_f32 v20, v28, v40, -v15
	v_mul_f32_e32 v15, v28, v41
	v_fma_f32 v21, v29, v40, v15
	global_store_dwordx2 v13, v[18:19], s[20:21] offset:48
	global_store_dwordx2 v13, v[38:39], s[20:21] offset:56
	global_store_dwordx2 v13, v[36:37], s[20:21] offset:112
	global_store_dwordx2 v13, v[22:23], s[20:21] offset:120
	global_store_dwordx2 v14, v[20:21], s[22:23] offset:48
	global_store_dwordx2 v14, v[36:37], s[22:23] offset:56
	s_nop 1
.Lstab_end:
	v_and_b32_e32 v2, 64, v200
	v_xor_b32_e32 v1, 1, v200
	v_add_u32_e32 v2, 64, v2
	v_cmp_lt_i32_e32 vcc, v1, v2
	v_readlane_b32 s0, v245, 38
	v_readlane_b32 s1, v245, 39
	v_cndmask_b32_e32 v1, v200, v1, vcc
	v_lshlrev_b32_e32 v21, 2, v1
	v_xor_b32_e32 v1, 2, v200
	v_cmp_lt_i32_e32 vcc, v1, v2
	s_and_b64 s[0:1], s[0:1], exec
	v_readlane_b32 s8, v247, 6
	v_cndmask_b32_e32 v1, v200, v1, vcc
	s_waitcnt lgkmcnt(0)
	v_lshlrev_b32_e32 v22, 2, v1
	v_xor_b32_e32 v1, 4, v200
	v_cmp_lt_i32_e32 vcc, v1, v2
	v_readlane_b32 s17, v247, 15
	v_readlane_b32 s0, v247, 29
	v_cndmask_b32_e32 v1, v200, v1, vcc
	v_readlane_b32 s9, v247, 7
	v_readlane_b32 s16, v247, 14
	v_readlane_b32 s1, v247, 30
	s_cselect_b32 s17, s8, s0
	s_mul_i32 s0, s24, 0x7800
	v_lshlrev_b32_e32 v23, 2, v1
	v_xor_b32_e32 v1, 8, v200
	s_cselect_b32 s16, s9, s1
	s_ashr_i32 s1, s0, 31
	v_cmp_lt_i32_e32 vcc, v1, v2
	v_readlane_b32 s18, v247, 16
	s_lshl_b64 s[0:1], s[0:1], 2
	v_cndmask_b32_e32 v1, v200, v1, vcc
	v_readlane_b32 s19, v247, 17
	s_add_u32 s18, s4, s0
	v_lshlrev_b32_e32 v24, 2, v1
	v_xor_b32_e32 v1, 16, v200
	s_addc_u32 s19, s5, s1
	v_readlane_b32 s0, v244, 14
	v_cmp_lt_i32_e32 vcc, v1, v2
	v_readlane_b32 s1, v244, 15
	s_add_u32 s0, s4, s0
	v_cndmask_b32_e32 v1, v200, v1, vcc
	s_addc_u32 s1, s5, s1
	v_lshlrev_b32_e32 v25, 2, v1
	v_xor_b32_e32 v1, 32, v200
	v_lshlrev_b32_e32 v136, 4, v205
	v_cmp_lt_i32_e32 vcc, v1, v2
	v_lshl_add_u64 v[2:3], s[0:1], 0, v[136:137]
	s_mov_b64 s[0:1], 0x100000
	v_lshl_add_u64 v[16:17], v[2:3], 0, s[0:1]
	v_readlane_b32 s0, v245, 45
	v_lshlrev_b32_e32 v136, 3, v205
	v_readlane_b32 s1, v245, 46
	v_readlane_b32 s6, v245, 41
	v_lshlrev_b32_e32 v0, 2, v205
	v_lshl_add_u64 v[18:19], s[0:1], 0, v[136:137]
	v_readlane_b32 s0, v245, 24
	v_readlane_b32 s1, v245, 25
	s_add_u32 s0, s6, s0
	v_readlane_b32 s6, v245, 42
	v_cndmask_b32_e32 v1, v200, v1, vcc
	v_or_b32_e32 v2, 0x100, v0
	v_or_b32_e32 v4, 0x200, v0
	v_or_b32_e32 v6, 0x300, v0
	s_addc_u32 s1, s6, s1
	v_readlane_b32 s6, v245, 21
	v_lshlrev_b32_e32 v26, 2, v1
	v_lshlrev_b32_e32 v27, 2, v0
	v_lshlrev_b32_e32 v28, 2, v2
	v_lshlrev_b32_e32 v29, 2, v4
	v_lshlrev_b32_e32 v30, 2, v6
	v_readlane_b32 s7, v245, 22
	v_readlane_b32 s10, v247, 8
	v_readlane_b32 s11, v247, 9
	v_readlane_b32 s12, v247, 10
	v_readlane_b32 s13, v247, 11
	v_readlane_b32 s14, v247, 12
	v_readlane_b32 s15, v247, 13
	v_readlane_b32 s20, v247, 18
	v_readlane_b32 s21, v247, 19
	v_readlane_b32 s22, v247, 20
	v_readlane_b32 s23, v247, 21
	s_branch .LBB0_616
